# epilogue overlap of the two wave groups (deferred closing barrier for the younger group) on all 11 GEMM phases
# speedup vs baseline: 1.0196x; 1.0070x over previous
; #define G_STAGE(bufoff, gbase, o0, h64) do { \
;         __builtin_amdgcn_global_load_lds((const unsigned*)((const char*)(gbase) + (o0)), (LAS unsigned*)(lds + (bufoff) + ldsw), 16, 0, 0); \
;         __builtin_amdgcn_global_load_lds((const unsigned*)((const char*)(gbase) + (h64) + (o0)), (LAS unsigned*)(lds + (bufoff) + ldsw + 8192), 16, 0, 0); } while (0)
; #define G_LDA(dst, b, h) do { _Pragma("unroll") for (int m = 0; m < 4; ++m) _Pragma("unroll") for (int k = 0; k < 2; ++k) dst[m][k] = *(const LAS bf16x8*)(lds + G_SA(b, h) + aoff + m * 2048 + k * 1024); } while (0)
; #define G_LDB(dst, b, h) do { _Pragma("unroll") for (int n = 0; n < 2; ++n) _Pragma("unroll") for (int k = 0; k < 2; ++k) dst[n][k] = *(const LAS bf16x8*)(lds + G_SB(b, h) + boff + n * 2048 + k * 1024); } while (0)
; #define G_WAIT_L(n) asm volatile("s_waitcnt lgkmcnt(" #n ")" ::: "memory")
; #define G_BAR __builtin_amdgcn_s_barrier()
; #define G_SCHED __builtin_amdgcn_sched_barrier(0)
;     ...
;         for (int t = 0; t < nt; t += 2) {
;             const bool last = (t == nt - 2);
;             const char* a1 = cA + (size_t)(t + 1) * ckA;
;             const char* a2 = last ? nA : cA + (size_t)(t + 2) * ckA; const char* b2 = last ? nB : cB + (size_t)(t + 2) * kB;
;             const char* a3 = a2 + ckA; const char* b3 = b2 + kB;
;             G_LDB(B0, 0, 0); G_SCHED; G_LDA(At, 0, 0); G_STAGE(G_SA(1, 1), a1 + chA, cA0, qA);
;             G_WAIT_L(8); G_BAR; G_WAIT_L(0); G_MMA(0, 0, At, B0); G_BAR; G_SCHED;
;             G_LDB(B1, 0, 1); G_STAGE(G_SB(0, 0), b2, cB0, qB);
;             G_BAR; G_WAIT_L(0); G_MMA(0, 1, At, B1); G_BAR;
;             G_LDA(At, 0, 1); G_STAGE(G_SA(0, 0), a2, cA0, qA);
;             G_BAR; G_WAIT_L(0); G_MMA(1, 0, At, B0); G_BAR; G_SCHED;
.LBB0_742:
	s_add_u32 s36, s2, s30
	s_addc_u32 s37, s3, s31
	s_add_u32 s19, s36, 0x100
	s_addc_u32 s35, s37, 0
	s_and_b64 s[4:5], s[26:27], exec
	s_cselect_b32 s34, s12, s19
	s_cselect_b32 s35, s13, s35
	s_add_u32 s4, s20, s30
	s_addc_u32 s5, s21, s31
	s_add_u32 s19, s4, 0x100
	s_addc_u32 s30, s5, 0
	s_add_i32 s44, 0, 0x10000
	v_add_u32_e32 v0, s44, v183
	ds_read_b128 v[56:59], v0
	ds_read_b128 v[60:63], v0 offset:1024
	ds_read_b128 v[144:147], v0 offset:2048
	ds_read_b128 v[148:151], v0 offset:3072
	s_and_b64 s[4:5], s[26:27], exec
	s_cselect_b32 s26, s16, s19
	s_cselect_b32 s27, s17, s30
	s_add_i32 s48, 0, 0x14000
	s_add_i32 s31, 0, 0x18000
	s_add_i32 s19, 0, 0x1c000
	s_add_i32 s49, s44, s38
	s_add_i32 s63, s48, s38
	s_add_i32 s30, s31, s38
	s_add_i32 s65, s19, s38
	s_add_i32 m0, s43, 0xc000
	s_add_i32 s45, s43, 0xe000
	s_add_i32 s66, s49, 0x2000
	s_add_i32 s62, s63, 0x2000
	s_add_i32 s67, s30, 0x2000
	s_add_i32 s64, s65, 0x2000
	v_lshl_add_u64 v[166:167], s[36:37], 0, v[160:161]
	s_mov_b64 s[4:5], 0x200080
	v_lshl_add_u64 v[180:181], v[166:167], 0, s[4:5]
	s_mov_b64 s[4:5], 0x300080
	ds_read_b128 v[152:155], v184
	ds_read_b128 v[156:159], v184 offset:1024
	ds_read_b128 v[162:165], v184 offset:2048
	ds_read_b128 v[172:175], v184 offset:3072
	ds_read_b128 v[176:179], v184 offset:4096
	ds_read_b128 v[196:199], v184 offset:5120
	ds_read_b128 v[200:203], v184 offset:6144
	ds_read_b128 v[204:207], v184 offset:7168
	global_load_lds_dwordx4 v[180:181], off
	v_lshl_add_u64 v[166:167], v[166:167], 0, s[4:5]
	s_mov_b32 m0, s45
	s_nop 0
	global_load_lds_dwordx4 v[166:167], off
	s_waitcnt lgkmcnt(8)
	s_barrier
	s_waitcnt lgkmcnt(0)
	s_setprio 3
	s_waitcnt lgkmcnt(0)
	v_mfma_f32_16x16x32_bf16 v[140:143], v[56:59], v[152:155], v[140:143]
	v_mfma_f32_16x16x32_bf16 v[136:139], v[144:147], v[152:155], v[136:139]
	v_mfma_f32_16x16x32_bf16 v[124:127], v[56:59], v[162:165], v[124:127]
	v_mfma_f32_16x16x32_bf16 v[120:123], v[144:147], v[162:165], v[120:123]
	v_mfma_f32_16x16x32_bf16 v[108:111], v[56:59], v[176:179], v[108:111]
	v_mfma_f32_16x16x32_bf16 v[104:107], v[144:147], v[176:179], v[104:107]
	v_mfma_f32_16x16x32_bf16 v[92:95], v[56:59], v[200:203], v[92:95]
	v_mfma_f32_16x16x32_bf16 v[88:91], v[144:147], v[200:203], v[88:91]
	v_mfma_f32_16x16x32_bf16 v[140:143], v[60:63], v[156:159], v[140:143]
	v_mfma_f32_16x16x32_bf16 v[136:139], v[148:151], v[156:159], v[136:139]
	v_mfma_f32_16x16x32_bf16 v[124:127], v[60:63], v[172:175], v[124:127]
	v_mfma_f32_16x16x32_bf16 v[120:123], v[148:151], v[172:175], v[120:123]
	v_mfma_f32_16x16x32_bf16 v[108:111], v[60:63], v[196:199], v[108:111]
	v_mfma_f32_16x16x32_bf16 v[104:107], v[148:151], v[196:199], v[104:107]
	v_mfma_f32_16x16x32_bf16 v[92:95], v[60:63], v[204:207], v[92:95]
	v_mfma_f32_16x16x32_bf16 v[88:91], v[148:151], v[204:207], v[88:91]
	s_setprio 0
	s_barrier
	s_mov_b32 m0, s49
	v_add_u32_e32 v0, s48, v183
	v_lshl_add_u64 v[166:167], s[26:27], 0, v[2:3]
	ds_read_b128 v[208:211], v0
	ds_read_b128 v[212:215], v0 offset:1024
	ds_read_b128 v[216:219], v0 offset:2048
	ds_read_b128 v[220:223], v0 offset:3072
	global_load_lds_dwordx4 v[166:167], off
	v_lshl_add_u64 v[180:181], v[166:167], 0, s[92:93]
	s_mov_b32 m0, s66
	s_nop 0
	global_load_lds_dwordx4 v[180:181], off
	s_barrier
	s_waitcnt lgkmcnt(0)
	s_setprio 3
	s_waitcnt lgkmcnt(0)
	v_mfma_f32_16x16x32_bf16 v[132:135], v[208:211], v[152:155], v[132:135]
	v_mfma_f32_16x16x32_bf16 v[128:131], v[216:219], v[152:155], v[128:131]
	v_mfma_f32_16x16x32_bf16 v[116:119], v[208:211], v[162:165], v[116:119]
	v_mfma_f32_16x16x32_bf16 v[112:115], v[216:219], v[162:165], v[112:115]
	v_mfma_f32_16x16x32_bf16 v[100:103], v[208:211], v[176:179], v[100:103]
	v_mfma_f32_16x16x32_bf16 v[96:99], v[216:219], v[176:179], v[96:99]
	v_mfma_f32_16x16x32_bf16 v[84:87], v[208:211], v[200:203], v[84:87]
	v_mfma_f32_16x16x32_bf16 v[80:83], v[216:219], v[200:203], v[80:83]
	v_mfma_f32_16x16x32_bf16 v[132:135], v[212:215], v[156:159], v[132:135]
	v_mfma_f32_16x16x32_bf16 v[128:131], v[220:223], v[156:159], v[128:131]
	v_mfma_f32_16x16x32_bf16 v[116:119], v[212:215], v[172:175], v[116:119]
	v_mfma_f32_16x16x32_bf16 v[112:115], v[220:223], v[172:175], v[112:115]
	v_mfma_f32_16x16x32_bf16 v[100:103], v[212:215], v[196:199], v[100:103]
	v_mfma_f32_16x16x32_bf16 v[96:99], v[220:223], v[196:199], v[96:99]
	v_mfma_f32_16x16x32_bf16 v[84:87], v[212:215], v[204:207], v[84:87]
	v_mfma_f32_16x16x32_bf16 v[80:83], v[220:223], v[204:207], v[80:83]
	s_setprio 0
	s_mov_b32 m0, s43
	v_lshl_add_u64 v[180:181], s[34:35], 0, v[160:161]
	s_barrier
	ds_read_b128 v[152:155], v184 offset:16384
	ds_read_b128 v[156:159], v184 offset:17408
	ds_read_b128 v[162:165], v184 offset:18432
	ds_read_b128 v[172:175], v184 offset:19456
	ds_read_b128 v[176:179], v184 offset:20480
	ds_read_b128 v[196:199], v184 offset:21504
	ds_read_b128 v[200:203], v184 offset:22528
	ds_read_b128 v[204:207], v184 offset:23552
	global_load_lds_dwordx4 v[180:181], off
	v_lshl_add_u64 v[224:225], v[180:181], 0, s[88:89]
	s_mov_b32 m0, s50
	s_nop 0
	global_load_lds_dwordx4 v[224:225], off
	s_barrier
; #define G_STAGE(bufoff, gbase, o0, h64) do { \
;         __builtin_amdgcn_global_load_lds((const unsigned*)((const char*)(gbase) + (o0)), (LAS unsigned*)(lds + (bufoff) + ldsw), 16, 0, 0); \
;         __builtin_amdgcn_global_load_lds((const unsigned*)((const char*)(gbase) + (h64) + (o0)), (LAS unsigned*)(lds + (bufoff) + ldsw + 8192), 16, 0, 0); } while (0)
; #define G_LDA(dst, b, h) do { _Pragma("unroll") for (int m = 0; m < 4; ++m) _Pragma("unroll") for (int k = 0; k < 2; ++k) dst[m][k] = *(const LAS bf16x8*)(lds + G_SA(b, h) + aoff + m * 2048 + k * 1024); } while (0)
; #define G_LDB(dst, b, h) do { _Pragma("unroll") for (int n = 0; n < 2; ++n) _Pragma("unroll") for (int k = 0; k < 2; ++k) dst[n][k] = *(const LAS bf16x8*)(lds + G_SB(b, h) + boff + n * 2048 + k * 1024); } while (0)
; #define G_WAIT_V(n) asm volatile("s_waitcnt vmcnt(" #n ")" ::: "memory")
; #define G_WAIT_L(n) asm volatile("s_waitcnt lgkmcnt(" #n ")" ::: "memory")
; #define G_BAR __builtin_amdgcn_s_barrier()
; #define G_SCHED __builtin_amdgcn_sched_barrier(0)
;     ...
;             G_BAR; G_WAIT_L(0); G_MMA(1, 0, At, B0); G_BAR; G_SCHED;
;             G_STAGE(G_SB(0, 1), b2 + chB, cB0, qB);
;             G_WAIT_V(6); G_BAR; G_MMA(1, 1, At, B1); G_BAR;
;             G_LDB(B0, 1, 0); G_SCHED; G_LDA(At, 1, 0); G_STAGE(G_SA(0, 1), a2 + chA, cA0, qA);
;             G_WAIT_L(8); G_BAR; G_WAIT_L(0); G_MMA(0, 0, At, B0); G_BAR; G_SCHED;
;             G_LDB(B1, 1, 1); G_STAGE(G_SB(1, 0), b3, cB0, qB);
	s_waitcnt lgkmcnt(0)
	s_setprio 3
	s_waitcnt lgkmcnt(0)
	v_mfma_f32_16x16x32_bf16 v[76:79], v[56:59], v[152:155], v[76:79]
	v_mfma_f32_16x16x32_bf16 v[72:75], v[144:147], v[152:155], v[72:75]
	v_mfma_f32_16x16x32_bf16 v[52:55], v[56:59], v[162:165], v[52:55]
	v_mfma_f32_16x16x32_bf16 v[48:51], v[144:147], v[162:165], v[48:51]
	v_mfma_f32_16x16x32_bf16 v[36:39], v[56:59], v[176:179], v[36:39]
	v_mfma_f32_16x16x32_bf16 v[32:35], v[144:147], v[176:179], v[32:35]
	v_mfma_f32_16x16x32_bf16 v[20:23], v[56:59], v[200:203], v[20:23]
	v_mfma_f32_16x16x32_bf16 v[16:19], v[144:147], v[200:203], v[16:19]
	v_mfma_f32_16x16x32_bf16 v[76:79], v[60:63], v[156:159], v[76:79]
	v_mfma_f32_16x16x32_bf16 v[72:75], v[148:151], v[156:159], v[72:75]
	v_mfma_f32_16x16x32_bf16 v[52:55], v[60:63], v[172:175], v[52:55]
	v_mfma_f32_16x16x32_bf16 v[48:51], v[148:151], v[172:175], v[48:51]
	v_mfma_f32_16x16x32_bf16 v[36:39], v[60:63], v[196:199], v[36:39]
	v_mfma_f32_16x16x32_bf16 v[32:35], v[148:151], v[196:199], v[32:35]
	v_mfma_f32_16x16x32_bf16 v[20:23], v[60:63], v[204:207], v[20:23]
	v_mfma_f32_16x16x32_bf16 v[16:19], v[148:151], v[204:207], v[16:19]
	s_setprio 0
	s_barrier
	s_mov_b32 m0, s63
	v_lshl_add_u64 v[56:57], v[166:167], 0, s[82:83]
	global_load_lds_dwordx4 v[56:57], off
	v_lshl_add_u64 v[56:57], v[166:167], 0, s[94:95]
	s_mov_b32 m0, s62
	s_nop 0
	global_load_lds_dwordx4 v[56:57], off
	s_waitcnt vmcnt(6)
	s_barrier
	s_setprio 3
	v_mfma_f32_16x16x32_bf16 v[44:47], v[208:211], v[162:165], v[44:47]
	v_mfma_f32_16x16x32_bf16 v[40:43], v[216:219], v[162:165], v[40:43]
	v_mfma_f32_16x16x32_bf16 v[28:31], v[208:211], v[176:179], v[28:31]
	v_mfma_f32_16x16x32_bf16 v[24:27], v[216:219], v[176:179], v[24:27]
	v_mfma_f32_16x16x32_bf16 v[12:15], v[208:211], v[200:203], v[12:15]
	v_mfma_f32_16x16x32_bf16 v[8:11], v[216:219], v[200:203], v[8:11]
	v_mfma_f32_16x16x32_bf16 v[56:59], v[208:211], v[152:155], v[68:71]
	v_mfma_f32_16x16x32_bf16 v[60:63], v[216:219], v[152:155], v[64:67]
	v_mfma_f32_16x16x32_bf16 v[44:47], v[212:215], v[172:175], v[44:47]
	v_mfma_f32_16x16x32_bf16 v[40:43], v[220:223], v[172:175], v[40:43]
	v_mfma_f32_16x16x32_bf16 v[28:31], v[212:215], v[196:199], v[28:31]
	v_mfma_f32_16x16x32_bf16 v[24:27], v[220:223], v[196:199], v[24:27]
	v_mfma_f32_16x16x32_bf16 v[12:15], v[212:215], v[204:207], v[12:15]
	v_mfma_f32_16x16x32_bf16 v[8:11], v[220:223], v[204:207], v[8:11]
	v_mfma_f32_16x16x32_bf16 v[56:59], v[212:215], v[156:159], v[56:59]
	v_mfma_f32_16x16x32_bf16 v[60:63], v[220:223], v[156:159], v[60:63]
	s_setprio 0
	v_add_u32_e32 v0, s31, v183
	s_barrier
	ds_read_b128 v[64:67], v0
	ds_read_b128 v[68:71], v0 offset:1024
	ds_read_b128 v[144:147], v0 offset:2048
	ds_read_b128 v[148:151], v0 offset:3072
	s_mov_b32 m0, s51
	v_lshl_add_u64 v[208:209], v[180:181], 0, s[86:87]
	ds_read_b128 v[152:155], v184 offset:32768
	ds_read_b128 v[156:159], v184 offset:33792
	ds_read_b128 v[162:165], v184 offset:34816
	ds_read_b128 v[172:175], v184 offset:35840
	ds_read_b128 v[176:179], v184 offset:36864
	ds_read_b128 v[196:199], v184 offset:37888
	ds_read_b128 v[200:203], v184 offset:38912
	ds_read_b128 v[204:207], v184 offset:39936
	global_load_lds_dwordx4 v[208:209], off
	v_lshl_add_u64 v[208:209], v[180:181], 0, s[96:97]
	s_mov_b32 m0, s52
	s_nop 0
	global_load_lds_dwordx4 v[208:209], off
	s_waitcnt lgkmcnt(8)
	s_barrier
	s_waitcnt lgkmcnt(0)
	s_setprio 3
	s_waitcnt lgkmcnt(0)
	v_mfma_f32_16x16x32_bf16 v[140:143], v[64:67], v[152:155], v[140:143]
	v_mfma_f32_16x16x32_bf16 v[136:139], v[144:147], v[152:155], v[136:139]
	v_mfma_f32_16x16x32_bf16 v[124:127], v[64:67], v[162:165], v[124:127]
	v_mfma_f32_16x16x32_bf16 v[120:123], v[144:147], v[162:165], v[120:123]
	v_mfma_f32_16x16x32_bf16 v[108:111], v[64:67], v[176:179], v[108:111]
	v_mfma_f32_16x16x32_bf16 v[104:107], v[144:147], v[176:179], v[104:107]
	v_mfma_f32_16x16x32_bf16 v[92:95], v[64:67], v[200:203], v[92:95]
	v_mfma_f32_16x16x32_bf16 v[88:91], v[144:147], v[200:203], v[88:91]
	v_mfma_f32_16x16x32_bf16 v[140:143], v[68:71], v[156:159], v[140:143]
	v_mfma_f32_16x16x32_bf16 v[136:139], v[148:151], v[156:159], v[136:139]
	v_mfma_f32_16x16x32_bf16 v[124:127], v[68:71], v[172:175], v[124:127]
	v_mfma_f32_16x16x32_bf16 v[120:123], v[148:151], v[172:175], v[120:123]
	v_mfma_f32_16x16x32_bf16 v[108:111], v[68:71], v[196:199], v[108:111]
	v_mfma_f32_16x16x32_bf16 v[104:107], v[148:151], v[196:199], v[104:107]
	v_mfma_f32_16x16x32_bf16 v[92:95], v[68:71], v[204:207], v[92:95]
	v_mfma_f32_16x16x32_bf16 v[88:91], v[148:151], v[204:207], v[88:91]
	s_setprio 0
	s_barrier
	s_mov_b32 m0, s30
	v_add_u32_e32 v0, s19, v183
	v_lshl_add_u64 v[224:225], v[166:167], 0, s[46:47]
	ds_read_b128 v[208:211], v0
	ds_read_b128 v[212:215], v0 offset:1024
	ds_read_b128 v[216:219], v0 offset:2048
	ds_read_b128 v[220:223], v0 offset:3072
	global_load_lds_dwordx4 v[224:225], off
	v_lshl_add_u64 v[224:225], v[166:167], 0, s[70:71]
	s_mov_b32 m0, s67
	s_nop 0
	global_load_lds_dwordx4 v[224:225], off
	s_barrier
; #define G_STAGE(bufoff, gbase, o0, h64) do { \
;         __builtin_amdgcn_global_load_lds((const unsigned*)((const char*)(gbase) + (o0)), (LAS unsigned*)(lds + (bufoff) + ldsw), 16, 0, 0); \
;         __builtin_amdgcn_global_load_lds((const unsigned*)((const char*)(gbase) + (h64) + (o0)), (LAS unsigned*)(lds + (bufoff) + ldsw + 8192), 16, 0, 0); } while (0)
; #define G_LDA(dst, b, h) do { _Pragma("unroll") for (int m = 0; m < 4; ++m) _Pragma("unroll") for (int k = 0; k < 2; ++k) dst[m][k] = *(const LAS bf16x8*)(lds + G_SA(b, h) + aoff + m * 2048 + k * 1024); } while (0)
; #define G_WAIT_V(n) asm volatile("s_waitcnt vmcnt(" #n ")" ::: "memory")
; #define G_WAIT_L(n) asm volatile("s_waitcnt lgkmcnt(" #n ")" ::: "memory")
; #define G_BAR __builtin_amdgcn_s_barrier()
; #define G_SCHED __builtin_amdgcn_sched_barrier(0)
;     ...
;             G_BAR; G_WAIT_L(0); G_MMA(0, 1, At, B1); G_BAR;
;             G_LDA(At, 1, 1); G_STAGE(G_SA(1, 0), a3, cA0, qA);
;             G_BAR; G_WAIT_L(0); G_MMA(1, 0, At, B0); G_BAR; G_SCHED;
;             G_STAGE(G_SB(1, 1), b3 + chB, cB0, qB);
;             G_WAIT_V(6); G_BAR; G_MMA(1, 1, At, B1); G_BAR;
;         }
;         E.template run<cs.kind>(acc, cur, tid);
;         if (!has_next) break;
	s_waitcnt lgkmcnt(0)
	s_setprio 3
	s_waitcnt lgkmcnt(0)
	v_mfma_f32_16x16x32_bf16 v[132:135], v[208:211], v[152:155], v[132:135]
	v_mfma_f32_16x16x32_bf16 v[128:131], v[216:219], v[152:155], v[128:131]
	v_mfma_f32_16x16x32_bf16 v[116:119], v[208:211], v[162:165], v[116:119]
	v_mfma_f32_16x16x32_bf16 v[112:115], v[216:219], v[162:165], v[112:115]
	v_mfma_f32_16x16x32_bf16 v[100:103], v[208:211], v[176:179], v[100:103]
	v_mfma_f32_16x16x32_bf16 v[96:99], v[216:219], v[176:179], v[96:99]
	v_mfma_f32_16x16x32_bf16 v[84:87], v[208:211], v[200:203], v[84:87]
	v_mfma_f32_16x16x32_bf16 v[80:83], v[216:219], v[200:203], v[80:83]
	v_mfma_f32_16x16x32_bf16 v[132:135], v[212:215], v[156:159], v[132:135]
	v_mfma_f32_16x16x32_bf16 v[128:131], v[220:223], v[156:159], v[128:131]
	v_mfma_f32_16x16x32_bf16 v[116:119], v[212:215], v[172:175], v[116:119]
	v_mfma_f32_16x16x32_bf16 v[112:115], v[220:223], v[172:175], v[112:115]
	v_mfma_f32_16x16x32_bf16 v[100:103], v[212:215], v[196:199], v[100:103]
	v_mfma_f32_16x16x32_bf16 v[96:99], v[220:223], v[196:199], v[96:99]
	v_mfma_f32_16x16x32_bf16 v[84:87], v[212:215], v[204:207], v[84:87]
	v_mfma_f32_16x16x32_bf16 v[80:83], v[220:223], v[204:207], v[80:83]
	s_setprio 0
	s_mov_b32 m0, s53
	v_lshl_add_u64 v[224:225], v[180:181], 0, s[46:47]
	s_barrier
	ds_read_b128 v[152:155], v184 offset:49152
	ds_read_b128 v[156:159], v184 offset:50176
	ds_read_b128 v[162:165], v184 offset:51200
	ds_read_b128 v[172:175], v184 offset:52224
	ds_read_b128 v[176:179], v184 offset:53248
	ds_read_b128 v[196:199], v184 offset:54272
	ds_read_b128 v[200:203], v184 offset:55296
	ds_read_b128 v[204:207], v184 offset:56320
	global_load_lds_dwordx4 v[224:225], off
	v_lshl_add_u64 v[180:181], v[180:181], 0, s[68:69]
	s_mov_b32 m0, s54
	s_nop 0
	global_load_lds_dwordx4 v[180:181], off
	s_barrier
	s_waitcnt lgkmcnt(0)
	s_setprio 3
	s_waitcnt lgkmcnt(0)
	v_mfma_f32_16x16x32_bf16 v[76:79], v[64:67], v[152:155], v[76:79]
	v_mfma_f32_16x16x32_bf16 v[72:75], v[144:147], v[152:155], v[72:75]
	v_mfma_f32_16x16x32_bf16 v[52:55], v[64:67], v[162:165], v[52:55]
	v_mfma_f32_16x16x32_bf16 v[48:51], v[144:147], v[162:165], v[48:51]
	v_mfma_f32_16x16x32_bf16 v[36:39], v[64:67], v[176:179], v[36:39]
	v_mfma_f32_16x16x32_bf16 v[32:35], v[144:147], v[176:179], v[32:35]
	v_mfma_f32_16x16x32_bf16 v[20:23], v[64:67], v[200:203], v[20:23]
	v_mfma_f32_16x16x32_bf16 v[16:19], v[144:147], v[200:203], v[16:19]
	v_mfma_f32_16x16x32_bf16 v[76:79], v[68:71], v[156:159], v[76:79]
	v_mfma_f32_16x16x32_bf16 v[72:75], v[148:151], v[156:159], v[72:75]
	v_mfma_f32_16x16x32_bf16 v[52:55], v[68:71], v[172:175], v[52:55]
	v_mfma_f32_16x16x32_bf16 v[48:51], v[148:151], v[172:175], v[48:51]
	v_mfma_f32_16x16x32_bf16 v[36:39], v[68:71], v[196:199], v[36:39]
	v_mfma_f32_16x16x32_bf16 v[32:35], v[148:151], v[196:199], v[32:35]
	v_mfma_f32_16x16x32_bf16 v[20:23], v[68:71], v[204:207], v[20:23]
	v_mfma_f32_16x16x32_bf16 v[16:19], v[148:151], v[204:207], v[16:19]
	s_setprio 0
	s_barrier
	s_mov_b32 m0, s65
	v_lshl_add_u64 v[64:65], v[166:167], 0, s[84:85]
	global_load_lds_dwordx4 v[64:65], off
	v_lshl_add_u64 v[64:65], v[166:167], 0, s[28:29]
	s_mov_b32 m0, s64
	s_nop 0
	global_load_lds_dwordx4 v[64:65], off
	s_waitcnt vmcnt(6)
	s_barrier
	s_setprio 3
	v_mfma_f32_16x16x32_bf16 v[56:59], v[208:211], v[152:155], v[56:59]
	v_mfma_f32_16x16x32_bf16 v[68:71], v[212:215], v[156:159], v[56:59]
	v_mfma_f32_16x16x32_bf16 v[56:59], v[216:219], v[152:155], v[60:63]
	v_mfma_f32_16x16x32_bf16 v[44:47], v[208:211], v[162:165], v[44:47]
	v_mfma_f32_16x16x32_bf16 v[40:43], v[216:219], v[162:165], v[40:43]
	v_mfma_f32_16x16x32_bf16 v[28:31], v[208:211], v[176:179], v[28:31]
	v_mfma_f32_16x16x32_bf16 v[24:27], v[216:219], v[176:179], v[24:27]
	v_mfma_f32_16x16x32_bf16 v[12:15], v[208:211], v[200:203], v[12:15]
	v_mfma_f32_16x16x32_bf16 v[8:11], v[216:219], v[200:203], v[8:11]
	v_mfma_f32_16x16x32_bf16 v[64:67], v[220:223], v[156:159], v[56:59]
	v_mfma_f32_16x16x32_bf16 v[44:47], v[212:215], v[172:175], v[44:47]
	v_mfma_f32_16x16x32_bf16 v[40:43], v[220:223], v[172:175], v[40:43]
	v_mfma_f32_16x16x32_bf16 v[28:31], v[212:215], v[196:199], v[28:31]
	v_mfma_f32_16x16x32_bf16 v[24:27], v[220:223], v[196:199], v[24:27]
	v_mfma_f32_16x16x32_bf16 v[12:15], v[212:215], v[204:207], v[12:15]
	v_mfma_f32_16x16x32_bf16 v[8:11], v[220:223], v[204:207], v[8:11]
	s_setprio 0
	s_andn2_b64 vcc, exec, s[24:25]
	s_mov_b64 s[26:27], -1
	s_mov_b64 s[24:25], 0
	s_mov_b64 s[30:31], 0x100
	s_cbranch_vccz .Ldb_SSM2_cont
	v_readfirstlane_b32 s101, v186
	s_cmpk_gt_u32 s101, 0xff
	s_cbranch_scc1 .Ldb_SSM2_exit
	s_barrier
	s_branch .Ldb_SSM2_exit

; __device__ __forceinline__ float gelu_tanh(float y) { const float z = 1.5957691216057308f * (y + 0.044715f * y * y * y); return y * sigmoidf_(z); }
; __device__ __forceinline__ void unpack8(const u32x4 w, f32x4& a, f32x4& b) { a[0] = bf_lo(w.x); a[1] = bf_hi(w.x); a[2] = bf_lo(w.y); a[3] = bf_hi(w.y); b[0] = bf_lo(w.z); b[1] = bf_hi(w.z); b[2] = bf_lo(w.w); b[3] = bf_hi(w.w); }
;     template <int KIND> __device__ __forceinline__ void run(f32x4 (&acc)[2][2][4][2], const Unit& u, int tid_in) const {
;     ...
;         if constexpr (KIND == K_SSM2) { const int g = u.aux; const int ch = g * 16 + 8 * (fq & 1); const f32x4 d0 = *(const f32x4*)(dskip + ch), d1 = *(const f32x4*)(dskip + ch + 4);
; #pragma unroll
;             for (int ai = 0; ai < 2; ++ai)
; #pragma unroll
;                 for (int mh = 0; mh < 2; ++mh) { u32x4 yv[2][2], uv[2][2];
; #pragma unroll
;                     for (int ml = 0; ml < 2; ++ml) { int R = rbase + ai * 128 + (mh * 2 + ml) * 16; asm volatile("" : "+v"(R));
; #pragma unroll
;                         for (int bj = 0; bj < 2; ++bj) { const int t = 16 * u.pn + 8 * bj + 2 * wc + (fq >> 1); const size_t tok = (size_t)R * LCH + t;
;                             yv[ml][bj] = *(const u32x4*)(yi + ((size_t)g * T_TOK + tok) * 16 + 8 * (fq & 1)); uv[ml][bj] = *(const u32x4*)((const bf16_t*)x + ((size_t)g * T_TOK + tok) * 16 + 8 * (fq & 1)); } }
; #pragma unroll
;                     for (int ml = 0; ml < 2; ++ml) { const int m = mh * 2 + ml; int R = rbase + ai * 128 + m * 16; asm volatile("" : "+v"(R));
; #pragma unroll
;                         for (int bj = 0; bj < 2; ++bj) { const int t = 16 * u.pn + 8 * bj + 2 * wc + (fq >> 1); const size_t tok = (size_t)R * LCH + t;
;                             f32x4 y0, y1, u0, u1; unpack8(yv[ml][bj], y0, y1); unpack8(uv[ml][bj], u0, u1);
;                             y0 = acc[ai][bj][m][0] + y0 + d0 * u0; y1 = acc[ai][bj][m][1] + y1 + d1 * u1;
; #pragma unroll
;                             for (int j = 0; j < 4; ++j) { y0[j] = gelu_tanh(y0[j]); y1[j] = gelu_tanh(y1[j]); }
.Ldb_SSM2_exit:
	v_mov_b32_e32 v0, v182
	s_lshl_b32 s3, s23, 8
	v_readfirstlane_b32 s2, v0
	s_ashr_i32 s4, s2, 2
	v_lshrrev_b32_e32 v56, 1, v0
	s_andn2_b32 s4, s4, 63
	v_and_b32_e32 v144, 8, v56
	s_add_i32 s4, s4, s3
	v_lshl_or_b32 v56, s22, 4, v144
	s_lshr_b32 s2, s2, 5
	v_and_or_b32 v185, v0, 15, s4
	v_ashrrev_i32_e32 v57, 31, v56
	s_and_b32 s2, s2, 6
	v_lshrrev_b32_e32 v0, 5, v0
	v_lshl_add_u64 v[60:61], v[56:57], 2, s[6:7]
	v_and_or_b32 v145, v0, 1, s2
	v_lshlrev_b32_e32 v0, 1, v144
	v_mov_b32_e32 v144, v185
	global_load_dwordx4 v[56:59], v[60:61], off offset:16
	s_nop 0
	global_load_dwordx4 v[60:63], v[60:61], off
	s_ashr_i32 s23, s22, 31
	v_lshl_or_b32 v212, s33, 4, v145
	v_ashrrev_i32_e32 v145, 31, v144
	s_lshl_b64 s[20:21], s[22:23], 19
	v_lshlrev_b64 v[144:145], 9, v[144:145]
	v_ashrrev_i32_e32 v213, 31, v212
	v_lshl_add_u64 v[144:145], v[144:145], 0, s[20:21]
	v_lshlrev_b64 v[172:173], 4, v[212:213]
	v_lshl_add_u64 v[146:147], v[144:145], 0, v[172:173]
	v_lshl_add_u64 v[164:165], s[10:11], 0, v[0:1]
	v_lshlrev_b64 v[146:147], 1, v[146:147]
	v_lshl_add_u64 v[148:149], v[164:165], 0, v[146:147]
	v_lshl_add_u64 v[166:167], s[8:9], 0, v[0:1]
	global_load_dwordx4 v[196:199], v[148:149], off
	v_lshl_add_u64 v[146:147], v[166:167], 0, v[146:147]
	global_load_dwordx4 v[200:203], v[146:147], off
	v_or_b32_e32 v176, 8, v212
	v_ashrrev_i32_e32 v177, 31, v176
	v_lshlrev_b64 v[174:175], 4, v[176:177]
	v_lshl_add_u64 v[144:145], v[174:175], 0, v[144:145]
	v_lshlrev_b64 v[144:145], 1, v[144:145]
	v_lshl_add_u64 v[148:149], v[164:165], 0, v[144:145]
	v_lshl_add_u64 v[144:145], v[166:167], 0, v[144:145]
	global_load_dwordx4 v[204:207], v[148:149], off
	global_load_dwordx4 v[208:211], v[144:145], off
	v_or_b32_e32 v178, 16, v185
	s_lshl_b64 s[2:3], s[22:23], 20
	v_mov_b32_e32 v146, v178
	s_add_u32 s2, s10, s2
	s_addc_u32 s3, s11, s3
	v_ashrrev_i32_e32 v147, 31, v146
	v_lshlrev_b64 v[144:145], 9, v[146:147]
	v_lshl_add_u64 v[162:163], s[2:3], 0, v[0:1]
	v_lshl_add_u64 v[144:145], v[144:145], 0, s[20:21]
	v_lshl_add_u64 v[146:147], v[144:145], 0, v[172:173]
	v_lshl_add_u64 v[144:145], v[144:145], 0, v[174:175]
	v_lshlrev_b64 v[146:147], 1, v[146:147]
	v_lshlrev_b64 v[144:145], 1, v[144:145]
	v_lshl_add_u64 v[148:149], v[164:165], 0, v[146:147]
	v_lshl_add_u64 v[146:147], v[166:167], 0, v[146:147]
	v_lshl_add_u64 v[150:151], v[164:165], 0, v[144:145]
	v_lshl_add_u64 v[144:145], v[166:167], 0, v[144:145]
	global_load_dwordx4 v[156:159], v[148:149], off
	global_load_dwordx4 v[152:155], v[146:147], off
	s_nop 0
	global_load_dwordx4 v[148:151], v[150:151], off
	s_nop 0
	global_load_dwordx4 v[144:147], v[144:145], off
	v_mov_b32_e32 v180, v185
	v_readlane_b32 s48, v230, 5
	v_ashrrev_i32_e32 v181, 31, v180
	v_lshlrev_b64 v[180:181], 10, v[180:181]
	v_lshl_add_u64 v[180:181], v[162:163], 0, v[180:181]
	v_readlane_b32 s49, v230, 6
	v_readlane_b32 s44, v230, 7
	s_and_b64 vcc, exec, s[14:15]
	s_mov_b32 s22, s18
	s_mov_b32 s33, s59
	s_mov_b32 s23, s58
	s_mov_b64 s[2:3], s[12:13]
	v_readlane_b32 s45, v230, 8
	s_movk_i32 s49, 0x4000
	s_mov_b64 s[68:69], 0x18080
	s_mov_b64 s[70:71], 0x800
	s_mov_b64 s[82:83], 0x1800
	s_mov_b64 s[84:85], 0x400800
	s_mov_b64 s[86:87], 0x58000
	s_mov_b64 s[88:89], 0xb0000
	s_mov_b64 s[64:65], 0x108000
	s_mov_b64 s[66:67], 0x58080
	s_mov_b32 s28, s74
	s_waitcnt vmcnt(0)
	v_lshlrev_b32_e32 v214, 16, v196
	v_and_b32_e32 v215, 0xffff0000, v196
	v_lshlrev_b32_e32 v216, 16, v198
	v_and_b32_e32 v217, 0xffff0000, v198
	v_lshlrev_b32_e32 v218, 16, v200
	v_and_b32_e32 v219, 0xffff0000, v200
	v_lshlrev_b32_e32 v220, 16, v202
	v_and_b32_e32 v221, 0xffff0000, v202
	v_pk_add_f32 v[140:141], v[140:141], v[214:215]
	v_pk_add_f32 v[136:137], v[136:137], v[216:217]
	v_pk_fma_f32 v[140:141], v[60:61], v[218:219], v[140:141]
	v_pk_fma_f32 v[136:137], v[56:57], v[220:221], v[136:137]
	v_mul_f32_e32 v0, 0x3d372713, v140
	v_mul_f32_e32 v179, 0x3d372713, v136
	v_mul_f32_e32 v195, 0x3d372713, v141
	v_mul_f32_e32 v0, v140, v0
	v_mul_f32_e32 v179, v136, v179
	v_mul_f32_e32 v195, v141, v195
	v_fma_f32 v0, v140, v0, v140
	v_fma_f32 v179, v136, v179, v136
	v_fma_f32 v195, v141, v195, v141
	v_mul_f32_e32 v0, 0x3fcc422a, v0
	v_mul_f32_e32 v179, 0x3fcc422a, v179
	v_mul_f32_e32 v195, 0x3fcc422a, v195
	v_mul_f32_e32 v0, 0xbfb8aa3b, v0
	v_mul_f32_e32 v179, 0xbfb8aa3b, v179
	v_mul_f32_e32 v195, 0xbfb8aa3b, v195
	v_exp_f32_e32 v0, v0
	v_exp_f32_e32 v179, v179
	v_exp_f32_e32 v195, v195
	v_lshlrev_b32_e32 v196, 16, v197
	v_and_b32_e32 v197, 0xffff0000, v197
	v_pk_add_f32 v[142:143], v[142:143], v[196:197]
	v_add_f32_e32 v0, 1.0, v0
	v_add_f32_e32 v179, 1.0, v179
	v_add_f32_e32 v195, 1.0, v195
	v_mul_f32_e32 v196, 0x3d372713, v137
	v_rcp_f32_e32 v0, v0
	v_rcp_f32_e32 v179, v179
	v_rcp_f32_e32 v195, v195
	v_mul_f32_e32 v196, v137, v196
	v_lshlrev_b32_e32 v198, 16, v199
	v_and_b32_e32 v199, 0xffff0000, v199
	v_fma_f32 v196, v137, v196, v137
	v_lshlrev_b32_e32 v200, 16, v201
	v_and_b32_e32 v201, 0xffff0000, v201
	v_lshlrev_b32_e32 v202, 16, v203
	v_and_b32_e32 v203, 0xffff0000, v203
	v_pk_add_f32 v[138:139], v[138:139], v[198:199]
	v_mul_f32_e32 v196, 0x3fcc422a, v196
	v_pk_fma_f32 v[142:143], v[62:63], v[200:201], v[142:143]
	v_pk_fma_f32 v[138:139], v[58:59], v[202:203], v[138:139]
	v_mul_f32_e32 v196, 0xbfb8aa3b, v196
	v_exp_f32_e32 v196, v196
	v_mul_f32_e32 v0, v140, v0
	v_mul_f32_e32 v136, v136, v179
	v_mul_f32_e32 v140, v141, v195
	v_mul_f32_e32 v179, 0x3d372713, v142
	v_mul_f32_e32 v195, 0x3d372713, v138
	v_mul_f32_e32 v179, v142, v179
	v_mul_f32_e32 v195, v138, v195
	v_fma_f32 v179, v142, v179, v142
	v_fma_f32 v195, v138, v195, v138
	v_mul_f32_e32 v179, 0x3fcc422a, v179
; __device__ __forceinline__ float gelu_tanh(float y) { const float z = 1.5957691216057308f * (y + 0.044715f * y * y * y); return y * sigmoidf_(z); }
; __device__ __forceinline__ u32x4 pack8(const f32x4 a, const f32x4 b) { u32x4 w; w.x = cvt_pk_bf16(a[0], a[1]); w.y = cvt_pk_bf16(a[2], a[3]); w.z = cvt_pk_bf16(b[0], b[1]); w.w = cvt_pk_bf16(b[2], b[3]); return w; }
; __device__ __forceinline__ void unpack8(const u32x4 w, f32x4& a, f32x4& b) { a[0] = bf_lo(w.x); a[1] = bf_hi(w.x); a[2] = bf_lo(w.y); a[3] = bf_hi(w.y); b[0] = bf_lo(w.z); b[1] = bf_hi(w.z); b[2] = bf_lo(w.w); b[3] = bf_hi(w.w); }
;     template <int KIND> __device__ __forceinline__ void run(f32x4 (&acc)[2][2][4][2], const Unit& u, int tid_in) const {
;     ...
;                     for (int ml = 0; ml < 2; ++ml) { const int m = mh * 2 + ml; int R = rbase + ai * 128 + m * 16; asm volatile("" : "+v"(R));
; #pragma unroll
;                         for (int bj = 0; bj < 2; ++bj) { const int t = 16 * u.pn + 8 * bj + 2 * wc + (fq >> 1); const size_t tok = (size_t)R * LCH + t;
;                             f32x4 y0, y1, u0, u1; unpack8(yv[ml][bj], y0, y1); unpack8(uv[ml][bj], u0, u1);
;                             y0 = acc[ai][bj][m][0] + y0 + d0 * u0; y1 = acc[ai][bj][m][1] + y1 + d1 * u1;
; #pragma unroll
;                             for (int j = 0; j < 4; ++j) { y0[j] = gelu_tanh(y0[j]); y1[j] = gelu_tanh(y1[j]); }
;                             *(u32x4*)(yi + ((size_t)g * T_TOK + tok) * 16 + 8 * (fq & 1)) = pack8(y0, y1); } }
	v_mul_f32_e32 v195, 0x3fcc422a, v195
	v_add_f32_e32 v141, 1.0, v196
	v_mul_f32_e32 v179, 0xbfb8aa3b, v179
	v_mul_f32_e32 v195, 0xbfb8aa3b, v195
	v_rcp_f32_e32 v141, v141
	v_exp_f32_e32 v179, v179
	v_exp_f32_e32 v195, v195
	v_mul_f32_e32 v196, 0x3d372713, v139
	v_mul_f32_e32 v137, v137, v141
	v_add_f32_e32 v141, 1.0, v179
	v_add_f32_e32 v179, 1.0, v195
	v_mul_f32_e32 v195, 0x3d372713, v143
	v_mul_f32_e32 v195, v143, v195
	v_mul_f32_e32 v196, v139, v196
	v_fma_f32 v195, v143, v195, v143
	v_fma_f32 v196, v139, v196, v139
	v_mul_f32_e32 v195, 0x3fcc422a, v195
	v_mul_f32_e32 v196, 0x3fcc422a, v196
	v_mul_f32_e32 v195, 0xbfb8aa3b, v195
	v_mul_f32_e32 v196, 0xbfb8aa3b, v196
	v_exp_f32_e32 v195, v195
	v_exp_f32_e32 v196, v196
	v_rcp_f32_e32 v141, v141
	v_rcp_f32_e32 v179, v179
	v_add_f32_e32 v195, 1.0, v195
	v_add_f32_e32 v196, 1.0, v196
	v_rcp_f32_e32 v195, v195
	v_rcp_f32_e32 v196, v196
	v_mul_f32_e32 v141, v142, v141
	v_mul_f32_e32 v142, v138, v179
	v_mul_f32_e32 v143, v143, v195
	v_mul_f32_e32 v179, v139, v196
	v_cvt_pk_bf16_f32 v138, v0, v140
	v_cvt_pk_bf16_f32 v139, v141, v143
	v_cvt_pk_bf16_f32 v140, v136, v137
	v_lshlrev_b64 v[136:137], 5, v[212:213]
	v_cvt_pk_bf16_f32 v141, v142, v179
	v_lshl_add_u64 v[142:143], v[180:181], 0, v[136:137]
	global_store_dwordx4 v[142:143], v[138:141], off
	v_lshlrev_b32_e32 v142, 16, v206
	v_and_b32_e32 v143, 0xffff0000, v206
	v_lshlrev_b32_e32 v138, 16, v204
	v_and_b32_e32 v139, 0xffff0000, v204
	v_lshlrev_b32_e32 v198, 16, v208
	v_and_b32_e32 v199, 0xffff0000, v208
	v_lshlrev_b32_e32 v202, 16, v210
	v_and_b32_e32 v203, 0xffff0000, v210
	v_pk_add_f32 v[132:133], v[132:133], v[138:139]
	v_pk_add_f32 v[128:129], v[128:129], v[142:143]
	v_pk_fma_f32 v[132:133], v[60:61], v[198:199], v[132:133]
	v_pk_fma_f32 v[128:129], v[56:57], v[202:203], v[128:129]
	v_mul_f32_e32 v0, 0x3d372713, v132
	v_mul_f32_e32 v138, 0x3d372713, v128
	v_mul_f32_e32 v139, 0x3d372713, v133
	v_mul_f32_e32 v0, v132, v0
	v_mul_f32_e32 v138, v128, v138
	v_mul_f32_e32 v139, v133, v139
	v_fma_f32 v0, v132, v0, v132
	v_fma_f32 v138, v128, v138, v128
	v_fma_f32 v139, v133, v139, v133
	v_mul_f32_e32 v0, 0x3fcc422a, v0
	v_mul_f32_e32 v138, 0x3fcc422a, v138
	v_mul_f32_e32 v139, 0x3fcc422a, v139
	v_mul_f32_e32 v0, 0xbfb8aa3b, v0
	v_mul_f32_e32 v138, 0xbfb8aa3b, v138
	v_mul_f32_e32 v139, 0xbfb8aa3b, v139
	v_exp_f32_e32 v0, v0
	v_exp_f32_e32 v138, v138
	v_exp_f32_e32 v139, v139
	v_lshlrev_b32_e32 v140, 16, v205
	v_and_b32_e32 v141, 0xffff0000, v205
	v_pk_add_f32 v[134:135], v[134:135], v[140:141]
	v_add_f32_e32 v0, 1.0, v0
	v_add_f32_e32 v138, 1.0, v138
	v_add_f32_e32 v139, 1.0, v139
	v_mul_f32_e32 v140, 0x3d372713, v129
	v_rcp_f32_e32 v0, v0
	v_rcp_f32_e32 v138, v138
	v_rcp_f32_e32 v139, v139
	v_mul_f32_e32 v140, v129, v140
	v_lshlrev_b32_e32 v196, 16, v207
	v_and_b32_e32 v197, 0xffff0000, v207
	v_fma_f32 v140, v129, v140, v129
	v_lshlrev_b32_e32 v200, 16, v209
	v_and_b32_e32 v201, 0xffff0000, v209
	v_lshlrev_b32_e32 v204, 16, v211
	v_and_b32_e32 v205, 0xffff0000, v211
	v_pk_add_f32 v[130:131], v[130:131], v[196:197]
	v_mul_f32_e32 v140, 0x3fcc422a, v140
	v_pk_fma_f32 v[134:135], v[62:63], v[200:201], v[134:135]
	v_pk_fma_f32 v[130:131], v[58:59], v[204:205], v[130:131]
	v_mul_f32_e32 v140, 0xbfb8aa3b, v140
	v_exp_f32_e32 v140, v140
	v_mul_f32_e32 v0, v132, v0
	v_mul_f32_e32 v128, v128, v138
	v_mul_f32_e32 v132, v133, v139
	v_mul_f32_e32 v138, 0x3d372713, v134
	v_mul_f32_e32 v139, 0x3d372713, v130
	v_mul_f32_e32 v138, v134, v138
	v_mul_f32_e32 v139, v130, v139
	v_fma_f32 v138, v134, v138, v134
	v_fma_f32 v139, v130, v139, v130
	v_mul_f32_e32 v138, 0x3fcc422a, v138
	v_mul_f32_e32 v139, 0x3fcc422a, v139
	v_add_f32_e32 v133, 1.0, v140
	v_mul_f32_e32 v138, 0xbfb8aa3b, v138
	v_mul_f32_e32 v139, 0xbfb8aa3b, v139
	v_rcp_f32_e32 v133, v133
	v_exp_f32_e32 v138, v138
	v_exp_f32_e32 v139, v139
	v_mul_f32_e32 v140, 0x3d372713, v131
	v_mul_f32_e32 v129, v129, v133
	v_add_f32_e32 v133, 1.0, v138
	v_add_f32_e32 v138, 1.0, v139
	v_mul_f32_e32 v139, 0x3d372713, v135
	v_mul_f32_e32 v139, v135, v139
	v_mul_f32_e32 v140, v131, v140
	v_fma_f32 v139, v135, v139, v135
	v_fma_f32 v140, v131, v140, v131
	v_mul_f32_e32 v139, 0x3fcc422a, v139
	v_mul_f32_e32 v140, 0x3fcc422a, v140
	v_mul_f32_e32 v139, 0xbfb8aa3b, v139
	v_mul_f32_e32 v140, 0xbfb8aa3b, v140
	v_exp_f32_e32 v139, v139
	v_exp_f32_e32 v140, v140
	v_rcp_f32_e32 v133, v133
	v_rcp_f32_e32 v138, v138
	v_add_f32_e32 v139, 1.0, v139
	v_add_f32_e32 v140, 1.0, v140
	v_rcp_f32_e32 v139, v139
	v_rcp_f32_e32 v140, v140
	v_mul_f32_e32 v133, v134, v133
	v_mul_f32_e32 v134, v130, v138
	v_mul_f32_e32 v135, v135, v139
	v_mul_f32_e32 v138, v131, v140
	v_cvt_pk_bf16_f32 v130, v0, v132
	v_cvt_pk_bf16_f32 v131, v133, v135
	v_cvt_pk_bf16_f32 v132, v128, v129
	v_lshlrev_b64 v[128:129], 5, v[176:177]
	v_cvt_pk_bf16_f32 v133, v134, v138
	v_lshl_add_u64 v[134:135], v[180:181], 0, v[128:129]
	global_store_dwordx4 v[134:135], v[130:133], off
	v_lshlrev_b32_e32 v138, 16, v158
	v_and_b32_e32 v139, 0xffff0000, v158
	v_lshlrev_b32_e32 v132, 16, v156
	v_and_b32_e32 v133, 0xffff0000, v156
	v_lshlrev_b32_e32 v134, 16, v157
	v_and_b32_e32 v135, 0xffff0000, v157
	v_lshlrev_b32_e32 v142, 16, v152
	v_and_b32_e32 v143, 0xffff0000, v152
	v_lshlrev_b32_e32 v156, 16, v154
	v_and_b32_e32 v157, 0xffff0000, v154
	v_pk_add_f32 v[124:125], v[124:125], v[132:133]
	v_pk_add_f32 v[120:121], v[120:121], v[138:139]
	v_pk_fma_f32 v[124:125], v[60:61], v[142:143], v[124:125]
	v_pk_fma_f32 v[120:121], v[56:57], v[156:157], v[120:121]
	v_mul_f32_e32 v0, 0x3d372713, v124
	v_mul_f32_e32 v132, 0x3d372713, v120
	v_mul_f32_e32 v133, 0x3d372713, v125
	v_mul_f32_e32 v0, v124, v0
; __device__ __forceinline__ float gelu_tanh(float y) { const float z = 1.5957691216057308f * (y + 0.044715f * y * y * y); return y * sigmoidf_(z); }
; __device__ __forceinline__ u32x4 pack8(const f32x4 a, const f32x4 b) { u32x4 w; w.x = cvt_pk_bf16(a[0], a[1]); w.y = cvt_pk_bf16(a[2], a[3]); w.z = cvt_pk_bf16(b[0], b[1]); w.w = cvt_pk_bf16(b[2], b[3]); return w; }
; __device__ __forceinline__ void unpack8(const u32x4 w, f32x4& a, f32x4& b) { a[0] = bf_lo(w.x); a[1] = bf_hi(w.x); a[2] = bf_lo(w.y); a[3] = bf_hi(w.y); b[0] = bf_lo(w.z); b[1] = bf_hi(w.z); b[2] = bf_lo(w.w); b[3] = bf_hi(w.w); }
;     template <int KIND> __device__ __forceinline__ void run(f32x4 (&acc)[2][2][4][2], const Unit& u, int tid_in) const {
;     ...
;                     for (int ml = 0; ml < 2; ++ml) { const int m = mh * 2 + ml; int R = rbase + ai * 128 + m * 16; asm volatile("" : "+v"(R));
; #pragma unroll
;                         for (int bj = 0; bj < 2; ++bj) { const int t = 16 * u.pn + 8 * bj + 2 * wc + (fq >> 1); const size_t tok = (size_t)R * LCH + t;
;                             f32x4 y0, y1, u0, u1; unpack8(yv[ml][bj], y0, y1); unpack8(uv[ml][bj], u0, u1);
;                             y0 = acc[ai][bj][m][0] + y0 + d0 * u0; y1 = acc[ai][bj][m][1] + y1 + d1 * u1;
; #pragma unroll
;                             for (int j = 0; j < 4; ++j) { y0[j] = gelu_tanh(y0[j]); y1[j] = gelu_tanh(y1[j]); }
;                             *(u32x4*)(yi + ((size_t)g * T_TOK + tok) * 16 + 8 * (fq & 1)) = pack8(y0, y1); } }
	v_mul_f32_e32 v132, v120, v132
	v_mul_f32_e32 v133, v125, v133
	v_fma_f32 v0, v124, v0, v124
	v_fma_f32 v132, v120, v132, v120
	v_fma_f32 v133, v125, v133, v125
	v_mul_f32_e32 v0, 0x3fcc422a, v0
	v_mul_f32_e32 v132, 0x3fcc422a, v132
	v_mul_f32_e32 v133, 0x3fcc422a, v133
	v_mul_f32_e32 v0, 0xbfb8aa3b, v0
	v_mul_f32_e32 v132, 0xbfb8aa3b, v132
	v_mul_f32_e32 v133, 0xbfb8aa3b, v133
	v_exp_f32_e32 v0, v0
	v_exp_f32_e32 v132, v132
	v_exp_f32_e32 v133, v133
	v_pk_add_f32 v[126:127], v[126:127], v[134:135]
	v_add_f32_e32 v0, 1.0, v0
	v_add_f32_e32 v132, 1.0, v132
	v_add_f32_e32 v133, 1.0, v133
	v_mul_f32_e32 v134, 0x3d372713, v121
	v_rcp_f32_e32 v0, v0
	v_rcp_f32_e32 v132, v132
	v_rcp_f32_e32 v133, v133
	v_mul_f32_e32 v134, v121, v134
	v_lshlrev_b32_e32 v140, 16, v159
	v_and_b32_e32 v141, 0xffff0000, v159
	v_fma_f32 v134, v121, v134, v121
	v_lshlrev_b32_e32 v152, 16, v153
	v_and_b32_e32 v153, 0xffff0000, v153
	v_lshlrev_b32_e32 v154, 16, v155
	v_and_b32_e32 v155, 0xffff0000, v155
	v_pk_add_f32 v[122:123], v[122:123], v[140:141]
	v_mul_f32_e32 v134, 0x3fcc422a, v134
	v_pk_fma_f32 v[126:127], v[62:63], v[152:153], v[126:127]
	v_pk_fma_f32 v[122:123], v[58:59], v[154:155], v[122:123]
	v_mul_f32_e32 v134, 0xbfb8aa3b, v134
	v_exp_f32_e32 v134, v134
	v_mul_f32_e32 v0, v124, v0
	v_mul_f32_e32 v124, v120, v132
	v_mul_f32_e32 v120, v125, v133
	v_mul_f32_e32 v132, 0x3d372713, v126
	v_mul_f32_e32 v133, 0x3d372713, v122
	v_mul_f32_e32 v132, v126, v132
	v_mul_f32_e32 v133, v122, v133
	v_fma_f32 v132, v126, v132, v126
	v_fma_f32 v133, v122, v133, v122
	v_mul_f32_e32 v132, 0x3fcc422a, v132
	v_mul_f32_e32 v133, 0x3fcc422a, v133
	v_add_f32_e32 v125, 1.0, v134
	v_mul_f32_e32 v132, 0xbfb8aa3b, v132
	v_mul_f32_e32 v133, 0xbfb8aa3b, v133
	v_rcp_f32_e32 v125, v125
	v_exp_f32_e32 v132, v132
	v_exp_f32_e32 v133, v133
	v_mul_f32_e32 v134, 0x3d372713, v123
	v_mul_f32_e32 v125, v121, v125
	v_add_f32_e32 v121, 1.0, v132
	v_add_f32_e32 v132, 1.0, v133
	v_mul_f32_e32 v133, 0x3d372713, v127
	v_mul_f32_e32 v133, v127, v133
	v_fma_f32 v133, v127, v133, v127
	v_mul_f32_e32 v134, v123, v134
	v_mul_f32_e32 v133, 0x3fcc422a, v133
	v_fma_f32 v134, v123, v134, v123
	v_mul_f32_e32 v133, 0xbfb8aa3b, v133
	v_mul_f32_e32 v134, 0x3fcc422a, v134
	v_exp_f32_e32 v133, v133
	v_mul_f32_e32 v134, 0xbfb8aa3b, v134
	v_exp_f32_e32 v134, v134
	v_rcp_f32_e32 v121, v121
	v_add_f32_e32 v133, 1.0, v133
	v_rcp_f32_e32 v132, v132
	v_rcp_f32_e32 v133, v133
	v_add_f32_e32 v134, 1.0, v134
	v_rcp_f32_e32 v134, v134
	v_mul_f32_e32 v121, v126, v121
	v_ashrrev_i32_e32 v179, 31, v178
	v_lshlrev_b64 v[130:131], 10, v[178:179]
	v_lshl_add_u64 v[130:131], v[162:163], 0, v[130:131]
	v_mul_f32_e32 v126, v122, v132
	v_mul_f32_e32 v122, v127, v133
	v_mul_f32_e32 v123, v123, v134
	v_cvt_pk_bf16_f32 v120, v0, v120
	v_cvt_pk_bf16_f32 v121, v121, v122
	v_cvt_pk_bf16_f32 v122, v124, v125
	v_lshl_add_u64 v[124:125], v[130:131], 0, v[136:137]
	v_cvt_pk_bf16_f32 v123, v126, v123
	global_store_dwordx4 v[124:125], v[120:123], off
	v_lshlrev_b32_e32 v124, 16, v150
	v_and_b32_e32 v125, 0xffff0000, v150
	v_lshlrev_b32_e32 v120, 16, v148
	v_and_b32_e32 v121, 0xffff0000, v148
	v_lshlrev_b32_e32 v132, 16, v144
	v_and_b32_e32 v133, 0xffff0000, v144
	v_lshlrev_b32_e32 v138, 16, v146
	v_and_b32_e32 v139, 0xffff0000, v146
	v_pk_add_f32 v[116:117], v[116:117], v[120:121]
	v_pk_add_f32 v[112:113], v[112:113], v[124:125]
	v_pk_fma_f32 v[116:117], v[60:61], v[132:133], v[116:117]
	v_pk_fma_f32 v[112:113], v[56:57], v[138:139], v[112:113]
	v_mul_f32_e32 v0, 0x3d372713, v116
	v_mul_f32_e32 v120, 0x3d372713, v112
	v_mul_f32_e32 v121, 0x3d372713, v117
	v_mul_f32_e32 v0, v116, v0
	v_mul_f32_e32 v120, v112, v120
	v_mul_f32_e32 v121, v117, v121
	v_fma_f32 v0, v116, v0, v116
	v_fma_f32 v120, v112, v120, v112
	v_fma_f32 v121, v117, v121, v117
	v_mul_f32_e32 v0, 0x3fcc422a, v0
	v_mul_f32_e32 v120, 0x3fcc422a, v120
	v_mul_f32_e32 v121, 0x3fcc422a, v121
	v_mul_f32_e32 v0, 0xbfb8aa3b, v0
	v_mul_f32_e32 v120, 0xbfb8aa3b, v120
	v_mul_f32_e32 v121, 0xbfb8aa3b, v121
	v_exp_f32_e32 v0, v0
	v_exp_f32_e32 v120, v120
	v_exp_f32_e32 v121, v121
	v_lshlrev_b32_e32 v122, 16, v149
	v_and_b32_e32 v123, 0xffff0000, v149
	v_pk_add_f32 v[118:119], v[118:119], v[122:123]
	v_add_f32_e32 v0, 1.0, v0
	v_add_f32_e32 v120, 1.0, v120
	v_add_f32_e32 v121, 1.0, v121
	v_mul_f32_e32 v122, 0x3d372713, v113
	v_rcp_f32_e32 v0, v0
	v_rcp_f32_e32 v120, v120
	v_rcp_f32_e32 v121, v121
	v_mul_f32_e32 v122, v113, v122
	v_lshlrev_b32_e32 v126, 16, v151
	v_and_b32_e32 v127, 0xffff0000, v151
	v_fma_f32 v122, v113, v122, v113
	v_lshlrev_b32_e32 v134, 16, v145
	v_and_b32_e32 v135, 0xffff0000, v145
	v_lshlrev_b32_e32 v140, 16, v147
	v_and_b32_e32 v141, 0xffff0000, v147
	v_pk_add_f32 v[114:115], v[114:115], v[126:127]
	v_mul_f32_e32 v122, 0x3fcc422a, v122
	v_pk_fma_f32 v[118:119], v[62:63], v[134:135], v[118:119]
	v_pk_fma_f32 v[114:115], v[58:59], v[140:141], v[114:115]
	v_mul_f32_e32 v122, 0xbfb8aa3b, v122
	v_exp_f32_e32 v122, v122
	v_mul_f32_e32 v0, v116, v0
	v_mul_f32_e32 v116, v112, v120
	v_mul_f32_e32 v112, v117, v121
	v_mul_f32_e32 v120, 0x3d372713, v118
	v_mul_f32_e32 v121, 0x3d372713, v114
	v_mul_f32_e32 v120, v118, v120
	v_mul_f32_e32 v121, v114, v121
	v_fma_f32 v120, v118, v120, v118
	v_fma_f32 v121, v114, v121, v114
	v_mul_f32_e32 v120, 0x3fcc422a, v120
	v_mul_f32_e32 v121, 0x3fcc422a, v121
	v_add_f32_e32 v117, 1.0, v122
	v_mul_f32_e32 v120, 0xbfb8aa3b, v120
	v_mul_f32_e32 v121, 0xbfb8aa3b, v121
	v_rcp_f32_e32 v117, v117
	v_exp_f32_e32 v120, v120
	v_exp_f32_e32 v121, v121
	v_mul_f32_e32 v122, 0x3d372713, v115
	v_mul_f32_e32 v117, v113, v117
	v_add_f32_e32 v113, 1.0, v120
; __device__ __forceinline__ float gelu_tanh(float y) { const float z = 1.5957691216057308f * (y + 0.044715f * y * y * y); return y * sigmoidf_(z); }
; __device__ __forceinline__ u32x4 pack8(const f32x4 a, const f32x4 b) { u32x4 w; w.x = cvt_pk_bf16(a[0], a[1]); w.y = cvt_pk_bf16(a[2], a[3]); w.z = cvt_pk_bf16(b[0], b[1]); w.w = cvt_pk_bf16(b[2], b[3]); return w; }
; __device__ __forceinline__ void unpack8(const u32x4 w, f32x4& a, f32x4& b) { a[0] = bf_lo(w.x); a[1] = bf_hi(w.x); a[2] = bf_lo(w.y); a[3] = bf_hi(w.y); b[0] = bf_lo(w.z); b[1] = bf_hi(w.z); b[2] = bf_lo(w.w); b[3] = bf_hi(w.w); }
;     template <int KIND> __device__ __forceinline__ void run(f32x4 (&acc)[2][2][4][2], const Unit& u, int tid_in) const {
;     ...
;                 for (int mh = 0; mh < 2; ++mh) { u32x4 yv[2][2], uv[2][2];
; #pragma unroll
;                     for (int ml = 0; ml < 2; ++ml) { int R = rbase + ai * 128 + (mh * 2 + ml) * 16; asm volatile("" : "+v"(R));
; #pragma unroll
;                         for (int bj = 0; bj < 2; ++bj) { const int t = 16 * u.pn + 8 * bj + 2 * wc + (fq >> 1); const size_t tok = (size_t)R * LCH + t;
;                             yv[ml][bj] = *(const u32x4*)(yi + ((size_t)g * T_TOK + tok) * 16 + 8 * (fq & 1)); uv[ml][bj] = *(const u32x4*)((const bf16_t*)x + ((size_t)g * T_TOK + tok) * 16 + 8 * (fq & 1)); } }
; #pragma unroll
;                     for (int ml = 0; ml < 2; ++ml) { const int m = mh * 2 + ml; int R = rbase + ai * 128 + m * 16; asm volatile("" : "+v"(R));
; #pragma unroll
;                         for (int bj = 0; bj < 2; ++bj) { const int t = 16 * u.pn + 8 * bj + 2 * wc + (fq >> 1); const size_t tok = (size_t)R * LCH + t;
;                             f32x4 y0, y1, u0, u1; unpack8(yv[ml][bj], y0, y1); unpack8(uv[ml][bj], u0, u1);
;                             y0 = acc[ai][bj][m][0] + y0 + d0 * u0; y1 = acc[ai][bj][m][1] + y1 + d1 * u1;
; #pragma unroll
;                             for (int j = 0; j < 4; ++j) { y0[j] = gelu_tanh(y0[j]); y1[j] = gelu_tanh(y1[j]); }
;                             *(u32x4*)(yi + ((size_t)g * T_TOK + tok) * 16 + 8 * (fq & 1)) = pack8(y0, y1); } }
	v_add_f32_e32 v120, 1.0, v121
	v_mul_f32_e32 v121, 0x3d372713, v119
	v_mul_f32_e32 v121, v119, v121
	v_fma_f32 v121, v119, v121, v119
	v_mul_f32_e32 v122, v115, v122
	v_mul_f32_e32 v121, 0x3fcc422a, v121
	v_fma_f32 v122, v115, v122, v115
	v_mul_f32_e32 v121, 0xbfb8aa3b, v121
	v_mul_f32_e32 v122, 0x3fcc422a, v122
	v_exp_f32_e32 v121, v121
	v_mul_f32_e32 v122, 0xbfb8aa3b, v122
	v_exp_f32_e32 v122, v122
	v_rcp_f32_e32 v113, v113
	v_add_f32_e32 v121, 1.0, v121
	v_rcp_f32_e32 v120, v120
	v_rcp_f32_e32 v121, v121
	v_add_f32_e32 v122, 1.0, v122
	v_rcp_f32_e32 v122, v122
	v_mul_f32_e32 v113, v118, v113
	v_mul_f32_e32 v118, v114, v120
	v_mul_f32_e32 v114, v119, v121
	v_mul_f32_e32 v115, v115, v122
	v_cvt_pk_bf16_f32 v112, v0, v112
	v_cvt_pk_bf16_f32 v113, v113, v114
	v_cvt_pk_bf16_f32 v114, v116, v117
	v_lshl_add_u64 v[116:117], v[130:131], 0, v[128:129]
	v_or_b32_e32 v132, 32, v185
	v_cvt_pk_bf16_f32 v115, v118, v115
	global_store_dwordx4 v[116:117], v[112:115], off
	v_or_b32_e32 v130, 48, v185
	s_nop 0
	v_mov_b32_e32 v112, v132
	s_nop 0
	v_ashrrev_i32_e32 v113, 31, v112
	v_lshlrev_b64 v[112:113], 9, v[112:113]
	v_lshl_add_u64 v[112:113], v[112:113], 0, s[20:21]
	v_lshl_add_u64 v[114:115], v[112:113], 0, v[172:173]
	v_lshlrev_b64 v[114:115], 1, v[114:115]
	v_lshl_add_u64 v[116:117], v[164:165], 0, v[114:115]
	global_load_dwordx4 v[138:141], v[116:117], off
	v_lshl_add_u64 v[114:115], v[166:167], 0, v[114:115]
	global_load_dwordx4 v[142:145], v[114:115], off
	v_lshl_add_u64 v[112:113], v[112:113], 0, v[174:175]
	v_lshlrev_b64 v[112:113], 1, v[112:113]
	v_lshl_add_u64 v[114:115], v[164:165], 0, v[112:113]
	global_load_dwordx4 v[146:149], v[114:115], off
	v_lshl_add_u64 v[112:113], v[166:167], 0, v[112:113]
	global_load_dwordx4 v[150:153], v[112:113], off
	v_mov_b32_e32 v112, v130
	s_waitcnt vmcnt(0)
	v_lshlrev_b32_e32 v134, 16, v138
	v_ashrrev_i32_e32 v113, 31, v112
	v_lshlrev_b64 v[112:113], 9, v[112:113]
	v_lshl_add_u64 v[112:113], v[112:113], 0, s[20:21]
	v_and_b32_e32 v135, 0xffff0000, v138
	v_lshlrev_b32_e32 v154, 16, v140
	v_and_b32_e32 v155, 0xffff0000, v140
	v_lshl_add_u64 v[114:115], v[112:113], 0, v[172:173]
	v_lshlrev_b32_e32 v156, 16, v142
	v_and_b32_e32 v157, 0xffff0000, v142
	v_lshlrev_b32_e32 v158, 16, v144
	v_and_b32_e32 v159, 0xffff0000, v144
	v_pk_add_f32 v[108:109], v[108:109], v[134:135]
	v_pk_add_f32 v[104:105], v[104:105], v[154:155]
	v_lshlrev_b64 v[114:115], 1, v[114:115]
	v_pk_fma_f32 v[108:109], v[60:61], v[156:157], v[108:109]
	v_pk_fma_f32 v[104:105], v[56:57], v[158:159], v[104:105]
	v_lshl_add_u64 v[116:117], v[164:165], 0, v[114:115]
	v_mul_f32_e32 v0, 0x3d372713, v108
	v_mul_f32_e32 v131, 0x3d372713, v104
	v_mul_f32_e32 v134, 0x3d372713, v109
	global_load_dwordx4 v[124:127], v[116:117], off
	v_lshl_add_u64 v[114:115], v[166:167], 0, v[114:115]
	v_mul_f32_e32 v0, v108, v0
	v_mul_f32_e32 v131, v104, v131
	v_mul_f32_e32 v134, v109, v134
	global_load_dwordx4 v[120:123], v[114:115], off
	v_fma_f32 v0, v108, v0, v108
	v_fma_f32 v131, v104, v131, v104
	v_fma_f32 v134, v109, v134, v109
	v_mul_f32_e32 v0, 0x3fcc422a, v0
	v_mul_f32_e32 v131, 0x3fcc422a, v131
	v_mul_f32_e32 v134, 0x3fcc422a, v134
	v_mul_f32_e32 v0, 0xbfb8aa3b, v0
	v_mul_f32_e32 v131, 0xbfb8aa3b, v131
	v_mul_f32_e32 v134, 0xbfb8aa3b, v134
	v_exp_f32_e32 v0, v0
	v_exp_f32_e32 v131, v131
	v_exp_f32_e32 v134, v134
	v_mul_f32_e32 v135, 0x3d372713, v105
	v_add_f32_e32 v0, 1.0, v0
	v_add_f32_e32 v131, 1.0, v131
	v_add_f32_e32 v134, 1.0, v134
	v_rcp_f32_e32 v0, v0
	v_rcp_f32_e32 v131, v131
	v_rcp_f32_e32 v134, v134
	v_mul_f32_e32 v135, v105, v135
	v_lshlrev_b32_e32 v138, 16, v139
	v_and_b32_e32 v139, 0xffff0000, v139
	v_lshlrev_b32_e32 v140, 16, v141
	v_and_b32_e32 v141, 0xffff0000, v141
	v_fma_f32 v135, v105, v135, v105
	v_lshlrev_b32_e32 v142, 16, v143
	v_and_b32_e32 v143, 0xffff0000, v143
	v_lshlrev_b32_e32 v144, 16, v145
	v_and_b32_e32 v145, 0xffff0000, v145
	v_pk_add_f32 v[110:111], v[110:111], v[138:139]
	v_pk_add_f32 v[106:107], v[106:107], v[140:141]
	v_mul_f32_e32 v135, 0x3fcc422a, v135
	v_pk_fma_f32 v[110:111], v[62:63], v[142:143], v[110:111]
	v_pk_fma_f32 v[106:107], v[58:59], v[144:145], v[106:107]
	v_mul_f32_e32 v135, 0xbfb8aa3b, v135
	v_exp_f32_e32 v135, v135
	v_mul_f32_e32 v0, v108, v0
	v_mul_f32_e32 v108, v104, v131
	v_mul_f32_e32 v104, v109, v134
	v_mul_f32_e32 v131, 0x3d372713, v110
	v_mul_f32_e32 v134, 0x3d372713, v106
	v_mul_f32_e32 v131, v110, v131
	v_mul_f32_e32 v134, v106, v134
	v_fma_f32 v131, v110, v131, v110
	v_fma_f32 v134, v106, v134, v106
	v_mul_f32_e32 v131, 0x3fcc422a, v131
	v_mul_f32_e32 v134, 0x3fcc422a, v134
	v_add_f32_e32 v109, 1.0, v135
	v_mul_f32_e32 v131, 0xbfb8aa3b, v131
	v_mul_f32_e32 v134, 0xbfb8aa3b, v134
	v_rcp_f32_e32 v109, v109
	v_exp_f32_e32 v131, v131
	v_exp_f32_e32 v134, v134
	v_mul_f32_e32 v135, 0x3d372713, v107
	v_mul_f32_e32 v109, v105, v109
	v_add_f32_e32 v105, 1.0, v131
	v_add_f32_e32 v131, 1.0, v134
	v_mul_f32_e32 v134, 0x3d372713, v111
	v_mul_f32_e32 v134, v111, v134
	v_fma_f32 v134, v111, v134, v111
	v_mul_f32_e32 v135, v107, v135
	v_mul_f32_e32 v134, 0x3fcc422a, v134
	v_fma_f32 v135, v107, v135, v107
	v_mul_f32_e32 v134, 0xbfb8aa3b, v134
	v_mul_f32_e32 v135, 0x3fcc422a, v135
	v_exp_f32_e32 v134, v134
	v_mul_f32_e32 v135, 0xbfb8aa3b, v135
	v_exp_f32_e32 v135, v135
	v_lshl_add_u64 v[112:113], v[112:113], 0, v[174:175]
	v_add_f32_e32 v134, 1.0, v134
	v_lshlrev_b64 v[112:113], 1, v[112:113]
	v_rcp_f32_e32 v105, v105
	v_rcp_f32_e32 v131, v131
	v_rcp_f32_e32 v134, v134
	v_add_f32_e32 v135, 1.0, v135
	v_lshl_add_u64 v[114:115], v[164:165], 0, v[112:113]
	v_lshl_add_u64 v[112:113], v[166:167], 0, v[112:113]
; __device__ __forceinline__ float gelu_tanh(float y) { const float z = 1.5957691216057308f * (y + 0.044715f * y * y * y); return y * sigmoidf_(z); }
; __device__ __forceinline__ u32x4 pack8(const f32x4 a, const f32x4 b) { u32x4 w; w.x = cvt_pk_bf16(a[0], a[1]); w.y = cvt_pk_bf16(a[2], a[3]); w.z = cvt_pk_bf16(b[0], b[1]); w.w = cvt_pk_bf16(b[2], b[3]); return w; }
; __device__ __forceinline__ void unpack8(const u32x4 w, f32x4& a, f32x4& b) { a[0] = bf_lo(w.x); a[1] = bf_hi(w.x); a[2] = bf_lo(w.y); a[3] = bf_hi(w.y); b[0] = bf_lo(w.z); b[1] = bf_hi(w.z); b[2] = bf_lo(w.w); b[3] = bf_hi(w.w); }
;     template <int KIND> __device__ __forceinline__ void run(f32x4 (&acc)[2][2][4][2], const Unit& u, int tid_in) const {
;     ...
;                     for (int ml = 0; ml < 2; ++ml) { const int m = mh * 2 + ml; int R = rbase + ai * 128 + m * 16; asm volatile("" : "+v"(R));
; #pragma unroll
;                         for (int bj = 0; bj < 2; ++bj) { const int t = 16 * u.pn + 8 * bj + 2 * wc + (fq >> 1); const size_t tok = (size_t)R * LCH + t;
;                             f32x4 y0, y1, u0, u1; unpack8(yv[ml][bj], y0, y1); unpack8(uv[ml][bj], u0, u1);
;                             y0 = acc[ai][bj][m][0] + y0 + d0 * u0; y1 = acc[ai][bj][m][1] + y1 + d1 * u1;
; #pragma unroll
;                             for (int j = 0; j < 4; ++j) { y0[j] = gelu_tanh(y0[j]); y1[j] = gelu_tanh(y1[j]); }
;                             *(u32x4*)(yi + ((size_t)g * T_TOK + tok) * 16 + 8 * (fq & 1)) = pack8(y0, y1); } }
	v_rcp_f32_e32 v135, v135
	global_load_dwordx4 v[116:119], v[114:115], off
	v_mul_f32_e32 v105, v110, v105
	global_load_dwordx4 v[112:115], v[112:113], off
	v_mul_f32_e32 v110, v106, v131
	v_ashrrev_i32_e32 v133, 31, v132
	v_lshlrev_b64 v[132:133], 10, v[132:133]
	v_lshl_add_u64 v[132:133], v[162:163], 0, v[132:133]
	v_mul_f32_e32 v106, v111, v134
	v_mul_f32_e32 v107, v107, v135
	v_cvt_pk_bf16_f32 v104, v0, v104
	v_cvt_pk_bf16_f32 v105, v105, v106
	v_cvt_pk_bf16_f32 v106, v108, v109
	v_lshl_add_u64 v[108:109], v[132:133], 0, v[136:137]
	v_cvt_pk_bf16_f32 v107, v110, v107
	global_store_dwordx4 v[108:109], v[104:107], off
	v_lshlrev_b32_e32 v108, 16, v148
	v_and_b32_e32 v109, 0xffff0000, v148
	v_lshlrev_b32_e32 v104, 16, v146
	v_and_b32_e32 v105, 0xffff0000, v146
	v_lshlrev_b32_e32 v134, 16, v150
	v_and_b32_e32 v135, 0xffff0000, v150
	v_lshlrev_b32_e32 v140, 16, v152
	v_and_b32_e32 v141, 0xffff0000, v152
	v_pk_add_f32 v[100:101], v[100:101], v[104:105]
	v_pk_add_f32 v[96:97], v[96:97], v[108:109]
	v_pk_fma_f32 v[100:101], v[60:61], v[134:135], v[100:101]
	v_pk_fma_f32 v[96:97], v[56:57], v[140:141], v[96:97]
	v_mul_f32_e32 v0, 0x3d372713, v100
	v_mul_f32_e32 v104, 0x3d372713, v96
	v_mul_f32_e32 v105, 0x3d372713, v101
	v_mul_f32_e32 v0, v100, v0
	v_mul_f32_e32 v104, v96, v104
	v_mul_f32_e32 v105, v101, v105
	v_fma_f32 v0, v100, v0, v100
	v_fma_f32 v104, v96, v104, v96
	v_fma_f32 v105, v101, v105, v101
	v_mul_f32_e32 v0, 0x3fcc422a, v0
	v_mul_f32_e32 v104, 0x3fcc422a, v104
	v_mul_f32_e32 v105, 0x3fcc422a, v105
	v_mul_f32_e32 v0, 0xbfb8aa3b, v0
	v_mul_f32_e32 v104, 0xbfb8aa3b, v104
	v_mul_f32_e32 v105, 0xbfb8aa3b, v105
	v_exp_f32_e32 v0, v0
	v_exp_f32_e32 v104, v104
	v_exp_f32_e32 v105, v105
	v_lshlrev_b32_e32 v106, 16, v147
	v_and_b32_e32 v107, 0xffff0000, v147
	v_pk_add_f32 v[102:103], v[102:103], v[106:107]
	v_add_f32_e32 v0, 1.0, v0
	v_add_f32_e32 v104, 1.0, v104
	v_add_f32_e32 v105, 1.0, v105
	v_mul_f32_e32 v106, 0x3d372713, v97
	v_rcp_f32_e32 v0, v0
	v_rcp_f32_e32 v104, v104
	v_rcp_f32_e32 v105, v105
	v_mul_f32_e32 v106, v97, v106
	v_lshlrev_b32_e32 v110, 16, v149
	v_and_b32_e32 v111, 0xffff0000, v149
	v_fma_f32 v106, v97, v106, v97
	v_lshlrev_b32_e32 v138, 16, v151
	v_and_b32_e32 v139, 0xffff0000, v151
	v_lshlrev_b32_e32 v142, 16, v153
	v_and_b32_e32 v143, 0xffff0000, v153
	v_pk_add_f32 v[98:99], v[98:99], v[110:111]
	v_mul_f32_e32 v106, 0x3fcc422a, v106
	v_pk_fma_f32 v[102:103], v[62:63], v[138:139], v[102:103]
	v_pk_fma_f32 v[98:99], v[58:59], v[142:143], v[98:99]
	v_mul_f32_e32 v106, 0xbfb8aa3b, v106
	v_exp_f32_e32 v106, v106
	v_mul_f32_e32 v0, v100, v0
	v_mul_f32_e32 v100, v96, v104
	v_mul_f32_e32 v96, v101, v105
	v_mul_f32_e32 v104, 0x3d372713, v102
	v_mul_f32_e32 v105, 0x3d372713, v98
	v_mul_f32_e32 v104, v102, v104
	v_mul_f32_e32 v105, v98, v105
	v_fma_f32 v104, v102, v104, v102
	v_fma_f32 v105, v98, v105, v98
	v_mul_f32_e32 v104, 0x3fcc422a, v104
	v_mul_f32_e32 v105, 0x3fcc422a, v105
	v_add_f32_e32 v101, 1.0, v106
	v_mul_f32_e32 v104, 0xbfb8aa3b, v104
	v_mul_f32_e32 v105, 0xbfb8aa3b, v105
	v_rcp_f32_e32 v101, v101
	v_exp_f32_e32 v104, v104
	v_exp_f32_e32 v105, v105
	v_mul_f32_e32 v106, 0x3d372713, v99
	v_mul_f32_e32 v101, v97, v101
	v_add_f32_e32 v97, 1.0, v104
	v_add_f32_e32 v104, 1.0, v105
	v_mul_f32_e32 v105, 0x3d372713, v103
	v_mul_f32_e32 v105, v103, v105
	v_mul_f32_e32 v106, v99, v106
	v_fma_f32 v105, v103, v105, v103
	v_fma_f32 v106, v99, v106, v99
	v_mul_f32_e32 v105, 0x3fcc422a, v105
	v_mul_f32_e32 v106, 0x3fcc422a, v106
	v_mul_f32_e32 v105, 0xbfb8aa3b, v105
	v_mul_f32_e32 v106, 0xbfb8aa3b, v106
	v_exp_f32_e32 v105, v105
	v_exp_f32_e32 v106, v106
	v_rcp_f32_e32 v97, v97
	v_rcp_f32_e32 v104, v104
	v_add_f32_e32 v105, 1.0, v105
	v_add_f32_e32 v106, 1.0, v106
	v_rcp_f32_e32 v105, v105
	v_rcp_f32_e32 v106, v106
	v_mul_f32_e32 v97, v102, v97
	v_mul_f32_e32 v102, v98, v104
	v_mul_f32_e32 v98, v103, v105
	v_mul_f32_e32 v99, v99, v106
	v_cvt_pk_bf16_f32 v96, v0, v96
	v_cvt_pk_bf16_f32 v97, v97, v98
	v_cvt_pk_bf16_f32 v98, v100, v101
	v_cvt_pk_bf16_f32 v99, v102, v99
	v_lshl_add_u64 v[100:101], v[132:133], 0, v[128:129]
	global_store_dwordx4 v[100:101], v[96:99], off
	s_waitcnt vmcnt(0)
	v_lshlrev_b32_e32 v102, 16, v126
	v_and_b32_e32 v103, 0xffff0000, v126
	v_lshlrev_b32_e32 v98, 16, v124
	v_and_b32_e32 v99, 0xffff0000, v124
	v_lshlrev_b32_e32 v106, 16, v120
	v_and_b32_e32 v107, 0xffff0000, v120
	v_lshlrev_b32_e32 v110, 16, v122
	v_and_b32_e32 v111, 0xffff0000, v122
	v_pk_add_f32 v[92:93], v[92:93], v[98:99]
	v_pk_add_f32 v[88:89], v[88:89], v[102:103]
	v_pk_fma_f32 v[92:93], v[60:61], v[106:107], v[92:93]
	v_pk_fma_f32 v[88:89], v[56:57], v[110:111], v[88:89]
	v_mul_f32_e32 v0, 0x3d372713, v92
	v_mul_f32_e32 v98, 0x3d372713, v88
	v_mul_f32_e32 v99, 0x3d372713, v93
	v_mul_f32_e32 v0, v92, v0
	v_mul_f32_e32 v98, v88, v98
	v_mul_f32_e32 v99, v93, v99
	v_fma_f32 v0, v92, v0, v92
	v_fma_f32 v98, v88, v98, v88
	v_fma_f32 v99, v93, v99, v93
	v_mul_f32_e32 v0, 0x3fcc422a, v0
	v_mul_f32_e32 v98, 0x3fcc422a, v98
	v_mul_f32_e32 v99, 0x3fcc422a, v99
	v_mul_f32_e32 v0, 0xbfb8aa3b, v0
	v_mul_f32_e32 v98, 0xbfb8aa3b, v98
	v_mul_f32_e32 v99, 0xbfb8aa3b, v99
	v_exp_f32_e32 v0, v0
	v_exp_f32_e32 v98, v98
	v_exp_f32_e32 v99, v99
	v_lshlrev_b32_e32 v100, 16, v125
	v_and_b32_e32 v101, 0xffff0000, v125
	v_pk_add_f32 v[94:95], v[94:95], v[100:101]
	v_add_f32_e32 v0, 1.0, v0
	v_add_f32_e32 v98, 1.0, v98
	v_add_f32_e32 v99, 1.0, v99
	v_mul_f32_e32 v100, 0x3d372713, v89
	v_rcp_f32_e32 v0, v0
	v_rcp_f32_e32 v98, v98
	v_rcp_f32_e32 v99, v99
	v_mul_f32_e32 v100, v89, v100
	v_lshlrev_b32_e32 v104, 16, v127
	v_and_b32_e32 v105, 0xffff0000, v127
; __device__ __forceinline__ float gelu_tanh(float y) { const float z = 1.5957691216057308f * (y + 0.044715f * y * y * y); return y * sigmoidf_(z); }
; __device__ __forceinline__ u32x4 pack8(const f32x4 a, const f32x4 b) { u32x4 w; w.x = cvt_pk_bf16(a[0], a[1]); w.y = cvt_pk_bf16(a[2], a[3]); w.z = cvt_pk_bf16(b[0], b[1]); w.w = cvt_pk_bf16(b[2], b[3]); return w; }
; __device__ __forceinline__ void unpack8(const u32x4 w, f32x4& a, f32x4& b) { a[0] = bf_lo(w.x); a[1] = bf_hi(w.x); a[2] = bf_lo(w.y); a[3] = bf_hi(w.y); b[0] = bf_lo(w.z); b[1] = bf_hi(w.z); b[2] = bf_lo(w.w); b[3] = bf_hi(w.w); }
;     template <int KIND> __device__ __forceinline__ void run(f32x4 (&acc)[2][2][4][2], const Unit& u, int tid_in) const {
;     ...
;                 for (int mh = 0; mh < 2; ++mh) { u32x4 yv[2][2], uv[2][2];
; #pragma unroll
;                     for (int ml = 0; ml < 2; ++ml) { int R = rbase + ai * 128 + (mh * 2 + ml) * 16; asm volatile("" : "+v"(R));
; #pragma unroll
;                         for (int bj = 0; bj < 2; ++bj) { const int t = 16 * u.pn + 8 * bj + 2 * wc + (fq >> 1); const size_t tok = (size_t)R * LCH + t;
;                             yv[ml][bj] = *(const u32x4*)(yi + ((size_t)g * T_TOK + tok) * 16 + 8 * (fq & 1)); uv[ml][bj] = *(const u32x4*)((const bf16_t*)x + ((size_t)g * T_TOK + tok) * 16 + 8 * (fq & 1)); } }
; #pragma unroll
;                     for (int ml = 0; ml < 2; ++ml) { const int m = mh * 2 + ml; int R = rbase + ai * 128 + m * 16; asm volatile("" : "+v"(R));
; #pragma unroll
;                         for (int bj = 0; bj < 2; ++bj) { const int t = 16 * u.pn + 8 * bj + 2 * wc + (fq >> 1); const size_t tok = (size_t)R * LCH + t;
;                             f32x4 y0, y1, u0, u1; unpack8(yv[ml][bj], y0, y1); unpack8(uv[ml][bj], u0, u1);
;                             y0 = acc[ai][bj][m][0] + y0 + d0 * u0; y1 = acc[ai][bj][m][1] + y1 + d1 * u1;
; #pragma unroll
;                             for (int j = 0; j < 4; ++j) { y0[j] = gelu_tanh(y0[j]); y1[j] = gelu_tanh(y1[j]); }
;                             *(u32x4*)(yi + ((size_t)g * T_TOK + tok) * 16 + 8 * (fq & 1)) = pack8(y0, y1); } }
	v_fma_f32 v100, v89, v100, v89
	v_lshlrev_b32_e32 v108, 16, v121
	v_and_b32_e32 v109, 0xffff0000, v121
	v_lshlrev_b32_e32 v120, 16, v123
	v_and_b32_e32 v121, 0xffff0000, v123
	v_pk_add_f32 v[90:91], v[90:91], v[104:105]
	v_mul_f32_e32 v100, 0x3fcc422a, v100
	v_pk_fma_f32 v[94:95], v[62:63], v[108:109], v[94:95]
	v_pk_fma_f32 v[90:91], v[58:59], v[120:121], v[90:91]
	v_mul_f32_e32 v100, 0xbfb8aa3b, v100
	v_exp_f32_e32 v100, v100
	v_mul_f32_e32 v0, v92, v0
	v_mul_f32_e32 v92, v88, v98
	v_mul_f32_e32 v88, v93, v99
	v_mul_f32_e32 v98, 0x3d372713, v94
	v_mul_f32_e32 v99, 0x3d372713, v90
	v_mul_f32_e32 v98, v94, v98
	v_mul_f32_e32 v99, v90, v99
	v_fma_f32 v98, v94, v98, v94
	v_fma_f32 v99, v90, v99, v90
	v_mul_f32_e32 v98, 0x3fcc422a, v98
	v_mul_f32_e32 v99, 0x3fcc422a, v99
	v_add_f32_e32 v93, 1.0, v100
	v_mul_f32_e32 v98, 0xbfb8aa3b, v98
	v_mul_f32_e32 v99, 0xbfb8aa3b, v99
	v_rcp_f32_e32 v93, v93
	v_exp_f32_e32 v98, v98
	v_exp_f32_e32 v99, v99
	v_mul_f32_e32 v100, 0x3d372713, v91
	v_mul_f32_e32 v93, v89, v93
	v_add_f32_e32 v89, 1.0, v98
	v_add_f32_e32 v98, 1.0, v99
	v_mul_f32_e32 v99, 0x3d372713, v95
	v_mul_f32_e32 v99, v95, v99
	v_fma_f32 v99, v95, v99, v95
	v_mul_f32_e32 v100, v91, v100
	v_mul_f32_e32 v99, 0x3fcc422a, v99
	v_fma_f32 v100, v91, v100, v91
	v_mul_f32_e32 v99, 0xbfb8aa3b, v99
	v_mul_f32_e32 v100, 0x3fcc422a, v100
	v_exp_f32_e32 v99, v99
	v_mul_f32_e32 v100, 0xbfb8aa3b, v100
	v_exp_f32_e32 v100, v100
	v_rcp_f32_e32 v89, v89
	v_add_f32_e32 v99, 1.0, v99
	v_rcp_f32_e32 v98, v98
	v_rcp_f32_e32 v99, v99
	v_add_f32_e32 v100, 1.0, v100
	v_rcp_f32_e32 v100, v100
	v_mul_f32_e32 v89, v94, v89
	v_ashrrev_i32_e32 v131, 31, v130
	v_lshlrev_b64 v[96:97], 10, v[130:131]
	v_lshl_add_u64 v[96:97], v[162:163], 0, v[96:97]
	v_mul_f32_e32 v94, v90, v98
	v_mul_f32_e32 v90, v95, v99
	v_mul_f32_e32 v91, v91, v100
	v_cvt_pk_bf16_f32 v88, v0, v88
	v_cvt_pk_bf16_f32 v89, v89, v90
	v_cvt_pk_bf16_f32 v90, v92, v93
	v_lshl_add_u64 v[92:93], v[96:97], 0, v[136:137]
	v_cvt_pk_bf16_f32 v91, v94, v91
	global_store_dwordx4 v[92:93], v[88:91], off
	v_lshlrev_b32_e32 v92, 16, v118
	v_and_b32_e32 v93, 0xffff0000, v118
	v_lshlrev_b32_e32 v88, 16, v116
	v_and_b32_e32 v89, 0xffff0000, v116
	v_lshlrev_b32_e32 v98, 16, v112
	v_and_b32_e32 v99, 0xffff0000, v112
	v_lshlrev_b32_e32 v102, 16, v114
	v_and_b32_e32 v103, 0xffff0000, v114
	v_pk_add_f32 v[84:85], v[84:85], v[88:89]
	v_pk_add_f32 v[80:81], v[80:81], v[92:93]
	v_pk_fma_f32 v[84:85], v[60:61], v[98:99], v[84:85]
	v_pk_fma_f32 v[80:81], v[56:57], v[102:103], v[80:81]
	v_mul_f32_e32 v0, 0x3d372713, v84
	v_mul_f32_e32 v88, 0x3d372713, v80
	v_mul_f32_e32 v89, 0x3d372713, v85
	v_mul_f32_e32 v0, v84, v0
	v_mul_f32_e32 v88, v80, v88
	v_mul_f32_e32 v89, v85, v89
	v_fma_f32 v0, v84, v0, v84
	v_fma_f32 v88, v80, v88, v80
	v_fma_f32 v89, v85, v89, v85
	v_mul_f32_e32 v0, 0x3fcc422a, v0
	v_mul_f32_e32 v88, 0x3fcc422a, v88
	v_mul_f32_e32 v89, 0x3fcc422a, v89
	v_mul_f32_e32 v0, 0xbfb8aa3b, v0
	v_mul_f32_e32 v88, 0xbfb8aa3b, v88
	v_mul_f32_e32 v89, 0xbfb8aa3b, v89
	v_exp_f32_e32 v0, v0
	v_exp_f32_e32 v88, v88
	v_exp_f32_e32 v89, v89
	v_lshlrev_b32_e32 v90, 16, v117
	v_and_b32_e32 v91, 0xffff0000, v117
	v_pk_add_f32 v[86:87], v[86:87], v[90:91]
	v_add_f32_e32 v0, 1.0, v0
	v_add_f32_e32 v88, 1.0, v88
	v_add_f32_e32 v89, 1.0, v89
	v_mul_f32_e32 v90, 0x3d372713, v81
	v_rcp_f32_e32 v0, v0
	v_rcp_f32_e32 v88, v88
	v_rcp_f32_e32 v89, v89
	v_mul_f32_e32 v90, v81, v90
	v_lshlrev_b32_e32 v94, 16, v119
	v_and_b32_e32 v95, 0xffff0000, v119
	v_fma_f32 v90, v81, v90, v81
	v_lshlrev_b32_e32 v100, 16, v113
	v_and_b32_e32 v101, 0xffff0000, v113
	v_lshlrev_b32_e32 v104, 16, v115
	v_and_b32_e32 v105, 0xffff0000, v115
	v_pk_add_f32 v[82:83], v[82:83], v[94:95]
	v_mul_f32_e32 v90, 0x3fcc422a, v90
	v_pk_fma_f32 v[86:87], v[62:63], v[100:101], v[86:87]
	v_pk_fma_f32 v[82:83], v[58:59], v[104:105], v[82:83]
	v_mul_f32_e32 v90, 0xbfb8aa3b, v90
	v_exp_f32_e32 v90, v90
	v_mul_f32_e32 v0, v84, v0
	v_mul_f32_e32 v84, v80, v88
	v_mul_f32_e32 v80, v85, v89
	v_mul_f32_e32 v88, 0x3d372713, v86
	v_mul_f32_e32 v89, 0x3d372713, v82
	v_mul_f32_e32 v88, v86, v88
	v_mul_f32_e32 v89, v82, v89
	v_fma_f32 v88, v86, v88, v86
	v_fma_f32 v89, v82, v89, v82
	v_mul_f32_e32 v88, 0x3fcc422a, v88
	v_mul_f32_e32 v89, 0x3fcc422a, v89
	v_add_f32_e32 v85, 1.0, v90
	v_mul_f32_e32 v88, 0xbfb8aa3b, v88
	v_mul_f32_e32 v89, 0xbfb8aa3b, v89
	v_rcp_f32_e32 v85, v85
	v_exp_f32_e32 v88, v88
	v_exp_f32_e32 v89, v89
	v_mul_f32_e32 v90, 0x3d372713, v83
	v_mul_f32_e32 v85, v81, v85
	v_add_f32_e32 v81, 1.0, v88
	v_add_f32_e32 v88, 1.0, v89
	v_mul_f32_e32 v89, 0x3d372713, v87
	v_mul_f32_e32 v89, v87, v89
	v_fma_f32 v89, v87, v89, v87
	v_mul_f32_e32 v90, v83, v90
	v_mul_f32_e32 v89, 0x3fcc422a, v89
	v_fma_f32 v90, v83, v90, v83
	v_mul_f32_e32 v89, 0xbfb8aa3b, v89
	v_mul_f32_e32 v90, 0x3fcc422a, v90
	v_exp_f32_e32 v89, v89
	v_mul_f32_e32 v90, 0xbfb8aa3b, v90
	v_exp_f32_e32 v90, v90
	v_rcp_f32_e32 v81, v81
	v_add_f32_e32 v89, 1.0, v89
	v_rcp_f32_e32 v88, v88
	v_rcp_f32_e32 v89, v89
	v_add_f32_e32 v90, 1.0, v90
	v_rcp_f32_e32 v90, v90
	v_mul_f32_e32 v81, v86, v81
	v_mul_f32_e32 v86, v82, v88
	v_mul_f32_e32 v82, v87, v89
	v_mul_f32_e32 v83, v83, v90
	v_cvt_pk_bf16_f32 v80, v0, v80
	v_cvt_pk_bf16_f32 v81, v81, v82
	v_cvt_pk_bf16_f32 v82, v84, v85
	v_lshl_add_u64 v[84:85], v[96:97], 0, v[128:129]
	v_add_u32_e32 v98, 0x80, v185
	v_cvt_pk_bf16_f32 v83, v86, v83
	global_store_dwordx4 v[84:85], v[80:83], off
	v_add_u32_e32 v96, 0x90, v185
	s_nop 0
	v_mov_b32_e32 v80, v98
	s_nop 0
	v_ashrrev_i32_e32 v81, 31, v80
	v_lshlrev_b64 v[80:81], 9, v[80:81]
	v_lshl_add_u64 v[80:81], v[80:81], 0, s[20:21]
	v_lshl_add_u64 v[82:83], v[80:81], 0, v[172:173]
	v_lshlrev_b64 v[82:83], 1, v[82:83]
	v_lshl_add_u64 v[84:85], v[164:165], 0, v[82:83]
	global_load_dwordx4 v[100:103], v[84:85], off
	v_lshl_add_u64 v[82:83], v[166:167], 0, v[82:83]
	global_load_dwordx4 v[104:107], v[82:83], off
	v_lshl_add_u64 v[80:81], v[80:81], 0, v[174:175]
	v_lshlrev_b64 v[80:81], 1, v[80:81]
	v_lshl_add_u64 v[82:83], v[164:165], 0, v[80:81]
	global_load_dwordx4 v[108:111], v[82:83], off
	v_lshl_add_u64 v[80:81], v[166:167], 0, v[80:81]
	global_load_dwordx4 v[112:115], v[80:81], off
	v_mov_b32_e32 v80, v96
	s_waitcnt vmcnt(0)
; __device__ __forceinline__ float gelu_tanh(float y) { const float z = 1.5957691216057308f * (y + 0.044715f * y * y * y); return y * sigmoidf_(z); }
; __device__ __forceinline__ u32x4 pack8(const f32x4 a, const f32x4 b) { u32x4 w; w.x = cvt_pk_bf16(a[0], a[1]); w.y = cvt_pk_bf16(a[2], a[3]); w.z = cvt_pk_bf16(b[0], b[1]); w.w = cvt_pk_bf16(b[2], b[3]); return w; }
; __device__ __forceinline__ void unpack8(const u32x4 w, f32x4& a, f32x4& b) { a[0] = bf_lo(w.x); a[1] = bf_hi(w.x); a[2] = bf_lo(w.y); a[3] = bf_hi(w.y); b[0] = bf_lo(w.z); b[1] = bf_hi(w.z); b[2] = bf_lo(w.w); b[3] = bf_hi(w.w); }
;     template <int KIND> __device__ __forceinline__ void run(f32x4 (&acc)[2][2][4][2], const Unit& u, int tid_in) const {
;     ...
;                     for (int ml = 0; ml < 2; ++ml) { const int m = mh * 2 + ml; int R = rbase + ai * 128 + m * 16; asm volatile("" : "+v"(R));
; #pragma unroll
;                         for (int bj = 0; bj < 2; ++bj) { const int t = 16 * u.pn + 8 * bj + 2 * wc + (fq >> 1); const size_t tok = (size_t)R * LCH + t;
;                             f32x4 y0, y1, u0, u1; unpack8(yv[ml][bj], y0, y1); unpack8(uv[ml][bj], u0, u1);
;                             y0 = acc[ai][bj][m][0] + y0 + d0 * u0; y1 = acc[ai][bj][m][1] + y1 + d1 * u1;
; #pragma unroll
;                             for (int j = 0; j < 4; ++j) { y0[j] = gelu_tanh(y0[j]); y1[j] = gelu_tanh(y1[j]); }
;                             *(u32x4*)(yi + ((size_t)g * T_TOK + tok) * 16 + 8 * (fq & 1)) = pack8(y0, y1); } }
	v_lshlrev_b32_e32 v116, 16, v100
	v_ashrrev_i32_e32 v81, 31, v80
	v_lshlrev_b64 v[80:81], 9, v[80:81]
	v_lshl_add_u64 v[80:81], v[80:81], 0, s[20:21]
	v_and_b32_e32 v117, 0xffff0000, v100
	v_lshlrev_b32_e32 v118, 16, v102
	v_and_b32_e32 v119, 0xffff0000, v102
	v_lshl_add_u64 v[82:83], v[80:81], 0, v[172:173]
	v_lshlrev_b32_e32 v120, 16, v104
	v_and_b32_e32 v121, 0xffff0000, v104
	v_lshlrev_b32_e32 v122, 16, v106
	v_and_b32_e32 v123, 0xffff0000, v106
	v_pk_add_f32 v[76:77], v[76:77], v[116:117]
	v_pk_add_f32 v[72:73], v[72:73], v[118:119]
	v_lshlrev_b64 v[82:83], 1, v[82:83]
	v_lshlrev_b32_e32 v100, 16, v101
	v_and_b32_e32 v101, 0xffff0000, v101
	v_pk_fma_f32 v[76:77], v[60:61], v[120:121], v[76:77]
	v_pk_fma_f32 v[72:73], v[56:57], v[122:123], v[72:73]
	v_lshl_add_u64 v[84:85], v[164:165], 0, v[82:83]
	v_pk_add_f32 v[78:79], v[78:79], v[100:101]
	v_mul_f32_e32 v0, 0x3d372713, v76
	v_mul_f32_e32 v97, 0x3d372713, v72
	v_mul_f32_e32 v100, 0x3d372713, v77
	global_load_dwordx4 v[92:95], v[84:85], off
	v_lshl_add_u64 v[82:83], v[166:167], 0, v[82:83]
	v_mul_f32_e32 v0, v76, v0
	v_mul_f32_e32 v97, v72, v97
	v_mul_f32_e32 v100, v77, v100
	global_load_dwordx4 v[88:91], v[82:83], off
	v_fma_f32 v0, v76, v0, v76
	v_fma_f32 v97, v72, v97, v72
	v_fma_f32 v100, v77, v100, v77
	v_mul_f32_e32 v0, 0x3fcc422a, v0
	v_mul_f32_e32 v97, 0x3fcc422a, v97
	v_mul_f32_e32 v100, 0x3fcc422a, v100
	v_mul_f32_e32 v0, 0xbfb8aa3b, v0
	v_mul_f32_e32 v97, 0xbfb8aa3b, v97
	v_mul_f32_e32 v100, 0xbfb8aa3b, v100
	v_exp_f32_e32 v0, v0
	v_exp_f32_e32 v97, v97
	v_exp_f32_e32 v100, v100
	v_mul_f32_e32 v101, 0x3d372713, v73
	v_add_f32_e32 v0, 1.0, v0
	v_add_f32_e32 v97, 1.0, v97
	v_add_f32_e32 v100, 1.0, v100
	v_rcp_f32_e32 v0, v0
	v_rcp_f32_e32 v97, v97
	v_rcp_f32_e32 v100, v100
	v_mul_f32_e32 v101, v73, v101
	v_lshlrev_b32_e32 v102, 16, v103
	v_and_b32_e32 v103, 0xffff0000, v103
	v_fma_f32 v101, v73, v101, v73
	v_lshlrev_b32_e32 v104, 16, v105
	v_and_b32_e32 v105, 0xffff0000, v105
	v_lshlrev_b32_e32 v106, 16, v107
	v_and_b32_e32 v107, 0xffff0000, v107
	v_pk_add_f32 v[74:75], v[74:75], v[102:103]
	v_mul_f32_e32 v101, 0x3fcc422a, v101
	v_pk_fma_f32 v[78:79], v[62:63], v[104:105], v[78:79]
	v_pk_fma_f32 v[74:75], v[58:59], v[106:107], v[74:75]
	v_mul_f32_e32 v101, 0xbfb8aa3b, v101
	v_exp_f32_e32 v101, v101
	v_mul_f32_e32 v0, v76, v0
	v_mul_f32_e32 v76, v72, v97
	v_mul_f32_e32 v72, v77, v100
	v_mul_f32_e32 v97, 0x3d372713, v78
	v_mul_f32_e32 v100, 0x3d372713, v74
	v_mul_f32_e32 v97, v78, v97
	v_mul_f32_e32 v100, v74, v100
	v_fma_f32 v97, v78, v97, v78
	v_fma_f32 v100, v74, v100, v74
	v_mul_f32_e32 v97, 0x3fcc422a, v97
	v_mul_f32_e32 v100, 0x3fcc422a, v100
	v_add_f32_e32 v77, 1.0, v101
	v_mul_f32_e32 v97, 0xbfb8aa3b, v97
	v_mul_f32_e32 v100, 0xbfb8aa3b, v100
	v_rcp_f32_e32 v77, v77
	v_exp_f32_e32 v97, v97
	v_exp_f32_e32 v100, v100
	v_mul_f32_e32 v101, 0x3d372713, v75
	v_mul_f32_e32 v77, v73, v77
	v_add_f32_e32 v73, 1.0, v97
	v_add_f32_e32 v97, 1.0, v100
	v_mul_f32_e32 v100, 0x3d372713, v79
	v_mul_f32_e32 v100, v79, v100
	v_fma_f32 v100, v79, v100, v79
	v_mul_f32_e32 v101, v75, v101
	v_mul_f32_e32 v100, 0x3fcc422a, v100
	v_fma_f32 v101, v75, v101, v75
	v_mul_f32_e32 v100, 0xbfb8aa3b, v100
	v_mul_f32_e32 v101, 0x3fcc422a, v101
	v_exp_f32_e32 v100, v100
	v_mul_f32_e32 v101, 0xbfb8aa3b, v101
	v_exp_f32_e32 v101, v101
	v_lshl_add_u64 v[80:81], v[80:81], 0, v[174:175]
	v_add_f32_e32 v100, 1.0, v100
	v_lshlrev_b64 v[80:81], 1, v[80:81]
	v_rcp_f32_e32 v73, v73
	v_rcp_f32_e32 v97, v97
	v_rcp_f32_e32 v100, v100
	v_add_f32_e32 v101, 1.0, v101
	v_lshl_add_u64 v[82:83], v[164:165], 0, v[80:81]
	v_lshl_add_u64 v[80:81], v[166:167], 0, v[80:81]
	v_rcp_f32_e32 v101, v101
	global_load_dwordx4 v[84:87], v[82:83], off
	v_mul_f32_e32 v73, v78, v73
	global_load_dwordx4 v[80:83], v[80:81], off
	v_mul_f32_e32 v78, v74, v97
	v_ashrrev_i32_e32 v99, 31, v98
	v_lshlrev_b64 v[98:99], 10, v[98:99]
	v_lshl_add_u64 v[98:99], v[162:163], 0, v[98:99]
	v_mul_f32_e32 v74, v79, v100
	v_mul_f32_e32 v75, v75, v101
	v_cvt_pk_bf16_f32 v72, v0, v72
	v_cvt_pk_bf16_f32 v73, v73, v74
	v_cvt_pk_bf16_f32 v74, v76, v77
	v_lshl_add_u64 v[76:77], v[98:99], 0, v[136:137]
	v_cvt_pk_bf16_f32 v75, v78, v75
	global_store_dwordx4 v[76:77], v[72:75], off
	v_lshlrev_b32_e32 v76, 16, v110
	v_and_b32_e32 v77, 0xffff0000, v110
	v_lshlrev_b32_e32 v72, 16, v108
	v_and_b32_e32 v73, 0xffff0000, v108
	v_lshlrev_b32_e32 v100, 16, v112
	v_and_b32_e32 v101, 0xffff0000, v112
	v_lshlrev_b32_e32 v104, 16, v114
	v_and_b32_e32 v105, 0xffff0000, v114
	v_pk_add_f32 v[68:69], v[68:69], v[72:73]
	v_pk_add_f32 v[64:65], v[64:65], v[76:77]
	v_pk_fma_f32 v[68:69], v[60:61], v[100:101], v[68:69]
	v_pk_fma_f32 v[64:65], v[56:57], v[104:105], v[64:65]
	v_mul_f32_e32 v0, 0x3d372713, v68
	v_mul_f32_e32 v72, 0x3d372713, v64
	v_mul_f32_e32 v73, 0x3d372713, v69
	v_mul_f32_e32 v0, v68, v0
	v_mul_f32_e32 v72, v64, v72
	v_mul_f32_e32 v73, v69, v73
	v_fma_f32 v0, v68, v0, v68
	v_fma_f32 v72, v64, v72, v64
	v_fma_f32 v73, v69, v73, v69
	v_mul_f32_e32 v0, 0x3fcc422a, v0
	v_mul_f32_e32 v72, 0x3fcc422a, v72
	v_mul_f32_e32 v73, 0x3fcc422a, v73
	v_mul_f32_e32 v0, 0xbfb8aa3b, v0
	v_mul_f32_e32 v72, 0xbfb8aa3b, v72
	v_mul_f32_e32 v73, 0xbfb8aa3b, v73
	v_exp_f32_e32 v0, v0
	v_exp_f32_e32 v72, v72
	v_exp_f32_e32 v73, v73
	v_lshlrev_b32_e32 v74, 16, v109
	v_and_b32_e32 v75, 0xffff0000, v109
	v_pk_add_f32 v[70:71], v[70:71], v[74:75]
	v_add_f32_e32 v0, 1.0, v0
	v_add_f32_e32 v72, 1.0, v72
	v_add_f32_e32 v73, 1.0, v73
	v_mul_f32_e32 v74, 0x3d372713, v65
	v_rcp_f32_e32 v0, v0
	v_rcp_f32_e32 v72, v72
	v_rcp_f32_e32 v73, v73
	v_mul_f32_e32 v74, v65, v74
	v_lshlrev_b32_e32 v78, 16, v111
; __device__ __forceinline__ float gelu_tanh(float y) { const float z = 1.5957691216057308f * (y + 0.044715f * y * y * y); return y * sigmoidf_(z); }
; __device__ __forceinline__ u32x4 pack8(const f32x4 a, const f32x4 b) { u32x4 w; w.x = cvt_pk_bf16(a[0], a[1]); w.y = cvt_pk_bf16(a[2], a[3]); w.z = cvt_pk_bf16(b[0], b[1]); w.w = cvt_pk_bf16(b[2], b[3]); return w; }
; __device__ __forceinline__ void unpack8(const u32x4 w, f32x4& a, f32x4& b) { a[0] = bf_lo(w.x); a[1] = bf_hi(w.x); a[2] = bf_lo(w.y); a[3] = bf_hi(w.y); b[0] = bf_lo(w.z); b[1] = bf_hi(w.z); b[2] = bf_lo(w.w); b[3] = bf_hi(w.w); }
;     template <int KIND> __device__ __forceinline__ void run(f32x4 (&acc)[2][2][4][2], const Unit& u, int tid_in) const {
;     ...
;                     for (int ml = 0; ml < 2; ++ml) { const int m = mh * 2 + ml; int R = rbase + ai * 128 + m * 16; asm volatile("" : "+v"(R));
; #pragma unroll
;                         for (int bj = 0; bj < 2; ++bj) { const int t = 16 * u.pn + 8 * bj + 2 * wc + (fq >> 1); const size_t tok = (size_t)R * LCH + t;
;                             f32x4 y0, y1, u0, u1; unpack8(yv[ml][bj], y0, y1); unpack8(uv[ml][bj], u0, u1);
;                             y0 = acc[ai][bj][m][0] + y0 + d0 * u0; y1 = acc[ai][bj][m][1] + y1 + d1 * u1;
; #pragma unroll
;                             for (int j = 0; j < 4; ++j) { y0[j] = gelu_tanh(y0[j]); y1[j] = gelu_tanh(y1[j]); }
;                             *(u32x4*)(yi + ((size_t)g * T_TOK + tok) * 16 + 8 * (fq & 1)) = pack8(y0, y1); } }
	v_and_b32_e32 v79, 0xffff0000, v111
	v_fma_f32 v74, v65, v74, v65
	v_lshlrev_b32_e32 v102, 16, v113
	v_and_b32_e32 v103, 0xffff0000, v113
	v_lshlrev_b32_e32 v106, 16, v115
	v_and_b32_e32 v107, 0xffff0000, v115
	v_pk_add_f32 v[66:67], v[66:67], v[78:79]
	v_mul_f32_e32 v74, 0x3fcc422a, v74
	v_pk_fma_f32 v[70:71], v[62:63], v[102:103], v[70:71]
	v_pk_fma_f32 v[66:67], v[58:59], v[106:107], v[66:67]
	v_mul_f32_e32 v74, 0xbfb8aa3b, v74
	v_exp_f32_e32 v74, v74
	v_mul_f32_e32 v0, v68, v0
	v_mul_f32_e32 v68, v64, v72
	v_mul_f32_e32 v64, v69, v73
	v_mul_f32_e32 v72, 0x3d372713, v70
	v_mul_f32_e32 v73, 0x3d372713, v66
	v_mul_f32_e32 v72, v70, v72
	v_mul_f32_e32 v73, v66, v73
	v_fma_f32 v72, v70, v72, v70
	v_fma_f32 v73, v66, v73, v66
	v_mul_f32_e32 v72, 0x3fcc422a, v72
	v_mul_f32_e32 v73, 0x3fcc422a, v73
	v_add_f32_e32 v69, 1.0, v74
	v_mul_f32_e32 v72, 0xbfb8aa3b, v72
	v_mul_f32_e32 v73, 0xbfb8aa3b, v73
	v_rcp_f32_e32 v69, v69
	v_exp_f32_e32 v72, v72
	v_exp_f32_e32 v73, v73
	v_mul_f32_e32 v74, 0x3d372713, v67
	v_mul_f32_e32 v69, v65, v69
	v_add_f32_e32 v65, 1.0, v72
	v_add_f32_e32 v72, 1.0, v73
	v_mul_f32_e32 v73, 0x3d372713, v71
	v_mul_f32_e32 v73, v71, v73
	v_mul_f32_e32 v74, v67, v74
	v_fma_f32 v73, v71, v73, v71
	v_fma_f32 v74, v67, v74, v67
	v_mul_f32_e32 v73, 0x3fcc422a, v73
	v_mul_f32_e32 v74, 0x3fcc422a, v74
	v_mul_f32_e32 v73, 0xbfb8aa3b, v73
	v_mul_f32_e32 v74, 0xbfb8aa3b, v74
	v_exp_f32_e32 v73, v73
	v_exp_f32_e32 v74, v74
	v_rcp_f32_e32 v65, v65
	v_rcp_f32_e32 v72, v72
	v_add_f32_e32 v73, 1.0, v73
	v_add_f32_e32 v74, 1.0, v74
	v_rcp_f32_e32 v73, v73
	v_rcp_f32_e32 v74, v74
	v_mul_f32_e32 v65, v70, v65
	v_mul_f32_e32 v70, v66, v72
	v_mul_f32_e32 v66, v71, v73
	v_mul_f32_e32 v67, v67, v74
	v_cvt_pk_bf16_f32 v64, v0, v64
	v_cvt_pk_bf16_f32 v65, v65, v66
	v_cvt_pk_bf16_f32 v66, v68, v69
	v_cvt_pk_bf16_f32 v67, v70, v67
	v_lshl_add_u64 v[68:69], v[98:99], 0, v[128:129]
	global_store_dwordx4 v[68:69], v[64:67], off
	s_waitcnt vmcnt(0)
	v_lshlrev_b32_e32 v70, 16, v94
	v_and_b32_e32 v71, 0xffff0000, v94
	v_lshlrev_b32_e32 v66, 16, v92
	v_and_b32_e32 v67, 0xffff0000, v92
	v_lshlrev_b32_e32 v74, 16, v88
	v_and_b32_e32 v75, 0xffff0000, v88
	v_lshlrev_b32_e32 v78, 16, v90
	v_and_b32_e32 v79, 0xffff0000, v90
	v_pk_add_f32 v[52:53], v[52:53], v[66:67]
	v_pk_add_f32 v[48:49], v[48:49], v[70:71]
	v_pk_fma_f32 v[52:53], v[60:61], v[74:75], v[52:53]
	v_pk_fma_f32 v[48:49], v[56:57], v[78:79], v[48:49]
	v_mul_f32_e32 v0, 0x3d372713, v52
	v_mul_f32_e32 v66, 0x3d372713, v48
	v_mul_f32_e32 v67, 0x3d372713, v53
	v_mul_f32_e32 v0, v52, v0
	v_mul_f32_e32 v66, v48, v66
	v_mul_f32_e32 v67, v53, v67
	v_fma_f32 v0, v52, v0, v52
	v_fma_f32 v66, v48, v66, v48
	v_fma_f32 v67, v53, v67, v53
	v_mul_f32_e32 v0, 0x3fcc422a, v0
	v_mul_f32_e32 v66, 0x3fcc422a, v66
	v_mul_f32_e32 v67, 0x3fcc422a, v67
	v_mul_f32_e32 v0, 0xbfb8aa3b, v0
	v_mul_f32_e32 v66, 0xbfb8aa3b, v66
	v_mul_f32_e32 v67, 0xbfb8aa3b, v67
	v_exp_f32_e32 v0, v0
	v_exp_f32_e32 v66, v66
	v_exp_f32_e32 v67, v67
	v_lshlrev_b32_e32 v68, 16, v93
	v_and_b32_e32 v69, 0xffff0000, v93
	v_pk_add_f32 v[54:55], v[54:55], v[68:69]
	v_add_f32_e32 v0, 1.0, v0
	v_add_f32_e32 v66, 1.0, v66
	v_add_f32_e32 v67, 1.0, v67
	v_mul_f32_e32 v68, 0x3d372713, v49
	v_rcp_f32_e32 v0, v0
	v_rcp_f32_e32 v66, v66
	v_rcp_f32_e32 v67, v67
	v_mul_f32_e32 v68, v49, v68
	v_lshlrev_b32_e32 v72, 16, v95
	v_and_b32_e32 v73, 0xffff0000, v95
	v_fma_f32 v68, v49, v68, v49
	v_lshlrev_b32_e32 v76, 16, v89
	v_and_b32_e32 v77, 0xffff0000, v89
	v_lshlrev_b32_e32 v88, 16, v91
	v_and_b32_e32 v89, 0xffff0000, v91
	v_pk_add_f32 v[50:51], v[50:51], v[72:73]
	v_mul_f32_e32 v68, 0x3fcc422a, v68
	v_pk_fma_f32 v[54:55], v[62:63], v[76:77], v[54:55]
	v_pk_fma_f32 v[50:51], v[58:59], v[88:89], v[50:51]
	v_mul_f32_e32 v68, 0xbfb8aa3b, v68
	v_exp_f32_e32 v68, v68
	v_mul_f32_e32 v0, v52, v0
	v_mul_f32_e32 v52, v48, v66
	v_mul_f32_e32 v48, v53, v67
	v_mul_f32_e32 v66, 0x3d372713, v54
	v_mul_f32_e32 v67, 0x3d372713, v50
	v_mul_f32_e32 v66, v54, v66
	v_mul_f32_e32 v67, v50, v67
	v_fma_f32 v66, v54, v66, v54
	v_fma_f32 v67, v50, v67, v50
	v_mul_f32_e32 v66, 0x3fcc422a, v66
	v_mul_f32_e32 v67, 0x3fcc422a, v67
	v_add_f32_e32 v53, 1.0, v68
	v_mul_f32_e32 v66, 0xbfb8aa3b, v66
	v_mul_f32_e32 v67, 0xbfb8aa3b, v67
	v_rcp_f32_e32 v53, v53
	v_exp_f32_e32 v66, v66
	v_exp_f32_e32 v67, v67
	v_mul_f32_e32 v68, 0x3d372713, v51
	v_mul_f32_e32 v53, v49, v53
	v_add_f32_e32 v49, 1.0, v66
	v_add_f32_e32 v66, 1.0, v67
	v_mul_f32_e32 v67, 0x3d372713, v55
	v_mul_f32_e32 v67, v55, v67
	v_fma_f32 v67, v55, v67, v55
	v_mul_f32_e32 v68, v51, v68
	v_mul_f32_e32 v67, 0x3fcc422a, v67
	v_fma_f32 v68, v51, v68, v51
	v_mul_f32_e32 v67, 0xbfb8aa3b, v67
	v_mul_f32_e32 v68, 0x3fcc422a, v68
	v_exp_f32_e32 v67, v67
	v_mul_f32_e32 v68, 0xbfb8aa3b, v68
	v_exp_f32_e32 v68, v68
	v_rcp_f32_e32 v49, v49
	v_add_f32_e32 v67, 1.0, v67
	v_rcp_f32_e32 v66, v66
	v_rcp_f32_e32 v67, v67
	v_add_f32_e32 v68, 1.0, v68
	v_rcp_f32_e32 v68, v68
	v_mul_f32_e32 v49, v54, v49
	v_ashrrev_i32_e32 v97, 31, v96
	v_lshlrev_b64 v[64:65], 10, v[96:97]
	v_lshl_add_u64 v[64:65], v[162:163], 0, v[64:65]
	v_mul_f32_e32 v54, v50, v66
	v_mul_f32_e32 v50, v55, v67
	v_mul_f32_e32 v51, v51, v68
	v_cvt_pk_bf16_f32 v48, v0, v48
	v_cvt_pk_bf16_f32 v49, v49, v50
	v_cvt_pk_bf16_f32 v50, v52, v53
	v_lshl_add_u64 v[52:53], v[64:65], 0, v[136:137]
	v_cvt_pk_bf16_f32 v51, v54, v51
	global_store_dwordx4 v[52:53], v[48:51], off
	v_lshlrev_b32_e32 v52, 16, v86
	v_and_b32_e32 v53, 0xffff0000, v86
	v_lshlrev_b32_e32 v48, 16, v84
	v_and_b32_e32 v49, 0xffff0000, v84
	v_lshlrev_b32_e32 v66, 16, v80
	v_and_b32_e32 v67, 0xffff0000, v80
	v_lshlrev_b32_e32 v70, 16, v82
; __device__ __forceinline__ float gelu_tanh(float y) { const float z = 1.5957691216057308f * (y + 0.044715f * y * y * y); return y * sigmoidf_(z); }
; __device__ __forceinline__ u32x4 pack8(const f32x4 a, const f32x4 b) { u32x4 w; w.x = cvt_pk_bf16(a[0], a[1]); w.y = cvt_pk_bf16(a[2], a[3]); w.z = cvt_pk_bf16(b[0], b[1]); w.w = cvt_pk_bf16(b[2], b[3]); return w; }
; __device__ __forceinline__ void unpack8(const u32x4 w, f32x4& a, f32x4& b) { a[0] = bf_lo(w.x); a[1] = bf_hi(w.x); a[2] = bf_lo(w.y); a[3] = bf_hi(w.y); b[0] = bf_lo(w.z); b[1] = bf_hi(w.z); b[2] = bf_lo(w.w); b[3] = bf_hi(w.w); }
;     template <int KIND> __device__ __forceinline__ void run(f32x4 (&acc)[2][2][4][2], const Unit& u, int tid_in) const {
;     ...
;                 for (int mh = 0; mh < 2; ++mh) { u32x4 yv[2][2], uv[2][2];
; #pragma unroll
;                     for (int ml = 0; ml < 2; ++ml) { int R = rbase + ai * 128 + (mh * 2 + ml) * 16; asm volatile("" : "+v"(R));
; #pragma unroll
;                         for (int bj = 0; bj < 2; ++bj) { const int t = 16 * u.pn + 8 * bj + 2 * wc + (fq >> 1); const size_t tok = (size_t)R * LCH + t;
;                             yv[ml][bj] = *(const u32x4*)(yi + ((size_t)g * T_TOK + tok) * 16 + 8 * (fq & 1)); uv[ml][bj] = *(const u32x4*)((const bf16_t*)x + ((size_t)g * T_TOK + tok) * 16 + 8 * (fq & 1)); } }
; #pragma unroll
;                     for (int ml = 0; ml < 2; ++ml) { const int m = mh * 2 + ml; int R = rbase + ai * 128 + m * 16; asm volatile("" : "+v"(R));
; #pragma unroll
;                         for (int bj = 0; bj < 2; ++bj) { const int t = 16 * u.pn + 8 * bj + 2 * wc + (fq >> 1); const size_t tok = (size_t)R * LCH + t;
;                             f32x4 y0, y1, u0, u1; unpack8(yv[ml][bj], y0, y1); unpack8(uv[ml][bj], u0, u1);
;                             y0 = acc[ai][bj][m][0] + y0 + d0 * u0; y1 = acc[ai][bj][m][1] + y1 + d1 * u1;
; #pragma unroll
;                             for (int j = 0; j < 4; ++j) { y0[j] = gelu_tanh(y0[j]); y1[j] = gelu_tanh(y1[j]); }
;                             *(u32x4*)(yi + ((size_t)g * T_TOK + tok) * 16 + 8 * (fq & 1)) = pack8(y0, y1); } }
	v_and_b32_e32 v71, 0xffff0000, v82
	v_pk_add_f32 v[44:45], v[44:45], v[48:49]
	v_pk_add_f32 v[40:41], v[40:41], v[52:53]
	v_pk_fma_f32 v[44:45], v[60:61], v[66:67], v[44:45]
	v_pk_fma_f32 v[40:41], v[56:57], v[70:71], v[40:41]
	v_mul_f32_e32 v0, 0x3d372713, v44
	v_mul_f32_e32 v48, 0x3d372713, v40
	v_mul_f32_e32 v49, 0x3d372713, v45
	v_mul_f32_e32 v0, v44, v0
	v_mul_f32_e32 v48, v40, v48
	v_mul_f32_e32 v49, v45, v49
	v_fma_f32 v0, v44, v0, v44
	v_fma_f32 v48, v40, v48, v40
	v_fma_f32 v49, v45, v49, v45
	v_mul_f32_e32 v0, 0x3fcc422a, v0
	v_mul_f32_e32 v48, 0x3fcc422a, v48
	v_mul_f32_e32 v49, 0x3fcc422a, v49
	v_mul_f32_e32 v0, 0xbfb8aa3b, v0
	v_mul_f32_e32 v48, 0xbfb8aa3b, v48
	v_mul_f32_e32 v49, 0xbfb8aa3b, v49
	v_exp_f32_e32 v0, v0
	v_exp_f32_e32 v48, v48
	v_exp_f32_e32 v49, v49
	v_lshlrev_b32_e32 v50, 16, v85
	v_and_b32_e32 v51, 0xffff0000, v85
	v_pk_add_f32 v[46:47], v[46:47], v[50:51]
	v_add_f32_e32 v0, 1.0, v0
	v_add_f32_e32 v48, 1.0, v48
	v_add_f32_e32 v49, 1.0, v49
	v_mul_f32_e32 v50, 0x3d372713, v41
	v_rcp_f32_e32 v0, v0
	v_rcp_f32_e32 v48, v48
	v_rcp_f32_e32 v49, v49
	v_mul_f32_e32 v50, v41, v50
	v_lshlrev_b32_e32 v54, 16, v87
	v_and_b32_e32 v55, 0xffff0000, v87
	v_fma_f32 v50, v41, v50, v41
	v_lshlrev_b32_e32 v68, 16, v81
	v_and_b32_e32 v69, 0xffff0000, v81
	v_lshlrev_b32_e32 v72, 16, v83
	v_and_b32_e32 v73, 0xffff0000, v83
	v_pk_add_f32 v[42:43], v[42:43], v[54:55]
	v_mul_f32_e32 v50, 0x3fcc422a, v50
	v_pk_fma_f32 v[46:47], v[62:63], v[68:69], v[46:47]
	v_pk_fma_f32 v[42:43], v[58:59], v[72:73], v[42:43]
	v_mul_f32_e32 v50, 0xbfb8aa3b, v50
	v_exp_f32_e32 v50, v50
	v_mul_f32_e32 v0, v44, v0
	v_mul_f32_e32 v44, v40, v48
	v_mul_f32_e32 v40, v45, v49
	v_mul_f32_e32 v48, 0x3d372713, v46
	v_mul_f32_e32 v49, 0x3d372713, v42
	v_mul_f32_e32 v48, v46, v48
	v_mul_f32_e32 v49, v42, v49
	v_fma_f32 v48, v46, v48, v46
	v_fma_f32 v49, v42, v49, v42
	v_mul_f32_e32 v48, 0x3fcc422a, v48
	v_mul_f32_e32 v49, 0x3fcc422a, v49
	v_add_f32_e32 v45, 1.0, v50
	v_mul_f32_e32 v48, 0xbfb8aa3b, v48
	v_mul_f32_e32 v49, 0xbfb8aa3b, v49
	v_rcp_f32_e32 v45, v45
	v_exp_f32_e32 v48, v48
	v_exp_f32_e32 v49, v49
	v_mul_f32_e32 v50, 0x3d372713, v43
	v_mul_f32_e32 v45, v41, v45
	v_add_f32_e32 v41, 1.0, v48
	v_add_f32_e32 v48, 1.0, v49
	v_mul_f32_e32 v49, 0x3d372713, v47
	v_mul_f32_e32 v49, v47, v49
	v_fma_f32 v49, v47, v49, v47
	v_mul_f32_e32 v50, v43, v50
	v_mul_f32_e32 v49, 0x3fcc422a, v49
	v_fma_f32 v50, v43, v50, v43
	v_mul_f32_e32 v49, 0xbfb8aa3b, v49
	v_mul_f32_e32 v50, 0x3fcc422a, v50
	v_exp_f32_e32 v49, v49
	v_mul_f32_e32 v50, 0xbfb8aa3b, v50
	v_exp_f32_e32 v50, v50
	v_rcp_f32_e32 v41, v41
	v_add_f32_e32 v49, 1.0, v49
	v_rcp_f32_e32 v48, v48
	v_rcp_f32_e32 v49, v49
	v_add_f32_e32 v50, 1.0, v50
	v_rcp_f32_e32 v50, v50
	v_mul_f32_e32 v41, v46, v41
	v_mul_f32_e32 v46, v42, v48
	v_mul_f32_e32 v42, v47, v49
	v_mul_f32_e32 v43, v43, v50
	v_cvt_pk_bf16_f32 v40, v0, v40
	v_cvt_pk_bf16_f32 v41, v41, v42
	v_cvt_pk_bf16_f32 v42, v44, v45
	v_lshl_add_u64 v[44:45], v[64:65], 0, v[128:129]
	v_add_u32_e32 v66, 0xa0, v185
	v_cvt_pk_bf16_f32 v43, v46, v43
	global_store_dwordx4 v[44:45], v[40:43], off
	v_add_u32_e32 v64, 0xb0, v185
	s_nop 0
	v_mov_b32_e32 v40, v66
	s_nop 0
	v_ashrrev_i32_e32 v41, 31, v40
	v_lshlrev_b64 v[40:41], 9, v[40:41]
	v_lshl_add_u64 v[40:41], v[40:41], 0, s[20:21]
	v_lshl_add_u64 v[42:43], v[40:41], 0, v[172:173]
	v_lshlrev_b64 v[42:43], 1, v[42:43]
	v_lshl_add_u64 v[44:45], v[164:165], 0, v[42:43]
	global_load_dwordx4 v[68:71], v[44:45], off
	v_lshl_add_u64 v[42:43], v[166:167], 0, v[42:43]
	global_load_dwordx4 v[72:75], v[42:43], off
	v_lshl_add_u64 v[40:41], v[40:41], 0, v[174:175]
	v_lshlrev_b64 v[40:41], 1, v[40:41]
	v_lshl_add_u64 v[42:43], v[164:165], 0, v[40:41]
	global_load_dwordx4 v[76:79], v[42:43], off
	v_lshl_add_u64 v[40:41], v[166:167], 0, v[40:41]
	global_load_dwordx4 v[80:83], v[40:41], off
	v_mov_b32_e32 v40, v64
	s_waitcnt vmcnt(0)
	v_lshlrev_b32_e32 v84, 16, v68
	v_ashrrev_i32_e32 v41, 31, v40
	v_lshlrev_b64 v[40:41], 9, v[40:41]
	v_lshl_add_u64 v[40:41], v[40:41], 0, s[20:21]
	v_and_b32_e32 v85, 0xffff0000, v68
	v_lshlrev_b32_e32 v86, 16, v70
	v_and_b32_e32 v87, 0xffff0000, v70
	v_lshl_add_u64 v[42:43], v[40:41], 0, v[172:173]
	v_lshlrev_b32_e32 v88, 16, v72
	v_and_b32_e32 v89, 0xffff0000, v72
	v_lshlrev_b32_e32 v90, 16, v74
	v_and_b32_e32 v91, 0xffff0000, v74
	v_pk_add_f32 v[36:37], v[36:37], v[84:85]
	v_pk_add_f32 v[32:33], v[32:33], v[86:87]
	v_lshlrev_b64 v[42:43], 1, v[42:43]
	v_lshlrev_b32_e32 v68, 16, v69
	v_and_b32_e32 v69, 0xffff0000, v69
	v_pk_fma_f32 v[36:37], v[60:61], v[88:89], v[36:37]
	v_pk_fma_f32 v[32:33], v[56:57], v[90:91], v[32:33]
	v_lshl_add_u64 v[44:45], v[164:165], 0, v[42:43]
	v_pk_add_f32 v[38:39], v[38:39], v[68:69]
	v_mul_f32_e32 v0, 0x3d372713, v36
	v_mul_f32_e32 v65, 0x3d372713, v32
	v_mul_f32_e32 v68, 0x3d372713, v37
	global_load_dwordx4 v[52:55], v[44:45], off
	v_lshl_add_u64 v[42:43], v[166:167], 0, v[42:43]
	v_mul_f32_e32 v0, v36, v0
	v_mul_f32_e32 v65, v32, v65
	v_mul_f32_e32 v68, v37, v68
	global_load_dwordx4 v[48:51], v[42:43], off
	v_fma_f32 v0, v36, v0, v36
	v_fma_f32 v65, v32, v65, v32
	v_fma_f32 v68, v37, v68, v37
	v_mul_f32_e32 v0, 0x3fcc422a, v0
	v_mul_f32_e32 v65, 0x3fcc422a, v65
	v_mul_f32_e32 v68, 0x3fcc422a, v68
	v_mul_f32_e32 v0, 0xbfb8aa3b, v0
	v_mul_f32_e32 v65, 0xbfb8aa3b, v65
	v_mul_f32_e32 v68, 0xbfb8aa3b, v68
	v_exp_f32_e32 v0, v0
	v_exp_f32_e32 v65, v65
	v_exp_f32_e32 v68, v68
	v_mul_f32_e32 v69, 0x3d372713, v33
	v_add_f32_e32 v0, 1.0, v0
	v_add_f32_e32 v65, 1.0, v65
	v_add_f32_e32 v68, 1.0, v68
	v_rcp_f32_e32 v0, v0
	v_rcp_f32_e32 v65, v65
	v_rcp_f32_e32 v68, v68
; __device__ __forceinline__ float gelu_tanh(float y) { const float z = 1.5957691216057308f * (y + 0.044715f * y * y * y); return y * sigmoidf_(z); }
; __device__ __forceinline__ u32x4 pack8(const f32x4 a, const f32x4 b) { u32x4 w; w.x = cvt_pk_bf16(a[0], a[1]); w.y = cvt_pk_bf16(a[2], a[3]); w.z = cvt_pk_bf16(b[0], b[1]); w.w = cvt_pk_bf16(b[2], b[3]); return w; }
; __device__ __forceinline__ void unpack8(const u32x4 w, f32x4& a, f32x4& b) { a[0] = bf_lo(w.x); a[1] = bf_hi(w.x); a[2] = bf_lo(w.y); a[3] = bf_hi(w.y); b[0] = bf_lo(w.z); b[1] = bf_hi(w.z); b[2] = bf_lo(w.w); b[3] = bf_hi(w.w); }
;     template <int KIND> __device__ __forceinline__ void run(f32x4 (&acc)[2][2][4][2], const Unit& u, int tid_in) const {
;     ...
;                     for (int ml = 0; ml < 2; ++ml) { const int m = mh * 2 + ml; int R = rbase + ai * 128 + m * 16; asm volatile("" : "+v"(R));
; #pragma unroll
;                         for (int bj = 0; bj < 2; ++bj) { const int t = 16 * u.pn + 8 * bj + 2 * wc + (fq >> 1); const size_t tok = (size_t)R * LCH + t;
;                             f32x4 y0, y1, u0, u1; unpack8(yv[ml][bj], y0, y1); unpack8(uv[ml][bj], u0, u1);
;                             y0 = acc[ai][bj][m][0] + y0 + d0 * u0; y1 = acc[ai][bj][m][1] + y1 + d1 * u1;
; #pragma unroll
;                             for (int j = 0; j < 4; ++j) { y0[j] = gelu_tanh(y0[j]); y1[j] = gelu_tanh(y1[j]); }
;                             *(u32x4*)(yi + ((size_t)g * T_TOK + tok) * 16 + 8 * (fq & 1)) = pack8(y0, y1); } }
	v_mul_f32_e32 v69, v33, v69
	v_lshlrev_b32_e32 v70, 16, v71
	v_and_b32_e32 v71, 0xffff0000, v71
	v_fma_f32 v69, v33, v69, v33
	v_lshlrev_b32_e32 v72, 16, v73
	v_and_b32_e32 v73, 0xffff0000, v73
	v_lshlrev_b32_e32 v74, 16, v75
	v_and_b32_e32 v75, 0xffff0000, v75
	v_pk_add_f32 v[34:35], v[34:35], v[70:71]
	v_mul_f32_e32 v69, 0x3fcc422a, v69
	v_pk_fma_f32 v[38:39], v[62:63], v[72:73], v[38:39]
	v_pk_fma_f32 v[34:35], v[58:59], v[74:75], v[34:35]
	v_mul_f32_e32 v69, 0xbfb8aa3b, v69
	v_exp_f32_e32 v69, v69
	v_mul_f32_e32 v0, v36, v0
	v_mul_f32_e32 v36, v32, v65
	v_mul_f32_e32 v32, v37, v68
	v_mul_f32_e32 v65, 0x3d372713, v38
	v_mul_f32_e32 v68, 0x3d372713, v34
	v_mul_f32_e32 v65, v38, v65
	v_mul_f32_e32 v68, v34, v68
	v_fma_f32 v65, v38, v65, v38
	v_fma_f32 v68, v34, v68, v34
	v_mul_f32_e32 v65, 0x3fcc422a, v65
	v_mul_f32_e32 v68, 0x3fcc422a, v68
	v_add_f32_e32 v37, 1.0, v69
	v_mul_f32_e32 v65, 0xbfb8aa3b, v65
	v_mul_f32_e32 v68, 0xbfb8aa3b, v68
	v_rcp_f32_e32 v37, v37
	v_exp_f32_e32 v65, v65
	v_exp_f32_e32 v68, v68
	v_mul_f32_e32 v69, 0x3d372713, v35
	v_mul_f32_e32 v37, v33, v37
	v_add_f32_e32 v33, 1.0, v65
	v_add_f32_e32 v65, 1.0, v68
	v_mul_f32_e32 v68, 0x3d372713, v39
	v_mul_f32_e32 v68, v39, v68
	v_fma_f32 v68, v39, v68, v39
	v_mul_f32_e32 v69, v35, v69
	v_mul_f32_e32 v68, 0x3fcc422a, v68
	v_fma_f32 v69, v35, v69, v35
	v_mul_f32_e32 v68, 0xbfb8aa3b, v68
	v_mul_f32_e32 v69, 0x3fcc422a, v69
	v_exp_f32_e32 v68, v68
	v_mul_f32_e32 v69, 0xbfb8aa3b, v69
	v_exp_f32_e32 v69, v69
	v_lshl_add_u64 v[40:41], v[40:41], 0, v[174:175]
	v_add_f32_e32 v68, 1.0, v68
	v_lshlrev_b64 v[40:41], 1, v[40:41]
	v_rcp_f32_e32 v33, v33
	v_rcp_f32_e32 v65, v65
	v_rcp_f32_e32 v68, v68
	v_add_f32_e32 v69, 1.0, v69
	v_lshl_add_u64 v[42:43], v[164:165], 0, v[40:41]
	v_lshl_add_u64 v[40:41], v[166:167], 0, v[40:41]
	v_rcp_f32_e32 v69, v69
	global_load_dwordx4 v[44:47], v[42:43], off
	v_mul_f32_e32 v33, v38, v33
	global_load_dwordx4 v[40:43], v[40:41], off
	v_mul_f32_e32 v38, v34, v65
	v_ashrrev_i32_e32 v67, 31, v66
	v_lshlrev_b64 v[66:67], 10, v[66:67]
	v_lshl_add_u64 v[66:67], v[162:163], 0, v[66:67]
	v_mul_f32_e32 v34, v39, v68
	v_mul_f32_e32 v35, v35, v69
	v_cvt_pk_bf16_f32 v32, v0, v32
	v_cvt_pk_bf16_f32 v33, v33, v34
	v_cvt_pk_bf16_f32 v34, v36, v37
	v_lshl_add_u64 v[36:37], v[66:67], 0, v[136:137]
	v_cvt_pk_bf16_f32 v35, v38, v35
	global_store_dwordx4 v[36:37], v[32:35], off
	v_lshlrev_b32_e32 v36, 16, v78
	v_and_b32_e32 v37, 0xffff0000, v78
	v_lshlrev_b32_e32 v32, 16, v76
	v_and_b32_e32 v33, 0xffff0000, v76
	v_lshlrev_b32_e32 v68, 16, v80
	v_and_b32_e32 v69, 0xffff0000, v80
	v_lshlrev_b32_e32 v72, 16, v82
	v_and_b32_e32 v73, 0xffff0000, v82
	v_pk_add_f32 v[28:29], v[28:29], v[32:33]
	v_pk_add_f32 v[24:25], v[24:25], v[36:37]
	v_pk_fma_f32 v[28:29], v[60:61], v[68:69], v[28:29]
	v_pk_fma_f32 v[24:25], v[56:57], v[72:73], v[24:25]
	v_mul_f32_e32 v0, 0x3d372713, v28
	v_mul_f32_e32 v32, 0x3d372713, v24
	v_mul_f32_e32 v33, 0x3d372713, v29
	v_mul_f32_e32 v0, v28, v0
	v_mul_f32_e32 v32, v24, v32
	v_mul_f32_e32 v33, v29, v33
	v_fma_f32 v0, v28, v0, v28
	v_fma_f32 v32, v24, v32, v24
	v_fma_f32 v33, v29, v33, v29
	v_mul_f32_e32 v0, 0x3fcc422a, v0
	v_mul_f32_e32 v32, 0x3fcc422a, v32
	v_mul_f32_e32 v33, 0x3fcc422a, v33
	v_mul_f32_e32 v0, 0xbfb8aa3b, v0
	v_mul_f32_e32 v32, 0xbfb8aa3b, v32
	v_mul_f32_e32 v33, 0xbfb8aa3b, v33
	v_exp_f32_e32 v0, v0
	v_exp_f32_e32 v32, v32
	v_exp_f32_e32 v33, v33
	v_lshlrev_b32_e32 v34, 16, v77
	v_and_b32_e32 v35, 0xffff0000, v77
	v_pk_add_f32 v[30:31], v[30:31], v[34:35]
	v_add_f32_e32 v0, 1.0, v0
	v_add_f32_e32 v32, 1.0, v32
	v_add_f32_e32 v33, 1.0, v33
	v_mul_f32_e32 v34, 0x3d372713, v25
	v_rcp_f32_e32 v0, v0
	v_rcp_f32_e32 v32, v32
	v_rcp_f32_e32 v33, v33
	v_mul_f32_e32 v34, v25, v34
	v_lshlrev_b32_e32 v38, 16, v79
	v_and_b32_e32 v39, 0xffff0000, v79
	v_fma_f32 v34, v25, v34, v25
	v_lshlrev_b32_e32 v70, 16, v81
	v_and_b32_e32 v71, 0xffff0000, v81
	v_lshlrev_b32_e32 v74, 16, v83
	v_and_b32_e32 v75, 0xffff0000, v83
	v_pk_add_f32 v[26:27], v[26:27], v[38:39]
	v_mul_f32_e32 v34, 0x3fcc422a, v34
	v_pk_fma_f32 v[30:31], v[62:63], v[70:71], v[30:31]
	v_pk_fma_f32 v[26:27], v[58:59], v[74:75], v[26:27]
	v_mul_f32_e32 v34, 0xbfb8aa3b, v34
	v_exp_f32_e32 v34, v34
	v_mul_f32_e32 v0, v28, v0
	v_mul_f32_e32 v28, v24, v32
	v_mul_f32_e32 v24, v29, v33
	v_mul_f32_e32 v32, 0x3d372713, v30
	v_mul_f32_e32 v33, 0x3d372713, v26
	v_mul_f32_e32 v32, v30, v32
	v_mul_f32_e32 v33, v26, v33
	v_fma_f32 v32, v30, v32, v30
	v_fma_f32 v33, v26, v33, v26
	v_mul_f32_e32 v32, 0x3fcc422a, v32
	v_mul_f32_e32 v33, 0x3fcc422a, v33
	v_add_f32_e32 v29, 1.0, v34
	v_mul_f32_e32 v32, 0xbfb8aa3b, v32
	v_mul_f32_e32 v33, 0xbfb8aa3b, v33
	v_rcp_f32_e32 v29, v29
	v_exp_f32_e32 v32, v32
	v_exp_f32_e32 v33, v33
	v_mul_f32_e32 v34, 0x3d372713, v27
	v_mul_f32_e32 v29, v25, v29
	v_add_f32_e32 v25, 1.0, v32
	v_add_f32_e32 v32, 1.0, v33
	v_mul_f32_e32 v33, 0x3d372713, v31
	v_mul_f32_e32 v33, v31, v33
	v_mul_f32_e32 v34, v27, v34
	v_fma_f32 v33, v31, v33, v31
	v_fma_f32 v34, v27, v34, v27
	v_mul_f32_e32 v33, 0x3fcc422a, v33
	v_mul_f32_e32 v34, 0x3fcc422a, v34
	v_mul_f32_e32 v33, 0xbfb8aa3b, v33
	v_mul_f32_e32 v34, 0xbfb8aa3b, v34
	v_exp_f32_e32 v33, v33
	v_exp_f32_e32 v34, v34
	v_rcp_f32_e32 v25, v25
	v_rcp_f32_e32 v32, v32
	v_add_f32_e32 v33, 1.0, v33
	v_add_f32_e32 v34, 1.0, v34
	v_rcp_f32_e32 v33, v33
	v_rcp_f32_e32 v34, v34
	v_mul_f32_e32 v25, v30, v25
	v_mul_f32_e32 v30, v26, v32
	v_mul_f32_e32 v26, v31, v33
	v_mul_f32_e32 v27, v27, v34
	v_cvt_pk_bf16_f32 v24, v0, v24
	v_cvt_pk_bf16_f32 v25, v25, v26
	v_cvt_pk_bf16_f32 v26, v28, v29
	v_cvt_pk_bf16_f32 v27, v30, v27
	v_lshl_add_u64 v[28:29], v[66:67], 0, v[128:129]
	global_store_dwordx4 v[28:29], v[24:27], off
	s_waitcnt vmcnt(0)
; __device__ __forceinline__ float gelu_tanh(float y) { const float z = 1.5957691216057308f * (y + 0.044715f * y * y * y); return y * sigmoidf_(z); }
; __device__ __forceinline__ u32x4 pack8(const f32x4 a, const f32x4 b) { u32x4 w; w.x = cvt_pk_bf16(a[0], a[1]); w.y = cvt_pk_bf16(a[2], a[3]); w.z = cvt_pk_bf16(b[0], b[1]); w.w = cvt_pk_bf16(b[2], b[3]); return w; }
; __device__ __forceinline__ void unpack8(const u32x4 w, f32x4& a, f32x4& b) { a[0] = bf_lo(w.x); a[1] = bf_hi(w.x); a[2] = bf_lo(w.y); a[3] = bf_hi(w.y); b[0] = bf_lo(w.z); b[1] = bf_hi(w.z); b[2] = bf_lo(w.w); b[3] = bf_hi(w.w); }
; #define G_WAIT_V(n) asm volatile("s_waitcnt vmcnt(" #n ")" ::: "memory")
; #define G_BAR __builtin_amdgcn_s_barrier()
;     template <int KIND> __device__ __forceinline__ void run(f32x4 (&acc)[2][2][4][2], const Unit& u, int tid_in) const {
;     ...
;                     for (int ml = 0; ml < 2; ++ml) { const int m = mh * 2 + ml; int R = rbase + ai * 128 + m * 16; asm volatile("" : "+v"(R));
; #pragma unroll
;                         for (int bj = 0; bj < 2; ++bj) { const int t = 16 * u.pn + 8 * bj + 2 * wc + (fq >> 1); const size_t tok = (size_t)R * LCH + t;
;                             f32x4 y0, y1, u0, u1; unpack8(yv[ml][bj], y0, y1); unpack8(uv[ml][bj], u0, u1);
;                             y0 = acc[ai][bj][m][0] + y0 + d0 * u0; y1 = acc[ai][bj][m][1] + y1 + d1 * u1;
; #pragma unroll
;                             for (int j = 0; j < 4; ++j) { y0[j] = gelu_tanh(y0[j]); y1[j] = gelu_tanh(y1[j]); }
;                             *(u32x4*)(yi + ((size_t)g * T_TOK + tok) * 16 + 8 * (fq & 1)) = pack8(y0, y1); } }
;     ...
;         E.template run<cs.kind>(acc, cur, tid);
;         if (!has_next) break;
;         if (!(cs.kind == K_MG_B && cur.aux < 2))
; #pragma unroll
;         for (int a = 0; a < 2; ++a)
; #pragma unroll
;             for (int b = 0; b < 2; ++b)
; #pragma unroll
;                 for (int m = 0; m < 4; ++m)
; #pragma unroll
;                     for (int n = 0; n < 2; ++n) acc[a][b][m][n] = (f32x4){0.f, 0.f, 0.f, 0.f};
;         cur = nxt; cA = nA; cB = nB; ++ui;
;     }
;     G_WAIT_V(0);
;     if (wr == 0) G_BAR;
;     G_BAR;
	v_lshlrev_b32_e32 v30, 16, v54
	v_and_b32_e32 v31, 0xffff0000, v54
	v_lshlrev_b32_e32 v26, 16, v52
	v_and_b32_e32 v27, 0xffff0000, v52
	v_lshlrev_b32_e32 v34, 16, v48
	v_and_b32_e32 v35, 0xffff0000, v48
	v_lshlrev_b32_e32 v38, 16, v50
	v_and_b32_e32 v39, 0xffff0000, v50
	v_pk_add_f32 v[20:21], v[20:21], v[26:27]
	v_pk_add_f32 v[16:17], v[16:17], v[30:31]
	v_pk_fma_f32 v[20:21], v[60:61], v[34:35], v[20:21]
	v_pk_fma_f32 v[16:17], v[56:57], v[38:39], v[16:17]
	v_mul_f32_e32 v0, 0x3d372713, v20
	v_mul_f32_e32 v26, 0x3d372713, v16
	v_mul_f32_e32 v27, 0x3d372713, v21
	v_mul_f32_e32 v0, v20, v0
	v_mul_f32_e32 v26, v16, v26
	v_mul_f32_e32 v27, v21, v27
	v_fma_f32 v0, v20, v0, v20
	v_fma_f32 v26, v16, v26, v16
	v_fma_f32 v27, v21, v27, v21
	v_mul_f32_e32 v0, 0x3fcc422a, v0
	v_mul_f32_e32 v26, 0x3fcc422a, v26
	v_mul_f32_e32 v27, 0x3fcc422a, v27
	v_mul_f32_e32 v0, 0xbfb8aa3b, v0
	v_mul_f32_e32 v26, 0xbfb8aa3b, v26
	v_mul_f32_e32 v27, 0xbfb8aa3b, v27
	v_exp_f32_e32 v0, v0
	v_exp_f32_e32 v26, v26
	v_exp_f32_e32 v27, v27
	v_lshlrev_b32_e32 v28, 16, v53
	v_and_b32_e32 v29, 0xffff0000, v53
	v_pk_add_f32 v[22:23], v[22:23], v[28:29]
	v_add_f32_e32 v0, 1.0, v0
	v_add_f32_e32 v26, 1.0, v26
	v_add_f32_e32 v27, 1.0, v27
	v_mul_f32_e32 v28, 0x3d372713, v17
	v_rcp_f32_e32 v0, v0
	v_rcp_f32_e32 v26, v26
	v_rcp_f32_e32 v27, v27
	v_mul_f32_e32 v28, v17, v28
	v_lshlrev_b32_e32 v32, 16, v55
	v_and_b32_e32 v33, 0xffff0000, v55
	v_fma_f32 v28, v17, v28, v17
	v_lshlrev_b32_e32 v36, 16, v49
	v_and_b32_e32 v37, 0xffff0000, v49
	v_lshlrev_b32_e32 v48, 16, v51
	v_and_b32_e32 v49, 0xffff0000, v51
	v_pk_add_f32 v[18:19], v[18:19], v[32:33]
	v_mul_f32_e32 v28, 0x3fcc422a, v28
	v_pk_fma_f32 v[22:23], v[62:63], v[36:37], v[22:23]
	v_pk_fma_f32 v[18:19], v[58:59], v[48:49], v[18:19]
	v_mul_f32_e32 v28, 0xbfb8aa3b, v28
	v_exp_f32_e32 v28, v28
	v_mul_f32_e32 v0, v20, v0
	v_mul_f32_e32 v20, v16, v26
	v_mul_f32_e32 v16, v21, v27
	v_mul_f32_e32 v26, 0x3d372713, v22
	v_mul_f32_e32 v27, 0x3d372713, v18
	v_mul_f32_e32 v26, v22, v26
	v_mul_f32_e32 v27, v18, v27
	v_fma_f32 v26, v22, v26, v22
	v_fma_f32 v27, v18, v27, v18
	v_mul_f32_e32 v26, 0x3fcc422a, v26
	v_mul_f32_e32 v27, 0x3fcc422a, v27
	v_add_f32_e32 v21, 1.0, v28
	v_mul_f32_e32 v26, 0xbfb8aa3b, v26
	v_mul_f32_e32 v27, 0xbfb8aa3b, v27
	v_rcp_f32_e32 v21, v21
	v_exp_f32_e32 v26, v26
	v_exp_f32_e32 v27, v27
	v_mul_f32_e32 v28, 0x3d372713, v19
	v_mul_f32_e32 v21, v17, v21
	v_add_f32_e32 v17, 1.0, v26
	v_add_f32_e32 v26, 1.0, v27
	v_mul_f32_e32 v27, 0x3d372713, v23
	v_mul_f32_e32 v27, v23, v27
	v_fma_f32 v27, v23, v27, v23
	v_mul_f32_e32 v28, v19, v28
	v_mul_f32_e32 v27, 0x3fcc422a, v27
	v_fma_f32 v28, v19, v28, v19
	v_mul_f32_e32 v27, 0xbfb8aa3b, v27
	v_mul_f32_e32 v28, 0x3fcc422a, v28
	v_exp_f32_e32 v27, v27
	v_mul_f32_e32 v28, 0xbfb8aa3b, v28
	v_exp_f32_e32 v28, v28
	v_rcp_f32_e32 v17, v17
	v_add_f32_e32 v27, 1.0, v27
	v_rcp_f32_e32 v26, v26
	v_rcp_f32_e32 v27, v27
	v_add_f32_e32 v28, 1.0, v28
	v_rcp_f32_e32 v28, v28
	v_mul_f32_e32 v17, v22, v17
	v_ashrrev_i32_e32 v65, 31, v64
	v_lshlrev_b64 v[24:25], 10, v[64:65]
	v_lshl_add_u64 v[24:25], v[162:163], 0, v[24:25]
	v_mul_f32_e32 v22, v18, v26
	v_mul_f32_e32 v18, v23, v27
	v_mul_f32_e32 v19, v19, v28
	v_cvt_pk_bf16_f32 v16, v0, v16
	v_cvt_pk_bf16_f32 v17, v17, v18
	v_cvt_pk_bf16_f32 v18, v20, v21
	v_lshl_add_u64 v[20:21], v[24:25], 0, v[136:137]
	v_cvt_pk_bf16_f32 v19, v22, v19
	global_store_dwordx4 v[20:21], v[16:19], off
	v_lshlrev_b32_e32 v20, 16, v46
	v_and_b32_e32 v21, 0xffff0000, v46
	v_lshlrev_b32_e32 v16, 16, v44
	v_and_b32_e32 v17, 0xffff0000, v44
	v_lshlrev_b32_e32 v26, 16, v40
	v_and_b32_e32 v27, 0xffff0000, v40
	v_lshlrev_b32_e32 v30, 16, v42
	v_and_b32_e32 v31, 0xffff0000, v42
	v_pk_add_f32 v[12:13], v[12:13], v[16:17]
	v_pk_add_f32 v[8:9], v[8:9], v[20:21]
	v_pk_fma_f32 v[12:13], v[60:61], v[26:27], v[12:13]
	v_pk_fma_f32 v[8:9], v[56:57], v[30:31], v[8:9]
	v_mul_f32_e32 v0, 0x3d372713, v12
	v_mul_f32_e32 v16, 0x3d372713, v8
	v_mul_f32_e32 v17, 0x3d372713, v13
	v_mul_f32_e32 v0, v12, v0
	v_mul_f32_e32 v16, v8, v16
	v_mul_f32_e32 v17, v13, v17
	v_fma_f32 v0, v12, v0, v12
	v_fma_f32 v16, v8, v16, v8
	v_fma_f32 v17, v13, v17, v13
	v_mul_f32_e32 v0, 0x3fcc422a, v0
	v_mul_f32_e32 v16, 0x3fcc422a, v16
	v_mul_f32_e32 v17, 0x3fcc422a, v17
	v_mul_f32_e32 v0, 0xbfb8aa3b, v0
	v_mul_f32_e32 v16, 0xbfb8aa3b, v16
	v_mul_f32_e32 v17, 0xbfb8aa3b, v17
	v_exp_f32_e32 v0, v0
	v_exp_f32_e32 v16, v16
	v_exp_f32_e32 v17, v17
	v_lshlrev_b32_e32 v18, 16, v45
	v_and_b32_e32 v19, 0xffff0000, v45
	v_pk_add_f32 v[14:15], v[14:15], v[18:19]
	v_add_f32_e32 v0, 1.0, v0
	v_add_f32_e32 v16, 1.0, v16
	v_add_f32_e32 v17, 1.0, v17
	v_mul_f32_e32 v18, 0x3d372713, v9
	v_rcp_f32_e32 v0, v0
	v_rcp_f32_e32 v16, v16
	v_rcp_f32_e32 v17, v17
	v_mul_f32_e32 v18, v9, v18
	v_lshlrev_b32_e32 v22, 16, v47
	v_and_b32_e32 v23, 0xffff0000, v47
	v_fma_f32 v18, v9, v18, v9
	v_lshlrev_b32_e32 v28, 16, v41
	v_and_b32_e32 v29, 0xffff0000, v41
	v_lshlrev_b32_e32 v32, 16, v43
	v_and_b32_e32 v33, 0xffff0000, v43
	v_pk_add_f32 v[10:11], v[10:11], v[22:23]
	v_mul_f32_e32 v18, 0x3fcc422a, v18
	v_pk_fma_f32 v[14:15], v[62:63], v[28:29], v[14:15]
	v_pk_fma_f32 v[10:11], v[58:59], v[32:33], v[10:11]
	v_mul_f32_e32 v18, 0xbfb8aa3b, v18
	v_exp_f32_e32 v18, v18
	v_mul_f32_e32 v0, v12, v0
	v_mul_f32_e32 v12, v8, v16
	v_mul_f32_e32 v8, v13, v17
	v_mul_f32_e32 v16, 0x3d372713, v14
	v_mul_f32_e32 v17, 0x3d372713, v10
	v_mul_f32_e32 v16, v14, v16
	v_mul_f32_e32 v17, v10, v17
	v_fma_f32 v16, v14, v16, v14
	v_fma_f32 v17, v10, v17, v10
	v_mul_f32_e32 v16, 0x3fcc422a, v16
	v_mul_f32_e32 v17, 0x3fcc422a, v17
	v_add_f32_e32 v13, 1.0, v18
	v_mul_f32_e32 v16, 0xbfb8aa3b, v16
	v_mul_f32_e32 v17, 0xbfb8aa3b, v17
	v_rcp_f32_e32 v13, v13
	v_exp_f32_e32 v16, v16
	v_exp_f32_e32 v17, v17
	v_mul_f32_e32 v18, 0x3d372713, v11
	v_mul_f32_e32 v13, v9, v13
	v_add_f32_e32 v9, 1.0, v16
	v_add_f32_e32 v16, 1.0, v17
	v_mul_f32_e32 v17, 0x3d372713, v15
	v_mul_f32_e32 v17, v15, v17
	v_fma_f32 v17, v15, v17, v15
	v_mul_f32_e32 v18, v11, v18
	v_mul_f32_e32 v17, 0x3fcc422a, v17
	v_fma_f32 v18, v11, v18, v11
	v_mul_f32_e32 v17, 0xbfb8aa3b, v17
	v_mul_f32_e32 v18, 0x3fcc422a, v18
	v_exp_f32_e32 v17, v17
	v_mul_f32_e32 v18, 0xbfb8aa3b, v18
	v_exp_f32_e32 v18, v18
	v_rcp_f32_e32 v9, v9
	v_add_f32_e32 v17, 1.0, v17
	v_rcp_f32_e32 v16, v16
	v_rcp_f32_e32 v17, v17
	v_add_f32_e32 v18, 1.0, v18
	v_rcp_f32_e32 v18, v18
	v_mul_f32_e32 v9, v14, v9
	v_mul_f32_e32 v14, v10, v16
	v_mul_f32_e32 v10, v15, v17
	v_mul_f32_e32 v11, v11, v18
	v_cvt_pk_bf16_f32 v8, v0, v8
	v_cvt_pk_bf16_f32 v9, v9, v10
	v_cvt_pk_bf16_f32 v10, v12, v13
	v_lshl_add_u64 v[12:13], v[24:25], 0, v[128:129]
	v_cvt_pk_bf16_f32 v11, v14, v11
	global_store_dwordx4 v[12:13], v[8:11], off
	s_mov_b64 s[20:21], s[16:17]
	s_cmpk_gt_u32 s101, 0xff
	s_cbranch_scc0 .Ldb_SSM2_nob
	s_barrier
.Ldb_SSM2_nob:
	s_cbranch_vccz .LBB0_737
	s_waitcnt vmcnt(0)
	s_cmpk_gt_u32 s61, 0xff
	s_cbranch_scc1 .LBB0_746
	s_barrier

; #define G_STAGE(bufoff, gbase, o0, h64) do { \
;         __builtin_amdgcn_global_load_lds((const unsigned*)((const char*)(gbase) + (o0)), (LAS unsigned*)(lds + (bufoff) + ldsw), 16, 0, 0); \
;         __builtin_amdgcn_global_load_lds((const unsigned*)((const char*)(gbase) + (h64) + (o0)), (LAS unsigned*)(lds + (bufoff) + ldsw + 8192), 16, 0, 0); } while (0)
; #define G_LDA(dst, b, h) do { _Pragma("unroll") for (int m = 0; m < 4; ++m) _Pragma("unroll") for (int k = 0; k < 2; ++k) dst[m][k] = *(const LAS bf16x8*)(lds + G_SA(b, h) + aoff + m * 2048 + k * 1024); } while (0)
; #define G_LDB(dst, b, h) do { _Pragma("unroll") for (int n = 0; n < 2; ++n) _Pragma("unroll") for (int k = 0; k < 2; ++k) dst[n][k] = *(const LAS bf16x8*)(lds + G_SB(b, h) + boff + n * 2048 + k * 1024); } while (0)
; #define G_WAIT_L(n) asm volatile("s_waitcnt lgkmcnt(" #n ")" ::: "memory")
; #define G_BAR __builtin_amdgcn_s_barrier()
; #define G_SCHED __builtin_amdgcn_sched_barrier(0)
;     ...
;         for (int t = 0; t < nt; t += 2) {
;             const bool last = (t == nt - 2);
;             const char* a1 = cA + (size_t)(t + 1) * ckA;
;             const char* a2 = last ? nA : cA + (size_t)(t + 2) * ckA; const char* b2 = last ? nB : cB + (size_t)(t + 2) * kB;
;             const char* a3 = a2 + ckA; const char* b3 = b2 + kB;
;             G_LDB(B0, 0, 0); G_SCHED; G_LDA(At, 0, 0); G_STAGE(G_SA(1, 1), a1 + chA, cA0, qA);
;             G_WAIT_L(8); G_BAR; G_WAIT_L(0); G_MMA(0, 0, At, B0); G_BAR; G_SCHED;
;             G_LDB(B1, 0, 1); G_STAGE(G_SB(0, 0), b2, cB0, qB);
;             G_BAR; G_WAIT_L(0); G_MMA(0, 1, At, B1); G_BAR;
;             G_LDA(At, 0, 1); G_STAGE(G_SA(0, 0), a2, cA0, qA);
;             G_BAR; G_WAIT_L(0); G_MMA(1, 0, At, B0); G_BAR; G_SCHED;
.LBB0_804:
	s_add_i32 s40, 0, 0x10000
	v_add_u32_e32 v0, s40, v196
	ds_read_b128 v[112:115], v0
	ds_read_b128 v[124:127], v0 offset:1024
	ds_read_b128 v[136:139], v0 offset:2048
	ds_read_b128 v[148:151], v0 offset:3072
	s_cmp_eq_u32 s19, 4
	s_cselect_b32 s5, s15, s3
	s_cselect_b32 s4, s14, s2
	s_cselect_b32 s37, s17, s18
	s_cselect_b32 s36, s16, s13
	s_mov_b32 s38, 0xffc01000
	v_lshl_add_u64 v[184:185], s[2:3], 0, v[166:167]
	s_mov_b32 s39, -1
	v_lshl_add_u64 v[206:207], v[184:185], 0, s[38:39]
	s_mov_b32 s38, 0xffc01800
	s_add_i32 m0, s24, 0xc000
	s_mov_b32 s39, -1
	ds_read_b128 v[152:155], v197
	ds_read_b128 v[156:159], v197 offset:1024
	ds_read_b128 v[160:163], v197 offset:2048
	ds_read_b128 v[172:175], v197 offset:3072
	ds_read_b128 v[176:179], v197 offset:4096
	ds_read_b128 v[180:183], v197 offset:5120
	ds_read_b128 v[198:201], v197 offset:6144
	ds_read_b128 v[202:205], v197 offset:7168
	global_load_lds_dwordx4 v[206:207], off
	v_lshl_add_u64 v[184:185], v[184:185], 0, s[38:39]
	s_add_i32 m0, s24, 0xe000
	s_nop 0
	global_load_lds_dwordx4 v[184:185], off
	s_waitcnt lgkmcnt(8)
	s_barrier
	s_waitcnt lgkmcnt(0)
	s_setprio 3
	s_waitcnt lgkmcnt(0)
	v_mfma_f32_16x16x32_bf16 v[144:147], v[112:115], v[152:155], v[144:147]
	v_mfma_f32_16x16x32_bf16 v[140:143], v[136:139], v[152:155], v[140:143]
	v_mfma_f32_16x16x32_bf16 v[120:123], v[112:115], v[160:163], v[120:123]
	v_mfma_f32_16x16x32_bf16 v[116:119], v[136:139], v[160:163], v[116:119]
	v_mfma_f32_16x16x32_bf16 v[100:103], v[112:115], v[176:179], v[100:103]
	v_mfma_f32_16x16x32_bf16 v[96:99], v[136:139], v[176:179], v[96:99]
	v_mfma_f32_16x16x32_bf16 v[84:87], v[112:115], v[198:201], v[84:87]
	v_mfma_f32_16x16x32_bf16 v[80:83], v[136:139], v[198:201], v[80:83]
	v_mfma_f32_16x16x32_bf16 v[144:147], v[124:127], v[156:159], v[144:147]
	v_mfma_f32_16x16x32_bf16 v[140:143], v[148:151], v[156:159], v[140:143]
	v_mfma_f32_16x16x32_bf16 v[120:123], v[124:127], v[172:175], v[120:123]
	v_mfma_f32_16x16x32_bf16 v[116:119], v[148:151], v[172:175], v[116:119]
	v_mfma_f32_16x16x32_bf16 v[100:103], v[124:127], v[180:183], v[100:103]
	v_mfma_f32_16x16x32_bf16 v[96:99], v[148:151], v[180:183], v[96:99]
	v_mfma_f32_16x16x32_bf16 v[84:87], v[124:127], v[202:205], v[84:87]
	v_mfma_f32_16x16x32_bf16 v[80:83], v[148:151], v[202:205], v[80:83]
	s_setprio 0
	s_barrier
	s_add_i32 s38, 0, 0x14000
	v_lshl_add_u64 v[184:185], s[36:37], 0, v[2:3]
	s_add_i32 s36, s40, s21
	v_add_u32_e32 v0, s38, v196
	s_mov_b32 m0, s36
	ds_read_b128 v[206:209], v0
	ds_read_b128 v[210:213], v0 offset:1024
	ds_read_b128 v[214:217], v0 offset:2048
	ds_read_b128 v[218:221], v0 offset:3072
	global_load_lds_dwordx4 v[184:185], off
	v_lshl_add_u64 v[222:223], v[184:185], 0, s[50:51]
	s_add_i32 m0, s36, 0x2000
	s_nop 0
	global_load_lds_dwordx4 v[222:223], off
	s_barrier
	s_waitcnt lgkmcnt(0)
	s_setprio 3
	s_waitcnt lgkmcnt(0)
	v_mfma_f32_16x16x32_bf16 v[132:135], v[206:209], v[152:155], v[132:135]
	v_mfma_f32_16x16x32_bf16 v[128:131], v[214:217], v[152:155], v[128:131]
	v_mfma_f32_16x16x32_bf16 v[108:111], v[206:209], v[160:163], v[108:111]
	v_mfma_f32_16x16x32_bf16 v[104:107], v[214:217], v[160:163], v[104:107]
	v_mfma_f32_16x16x32_bf16 v[92:95], v[206:209], v[176:179], v[92:95]
	v_mfma_f32_16x16x32_bf16 v[88:91], v[214:217], v[176:179], v[88:91]
	v_mfma_f32_16x16x32_bf16 v[76:79], v[206:209], v[198:201], v[76:79]
	v_mfma_f32_16x16x32_bf16 v[72:75], v[214:217], v[198:201], v[72:75]
	v_mfma_f32_16x16x32_bf16 v[132:135], v[210:213], v[156:159], v[132:135]
	v_mfma_f32_16x16x32_bf16 v[128:131], v[218:221], v[156:159], v[128:131]
	v_mfma_f32_16x16x32_bf16 v[108:111], v[210:213], v[172:175], v[108:111]
	v_mfma_f32_16x16x32_bf16 v[104:107], v[218:221], v[172:175], v[104:107]
	v_mfma_f32_16x16x32_bf16 v[92:95], v[210:213], v[180:183], v[92:95]
	v_mfma_f32_16x16x32_bf16 v[88:91], v[218:221], v[180:183], v[88:91]
	v_mfma_f32_16x16x32_bf16 v[76:79], v[210:213], v[202:205], v[76:79]
	v_mfma_f32_16x16x32_bf16 v[72:75], v[218:221], v[202:205], v[72:75]
	s_setprio 0
	s_mov_b32 m0, s24
	v_lshl_add_u64 v[222:223], s[4:5], 0, v[164:165]
	s_barrier
	ds_read_b128 v[152:155], v197 offset:16384
	ds_read_b128 v[156:159], v197 offset:17408
	ds_read_b128 v[160:163], v197 offset:18432
	ds_read_b128 v[172:175], v197 offset:19456
	ds_read_b128 v[176:179], v197 offset:20480
	ds_read_b128 v[180:183], v197 offset:21504
	ds_read_b128 v[198:201], v197 offset:22528
	ds_read_b128 v[202:205], v197 offset:23552
	global_load_lds_dwordx4 v[222:223], off
	v_lshl_add_u64 v[224:225], v[222:223], 0, s[70:71]
	s_mov_b32 m0, s25
	s_nop 0
	global_load_lds_dwordx4 v[224:225], off
	s_barrier
	s_waitcnt lgkmcnt(0)
	s_setprio 3
	s_waitcnt lgkmcnt(0)
	v_mfma_f32_16x16x32_bf16 v[68:71], v[112:115], v[152:155], v[68:71]
	v_mfma_f32_16x16x32_bf16 v[64:67], v[136:139], v[152:155], v[64:67]
	v_mfma_f32_16x16x32_bf16 v[52:55], v[112:115], v[160:163], v[52:55]
	v_mfma_f32_16x16x32_bf16 v[48:51], v[136:139], v[160:163], v[48:51]
	v_mfma_f32_16x16x32_bf16 v[36:39], v[112:115], v[176:179], v[36:39]
	v_mfma_f32_16x16x32_bf16 v[32:35], v[136:139], v[176:179], v[32:35]
	v_mfma_f32_16x16x32_bf16 v[20:23], v[112:115], v[198:201], v[20:23]
	v_mfma_f32_16x16x32_bf16 v[16:19], v[136:139], v[198:201], v[16:19]
	v_mfma_f32_16x16x32_bf16 v[68:71], v[124:127], v[156:159], v[68:71]
	v_mfma_f32_16x16x32_bf16 v[64:67], v[148:151], v[156:159], v[64:67]
	v_mfma_f32_16x16x32_bf16 v[52:55], v[124:127], v[172:175], v[52:55]
	v_mfma_f32_16x16x32_bf16 v[48:51], v[148:151], v[172:175], v[48:51]
	v_mfma_f32_16x16x32_bf16 v[36:39], v[124:127], v[180:183], v[36:39]
	v_mfma_f32_16x16x32_bf16 v[32:35], v[148:151], v[180:183], v[32:35]
	v_mfma_f32_16x16x32_bf16 v[20:23], v[124:127], v[202:205], v[20:23]
	v_mfma_f32_16x16x32_bf16 v[16:19], v[148:151], v[202:205], v[16:19]
	s_setprio 0
	s_barrier
; #define G_STAGE(bufoff, gbase, o0, h64) do { \
;         __builtin_amdgcn_global_load_lds((const unsigned*)((const char*)(gbase) + (o0)), (LAS unsigned*)(lds + (bufoff) + ldsw), 16, 0, 0); \
;         __builtin_amdgcn_global_load_lds((const unsigned*)((const char*)(gbase) + (h64) + (o0)), (LAS unsigned*)(lds + (bufoff) + ldsw + 8192), 16, 0, 0); } while (0)
; #define G_LDA(dst, b, h) do { _Pragma("unroll") for (int m = 0; m < 4; ++m) _Pragma("unroll") for (int k = 0; k < 2; ++k) dst[m][k] = *(const LAS bf16x8*)(lds + G_SA(b, h) + aoff + m * 2048 + k * 1024); } while (0)
; #define G_LDB(dst, b, h) do { _Pragma("unroll") for (int n = 0; n < 2; ++n) _Pragma("unroll") for (int k = 0; k < 2; ++k) dst[n][k] = *(const LAS bf16x8*)(lds + G_SB(b, h) + boff + n * 2048 + k * 1024); } while (0)
; #define G_WAIT_V(n) asm volatile("s_waitcnt vmcnt(" #n ")" ::: "memory")
; #define G_WAIT_L(n) asm volatile("s_waitcnt lgkmcnt(" #n ")" ::: "memory")
; #define G_BAR __builtin_amdgcn_s_barrier()
; #define G_SCHED __builtin_amdgcn_sched_barrier(0)
;     ...
;             G_BAR; G_WAIT_L(0); G_MMA(1, 0, At, B0); G_BAR; G_SCHED;
;             G_STAGE(G_SB(0, 1), b2 + chB, cB0, qB);
;             G_WAIT_V(6); G_BAR; G_MMA(1, 1, At, B1); G_BAR;
;             G_LDB(B0, 1, 0); G_SCHED; G_LDA(At, 1, 0); G_STAGE(G_SA(0, 1), a2 + chA, cA0, qA);
;             G_WAIT_L(8); G_BAR; G_WAIT_L(0); G_MMA(0, 0, At, B0); G_BAR; G_SCHED;
;             G_LDB(B1, 1, 1); G_STAGE(G_SB(1, 0), b3, cB0, qB);
	s_add_i32 s4, s38, s21
	v_lshl_add_u64 v[112:113], v[184:185], 0, s[0:1]
	s_mov_b32 m0, s4
	s_nop 0
	global_load_lds_dwordx4 v[112:113], off
	v_lshl_add_u64 v[112:113], v[184:185], 0, s[52:53]
	s_add_i32 m0, s4, 0x2000
	s_nop 0
	global_load_lds_dwordx4 v[112:113], off
	s_waitcnt vmcnt(6)
	s_barrier
	s_setprio 3
	v_mfma_f32_16x16x32_bf16 v[60:63], v[206:209], v[152:155], v[60:63]
	v_mfma_f32_16x16x32_bf16 v[56:59], v[214:217], v[152:155], v[56:59]
	v_mfma_f32_16x16x32_bf16 v[44:47], v[206:209], v[160:163], v[44:47]
	v_mfma_f32_16x16x32_bf16 v[40:43], v[214:217], v[160:163], v[40:43]
	v_mfma_f32_16x16x32_bf16 v[28:31], v[206:209], v[176:179], v[28:31]
	v_mfma_f32_16x16x32_bf16 v[24:27], v[214:217], v[176:179], v[24:27]
	v_mfma_f32_16x16x32_bf16 v[12:15], v[206:209], v[198:201], v[12:15]
	v_mfma_f32_16x16x32_bf16 v[8:11], v[214:217], v[198:201], v[8:11]
	v_mfma_f32_16x16x32_bf16 v[60:63], v[210:213], v[156:159], v[60:63]
	v_mfma_f32_16x16x32_bf16 v[56:59], v[218:221], v[156:159], v[56:59]
	v_mfma_f32_16x16x32_bf16 v[44:47], v[210:213], v[172:175], v[44:47]
	v_mfma_f32_16x16x32_bf16 v[40:43], v[218:221], v[172:175], v[40:43]
	v_mfma_f32_16x16x32_bf16 v[28:31], v[210:213], v[180:183], v[28:31]
	v_mfma_f32_16x16x32_bf16 v[24:27], v[218:221], v[180:183], v[24:27]
	v_mfma_f32_16x16x32_bf16 v[12:15], v[210:213], v[202:205], v[12:15]
	v_mfma_f32_16x16x32_bf16 v[8:11], v[218:221], v[202:205], v[8:11]
	s_setprio 0
	s_add_i32 s4, 0, 0x18000
	v_add_u32_e32 v0, s4, v196
	s_barrier
	ds_read_b128 v[112:115], v0
	ds_read_b128 v[124:127], v0 offset:1024
	ds_read_b128 v[136:139], v0 offset:2048
	ds_read_b128 v[148:151], v0 offset:3072
	s_mov_b32 m0, s26
	v_lshl_add_u64 v[206:207], v[222:223], 0, s[80:81]
	ds_read_b128 v[152:155], v197 offset:32768
	ds_read_b128 v[156:159], v197 offset:33792
	ds_read_b128 v[160:163], v197 offset:34816
	ds_read_b128 v[172:175], v197 offset:35840
	ds_read_b128 v[176:179], v197 offset:36864
	ds_read_b128 v[180:183], v197 offset:37888
	ds_read_b128 v[198:201], v197 offset:38912
	ds_read_b128 v[202:205], v197 offset:39936
	global_load_lds_dwordx4 v[206:207], off
	v_lshl_add_u64 v[206:207], v[222:223], 0, s[82:83]
	s_mov_b32 m0, s27
	s_nop 0
	global_load_lds_dwordx4 v[206:207], off
	s_waitcnt lgkmcnt(8)
	s_barrier
	s_waitcnt lgkmcnt(0)
	s_setprio 3
	s_waitcnt lgkmcnt(0)
	v_mfma_f32_16x16x32_bf16 v[144:147], v[112:115], v[152:155], v[144:147]
	v_mfma_f32_16x16x32_bf16 v[140:143], v[136:139], v[152:155], v[140:143]
	v_mfma_f32_16x16x32_bf16 v[120:123], v[112:115], v[160:163], v[120:123]
	v_mfma_f32_16x16x32_bf16 v[116:119], v[136:139], v[160:163], v[116:119]
	v_mfma_f32_16x16x32_bf16 v[100:103], v[112:115], v[176:179], v[100:103]
	v_mfma_f32_16x16x32_bf16 v[96:99], v[136:139], v[176:179], v[96:99]
	v_mfma_f32_16x16x32_bf16 v[84:87], v[112:115], v[198:201], v[84:87]
	v_mfma_f32_16x16x32_bf16 v[80:83], v[136:139], v[198:201], v[80:83]
	v_mfma_f32_16x16x32_bf16 v[144:147], v[124:127], v[156:159], v[144:147]
	v_mfma_f32_16x16x32_bf16 v[140:143], v[148:151], v[156:159], v[140:143]
	v_mfma_f32_16x16x32_bf16 v[120:123], v[124:127], v[172:175], v[120:123]
	v_mfma_f32_16x16x32_bf16 v[116:119], v[148:151], v[172:175], v[116:119]
	v_mfma_f32_16x16x32_bf16 v[100:103], v[124:127], v[180:183], v[100:103]
	v_mfma_f32_16x16x32_bf16 v[96:99], v[148:151], v[180:183], v[96:99]
	v_mfma_f32_16x16x32_bf16 v[84:87], v[124:127], v[202:205], v[84:87]
	v_mfma_f32_16x16x32_bf16 v[80:83], v[148:151], v[202:205], v[80:83]
	s_setprio 0
	s_barrier
	s_add_i32 s5, 0, 0x1c000
	s_add_i32 s4, s4, s21
	v_add_u32_e32 v0, s5, v196
	v_lshl_add_u64 v[224:225], v[184:185], 0, s[46:47]
	s_mov_b32 m0, s4
	ds_read_b128 v[206:209], v0
	ds_read_b128 v[210:213], v0 offset:1024
	ds_read_b128 v[214:217], v0 offset:2048
	ds_read_b128 v[218:221], v0 offset:3072
	global_load_lds_dwordx4 v[224:225], off
	v_lshl_add_u64 v[224:225], v[184:185], 0, s[54:55]
	s_add_i32 m0, s4, 0x2000
	s_nop 0
	global_load_lds_dwordx4 v[224:225], off
	s_barrier
; #define G_STAGE(bufoff, gbase, o0, h64) do { \
;         __builtin_amdgcn_global_load_lds((const unsigned*)((const char*)(gbase) + (o0)), (LAS unsigned*)(lds + (bufoff) + ldsw), 16, 0, 0); \
;         __builtin_amdgcn_global_load_lds((const unsigned*)((const char*)(gbase) + (h64) + (o0)), (LAS unsigned*)(lds + (bufoff) + ldsw + 8192), 16, 0, 0); } while (0)
; #define G_LDA(dst, b, h) do { _Pragma("unroll") for (int m = 0; m < 4; ++m) _Pragma("unroll") for (int k = 0; k < 2; ++k) dst[m][k] = *(const LAS bf16x8*)(lds + G_SA(b, h) + aoff + m * 2048 + k * 1024); } while (0)
; #define G_WAIT_V(n) asm volatile("s_waitcnt vmcnt(" #n ")" ::: "memory")
; #define G_WAIT_L(n) asm volatile("s_waitcnt lgkmcnt(" #n ")" ::: "memory")
; #define G_BAR __builtin_amdgcn_s_barrier()
; #define G_SCHED __builtin_amdgcn_sched_barrier(0)
;     ...
;             G_BAR; G_WAIT_L(0); G_MMA(0, 1, At, B1); G_BAR;
;             G_LDA(At, 1, 1); G_STAGE(G_SA(1, 0), a3, cA0, qA);
;             G_BAR; G_WAIT_L(0); G_MMA(1, 0, At, B0); G_BAR; G_SCHED;
;             G_STAGE(G_SB(1, 1), b3 + chB, cB0, qB);
;             G_WAIT_V(6); G_BAR; G_MMA(1, 1, At, B1); G_BAR;
;         }
;         E.template run<cs.kind>(acc, cur, tid);
;         if (!has_next) break;
	s_waitcnt lgkmcnt(0)
	s_setprio 3
	s_waitcnt lgkmcnt(0)
	v_mfma_f32_16x16x32_bf16 v[132:135], v[206:209], v[152:155], v[132:135]
	v_mfma_f32_16x16x32_bf16 v[128:131], v[214:217], v[152:155], v[128:131]
	v_mfma_f32_16x16x32_bf16 v[108:111], v[206:209], v[160:163], v[108:111]
	v_mfma_f32_16x16x32_bf16 v[104:107], v[214:217], v[160:163], v[104:107]
	v_mfma_f32_16x16x32_bf16 v[92:95], v[206:209], v[176:179], v[92:95]
	v_mfma_f32_16x16x32_bf16 v[88:91], v[214:217], v[176:179], v[88:91]
	v_mfma_f32_16x16x32_bf16 v[76:79], v[206:209], v[198:201], v[76:79]
	v_mfma_f32_16x16x32_bf16 v[72:75], v[214:217], v[198:201], v[72:75]
	v_mfma_f32_16x16x32_bf16 v[132:135], v[210:213], v[156:159], v[132:135]
	v_mfma_f32_16x16x32_bf16 v[128:131], v[218:221], v[156:159], v[128:131]
	v_mfma_f32_16x16x32_bf16 v[108:111], v[210:213], v[172:175], v[108:111]
	v_mfma_f32_16x16x32_bf16 v[104:107], v[218:221], v[172:175], v[104:107]
	v_mfma_f32_16x16x32_bf16 v[92:95], v[210:213], v[180:183], v[92:95]
	v_mfma_f32_16x16x32_bf16 v[88:91], v[218:221], v[180:183], v[88:91]
	v_mfma_f32_16x16x32_bf16 v[76:79], v[210:213], v[202:205], v[76:79]
	v_mfma_f32_16x16x32_bf16 v[72:75], v[218:221], v[202:205], v[72:75]
	s_setprio 0
	s_mov_b32 m0, s29
	v_lshl_add_u64 v[224:225], v[222:223], 0, s[62:63]
	s_barrier
	ds_read_b128 v[152:155], v197 offset:49152
	ds_read_b128 v[156:159], v197 offset:50176
	ds_read_b128 v[160:163], v197 offset:51200
	ds_read_b128 v[172:175], v197 offset:52224
	ds_read_b128 v[176:179], v197 offset:53248
	ds_read_b128 v[180:183], v197 offset:54272
	ds_read_b128 v[198:201], v197 offset:55296
	ds_read_b128 v[202:205], v197 offset:56320
	global_load_lds_dwordx4 v[224:225], off
	v_lshl_add_u64 v[222:223], v[222:223], 0, s[84:85]
	s_mov_b32 m0, s30
	s_nop 0
	global_load_lds_dwordx4 v[222:223], off
	s_barrier
	s_waitcnt lgkmcnt(0)
	s_setprio 3
	s_waitcnt lgkmcnt(0)
	v_mfma_f32_16x16x32_bf16 v[68:71], v[112:115], v[152:155], v[68:71]
	v_mfma_f32_16x16x32_bf16 v[64:67], v[136:139], v[152:155], v[64:67]
	v_mfma_f32_16x16x32_bf16 v[52:55], v[112:115], v[160:163], v[52:55]
	v_mfma_f32_16x16x32_bf16 v[48:51], v[136:139], v[160:163], v[48:51]
	v_mfma_f32_16x16x32_bf16 v[36:39], v[112:115], v[176:179], v[36:39]
	v_mfma_f32_16x16x32_bf16 v[32:35], v[136:139], v[176:179], v[32:35]
	v_mfma_f32_16x16x32_bf16 v[20:23], v[112:115], v[198:201], v[20:23]
	v_mfma_f32_16x16x32_bf16 v[16:19], v[136:139], v[198:201], v[16:19]
	v_mfma_f32_16x16x32_bf16 v[68:71], v[124:127], v[156:159], v[68:71]
	v_mfma_f32_16x16x32_bf16 v[64:67], v[148:151], v[156:159], v[64:67]
	v_mfma_f32_16x16x32_bf16 v[52:55], v[124:127], v[172:175], v[52:55]
	v_mfma_f32_16x16x32_bf16 v[48:51], v[148:151], v[172:175], v[48:51]
	v_mfma_f32_16x16x32_bf16 v[36:39], v[124:127], v[180:183], v[36:39]
	v_mfma_f32_16x16x32_bf16 v[32:35], v[148:151], v[180:183], v[32:35]
	v_mfma_f32_16x16x32_bf16 v[20:23], v[124:127], v[202:205], v[20:23]
	v_mfma_f32_16x16x32_bf16 v[16:19], v[148:151], v[202:205], v[16:19]
	s_setprio 0
	s_barrier
	s_add_i32 s4, s5, s21
	v_lshl_add_u64 v[112:113], v[184:185], 0, s[42:43]
	s_mov_b32 m0, s4
	s_nop 0
	global_load_lds_dwordx4 v[112:113], off
	v_lshl_add_u64 v[112:113], v[184:185], 0, s[58:59]
	s_add_i32 m0, s4, 0x2000
	s_nop 0
	global_load_lds_dwordx4 v[112:113], off
	s_waitcnt vmcnt(6)
	s_barrier
	s_setprio 3
	v_mfma_f32_16x16x32_bf16 v[60:63], v[206:209], v[152:155], v[60:63]
	v_mfma_f32_16x16x32_bf16 v[56:59], v[214:217], v[152:155], v[56:59]
	v_mfma_f32_16x16x32_bf16 v[44:47], v[206:209], v[160:163], v[44:47]
	v_mfma_f32_16x16x32_bf16 v[40:43], v[214:217], v[160:163], v[40:43]
	v_mfma_f32_16x16x32_bf16 v[28:31], v[206:209], v[176:179], v[28:31]
	v_mfma_f32_16x16x32_bf16 v[24:27], v[214:217], v[176:179], v[24:27]
	v_mfma_f32_16x16x32_bf16 v[12:15], v[206:209], v[198:201], v[12:15]
	v_mfma_f32_16x16x32_bf16 v[8:11], v[214:217], v[198:201], v[8:11]
	v_mfma_f32_16x16x32_bf16 v[60:63], v[210:213], v[156:159], v[60:63]
	v_mfma_f32_16x16x32_bf16 v[56:59], v[218:221], v[156:159], v[56:59]
	v_mfma_f32_16x16x32_bf16 v[44:47], v[210:213], v[172:175], v[44:47]
	v_mfma_f32_16x16x32_bf16 v[40:43], v[218:221], v[172:175], v[40:43]
	v_mfma_f32_16x16x32_bf16 v[28:31], v[210:213], v[180:183], v[28:31]
	v_mfma_f32_16x16x32_bf16 v[24:27], v[218:221], v[180:183], v[24:27]
	v_mfma_f32_16x16x32_bf16 v[12:15], v[210:213], v[202:205], v[12:15]
	v_mfma_f32_16x16x32_bf16 v[8:11], v[218:221], v[202:205], v[8:11]
	s_setprio 0
	s_add_i32 s19, s19, 2
	s_add_u32 s13, s13, 0x100
	s_addc_u32 s18, s18, 0
	s_add_u32 s2, s2, 0x800000
	s_addc_u32 s3, s3, 0
	s_cmp_gt_u32 s19, 5
	s_cbranch_scc0 .Ldb_GLU_cont
	v_readfirstlane_b32 s101, v186
	s_cmpk_gt_u32 s101, 0xff
	s_cbranch_scc1 .Ldb_GLU_exit
	s_barrier
	s_branch .Ldb_GLU_exit

; __device__ __forceinline__ float sigmoidf_(float v) { return __builtin_amdgcn_rcpf(1.0f + __expf(-v)); }
; __device__ __forceinline__ u32x4 pack8(const f32x4 a, const f32x4 b) { u32x4 w; w.x = cvt_pk_bf16(a[0], a[1]); w.y = cvt_pk_bf16(a[2], a[3]); w.z = cvt_pk_bf16(b[0], b[1]); w.w = cvt_pk_bf16(b[2], b[3]); return w; }
; __device__ __forceinline__ void unpack8(const u32x4 w, f32x4& a, f32x4& b) { a[0] = bf_lo(w.x); a[1] = bf_hi(w.x); a[2] = bf_lo(w.y); a[3] = bf_hi(w.y); b[0] = bf_lo(w.z); b[1] = bf_hi(w.z); b[2] = bf_lo(w.w); b[3] = bf_hi(w.w); }
;     template <int KIND> __device__ __forceinline__ void run(f32x4 (&acc)[2][2][4][2], const Unit& u, int tid_in) const {
;     ...
;         if constexpr (KIND == K_GLU) {
; #pragma unroll
;             for (int ai = 0; ai < 2; ++ai) { u32x4 yv[4][2];
; #pragma unroll
;                 for (int m = 0; m < 4; ++m) { int row = rbase + ai * 128 + m * 16; asm volatile("" : "+v"(row));
; #pragma unroll
;                     for (int bj = 0; bj < 2; ++bj) { const int col = u.pn * 256 + bj * 128 + cl; yv[m][bj] = *(const u32x4*)(yi + ((size_t)(col >> 4) * T_TOK + row) * 16 + (col & 15)); } }
; #pragma unroll
;                 for (int m = 0; m < 4; ++m) { int row = rbase + ai * 128 + m * 16; asm volatile("" : "+v"(row));
; #pragma unroll
;                     for (int bj = 0; bj < 2; ++bj) { const int col = u.pn * 256 + bj * 128 + cl; f32x4 y0, y1; unpack8(yv[m][bj], y0, y1);
; #pragma unroll
;                         for (int j = 0; j < 4; ++j) { y0[j] *= sigmoidf_(acc[ai][bj][m][0][j]); y1[j] *= sigmoidf_(acc[ai][bj][m][1][j]); }
;                         *(u32x4*)(zb + (size_t)row * ZW + 1024 + col) = pack8(y0, y1); } }
.Ldb_GLU_exit:
	v_mov_b32_e32 v0, v195
	s_lshl_b32 s3, s35, 8
	v_readfirstlane_b32 s2, v0
	s_ashr_i32 s4, s2, 2
	s_lshr_b32 s2, s2, 1
	s_and_b32 s2, s2, 0x60
	v_lshrrev_b32_e32 v112, 1, v0
	v_and_or_b32 v112, v112, 24, s2
	s_andn2_b32 s4, s4, 63
	v_lshl_or_b32 v182, s33, 8, v112
	s_add_i32 s4, s4, s3
	v_ashrrev_i32_e32 v112, 4, v182
	v_and_or_b32 v198, v0, 15, s4
	v_ashrrev_i32_e32 v113, 31, v112
	v_lshlrev_b64 v[176:177], 20, v[112:113]
	v_mov_b32_e32 v112, v198
	v_and_b32_e32 v0, 16, v0
	v_lshl_add_u64 v[174:175], s[8:9], 0, v[0:1]
	v_ashrrev_i32_e32 v113, 31, v112
	v_lshlrev_b64 v[112:113], 5, v[112:113]
	v_lshl_add_u64 v[112:113], v[174:175], 0, v[112:113]
	v_lshl_add_u64 v[114:115], v[112:113], 0, v[176:177]
	global_load_dwordx4 v[202:205], v[114:115], off
	v_or_b32_e32 v180, 0x80, v182
	v_ashrrev_i32_e32 v114, 4, v180
	v_ashrrev_i32_e32 v115, 31, v114
	v_lshlrev_b64 v[178:179], 20, v[114:115]
	v_lshl_add_u64 v[112:113], v[112:113], 0, v[178:179]
	global_load_dwordx4 v[160:163], v[112:113], off
	v_or_b32_e32 v200, 16, v198
	v_mov_b32_e32 v112, v200
	v_or_b32_e32 v199, 32, v198
	v_ashrrev_i32_e32 v113, 31, v112
	v_lshlrev_b64 v[112:113], 5, v[112:113]
	v_lshl_add_u64 v[112:113], v[174:175], 0, v[112:113]
	v_lshl_add_u64 v[114:115], v[112:113], 0, v[176:177]
	global_load_dwordx4 v[156:159], v[114:115], off
	v_lshl_add_u64 v[112:113], v[112:113], 0, v[178:179]
	global_load_dwordx4 v[152:155], v[112:113], off
	v_mov_b32_e32 v112, v199
	v_mul_f32_e32 v144, 0xbfb8aa3b, v144
	v_ashrrev_i32_e32 v113, 31, v112
	v_lshlrev_b64 v[112:113], 5, v[112:113]
	v_mul_f32_e32 v142, 0xbfb8aa3b, v142
	v_lshl_add_u64 v[112:113], v[174:175], 0, v[112:113]
	v_exp_f32_e32 v144, v144
	v_exp_f32_e32 v142, v142
	v_lshl_add_u64 v[114:115], v[112:113], 0, v[176:177]
	v_lshl_add_u64 v[112:113], v[112:113], 0, v[178:179]
	v_or_b32_e32 v0, 48, v198
	global_load_dwordx4 v[148:151], v[114:115], off
	global_load_dwordx4 v[136:139], v[112:113], off
	v_mov_b32_e32 v112, v0
	v_add_f32_e32 v144, 1.0, v144
	v_ashrrev_i32_e32 v113, 31, v112
	v_lshlrev_b64 v[112:113], 5, v[112:113]
	v_add_f32_e32 v142, 1.0, v142
	v_lshl_add_u64 v[112:113], v[174:175], 0, v[112:113]
	v_rcp_f32_e32 v144, v144
	v_rcp_f32_e32 v142, v142
	v_lshl_add_u64 v[114:115], v[112:113], 0, v[176:177]
	v_lshl_add_u64 v[112:113], v[112:113], 0, v[178:179]
	v_mov_b32_e32 v181, v198
	global_load_dwordx4 v[124:127], v[114:115], off
	v_mov_b64_e32 v[172:173], s[6:7]
	global_load_dwordx4 v[112:115], v[112:113], off
	v_mul_f32_e32 v145, 0xbfb8aa3b, v145
	v_mad_i64_i32 v[184:185], s[2:3], v181, s76, v[172:173]
	v_mul_f32_e32 v140, 0xbfb8aa3b, v140
	v_exp_f32_e32 v145, v145
	v_mul_f32_e32 v141, 0xbfb8aa3b, v141
	v_mul_f32_e32 v146, 0xbfb8aa3b, v146
	v_exp_f32_e32 v140, v140
	v_exp_f32_e32 v141, v141
	v_exp_f32_e32 v146, v146
	v_add_f32_e32 v145, 1.0, v145
	v_mul_f32_e32 v132, 0xbfb8aa3b, v132
	v_mul_f32_e32 v130, 0xbfb8aa3b, v130
	v_add_f32_e32 v140, 1.0, v140
	v_rcp_f32_e32 v145, v145
	v_add_f32_e32 v141, 1.0, v141
	v_add_f32_e32 v146, 1.0, v146
	v_exp_f32_e32 v132, v132
	v_exp_f32_e32 v130, v130
	v_rcp_f32_e32 v140, v140
	v_rcp_f32_e32 v141, v141
	v_rcp_f32_e32 v146, v146
	v_add_f32_e32 v132, 1.0, v132
	v_add_f32_e32 v130, 1.0, v130
	s_mov_b64 s[4:5], 0xae00800
	v_rcp_f32_e32 v132, v132
	v_rcp_f32_e32 v130, v130
	v_lshl_add_u64 v[184:185], v[184:185], 0, s[4:5]
	v_mul_f32_e32 v128, 0xbfb8aa3b, v128
	v_mul_f32_e32 v129, 0xbfb8aa3b, v129
	v_exp_f32_e32 v128, v128
	v_mul_f32_e32 v133, 0xbfb8aa3b, v133
	s_waitcnt vmcnt(0)
	v_lshlrev_b32_e32 v181, 16, v202
	v_lshlrev_b32_e32 v206, 16, v205
	v_mul_f32_e32 v144, v144, v181
	v_mul_f32_e32 v181, v142, v206
	v_mul_f32_e32 v142, 0xbfb8aa3b, v147
	v_exp_f32_e32 v142, v142
	v_and_b32_e32 v183, 0xffff0000, v202
	v_and_b32_e32 v202, 0xffff0000, v203
	v_and_b32_e32 v205, 0xffff0000, v205
	v_add_f32_e32 v142, 1.0, v142
	v_rcp_f32_e32 v142, v142
	v_lshlrev_b32_e32 v201, 16, v203
	v_lshlrev_b32_e32 v203, 16, v204
	v_and_b32_e32 v204, 0xffff0000, v204
	v_mul_f32_e32 v147, v142, v202
	v_mul_f32_e32 v142, 0xbfb8aa3b, v143
	v_exp_f32_e32 v142, v142
	v_mul_f32_e32 v145, v145, v183
	v_mul_f32_e32 v140, v140, v203
	v_mul_f32_e32 v141, v141, v204
	v_add_f32_e32 v142, 1.0, v142
	v_rcp_f32_e32 v142, v142
	v_mul_f32_e32 v146, v146, v201
	v_exp_f32_e32 v129, v129
	v_mul_f32_e32 v134, 0xbfb8aa3b, v134
	v_mul_f32_e32 v183, v142, v205
	v_cvt_pk_bf16_f32 v142, v144, v145
	v_cvt_pk_bf16_f32 v143, v146, v147
	v_cvt_pk_bf16_f32 v144, v140, v141
	v_cvt_pk_bf16_f32 v145, v181, v183
	v_ashrrev_i32_e32 v183, 31, v182
	v_lshlrev_b64 v[140:141], 1, v[182:183]
	v_lshl_add_u64 v[146:147], v[184:185], 0, v[140:141]
	global_store_dwordx4 v[146:147], v[142:145], off
	v_exp_f32_e32 v133, v133
	v_exp_f32_e32 v134, v134
	v_lshlrev_b32_e32 v142, 16, v160
	v_and_b32_e32 v143, 0xffff0000, v160
	v_lshlrev_b32_e32 v160, 16, v163
	v_mul_f32_e32 v132, v132, v142
	v_mul_f32_e32 v142, v130, v160
	v_mul_f32_e32 v130, 0xbfb8aa3b, v135
	v_exp_f32_e32 v130, v130
	v_and_b32_e32 v145, 0xffff0000, v161
	v_mul_f32_e32 v120, 0xbfb8aa3b, v120
	v_mul_f32_e32 v116, 0xbfb8aa3b, v116
	v_add_f32_e32 v130, 1.0, v130
	v_rcp_f32_e32 v130, v130
	v_mul_f32_e32 v117, 0xbfb8aa3b, v117
	v_mul_f32_e32 v118, 0xbfb8aa3b, v118
	v_add_f32_e32 v128, 1.0, v128
	v_mul_f32_e32 v135, v130, v145
	v_mul_f32_e32 v130, 0xbfb8aa3b, v131
	v_exp_f32_e32 v130, v130
	v_add_f32_e32 v129, 1.0, v129
	v_exp_f32_e32 v120, v120
	v_exp_f32_e32 v116, v116
	v_exp_f32_e32 v117, v117
	v_exp_f32_e32 v118, v118
	v_rcp_f32_e32 v128, v128
	v_add_f32_e32 v133, 1.0, v133
	v_rcp_f32_e32 v129, v129
	v_add_f32_e32 v134, 1.0, v134
	v_add_f32_e32 v130, 1.0, v130
	v_rcp_f32_e32 v133, v133
; __device__ __forceinline__ float sigmoidf_(float v) { return __builtin_amdgcn_rcpf(1.0f + __expf(-v)); }
; __device__ __forceinline__ u32x4 pack8(const f32x4 a, const f32x4 b) { u32x4 w; w.x = cvt_pk_bf16(a[0], a[1]); w.y = cvt_pk_bf16(a[2], a[3]); w.z = cvt_pk_bf16(b[0], b[1]); w.w = cvt_pk_bf16(b[2], b[3]); return w; }
; __device__ __forceinline__ void unpack8(const u32x4 w, f32x4& a, f32x4& b) { a[0] = bf_lo(w.x); a[1] = bf_hi(w.x); a[2] = bf_lo(w.y); a[3] = bf_hi(w.y); b[0] = bf_lo(w.z); b[1] = bf_hi(w.z); b[2] = bf_lo(w.w); b[3] = bf_hi(w.w); }
;     template <int KIND> __device__ __forceinline__ void run(f32x4 (&acc)[2][2][4][2], const Unit& u, int tid_in) const {
;     ...
;                 for (int m = 0; m < 4; ++m) { int row = rbase + ai * 128 + m * 16; asm volatile("" : "+v"(row));
; #pragma unroll
;                     for (int bj = 0; bj < 2; ++bj) { const int col = u.pn * 256 + bj * 128 + cl; yv[m][bj] = *(const u32x4*)(yi + ((size_t)(col >> 4) * T_TOK + row) * 16 + (col & 15)); } }
; #pragma unroll
;                 for (int m = 0; m < 4; ++m) { int row = rbase + ai * 128 + m * 16; asm volatile("" : "+v"(row));
; #pragma unroll
;                     for (int bj = 0; bj < 2; ++bj) { const int col = u.pn * 256 + bj * 128 + cl; f32x4 y0, y1; unpack8(yv[m][bj], y0, y1);
; #pragma unroll
;                         for (int j = 0; j < 4; ++j) { y0[j] *= sigmoidf_(acc[ai][bj][m][0][j]); y1[j] *= sigmoidf_(acc[ai][bj][m][1][j]); }
;                         *(u32x4*)(zb + (size_t)row * ZW + 1024 + col) = pack8(y0, y1); } }
	v_rcp_f32_e32 v134, v134
	v_rcp_f32_e32 v130, v130
	v_lshlrev_b32_e32 v146, 16, v162
	v_and_b32_e32 v147, 0xffff0000, v162
	v_add_f32_e32 v120, 1.0, v120
	v_add_f32_e32 v116, 1.0, v116
	v_add_f32_e32 v117, 1.0, v117
	v_add_f32_e32 v118, 1.0, v118
	v_lshlrev_b32_e32 v144, 16, v161
	v_and_b32_e32 v161, 0xffff0000, v163
	v_mul_f32_e32 v128, v128, v146
	v_mul_f32_e32 v129, v129, v147
	v_ashrrev_i32_e32 v181, 31, v180
	v_rcp_f32_e32 v120, v120
	v_rcp_f32_e32 v116, v116
	v_rcp_f32_e32 v117, v117
	v_rcp_f32_e32 v118, v118
	v_mul_f32_e32 v133, v133, v143
	v_mul_f32_e32 v134, v134, v144
	v_mul_f32_e32 v143, v130, v161
	v_cvt_pk_bf16_f32 v130, v132, v133
	v_cvt_pk_bf16_f32 v131, v134, v135
	v_cvt_pk_bf16_f32 v132, v128, v129
	v_lshlrev_b64 v[128:129], 1, v[180:181]
	v_lshl_add_u64 v[134:135], v[184:185], 0, v[128:129]
	v_cvt_pk_bf16_f32 v133, v142, v143
	global_store_dwordx4 v[134:135], v[130:133], off
	v_lshlrev_b32_e32 v142, 16, v158
	v_and_b32_e32 v143, 0xffff0000, v158
	v_lshlrev_b32_e32 v132, 16, v156
	v_lshlrev_b32_e32 v144, 16, v159
	v_mul_f32_e32 v120, v120, v132
	v_mul_f32_e32 v132, v116, v142
	v_mul_f32_e32 v116, 0xbfb8aa3b, v121
	v_mul_f32_e32 v121, v117, v143
	v_mul_f32_e32 v117, 0xbfb8aa3b, v122
	v_mul_f32_e32 v122, v118, v144
	v_mul_f32_e32 v118, 0xbfb8aa3b, v123
	v_exp_f32_e32 v116, v116
	v_exp_f32_e32 v117, v117
	v_exp_f32_e32 v118, v118
	v_mul_f32_e32 v119, 0xbfb8aa3b, v119
	v_exp_f32_e32 v119, v119
	v_mul_f32_e32 v108, 0xbfb8aa3b, v108
	v_mul_f32_e32 v104, 0xbfb8aa3b, v104
	v_mul_f32_e32 v105, 0xbfb8aa3b, v105
	v_mul_f32_e32 v106, 0xbfb8aa3b, v106
	v_exp_f32_e32 v108, v108
	v_exp_f32_e32 v104, v104
	v_exp_f32_e32 v105, v105
	v_exp_f32_e32 v106, v106
	v_add_f32_e32 v116, 1.0, v116
	v_add_f32_e32 v117, 1.0, v117
	v_add_f32_e32 v118, 1.0, v118
	v_rcp_f32_e32 v116, v116
	v_rcp_f32_e32 v117, v117
	v_rcp_f32_e32 v118, v118
	v_add_f32_e32 v119, 1.0, v119
	v_rcp_f32_e32 v119, v119
	v_add_f32_e32 v108, 1.0, v108
	v_add_f32_e32 v104, 1.0, v104
	v_add_f32_e32 v105, 1.0, v105
	v_add_f32_e32 v106, 1.0, v106
	v_and_b32_e32 v133, 0xffff0000, v156
	v_mad_i64_i32 v[130:131], s[2:3], v200, s76, v[172:173]
	v_lshlrev_b32_e32 v134, 16, v157
	v_and_b32_e32 v135, 0xffff0000, v157
	v_rcp_f32_e32 v108, v108
	v_rcp_f32_e32 v104, v104
	v_rcp_f32_e32 v105, v105
	v_rcp_f32_e32 v106, v106
	v_lshl_add_u64 v[130:131], v[130:131], 0, s[4:5]
	v_and_b32_e32 v145, 0xffff0000, v159
	v_mul_f32_e32 v116, v116, v133
	v_mul_f32_e32 v117, v117, v134
	v_mul_f32_e32 v118, v118, v135
	v_mul_f32_e32 v119, v119, v145
	v_cvt_pk_bf16_f32 v116, v120, v116
	v_cvt_pk_bf16_f32 v117, v117, v118
	v_cvt_pk_bf16_f32 v118, v132, v121
	v_lshl_add_u64 v[120:121], v[130:131], 0, v[140:141]
	v_cvt_pk_bf16_f32 v119, v122, v119
	global_store_dwordx4 v[120:121], v[116:119], off
	v_lshlrev_b32_e32 v120, 16, v154
	v_and_b32_e32 v121, 0xffff0000, v154
	v_lshlrev_b32_e32 v116, 16, v152
	v_lshlrev_b32_e32 v122, 16, v155
	v_mul_f32_e32 v108, v108, v116
	v_mul_f32_e32 v116, v104, v120
	v_mul_f32_e32 v104, 0xbfb8aa3b, v109
	v_mul_f32_e32 v109, v105, v121
	v_mul_f32_e32 v105, 0xbfb8aa3b, v110
	v_mul_f32_e32 v110, v106, v122
	v_mul_f32_e32 v106, 0xbfb8aa3b, v111
	v_exp_f32_e32 v104, v104
	v_exp_f32_e32 v105, v105
	v_exp_f32_e32 v106, v106
	v_mul_f32_e32 v107, 0xbfb8aa3b, v107
	v_exp_f32_e32 v107, v107
	v_mul_f32_e32 v100, 0xbfb8aa3b, v100
	v_mul_f32_e32 v96, 0xbfb8aa3b, v96
	v_mul_f32_e32 v97, 0xbfb8aa3b, v97
	v_mul_f32_e32 v98, 0xbfb8aa3b, v98
	v_exp_f32_e32 v100, v100
	v_exp_f32_e32 v96, v96
	v_exp_f32_e32 v97, v97
	v_exp_f32_e32 v98, v98
	v_add_f32_e32 v104, 1.0, v104
	v_add_f32_e32 v105, 1.0, v105
	v_add_f32_e32 v106, 1.0, v106
	v_rcp_f32_e32 v104, v104
	v_rcp_f32_e32 v105, v105
	v_rcp_f32_e32 v106, v106
	v_add_f32_e32 v107, 1.0, v107
	v_rcp_f32_e32 v107, v107
	v_add_f32_e32 v100, 1.0, v100
	v_add_f32_e32 v96, 1.0, v96
	v_add_f32_e32 v97, 1.0, v97
	v_add_f32_e32 v98, 1.0, v98
	v_and_b32_e32 v117, 0xffff0000, v152
	v_lshlrev_b32_e32 v118, 16, v153
	v_and_b32_e32 v119, 0xffff0000, v153
	v_rcp_f32_e32 v100, v100
	v_rcp_f32_e32 v96, v96
	v_rcp_f32_e32 v97, v97
	v_rcp_f32_e32 v98, v98
	v_and_b32_e32 v123, 0xffff0000, v155
	v_mul_f32_e32 v104, v104, v117
	v_mul_f32_e32 v105, v105, v118
	v_mul_f32_e32 v106, v106, v119
	v_mul_f32_e32 v107, v107, v123
	v_cvt_pk_bf16_f32 v104, v108, v104
	v_cvt_pk_bf16_f32 v105, v105, v106
	v_cvt_pk_bf16_f32 v106, v116, v109
	v_lshl_add_u64 v[108:109], v[130:131], 0, v[128:129]
	v_cvt_pk_bf16_f32 v107, v110, v107
	global_store_dwordx4 v[108:109], v[104:107], off
	v_lshlrev_b32_e32 v110, 16, v150
	v_and_b32_e32 v111, 0xffff0000, v150
	v_lshlrev_b32_e32 v106, 16, v148
	v_lshlrev_b32_e32 v116, 16, v151
	v_mul_f32_e32 v100, v100, v106
	v_mul_f32_e32 v106, v96, v110
	v_mul_f32_e32 v96, 0xbfb8aa3b, v101
	v_mul_f32_e32 v101, v97, v111
	v_mul_f32_e32 v97, 0xbfb8aa3b, v102
	v_mul_f32_e32 v102, v98, v116
	v_mul_f32_e32 v98, 0xbfb8aa3b, v103
	v_exp_f32_e32 v96, v96
	v_exp_f32_e32 v97, v97
	v_exp_f32_e32 v98, v98
	v_mul_f32_e32 v99, 0xbfb8aa3b, v99
	v_exp_f32_e32 v99, v99
	v_mul_f32_e32 v92, 0xbfb8aa3b, v92
	v_mul_f32_e32 v88, 0xbfb8aa3b, v88
	v_mul_f32_e32 v89, 0xbfb8aa3b, v89
	v_mul_f32_e32 v90, 0xbfb8aa3b, v90
	v_exp_f32_e32 v92, v92
	v_exp_f32_e32 v88, v88
	v_exp_f32_e32 v89, v89
	v_exp_f32_e32 v90, v90
	v_add_f32_e32 v96, 1.0, v96
	v_add_f32_e32 v97, 1.0, v97
	v_add_f32_e32 v98, 1.0, v98
	v_rcp_f32_e32 v96, v96
	v_rcp_f32_e32 v97, v97
	v_rcp_f32_e32 v98, v98
	v_add_f32_e32 v99, 1.0, v99
	v_rcp_f32_e32 v99, v99
	v_add_f32_e32 v92, 1.0, v92
	v_add_f32_e32 v88, 1.0, v88
	v_add_f32_e32 v89, 1.0, v89
	v_add_f32_e32 v90, 1.0, v90
	v_and_b32_e32 v107, 0xffff0000, v148
; __device__ __forceinline__ float sigmoidf_(float v) { return __builtin_amdgcn_rcpf(1.0f + __expf(-v)); }
; __device__ __forceinline__ u32x4 pack8(const f32x4 a, const f32x4 b) { u32x4 w; w.x = cvt_pk_bf16(a[0], a[1]); w.y = cvt_pk_bf16(a[2], a[3]); w.z = cvt_pk_bf16(b[0], b[1]); w.w = cvt_pk_bf16(b[2], b[3]); return w; }
; __device__ __forceinline__ void unpack8(const u32x4 w, f32x4& a, f32x4& b) { a[0] = bf_lo(w.x); a[1] = bf_hi(w.x); a[2] = bf_lo(w.y); a[3] = bf_hi(w.y); b[0] = bf_lo(w.z); b[1] = bf_hi(w.z); b[2] = bf_lo(w.w); b[3] = bf_hi(w.w); }
;     template <int KIND> __device__ __forceinline__ void run(f32x4 (&acc)[2][2][4][2], const Unit& u, int tid_in) const {
;     ...
;                 for (int m = 0; m < 4; ++m) { int row = rbase + ai * 128 + m * 16; asm volatile("" : "+v"(row));
; #pragma unroll
;                     for (int bj = 0; bj < 2; ++bj) { const int col = u.pn * 256 + bj * 128 + cl; yv[m][bj] = *(const u32x4*)(yi + ((size_t)(col >> 4) * T_TOK + row) * 16 + (col & 15)); } }
; #pragma unroll
;                 for (int m = 0; m < 4; ++m) { int row = rbase + ai * 128 + m * 16; asm volatile("" : "+v"(row));
; #pragma unroll
;                     for (int bj = 0; bj < 2; ++bj) { const int col = u.pn * 256 + bj * 128 + cl; f32x4 y0, y1; unpack8(yv[m][bj], y0, y1);
; #pragma unroll
;                         for (int j = 0; j < 4; ++j) { y0[j] *= sigmoidf_(acc[ai][bj][m][0][j]); y1[j] *= sigmoidf_(acc[ai][bj][m][1][j]); }
;                         *(u32x4*)(zb + (size_t)row * ZW + 1024 + col) = pack8(y0, y1); } }
	v_mad_i64_i32 v[104:105], s[2:3], v199, s76, v[172:173]
	v_lshlrev_b32_e32 v108, 16, v149
	v_and_b32_e32 v109, 0xffff0000, v149
	v_rcp_f32_e32 v92, v92
	v_rcp_f32_e32 v88, v88
	v_rcp_f32_e32 v89, v89
	v_rcp_f32_e32 v90, v90
	v_lshl_add_u64 v[104:105], v[104:105], 0, s[4:5]
	v_and_b32_e32 v117, 0xffff0000, v151
	v_mul_f32_e32 v96, v96, v107
	v_mul_f32_e32 v97, v97, v108
	v_mul_f32_e32 v98, v98, v109
	v_mul_f32_e32 v99, v99, v117
	v_cvt_pk_bf16_f32 v96, v100, v96
	v_cvt_pk_bf16_f32 v97, v97, v98
	v_cvt_pk_bf16_f32 v98, v106, v101
	v_lshl_add_u64 v[100:101], v[104:105], 0, v[140:141]
	v_cvt_pk_bf16_f32 v99, v102, v99
	global_store_dwordx4 v[100:101], v[96:99], off
	v_lshlrev_b32_e32 v100, 16, v138
	v_and_b32_e32 v101, 0xffff0000, v138
	v_lshlrev_b32_e32 v96, 16, v136
	v_lshlrev_b32_e32 v102, 16, v139
	v_mul_f32_e32 v92, v92, v96
	v_mul_f32_e32 v96, v88, v100
	v_mul_f32_e32 v88, 0xbfb8aa3b, v93
	v_mul_f32_e32 v93, v89, v101
	v_mul_f32_e32 v89, 0xbfb8aa3b, v94
	v_mul_f32_e32 v94, v90, v102
	v_mul_f32_e32 v90, 0xbfb8aa3b, v95
	v_exp_f32_e32 v88, v88
	v_exp_f32_e32 v89, v89
	v_exp_f32_e32 v90, v90
	v_mul_f32_e32 v91, 0xbfb8aa3b, v91
	v_exp_f32_e32 v91, v91
	v_mul_f32_e32 v84, 0xbfb8aa3b, v84
	v_mul_f32_e32 v80, 0xbfb8aa3b, v80
	v_mul_f32_e32 v81, 0xbfb8aa3b, v81
	v_mul_f32_e32 v82, 0xbfb8aa3b, v82
	v_add_f32_e32 v88, 1.0, v88
	v_add_f32_e32 v89, 1.0, v89
	v_add_f32_e32 v90, 1.0, v90
	v_exp_f32_e32 v84, v84
	v_exp_f32_e32 v80, v80
	v_exp_f32_e32 v81, v81
	v_exp_f32_e32 v82, v82
	v_rcp_f32_e32 v88, v88
	v_rcp_f32_e32 v89, v89
	v_rcp_f32_e32 v90, v90
	v_add_f32_e32 v91, 1.0, v91
	v_rcp_f32_e32 v91, v91
	v_and_b32_e32 v97, 0xffff0000, v136
	v_lshlrev_b32_e32 v98, 16, v137
	v_and_b32_e32 v99, 0xffff0000, v137
	v_add_f32_e32 v84, 1.0, v84
	v_add_f32_e32 v80, 1.0, v80
	v_add_f32_e32 v81, 1.0, v81
	v_add_f32_e32 v82, 1.0, v82
	v_and_b32_e32 v103, 0xffff0000, v139
	v_mul_f32_e32 v88, v88, v97
	v_mul_f32_e32 v89, v89, v98
	v_mul_f32_e32 v90, v90, v99
	v_rcp_f32_e32 v84, v84
	v_rcp_f32_e32 v80, v80
	v_rcp_f32_e32 v81, v81
	v_rcp_f32_e32 v82, v82
	v_mul_f32_e32 v91, v91, v103
	v_cvt_pk_bf16_f32 v88, v92, v88
	v_cvt_pk_bf16_f32 v89, v89, v90
	v_cvt_pk_bf16_f32 v90, v96, v93
	v_lshl_add_u64 v[92:93], v[104:105], 0, v[128:129]
	v_cvt_pk_bf16_f32 v91, v94, v91
	global_store_dwordx4 v[92:93], v[88:91], off
	v_lshlrev_b32_e32 v93, 16, v126
	v_and_b32_e32 v94, 0xffff0000, v126
	v_mad_i64_i32 v[88:89], s[2:3], v0, s76, v[172:173]
	v_lshlrev_b32_e32 v0, 16, v124
	v_lshlrev_b32_e32 v95, 16, v127
	v_mul_f32_e32 v0, v84, v0
	v_mul_f32_e32 v84, v80, v93
	v_mul_f32_e32 v80, 0xbfb8aa3b, v85
	v_mul_f32_e32 v85, v81, v94
	v_mul_f32_e32 v81, 0xbfb8aa3b, v86
	v_mul_f32_e32 v86, v82, v95
	v_mul_f32_e32 v82, 0xbfb8aa3b, v87
	v_mul_f32_e32 v83, 0xbfb8aa3b, v83
	v_exp_f32_e32 v80, v80
	v_exp_f32_e32 v81, v81
	v_exp_f32_e32 v82, v82
	v_exp_f32_e32 v83, v83
	v_mul_f32_e32 v76, 0xbfb8aa3b, v76
	v_mul_f32_e32 v72, 0xbfb8aa3b, v72
	v_mul_f32_e32 v73, 0xbfb8aa3b, v73
	v_mul_f32_e32 v74, 0xbfb8aa3b, v74
	v_exp_f32_e32 v76, v76
	v_exp_f32_e32 v72, v72
	v_exp_f32_e32 v73, v73
	v_exp_f32_e32 v74, v74
	v_add_f32_e32 v80, 1.0, v80
	v_add_f32_e32 v81, 1.0, v81
	v_add_f32_e32 v82, 1.0, v82
	v_add_f32_e32 v83, 1.0, v83
	v_rcp_f32_e32 v80, v80
	v_rcp_f32_e32 v81, v81
	v_rcp_f32_e32 v82, v82
	v_rcp_f32_e32 v83, v83
	v_add_f32_e32 v76, 1.0, v76
	v_add_f32_e32 v72, 1.0, v72
	v_add_f32_e32 v73, 1.0, v73
	v_add_f32_e32 v74, 1.0, v74
	v_and_b32_e32 v90, 0xffff0000, v124
	v_lshlrev_b32_e32 v91, 16, v125
	v_and_b32_e32 v92, 0xffff0000, v125
	v_and_b32_e32 v96, 0xffff0000, v127
	v_rcp_f32_e32 v76, v76
	v_rcp_f32_e32 v72, v72
	v_rcp_f32_e32 v73, v73
	v_rcp_f32_e32 v74, v74
	v_lshl_add_u64 v[88:89], v[88:89], 0, s[4:5]
	v_mul_f32_e32 v80, v80, v90
	v_mul_f32_e32 v81, v81, v91
	v_mul_f32_e32 v82, v82, v92
	v_mul_f32_e32 v83, v83, v96
	v_cvt_pk_bf16_f32 v80, v0, v80
	v_cvt_pk_bf16_f32 v81, v81, v82
	v_cvt_pk_bf16_f32 v82, v84, v85
	v_cvt_pk_bf16_f32 v83, v86, v83
	v_lshl_add_u64 v[84:85], v[88:89], 0, v[140:141]
	global_store_dwordx4 v[84:85], v[80:83], off
	v_lshlrev_b32_e32 v0, 16, v112
	v_and_b32_e32 v84, 0xffff0000, v114
	v_lshlrev_b32_e32 v83, 16, v114
	v_lshlrev_b32_e32 v85, 16, v115
	v_mul_f32_e32 v0, v76, v0
	v_mul_f32_e32 v76, v72, v83
	v_mul_f32_e32 v72, 0xbfb8aa3b, v77
	v_mul_f32_e32 v77, v73, v84
	v_mul_f32_e32 v73, 0xbfb8aa3b, v78
	v_mul_f32_e32 v78, v74, v85
	v_mul_f32_e32 v74, 0xbfb8aa3b, v79
	v_exp_f32_e32 v72, v72
	v_exp_f32_e32 v73, v73
	v_exp_f32_e32 v74, v74
	v_mul_f32_e32 v75, 0xbfb8aa3b, v75
	v_exp_f32_e32 v75, v75
	v_add_f32_e32 v72, 1.0, v72
	v_add_f32_e32 v73, 1.0, v73
	v_add_f32_e32 v74, 1.0, v74
	v_rcp_f32_e32 v72, v72
	v_rcp_f32_e32 v73, v73
	v_rcp_f32_e32 v74, v74
	v_add_f32_e32 v75, 1.0, v75
	v_rcp_f32_e32 v75, v75
	v_and_b32_e32 v80, 0xffff0000, v112
	v_lshlrev_b32_e32 v81, 16, v113
	v_and_b32_e32 v82, 0xffff0000, v113
	v_and_b32_e32 v86, 0xffff0000, v115
	v_mul_f32_e32 v72, v72, v80
	v_mul_f32_e32 v73, v73, v81
	v_mul_f32_e32 v74, v74, v82
	v_mul_f32_e32 v75, v75, v86
	v_cvt_pk_bf16_f32 v72, v0, v72
	v_cvt_pk_bf16_f32 v73, v73, v74
	v_cvt_pk_bf16_f32 v74, v76, v77
	v_lshl_add_u64 v[76:77], v[88:89], 0, v[128:129]
	v_add_u32_e32 v100, 0x80, v198
	v_cvt_pk_bf16_f32 v75, v78, v75
	global_store_dwordx4 v[76:77], v[72:75], off
	v_add_u32_e32 v103, 0x90, v198
	v_add_u32_e32 v102, 0xa0, v198
	v_mov_b32_e32 v72, v100
	v_mul_f32_e32 v68, 0xbfb8aa3b, v68
	v_ashrrev_i32_e32 v73, 31, v72
	v_lshlrev_b64 v[72:73], 5, v[72:73]
	v_lshl_add_u64 v[72:73], v[174:175], 0, v[72:73]
	v_lshl_add_u64 v[74:75], v[72:73], 0, v[176:177]
	global_load_dwordx4 v[104:107], v[74:75], off
; __device__ __forceinline__ float sigmoidf_(float v) { return __builtin_amdgcn_rcpf(1.0f + __expf(-v)); }
; __device__ __forceinline__ u32x4 pack8(const f32x4 a, const f32x4 b) { u32x4 w; w.x = cvt_pk_bf16(a[0], a[1]); w.y = cvt_pk_bf16(a[2], a[3]); w.z = cvt_pk_bf16(b[0], b[1]); w.w = cvt_pk_bf16(b[2], b[3]); return w; }
; __device__ __forceinline__ void unpack8(const u32x4 w, f32x4& a, f32x4& b) { a[0] = bf_lo(w.x); a[1] = bf_hi(w.x); a[2] = bf_lo(w.y); a[3] = bf_hi(w.y); b[0] = bf_lo(w.z); b[1] = bf_hi(w.z); b[2] = bf_lo(w.w); b[3] = bf_hi(w.w); }
;     template <int KIND> __device__ __forceinline__ void run(f32x4 (&acc)[2][2][4][2], const Unit& u, int tid_in) const {
;     ...
;         if constexpr (KIND == K_GLU) {
; #pragma unroll
;             for (int ai = 0; ai < 2; ++ai) { u32x4 yv[4][2];
; #pragma unroll
;                 for (int m = 0; m < 4; ++m) { int row = rbase + ai * 128 + m * 16; asm volatile("" : "+v"(row));
; #pragma unroll
;                     for (int bj = 0; bj < 2; ++bj) { const int col = u.pn * 256 + bj * 128 + cl; yv[m][bj] = *(const u32x4*)(yi + ((size_t)(col >> 4) * T_TOK + row) * 16 + (col & 15)); } }
; #pragma unroll
;                 for (int m = 0; m < 4; ++m) { int row = rbase + ai * 128 + m * 16; asm volatile("" : "+v"(row));
; #pragma unroll
;                     for (int bj = 0; bj < 2; ++bj) { const int col = u.pn * 256 + bj * 128 + cl; f32x4 y0, y1; unpack8(yv[m][bj], y0, y1);
; #pragma unroll
;                         for (int j = 0; j < 4; ++j) { y0[j] *= sigmoidf_(acc[ai][bj][m][0][j]); y1[j] *= sigmoidf_(acc[ai][bj][m][1][j]); }
;                         *(u32x4*)(zb + (size_t)row * ZW + 1024 + col) = pack8(y0, y1); } }
	v_lshl_add_u64 v[72:73], v[72:73], 0, v[178:179]
	global_load_dwordx4 v[96:99], v[72:73], off
	v_mov_b32_e32 v72, v103
	v_mul_f32_e32 v64, 0xbfb8aa3b, v64
	v_ashrrev_i32_e32 v73, 31, v72
	v_lshlrev_b64 v[72:73], 5, v[72:73]
	v_lshl_add_u64 v[72:73], v[174:175], 0, v[72:73]
	v_lshl_add_u64 v[74:75], v[72:73], 0, v[176:177]
	global_load_dwordx4 v[92:95], v[74:75], off
	v_lshl_add_u64 v[72:73], v[72:73], 0, v[178:179]
	global_load_dwordx4 v[88:91], v[72:73], off
	v_mov_b32_e32 v72, v102
	v_mul_f32_e32 v65, 0xbfb8aa3b, v65
	v_ashrrev_i32_e32 v73, 31, v72
	v_lshlrev_b64 v[72:73], 5, v[72:73]
	v_lshl_add_u64 v[72:73], v[174:175], 0, v[72:73]
	v_lshl_add_u64 v[74:75], v[72:73], 0, v[176:177]
	global_load_dwordx4 v[84:87], v[74:75], off
	v_lshl_add_u64 v[72:73], v[72:73], 0, v[178:179]
	global_load_dwordx4 v[80:83], v[72:73], off
	v_mul_f32_e32 v66, 0xbfb8aa3b, v66
	v_exp_f32_e32 v68, v68
	v_exp_f32_e32 v64, v64
	v_exp_f32_e32 v65, v65
	v_exp_f32_e32 v66, v66
	v_add_u32_e32 v0, 0xb0, v198
	v_mov_b32_e32 v72, v0
	v_add_f32_e32 v68, 1.0, v68
	v_ashrrev_i32_e32 v73, 31, v72
	v_lshlrev_b64 v[72:73], 5, v[72:73]
	v_add_f32_e32 v64, 1.0, v64
	v_add_f32_e32 v65, 1.0, v65
	v_add_f32_e32 v66, 1.0, v66
	v_lshl_add_u64 v[72:73], v[174:175], 0, v[72:73]
	v_rcp_f32_e32 v68, v68
	v_rcp_f32_e32 v64, v64
	v_rcp_f32_e32 v65, v65
	v_rcp_f32_e32 v66, v66
	v_lshl_add_u64 v[74:75], v[72:73], 0, v[176:177]
	global_load_dwordx4 v[76:79], v[74:75], off
	v_mul_f32_e32 v67, 0xbfb8aa3b, v67
	v_exp_f32_e32 v67, v67
	v_mul_f32_e32 v60, 0xbfb8aa3b, v60
	v_mul_f32_e32 v56, 0xbfb8aa3b, v56
	v_mul_f32_e32 v57, 0xbfb8aa3b, v57
	v_mul_f32_e32 v58, 0xbfb8aa3b, v58
	v_exp_f32_e32 v60, v60
	v_exp_f32_e32 v56, v56
	v_exp_f32_e32 v57, v57
	v_exp_f32_e32 v58, v58
	v_add_f32_e32 v67, 1.0, v67
	v_lshl_add_u64 v[72:73], v[72:73], 0, v[178:179]
	v_rcp_f32_e32 v67, v67
	global_load_dwordx4 v[72:75], v[72:73], off
	v_add_f32_e32 v60, 1.0, v60
	v_add_f32_e32 v56, 1.0, v56
	v_add_f32_e32 v57, 1.0, v57
	v_add_f32_e32 v58, 1.0, v58
	v_mad_i64_i32 v[100:101], s[2:3], v100, s76, v[172:173]
	v_rcp_f32_e32 v60, v60
	v_rcp_f32_e32 v56, v56
	v_rcp_f32_e32 v57, v57
	v_rcp_f32_e32 v58, v58
	v_lshl_add_u64 v[100:101], v[100:101], 0, s[4:5]
	v_mul_f32_e32 v59, 0xbfb8aa3b, v59
	v_exp_f32_e32 v59, v59
	v_mul_f32_e32 v52, 0xbfb8aa3b, v52
	v_mul_f32_e32 v48, 0xbfb8aa3b, v48
	v_mul_f32_e32 v49, 0xbfb8aa3b, v49
	v_mul_f32_e32 v50, 0xbfb8aa3b, v50
	v_exp_f32_e32 v52, v52
	v_exp_f32_e32 v48, v48
	v_exp_f32_e32 v49, v49
	v_exp_f32_e32 v50, v50
	s_waitcnt vmcnt(0)
	v_lshlrev_b32_e32 v108, 16, v104
	v_lshlrev_b32_e32 v110, 16, v106
	v_and_b32_e32 v106, 0xffff0000, v106
	v_lshlrev_b32_e32 v111, 16, v107
	v_mul_f32_e32 v68, v68, v108
	v_mul_f32_e32 v108, v64, v110
	v_mul_f32_e32 v64, 0xbfb8aa3b, v69
	v_mul_f32_e32 v69, v65, v106
	v_mul_f32_e32 v65, 0xbfb8aa3b, v70
	v_mul_f32_e32 v70, v66, v111
	v_mul_f32_e32 v66, 0xbfb8aa3b, v71
	v_exp_f32_e32 v64, v64
	v_exp_f32_e32 v65, v65
	v_exp_f32_e32 v66, v66
	v_and_b32_e32 v104, 0xffff0000, v104
	v_add_f32_e32 v64, 1.0, v64
	v_add_f32_e32 v65, 1.0, v65
	v_add_f32_e32 v66, 1.0, v66
	v_rcp_f32_e32 v64, v64
	v_rcp_f32_e32 v65, v65
	v_rcp_f32_e32 v66, v66
	v_lshlrev_b32_e32 v109, 16, v105
	v_and_b32_e32 v105, 0xffff0000, v105
	v_and_b32_e32 v107, 0xffff0000, v107
	v_mul_f32_e32 v64, v64, v104
	v_mul_f32_e32 v65, v65, v109
	v_mul_f32_e32 v66, v66, v105
	v_mul_f32_e32 v67, v67, v107
	v_cvt_pk_bf16_f32 v64, v68, v64
	v_cvt_pk_bf16_f32 v65, v65, v66
	v_cvt_pk_bf16_f32 v66, v108, v69
	v_lshl_add_u64 v[68:69], v[100:101], 0, v[140:141]
	v_cvt_pk_bf16_f32 v67, v70, v67
	global_store_dwordx4 v[68:69], v[64:67], off
	v_lshlrev_b32_e32 v68, 16, v98
	v_and_b32_e32 v69, 0xffff0000, v98
	v_lshlrev_b32_e32 v64, 16, v96
	v_lshlrev_b32_e32 v70, 16, v99
	v_mul_f32_e32 v60, v60, v64
	v_mul_f32_e32 v64, v56, v68
	v_mul_f32_e32 v56, 0xbfb8aa3b, v61
	v_mul_f32_e32 v61, v57, v69
	v_mul_f32_e32 v57, 0xbfb8aa3b, v62
	v_mul_f32_e32 v62, v58, v70
	v_mul_f32_e32 v58, 0xbfb8aa3b, v63
	v_exp_f32_e32 v56, v56
	v_exp_f32_e32 v57, v57
	v_exp_f32_e32 v58, v58
	v_add_f32_e32 v59, 1.0, v59
	v_add_f32_e32 v56, 1.0, v56
	v_add_f32_e32 v57, 1.0, v57
	v_add_f32_e32 v58, 1.0, v58
	v_rcp_f32_e32 v56, v56
	v_rcp_f32_e32 v57, v57
	v_rcp_f32_e32 v58, v58
	v_rcp_f32_e32 v59, v59
	v_add_f32_e32 v52, 1.0, v52
	v_add_f32_e32 v48, 1.0, v48
	v_add_f32_e32 v49, 1.0, v49
	v_add_f32_e32 v50, 1.0, v50
	v_and_b32_e32 v65, 0xffff0000, v96
	v_lshlrev_b32_e32 v66, 16, v97
	v_and_b32_e32 v67, 0xffff0000, v97
	v_rcp_f32_e32 v52, v52
	v_rcp_f32_e32 v48, v48
	v_rcp_f32_e32 v49, v49
	v_rcp_f32_e32 v50, v50
	v_and_b32_e32 v71, 0xffff0000, v99
	v_mul_f32_e32 v56, v56, v65
	v_mul_f32_e32 v57, v57, v66
	v_mul_f32_e32 v58, v58, v67
	v_mul_f32_e32 v59, v59, v71
	v_cvt_pk_bf16_f32 v56, v60, v56
	v_cvt_pk_bf16_f32 v57, v57, v58
	v_cvt_pk_bf16_f32 v58, v64, v61
	v_lshl_add_u64 v[60:61], v[100:101], 0, v[128:129]
	v_cvt_pk_bf16_f32 v59, v62, v59
	global_store_dwordx4 v[60:61], v[56:59], off
	v_lshlrev_b32_e32 v62, 16, v94
	v_and_b32_e32 v63, 0xffff0000, v94
	v_lshlrev_b32_e32 v58, 16, v92
	v_lshlrev_b32_e32 v64, 16, v95
	v_mul_f32_e32 v52, v52, v58
	v_mul_f32_e32 v58, v48, v62
	v_mul_f32_e32 v48, 0xbfb8aa3b, v53
	v_mul_f32_e32 v53, v49, v63
	v_mul_f32_e32 v49, 0xbfb8aa3b, v54
	v_mul_f32_e32 v54, v50, v64
	v_mul_f32_e32 v50, 0xbfb8aa3b, v55
	v_exp_f32_e32 v48, v48
	v_exp_f32_e32 v49, v49
	v_exp_f32_e32 v50, v50
	v_mul_f32_e32 v51, 0xbfb8aa3b, v51
	v_exp_f32_e32 v51, v51
	v_mul_f32_e32 v44, 0xbfb8aa3b, v44
	v_mul_f32_e32 v40, 0xbfb8aa3b, v40
	v_mul_f32_e32 v41, 0xbfb8aa3b, v41
	v_mul_f32_e32 v42, 0xbfb8aa3b, v42
	v_exp_f32_e32 v44, v44
	v_exp_f32_e32 v40, v40
; __device__ __forceinline__ float sigmoidf_(float v) { return __builtin_amdgcn_rcpf(1.0f + __expf(-v)); }
; __device__ __forceinline__ u32x4 pack8(const f32x4 a, const f32x4 b) { u32x4 w; w.x = cvt_pk_bf16(a[0], a[1]); w.y = cvt_pk_bf16(a[2], a[3]); w.z = cvt_pk_bf16(b[0], b[1]); w.w = cvt_pk_bf16(b[2], b[3]); return w; }
; __device__ __forceinline__ void unpack8(const u32x4 w, f32x4& a, f32x4& b) { a[0] = bf_lo(w.x); a[1] = bf_hi(w.x); a[2] = bf_lo(w.y); a[3] = bf_hi(w.y); b[0] = bf_lo(w.z); b[1] = bf_hi(w.z); b[2] = bf_lo(w.w); b[3] = bf_hi(w.w); }
; #define MEMFENCE asm volatile("" ::: "memory")
;     template <int KIND> __device__ __forceinline__ void run(f32x4 (&acc)[2][2][4][2], const Unit& u, int tid_in) const {
;     ...
;                 for (int m = 0; m < 4; ++m) { int row = rbase + ai * 128 + m * 16; asm volatile("" : "+v"(row));
; #pragma unroll
;                     for (int bj = 0; bj < 2; ++bj) { const int col = u.pn * 256 + bj * 128 + cl; f32x4 y0, y1; unpack8(yv[m][bj], y0, y1);
; #pragma unroll
;                         for (int j = 0; j < 4; ++j) { y0[j] *= sigmoidf_(acc[ai][bj][m][0][j]); y1[j] *= sigmoidf_(acc[ai][bj][m][1][j]); }
;                         *(u32x4*)(zb + (size_t)row * ZW + 1024 + col) = pack8(y0, y1); } }
;                 MEMFENCE; }
	v_exp_f32_e32 v41, v41
	v_exp_f32_e32 v42, v42
	v_add_f32_e32 v48, 1.0, v48
	v_add_f32_e32 v49, 1.0, v49
	v_add_f32_e32 v50, 1.0, v50
	v_rcp_f32_e32 v48, v48
	v_rcp_f32_e32 v49, v49
	v_rcp_f32_e32 v50, v50
	v_add_f32_e32 v51, 1.0, v51
	v_rcp_f32_e32 v51, v51
	v_add_f32_e32 v44, 1.0, v44
	v_add_f32_e32 v40, 1.0, v40
	v_add_f32_e32 v41, 1.0, v41
	v_add_f32_e32 v42, 1.0, v42
	v_and_b32_e32 v59, 0xffff0000, v92
	v_mad_i64_i32 v[56:57], s[2:3], v103, s76, v[172:173]
	v_lshlrev_b32_e32 v60, 16, v93
	v_and_b32_e32 v61, 0xffff0000, v93
	v_rcp_f32_e32 v44, v44
	v_rcp_f32_e32 v40, v40
	v_rcp_f32_e32 v41, v41
	v_rcp_f32_e32 v42, v42
	v_lshl_add_u64 v[56:57], v[56:57], 0, s[4:5]
	v_and_b32_e32 v65, 0xffff0000, v95
	v_mul_f32_e32 v48, v48, v59
	v_mul_f32_e32 v49, v49, v60
	v_mul_f32_e32 v50, v50, v61
	v_mul_f32_e32 v51, v51, v65
	v_cvt_pk_bf16_f32 v48, v52, v48
	v_cvt_pk_bf16_f32 v49, v49, v50
	v_cvt_pk_bf16_f32 v50, v58, v53
	v_lshl_add_u64 v[52:53], v[56:57], 0, v[140:141]
	v_cvt_pk_bf16_f32 v51, v54, v51
	global_store_dwordx4 v[52:53], v[48:51], off
	v_lshlrev_b32_e32 v52, 16, v90
	v_and_b32_e32 v53, 0xffff0000, v90
	v_lshlrev_b32_e32 v48, 16, v88
	v_lshlrev_b32_e32 v54, 16, v91
	v_mul_f32_e32 v44, v44, v48
	v_mul_f32_e32 v48, v40, v52
	v_mul_f32_e32 v40, 0xbfb8aa3b, v45
	v_mul_f32_e32 v45, v41, v53
	v_mul_f32_e32 v41, 0xbfb8aa3b, v46
	v_mul_f32_e32 v46, v42, v54
	v_mul_f32_e32 v42, 0xbfb8aa3b, v47
	v_exp_f32_e32 v40, v40
	v_exp_f32_e32 v41, v41
	v_exp_f32_e32 v42, v42
	v_mul_f32_e32 v43, 0xbfb8aa3b, v43
	v_exp_f32_e32 v43, v43
	v_mul_f32_e32 v36, 0xbfb8aa3b, v36
	v_mul_f32_e32 v32, 0xbfb8aa3b, v32
	v_mul_f32_e32 v33, 0xbfb8aa3b, v33
	v_mul_f32_e32 v34, 0xbfb8aa3b, v34
	v_exp_f32_e32 v36, v36
	v_exp_f32_e32 v32, v32
	v_exp_f32_e32 v33, v33
	v_exp_f32_e32 v34, v34
	v_add_f32_e32 v40, 1.0, v40
	v_add_f32_e32 v41, 1.0, v41
	v_add_f32_e32 v42, 1.0, v42
	v_rcp_f32_e32 v40, v40
	v_rcp_f32_e32 v41, v41
	v_rcp_f32_e32 v42, v42
	v_add_f32_e32 v43, 1.0, v43
	v_rcp_f32_e32 v43, v43
	v_add_f32_e32 v36, 1.0, v36
	v_add_f32_e32 v32, 1.0, v32
	v_add_f32_e32 v33, 1.0, v33
	v_add_f32_e32 v34, 1.0, v34
	v_and_b32_e32 v49, 0xffff0000, v88
	v_lshlrev_b32_e32 v50, 16, v89
	v_and_b32_e32 v51, 0xffff0000, v89
	v_rcp_f32_e32 v36, v36
	v_rcp_f32_e32 v32, v32
	v_rcp_f32_e32 v33, v33
	v_rcp_f32_e32 v34, v34
	v_and_b32_e32 v55, 0xffff0000, v91
	v_mul_f32_e32 v40, v40, v49
	v_mul_f32_e32 v41, v41, v50
	v_mul_f32_e32 v42, v42, v51
	v_mul_f32_e32 v43, v43, v55
	v_cvt_pk_bf16_f32 v40, v44, v40
	v_cvt_pk_bf16_f32 v41, v41, v42
	v_cvt_pk_bf16_f32 v42, v48, v45
	v_lshl_add_u64 v[44:45], v[56:57], 0, v[128:129]
	v_cvt_pk_bf16_f32 v43, v46, v43
	global_store_dwordx4 v[44:45], v[40:43], off
	v_lshlrev_b32_e32 v46, 16, v86
	v_and_b32_e32 v47, 0xffff0000, v86
	v_lshlrev_b32_e32 v42, 16, v84
	v_lshlrev_b32_e32 v48, 16, v87
	v_mul_f32_e32 v36, v36, v42
	v_mul_f32_e32 v42, v32, v46
	v_mul_f32_e32 v32, 0xbfb8aa3b, v37
	v_mul_f32_e32 v37, v33, v47
	v_mul_f32_e32 v33, 0xbfb8aa3b, v38
	v_mul_f32_e32 v38, v34, v48
	v_mul_f32_e32 v34, 0xbfb8aa3b, v39
	v_exp_f32_e32 v32, v32
	v_exp_f32_e32 v33, v33
	v_exp_f32_e32 v34, v34
	v_mul_f32_e32 v35, 0xbfb8aa3b, v35
	v_exp_f32_e32 v35, v35
	v_mul_f32_e32 v28, 0xbfb8aa3b, v28
	v_mul_f32_e32 v24, 0xbfb8aa3b, v24
	v_mul_f32_e32 v25, 0xbfb8aa3b, v25
	v_mul_f32_e32 v26, 0xbfb8aa3b, v26
	v_exp_f32_e32 v28, v28
	v_exp_f32_e32 v24, v24
	v_exp_f32_e32 v25, v25
	v_exp_f32_e32 v26, v26
	v_add_f32_e32 v32, 1.0, v32
	v_add_f32_e32 v33, 1.0, v33
	v_add_f32_e32 v34, 1.0, v34
	v_rcp_f32_e32 v32, v32
	v_rcp_f32_e32 v33, v33
	v_rcp_f32_e32 v34, v34
	v_add_f32_e32 v35, 1.0, v35
	v_rcp_f32_e32 v35, v35
	v_add_f32_e32 v28, 1.0, v28
	v_add_f32_e32 v24, 1.0, v24
	v_add_f32_e32 v25, 1.0, v25
	v_add_f32_e32 v26, 1.0, v26
	v_and_b32_e32 v43, 0xffff0000, v84
	v_mad_i64_i32 v[40:41], s[2:3], v102, s76, v[172:173]
	v_lshlrev_b32_e32 v44, 16, v85
	v_and_b32_e32 v45, 0xffff0000, v85
	v_rcp_f32_e32 v28, v28
	v_rcp_f32_e32 v24, v24
	v_rcp_f32_e32 v25, v25
	v_rcp_f32_e32 v26, v26
	v_lshl_add_u64 v[40:41], v[40:41], 0, s[4:5]
	v_and_b32_e32 v49, 0xffff0000, v87
	v_mul_f32_e32 v32, v32, v43
	v_mul_f32_e32 v33, v33, v44
	v_mul_f32_e32 v34, v34, v45
	v_mul_f32_e32 v35, v35, v49
	v_cvt_pk_bf16_f32 v32, v36, v32
	v_cvt_pk_bf16_f32 v33, v33, v34
	v_cvt_pk_bf16_f32 v34, v42, v37
	v_lshl_add_u64 v[36:37], v[40:41], 0, v[140:141]
	v_cvt_pk_bf16_f32 v35, v38, v35
	global_store_dwordx4 v[36:37], v[32:35], off
	v_lshlrev_b32_e32 v36, 16, v82
	v_and_b32_e32 v37, 0xffff0000, v82
	v_lshlrev_b32_e32 v32, 16, v80
	v_lshlrev_b32_e32 v38, 16, v83
; __device__ __forceinline__ float sigmoidf_(float v) { return __builtin_amdgcn_rcpf(1.0f + __expf(-v)); }
; __device__ __forceinline__ u32x4 pack8(const f32x4 a, const f32x4 b) { u32x4 w; w.x = cvt_pk_bf16(a[0], a[1]); w.y = cvt_pk_bf16(a[2], a[3]); w.z = cvt_pk_bf16(b[0], b[1]); w.w = cvt_pk_bf16(b[2], b[3]); return w; }
; __device__ __forceinline__ void unpack8(const u32x4 w, f32x4& a, f32x4& b) { a[0] = bf_lo(w.x); a[1] = bf_hi(w.x); a[2] = bf_lo(w.y); a[3] = bf_hi(w.y); b[0] = bf_lo(w.z); b[1] = bf_hi(w.z); b[2] = bf_lo(w.w); b[3] = bf_hi(w.w); }
; #define MEMFENCE asm volatile("" ::: "memory")
;     template <int KIND> __device__ __forceinline__ void run(f32x4 (&acc)[2][2][4][2], const Unit& u, int tid_in) const {
;     ...
;                 for (int m = 0; m < 4; ++m) { int row = rbase + ai * 128 + m * 16; asm volatile("" : "+v"(row));
; #pragma unroll
;                     for (int bj = 0; bj < 2; ++bj) { const int col = u.pn * 256 + bj * 128 + cl; f32x4 y0, y1; unpack8(yv[m][bj], y0, y1);
; #pragma unroll
;                         for (int j = 0; j < 4; ++j) { y0[j] *= sigmoidf_(acc[ai][bj][m][0][j]); y1[j] *= sigmoidf_(acc[ai][bj][m][1][j]); }
;                         *(u32x4*)(zb + (size_t)row * ZW + 1024 + col) = pack8(y0, y1); } }
;                 MEMFENCE; }
;         }
;     ...
;         cur = nxt; cA = nA; cB = nB; ++ui;
	v_mul_f32_e32 v28, v28, v32
	v_mul_f32_e32 v32, v24, v36
	v_mul_f32_e32 v24, 0xbfb8aa3b, v29
	v_mul_f32_e32 v29, v25, v37
	v_mul_f32_e32 v25, 0xbfb8aa3b, v30
	v_mul_f32_e32 v30, v26, v38
	v_mul_f32_e32 v26, 0xbfb8aa3b, v31
	v_exp_f32_e32 v24, v24
	v_exp_f32_e32 v25, v25
	v_exp_f32_e32 v26, v26
	v_mul_f32_e32 v27, 0xbfb8aa3b, v27
	v_exp_f32_e32 v27, v27
	v_mul_f32_e32 v20, 0xbfb8aa3b, v20
	v_mul_f32_e32 v16, 0xbfb8aa3b, v16
	v_mul_f32_e32 v17, 0xbfb8aa3b, v17
	v_mul_f32_e32 v18, 0xbfb8aa3b, v18
	v_add_f32_e32 v24, 1.0, v24
	v_add_f32_e32 v25, 1.0, v25
	v_add_f32_e32 v26, 1.0, v26
	v_exp_f32_e32 v20, v20
	v_exp_f32_e32 v16, v16
	v_exp_f32_e32 v17, v17
	v_exp_f32_e32 v18, v18
	v_rcp_f32_e32 v24, v24
	v_rcp_f32_e32 v25, v25
	v_rcp_f32_e32 v26, v26
	v_add_f32_e32 v27, 1.0, v27
	v_rcp_f32_e32 v27, v27
	v_and_b32_e32 v33, 0xffff0000, v80
	v_lshlrev_b32_e32 v34, 16, v81
	v_and_b32_e32 v35, 0xffff0000, v81
	v_add_f32_e32 v20, 1.0, v20
	v_add_f32_e32 v16, 1.0, v16
	v_add_f32_e32 v17, 1.0, v17
	v_add_f32_e32 v18, 1.0, v18
	v_and_b32_e32 v39, 0xffff0000, v83
	v_mul_f32_e32 v24, v24, v33
	v_mul_f32_e32 v25, v25, v34
	v_mul_f32_e32 v26, v26, v35
	v_rcp_f32_e32 v20, v20
	v_rcp_f32_e32 v16, v16
	v_rcp_f32_e32 v17, v17
	v_rcp_f32_e32 v18, v18
	v_mul_f32_e32 v27, v27, v39
	v_cvt_pk_bf16_f32 v24, v28, v24
	v_cvt_pk_bf16_f32 v25, v25, v26
	v_cvt_pk_bf16_f32 v26, v32, v29
	v_lshl_add_u64 v[28:29], v[40:41], 0, v[128:129]
	v_cvt_pk_bf16_f32 v27, v30, v27
	global_store_dwordx4 v[28:29], v[24:27], off
	v_lshlrev_b32_e32 v29, 16, v78
	v_and_b32_e32 v30, 0xffff0000, v78
	v_mad_i64_i32 v[24:25], s[2:3], v0, s76, v[172:173]
	v_lshlrev_b32_e32 v0, 16, v76
	v_lshlrev_b32_e32 v31, 16, v79
	v_mul_f32_e32 v0, v20, v0
	v_mul_f32_e32 v20, v16, v29
	v_mul_f32_e32 v16, 0xbfb8aa3b, v21
	v_mul_f32_e32 v21, v17, v30
	v_mul_f32_e32 v17, 0xbfb8aa3b, v22
	v_mul_f32_e32 v22, v18, v31
	v_mul_f32_e32 v18, 0xbfb8aa3b, v23
	v_mul_f32_e32 v19, 0xbfb8aa3b, v19
	v_exp_f32_e32 v16, v16
	v_exp_f32_e32 v17, v17
	v_exp_f32_e32 v18, v18
	v_exp_f32_e32 v19, v19
	v_mul_f32_e32 v12, 0xbfb8aa3b, v12
	v_mul_f32_e32 v8, 0xbfb8aa3b, v8
	v_mul_f32_e32 v9, 0xbfb8aa3b, v9
	v_mul_f32_e32 v10, 0xbfb8aa3b, v10
	v_exp_f32_e32 v12, v12
	v_exp_f32_e32 v8, v8
	v_exp_f32_e32 v9, v9
	v_exp_f32_e32 v10, v10
	v_add_f32_e32 v16, 1.0, v16
	v_add_f32_e32 v17, 1.0, v17
	v_add_f32_e32 v18, 1.0, v18
	v_add_f32_e32 v19, 1.0, v19
	v_rcp_f32_e32 v16, v16
	v_rcp_f32_e32 v17, v17
	v_rcp_f32_e32 v18, v18
	v_rcp_f32_e32 v19, v19
	v_add_f32_e32 v12, 1.0, v12
	v_add_f32_e32 v8, 1.0, v8
	v_add_f32_e32 v9, 1.0, v9
	v_add_f32_e32 v10, 1.0, v10
	v_and_b32_e32 v26, 0xffff0000, v76
	v_lshlrev_b32_e32 v27, 16, v77
	v_and_b32_e32 v28, 0xffff0000, v77
	v_and_b32_e32 v32, 0xffff0000, v79
	v_rcp_f32_e32 v12, v12
	v_rcp_f32_e32 v8, v8
	v_rcp_f32_e32 v9, v9
	v_rcp_f32_e32 v10, v10
	v_lshl_add_u64 v[24:25], v[24:25], 0, s[4:5]
	v_mul_f32_e32 v16, v16, v26
	v_mul_f32_e32 v17, v17, v27
	v_mul_f32_e32 v18, v18, v28
	v_mul_f32_e32 v19, v19, v32
	v_cvt_pk_bf16_f32 v16, v0, v16
	v_cvt_pk_bf16_f32 v17, v17, v18
	v_cvt_pk_bf16_f32 v18, v20, v21
	v_cvt_pk_bf16_f32 v19, v22, v19
	v_lshl_add_u64 v[20:21], v[24:25], 0, v[140:141]
	global_store_dwordx4 v[20:21], v[16:19], off
	v_lshlrev_b32_e32 v0, 16, v72
	v_and_b32_e32 v20, 0xffff0000, v74
	v_lshlrev_b32_e32 v19, 16, v74
	v_lshlrev_b32_e32 v21, 16, v75
	v_mul_f32_e32 v0, v12, v0
	v_mul_f32_e32 v12, v8, v19
	v_mul_f32_e32 v8, 0xbfb8aa3b, v13
	v_mul_f32_e32 v13, v9, v20
	v_mul_f32_e32 v9, 0xbfb8aa3b, v14
	v_mul_f32_e32 v14, v10, v21
	v_mul_f32_e32 v10, 0xbfb8aa3b, v15
	v_exp_f32_e32 v8, v8
	v_exp_f32_e32 v9, v9
	v_exp_f32_e32 v10, v10
	v_mul_f32_e32 v11, 0xbfb8aa3b, v11
	v_exp_f32_e32 v11, v11
	v_add_f32_e32 v8, 1.0, v8
	v_add_f32_e32 v9, 1.0, v9
	v_add_f32_e32 v10, 1.0, v10
	v_rcp_f32_e32 v8, v8
	v_rcp_f32_e32 v9, v9
	v_rcp_f32_e32 v10, v10
	v_add_f32_e32 v11, 1.0, v11
	v_rcp_f32_e32 v11, v11
	v_and_b32_e32 v16, 0xffff0000, v72
	v_lshlrev_b32_e32 v17, 16, v73
	v_and_b32_e32 v18, 0xffff0000, v73
	v_and_b32_e32 v22, 0xffff0000, v75
	v_mul_f32_e32 v8, v8, v16
	v_mul_f32_e32 v9, v9, v17
	v_mul_f32_e32 v10, v10, v18
	v_mul_f32_e32 v11, v11, v22
	v_cvt_pk_bf16_f32 v8, v0, v8
	v_cvt_pk_bf16_f32 v9, v9, v10
	v_cvt_pk_bf16_f32 v10, v12, v13
	v_lshl_add_u64 v[12:13], v[24:25], 0, v[128:129]
	v_cvt_pk_bf16_f32 v11, v14, v11
	global_store_dwordx4 v[12:13], v[8:11], off
	s_and_b64 vcc, exec, s[10:11]
	s_mov_b32 s33, s34
	s_mov_b32 s35, s12
	s_mov_b64 s[18:19], s[16:17]
	s_mov_b64 s[2:3], s[14:15]
	s_cmpk_gt_u32 s101, 0xff
	s_cbranch_scc0 .Ldb_GLU_nob
	s_barrier

; #define G_STAGE(bufoff, gbase, o0, h64) do { \
;         __builtin_amdgcn_global_load_lds((const unsigned*)((const char*)(gbase) + (o0)), (LAS unsigned*)(lds + (bufoff) + ldsw), 16, 0, 0); \
;         __builtin_amdgcn_global_load_lds((const unsigned*)((const char*)(gbase) + (h64) + (o0)), (LAS unsigned*)(lds + (bufoff) + ldsw + 8192), 16, 0, 0); } while (0)
; #define G_LDA(dst, b, h) do { _Pragma("unroll") for (int m = 0; m < 4; ++m) _Pragma("unroll") for (int k = 0; k < 2; ++k) dst[m][k] = *(const LAS bf16x8*)(lds + G_SA(b, h) + aoff + m * 2048 + k * 1024); } while (0)
; #define G_LDB(dst, b, h) do { _Pragma("unroll") for (int n = 0; n < 2; ++n) _Pragma("unroll") for (int k = 0; k < 2; ++k) dst[n][k] = *(const LAS bf16x8*)(lds + G_SB(b, h) + boff + n * 2048 + k * 1024); } while (0)
; #define G_WAIT_V(n) asm volatile("s_waitcnt vmcnt(" #n ")" ::: "memory")
; #define G_WAIT_L(n) asm volatile("s_waitcnt lgkmcnt(" #n ")" ::: "memory")
; #define G_BAR __builtin_amdgcn_s_barrier()
; #define G_SCHED __builtin_amdgcn_sched_barrier(0)
;     ...
;         for (int t = 0; t < nt; t += 2) {
;             const bool last = (t == nt - 2);
;             const char* a1 = cA + (size_t)(t + 1) * ckA;
;             const char* a2 = last ? nA : cA + (size_t)(t + 2) * ckA; const char* b2 = last ? nB : cB + (size_t)(t + 2) * kB;
;             const char* a3 = a2 + ckA; const char* b3 = b2 + kB;
;             G_LDB(B0, 0, 0); G_SCHED; G_LDA(At, 0, 0); G_STAGE(G_SA(1, 1), a1 + chA, cA0, qA);
;             G_WAIT_L(8); G_BAR; G_WAIT_L(0); G_MMA(0, 0, At, B0); G_BAR; G_SCHED;
;             G_LDB(B1, 0, 1); G_STAGE(G_SB(0, 0), b2, cB0, qB);
;             G_BAR; G_WAIT_L(0); G_MMA(0, 1, At, B1); G_BAR;
;             G_LDA(At, 0, 1); G_STAGE(G_SA(0, 0), a2, cA0, qA);
;             G_BAR; G_WAIT_L(0); G_MMA(1, 0, At, B0); G_BAR; G_SCHED;
;             G_STAGE(G_SB(0, 1), b2 + chB, cB0, qB);
;             G_WAIT_V(6); G_BAR; G_MMA(1, 1, At, B1); G_BAR;
;             G_LDB(B0, 1, 0); G_SCHED; G_LDA(At, 1, 0); G_STAGE(G_SA(0, 1), a2 + chA, cA0, qA);
;             G_WAIT_L(8); G_BAR; G_WAIT_L(0); G_MMA(0, 0, At, B0); G_BAR; G_SCHED;
.LBB0_872:
	s_add_u32 s4, s2, 0xfff50080
	s_addc_u32 s5, s3, -1
	s_add_i32 s40, 0, 0x10000
	v_add_u32_e32 v140, s40, v159
	ds_read_b128 v[144:147], v140
	ds_read_b128 v[148:151], v140 offset:1024
	ds_read_b128 v[136:139], v140 offset:2048
	ds_read_b128 v[140:143], v140 offset:3072
	s_cmp_eq_u32 s39, 4
	s_cselect_b32 s13, s9, s5
	s_cselect_b32 s12, s8, s4
	s_cselect_b32 s15, s11, s38
	s_cselect_b32 s14, s10, s37
	v_lshl_add_u64 v[154:155], s[2:3], 0, v[152:153]
	s_add_i32 m0, s22, 0xc000
	ds_read_b128 v[160:163], v236
	ds_read_b128 v[164:167], v236 offset:1024
	ds_read_b128 v[176:179], v236 offset:2048
	ds_read_b128 v[180:183], v236 offset:3072
	ds_read_b128 v[196:199], v236 offset:4096
	ds_read_b128 v[200:203], v236 offset:5120
	ds_read_b128 v[204:207], v236 offset:6144
	ds_read_b128 v[208:211], v236 offset:7168
	global_load_lds_dwordx4 v[154:155], off
	v_lshl_add_u64 v[154:155], v[154:155], 0, s[86:87]
	s_add_i32 m0, s22, 0xe000
	s_nop 0
	global_load_lds_dwordx4 v[154:155], off
	s_waitcnt lgkmcnt(8)
	s_barrier
	s_waitcnt lgkmcnt(0)
	s_setprio 3
	s_waitcnt lgkmcnt(0)
	v_mfma_f32_16x16x128_f8f6f4 v[128:131], v[144:151], v[160:167], v[128:131]
	v_mfma_f32_16x16x128_f8f6f4 v[132:135], v[136:143], v[160:167], v[132:135]
	v_mfma_f32_16x16x128_f8f6f4 v[112:115], v[144:151], v[176:183], v[112:115]
	v_mfma_f32_16x16x128_f8f6f4 v[116:119], v[136:143], v[176:183], v[116:119]
	v_mfma_f32_16x16x128_f8f6f4 v[96:99], v[144:151], v[196:203], v[96:99]
	v_mfma_f32_16x16x128_f8f6f4 v[100:103], v[136:143], v[196:203], v[100:103]
	v_mfma_f32_16x16x128_f8f6f4 v[80:83], v[144:151], v[204:211], v[80:83]
	v_mfma_f32_16x16x128_f8f6f4 v[84:87], v[136:143], v[204:211], v[84:87]
	s_setprio 0
	s_barrier
	s_add_i32 s4, 0, 0x14000
	v_add_u32_e32 v154, s4, v159
	s_add_i32 s5, s40, s17
	ds_read_b128 v[212:215], v154
	ds_read_b128 v[216:219], v154 offset:1024
	ds_read_b128 v[220:223], v154 offset:2048
	ds_read_b128 v[224:227], v154 offset:3072
	v_lshl_add_u64 v[154:155], s[14:15], 0, v[0:1]
	s_mov_b32 m0, s5
	v_lshl_add_u64 v[156:157], v[154:155], 0, s[50:51]
	global_load_lds_dwordx4 v[154:155], off
	s_add_i32 m0, s5, 0x2000
	s_nop 0
	global_load_lds_dwordx4 v[156:157], off
	s_barrier
	s_waitcnt lgkmcnt(0)
	s_setprio 3
	s_waitcnt lgkmcnt(0)
	v_mfma_f32_16x16x128_f8f6f4 v[124:127], v[212:219], v[160:167], v[124:127]
	v_mfma_f32_16x16x128_f8f6f4 v[120:123], v[220:227], v[160:167], v[120:123]
	v_mfma_f32_16x16x128_f8f6f4 v[108:111], v[212:219], v[176:183], v[108:111]
	v_mfma_f32_16x16x128_f8f6f4 v[104:107], v[220:227], v[176:183], v[104:107]
	v_mfma_f32_16x16x128_f8f6f4 v[92:95], v[212:219], v[196:203], v[92:95]
	v_mfma_f32_16x16x128_f8f6f4 v[88:91], v[220:227], v[196:203], v[88:91]
	v_mfma_f32_16x16x128_f8f6f4 v[76:79], v[212:219], v[204:211], v[76:79]
	v_mfma_f32_16x16x128_f8f6f4 v[72:75], v[220:227], v[204:211], v[72:75]
	s_setprio 0
	s_mov_b32 m0, s22
	v_lshl_add_u64 v[156:157], s[12:13], 0, v[2:3]
	s_barrier
	ds_read_b128 v[160:163], v236 offset:16384
	ds_read_b128 v[164:167], v236 offset:17408
	ds_read_b128 v[176:179], v236 offset:18432
	ds_read_b128 v[180:183], v236 offset:19456
	ds_read_b128 v[196:199], v236 offset:20480
	ds_read_b128 v[200:203], v236 offset:21504
	ds_read_b128 v[204:207], v236 offset:22528
	ds_read_b128 v[208:211], v236 offset:23552
	global_load_lds_dwordx4 v[156:157], off
	v_lshl_add_u64 v[234:235], v[156:157], 0, s[86:87]
	s_mov_b32 m0, s23
	s_nop 0
	global_load_lds_dwordx4 v[234:235], off
	s_barrier
	s_waitcnt lgkmcnt(0)
	s_setprio 3
	s_waitcnt lgkmcnt(0)
	v_mfma_f32_16x16x128_f8f6f4 v[64:67], v[144:151], v[160:167], v[64:67]
	v_mfma_f32_16x16x128_f8f6f4 v[68:71], v[136:143], v[160:167], v[68:71]
	v_mfma_f32_16x16x128_f8f6f4 v[48:51], v[144:151], v[176:183], v[48:51]
	v_mfma_f32_16x16x128_f8f6f4 v[52:55], v[136:143], v[176:183], v[52:55]
	v_mfma_f32_16x16x128_f8f6f4 v[32:35], v[144:151], v[196:203], v[32:35]
	v_mfma_f32_16x16x128_f8f6f4 v[36:39], v[136:143], v[196:203], v[36:39]
	v_mfma_f32_16x16x128_f8f6f4 v[20:23], v[144:151], v[204:211], v[20:23]
	v_mfma_f32_16x16x128_f8f6f4 v[16:19], v[136:143], v[204:211], v[16:19]
	s_setprio 0
	s_barrier
	s_add_i32 s4, s4, s17
	v_lshl_add_u64 v[140:141], v[154:155], 0, s[0:1]
	s_mov_b32 m0, s4
	s_nop 0
	global_load_lds_dwordx4 v[140:141], off
	v_lshl_add_u64 v[140:141], v[154:155], 0, s[52:53]
	s_add_i32 m0, s4, 0x2000
	s_nop 0
	global_load_lds_dwordx4 v[140:141], off
	s_waitcnt vmcnt(6)
	s_barrier
	s_setprio 3
	v_mfma_f32_16x16x128_f8f6f4 v[60:63], v[212:219], v[160:167], v[60:63]
	v_mfma_f32_16x16x128_f8f6f4 v[56:59], v[220:227], v[160:167], v[56:59]
	v_mfma_f32_16x16x128_f8f6f4 v[44:47], v[212:219], v[176:183], v[44:47]
	v_mfma_f32_16x16x128_f8f6f4 v[40:43], v[220:227], v[176:183], v[40:43]
	v_mfma_f32_16x16x128_f8f6f4 v[28:31], v[212:219], v[196:203], v[28:31]
	v_mfma_f32_16x16x128_f8f6f4 v[24:27], v[220:227], v[196:203], v[24:27]
	v_mfma_f32_16x16x128_f8f6f4 v[12:15], v[212:219], v[204:211], v[12:15]
	v_mfma_f32_16x16x128_f8f6f4 v[8:11], v[220:227], v[204:211], v[8:11]
	s_setprio 0
	s_add_i32 s4, 0, 0x18000
	v_add_u32_e32 v140, s4, v159
	s_barrier
; #define G_STAGE(bufoff, gbase, o0, h64) do { \
;         __builtin_amdgcn_global_load_lds((const unsigned*)((const char*)(gbase) + (o0)), (LAS unsigned*)(lds + (bufoff) + ldsw), 16, 0, 0); \
;         __builtin_amdgcn_global_load_lds((const unsigned*)((const char*)(gbase) + (h64) + (o0)), (LAS unsigned*)(lds + (bufoff) + ldsw + 8192), 16, 0, 0); } while (0)
; #define G_LDA(dst, b, h) do { _Pragma("unroll") for (int m = 0; m < 4; ++m) _Pragma("unroll") for (int k = 0; k < 2; ++k) dst[m][k] = *(const LAS bf16x8*)(lds + G_SA(b, h) + aoff + m * 2048 + k * 1024); } while (0)
; #define G_LDB(dst, b, h) do { _Pragma("unroll") for (int n = 0; n < 2; ++n) _Pragma("unroll") for (int k = 0; k < 2; ++k) dst[n][k] = *(const LAS bf16x8*)(lds + G_SB(b, h) + boff + n * 2048 + k * 1024); } while (0)
; #define G_WAIT_V(n) asm volatile("s_waitcnt vmcnt(" #n ")" ::: "memory")
; #define G_WAIT_L(n) asm volatile("s_waitcnt lgkmcnt(" #n ")" ::: "memory")
; #define G_BAR __builtin_amdgcn_s_barrier()
; #define G_SCHED __builtin_amdgcn_sched_barrier(0)
;     ...
;             G_LDB(B0, 1, 0); G_SCHED; G_LDA(At, 1, 0); G_STAGE(G_SA(0, 1), a2 + chA, cA0, qA);
;             G_WAIT_L(8); G_BAR; G_WAIT_L(0); G_MMA(0, 0, At, B0); G_BAR; G_SCHED;
;             G_LDB(B1, 1, 1); G_STAGE(G_SB(1, 0), b3, cB0, qB);
;             G_BAR; G_WAIT_L(0); G_MMA(0, 1, At, B1); G_BAR;
;             G_LDA(At, 1, 1); G_STAGE(G_SA(1, 0), a3, cA0, qA);
;             G_BAR; G_WAIT_L(0); G_MMA(1, 0, At, B0); G_BAR; G_SCHED;
;             G_STAGE(G_SB(1, 1), b3 + chB, cB0, qB);
;             G_WAIT_V(6); G_BAR; G_MMA(1, 1, At, B1); G_BAR;
;         }
	ds_read_b128 v[144:147], v140
	ds_read_b128 v[148:151], v140 offset:1024
	ds_read_b128 v[136:139], v140 offset:2048
	ds_read_b128 v[140:143], v140 offset:3072
	s_mov_b32 m0, s24
	v_lshl_add_u64 v[234:235], v[156:157], 0, s[88:89]
	ds_read_b128 v[160:163], v236 offset:32768
	ds_read_b128 v[164:167], v236 offset:33792
	ds_read_b128 v[176:179], v236 offset:34816
	ds_read_b128 v[180:183], v236 offset:35840
	ds_read_b128 v[196:199], v236 offset:36864
	ds_read_b128 v[200:203], v236 offset:37888
	ds_read_b128 v[204:207], v236 offset:38912
	ds_read_b128 v[208:211], v236 offset:39936
	global_load_lds_dwordx4 v[234:235], off
	v_lshl_add_u64 v[234:235], v[156:157], 0, s[64:65]
	s_mov_b32 m0, s25
	s_nop 0
	global_load_lds_dwordx4 v[234:235], off
	s_waitcnt lgkmcnt(8)
	s_barrier
	s_waitcnt lgkmcnt(0)
	s_setprio 3
	s_waitcnt lgkmcnt(0)
	v_mfma_f32_16x16x128_f8f6f4 v[128:131], v[144:151], v[160:167], v[128:131]
	v_mfma_f32_16x16x128_f8f6f4 v[132:135], v[136:143], v[160:167], v[132:135]
	v_mfma_f32_16x16x128_f8f6f4 v[112:115], v[144:151], v[176:183], v[112:115]
	v_mfma_f32_16x16x128_f8f6f4 v[116:119], v[136:143], v[176:183], v[116:119]
	v_mfma_f32_16x16x128_f8f6f4 v[96:99], v[144:151], v[196:203], v[96:99]
	v_mfma_f32_16x16x128_f8f6f4 v[100:103], v[136:143], v[196:203], v[100:103]
	v_mfma_f32_16x16x128_f8f6f4 v[80:83], v[144:151], v[204:211], v[80:83]
	v_mfma_f32_16x16x128_f8f6f4 v[84:87], v[136:143], v[204:211], v[84:87]
	s_setprio 0
	s_barrier
	s_add_i32 s5, 0, 0x1c000
	s_add_i32 s4, s4, s17
	v_add_u32_e32 v237, s5, v159
	v_lshl_add_u64 v[234:235], v[154:155], 0, s[46:47]
	s_mov_b32 m0, s4
	ds_read_b128 v[212:215], v237
	ds_read_b128 v[216:219], v237 offset:1024
	ds_read_b128 v[220:223], v237 offset:2048
	ds_read_b128 v[224:227], v237 offset:3072
	global_load_lds_dwordx4 v[234:235], off
	v_lshl_add_u64 v[234:235], v[154:155], 0, s[54:55]
	s_add_i32 m0, s4, 0x2000
	s_nop 0
	global_load_lds_dwordx4 v[234:235], off
	s_barrier
	s_waitcnt lgkmcnt(0)
	s_setprio 3
	s_waitcnt lgkmcnt(0)
	v_mfma_f32_16x16x128_f8f6f4 v[124:127], v[212:219], v[160:167], v[124:127]
	v_mfma_f32_16x16x128_f8f6f4 v[120:123], v[220:227], v[160:167], v[120:123]
	v_mfma_f32_16x16x128_f8f6f4 v[108:111], v[212:219], v[176:183], v[108:111]
	v_mfma_f32_16x16x128_f8f6f4 v[104:107], v[220:227], v[176:183], v[104:107]
	v_mfma_f32_16x16x128_f8f6f4 v[92:95], v[212:219], v[196:203], v[92:95]
	v_mfma_f32_16x16x128_f8f6f4 v[88:91], v[220:227], v[196:203], v[88:91]
	v_mfma_f32_16x16x128_f8f6f4 v[76:79], v[212:219], v[204:211], v[76:79]
	v_mfma_f32_16x16x128_f8f6f4 v[72:75], v[220:227], v[204:211], v[72:75]
	s_setprio 0
	s_mov_b32 m0, s26
	v_lshl_add_u64 v[234:235], v[156:157], 0, s[46:47]
	s_barrier
	ds_read_b128 v[160:163], v236 offset:49152
	ds_read_b128 v[164:167], v236 offset:50176
	ds_read_b128 v[176:179], v236 offset:51200
	ds_read_b128 v[180:183], v236 offset:52224
	ds_read_b128 v[196:199], v236 offset:53248
	ds_read_b128 v[200:203], v236 offset:54272
	ds_read_b128 v[204:207], v236 offset:55296
	ds_read_b128 v[208:211], v236 offset:56320
	global_load_lds_dwordx4 v[234:235], off
	v_lshl_add_u64 v[156:157], v[156:157], 0, s[66:67]
	s_mov_b32 m0, s27
	s_nop 0
	global_load_lds_dwordx4 v[156:157], off
	s_barrier
	s_waitcnt lgkmcnt(0)
	s_setprio 3
	s_waitcnt lgkmcnt(0)
	v_mfma_f32_16x16x128_f8f6f4 v[64:67], v[144:151], v[160:167], v[64:67]
	v_mfma_f32_16x16x128_f8f6f4 v[68:71], v[136:143], v[160:167], v[68:71]
	v_mfma_f32_16x16x128_f8f6f4 v[48:51], v[144:151], v[176:183], v[48:51]
	v_mfma_f32_16x16x128_f8f6f4 v[52:55], v[136:143], v[176:183], v[52:55]
	v_mfma_f32_16x16x128_f8f6f4 v[32:35], v[144:151], v[196:203], v[32:35]
	v_mfma_f32_16x16x128_f8f6f4 v[36:39], v[136:143], v[196:203], v[36:39]
	v_mfma_f32_16x16x128_f8f6f4 v[20:23], v[144:151], v[204:211], v[20:23]
	v_mfma_f32_16x16x128_f8f6f4 v[16:19], v[136:143], v[204:211], v[16:19]
	s_setprio 0
	s_barrier
	s_add_i32 s4, s5, s17
	v_lshl_add_u64 v[140:141], v[154:155], 0, s[42:43]
	s_mov_b32 m0, s4
	s_nop 0
	global_load_lds_dwordx4 v[140:141], off
	v_lshl_add_u64 v[140:141], v[154:155], 0, s[58:59]
	s_add_i32 m0, s4, 0x2000
	s_nop 0
	global_load_lds_dwordx4 v[140:141], off
	s_waitcnt vmcnt(6)
	s_barrier
	s_setprio 3
	v_mfma_f32_16x16x128_f8f6f4 v[60:63], v[212:219], v[160:167], v[60:63]
	v_mfma_f32_16x16x128_f8f6f4 v[56:59], v[220:227], v[160:167], v[56:59]
	v_mfma_f32_16x16x128_f8f6f4 v[44:47], v[212:219], v[176:183], v[44:47]
	v_mfma_f32_16x16x128_f8f6f4 v[40:43], v[220:227], v[176:183], v[40:43]
	v_mfma_f32_16x16x128_f8f6f4 v[28:31], v[212:219], v[196:203], v[28:31]
	v_mfma_f32_16x16x128_f8f6f4 v[24:27], v[220:227], v[196:203], v[24:27]
	v_mfma_f32_16x16x128_f8f6f4 v[12:15], v[212:219], v[204:211], v[12:15]
	v_mfma_f32_16x16x128_f8f6f4 v[8:11], v[220:227], v[204:211], v[8:11]
	s_setprio 0
	s_add_i32 s39, s39, 2
	s_add_u32 s2, s2, 0x100
	s_addc_u32 s3, s3, 0
	s_add_u32 s37, s37, 0x100
	s_addc_u32 s38, s38, 0
	s_cmp_gt_u32 s39, 5
	s_cbranch_scc0 .Ldb_MG0_cont
	v_readfirstlane_b32 s101, v186
	s_cmpk_gt_u32 s101, 0xff
	s_cbranch_scc1 .Ldb_MG0_exit
	s_barrier
	s_branch .Ldb_MG0_exit

; __device__ __forceinline__ float sigmoidf_(float v) { return __builtin_amdgcn_rcpf(1.0f + __expf(-v)); }
; #define MEMFENCE asm volatile("" ::: "memory")
;     __device__ __forceinline__ void get_rs(const Unit& u, int wr, int fr, float (&rs)[8]) const {
; #pragma unroll
;         for (int r8 = 0; r8 < 8; ++r8) rs[r8] = rstab[u.ord * 256 + (r8 >> 2) * 128 + wr * 64 + (r8 & 3) * 16 + fr];
;     }
;     template <int KIND> __device__ __forceinline__ void run(f32x4 (&acc)[2][2][4][2], const Unit& u, int tid_in) const {
;     ...
;         if constexpr (KIND == K_MG_G) { float rs[8]; get_rs(u, wr, fr, rs);
;             u32x4* gst = (u32x4*)((unsigned char*)x + 32 * MiB) + ((size_t)(blockIdx.x * 2 + (u.ord & 1)) * 3 + u.aux) * 4096;
; #pragma unroll
;             for (int ai = 0; ai < 2; ++ai)
; #pragma unroll
;                 for (int m = 0; m < 4; ++m) { const float r = rs[ai * 4 + m] * (1.0f / GATE_WSCALE); u32x4 w;
; #pragma unroll
;                     for (int bj = 0; bj < 2; ++bj) { f32x4 a = acc[ai][bj][m][0] * r, b = acc[ai][bj][m][1] * r;
; #pragma unroll
;                         for (int j = 0; j < 4; ++j) { a[j] = sigmoidf_(a[j]); b[j] = sigmoidf_(b[j]); }
;                         if (bj == 0) { w.x = pack4_u8c(a); w.y = pack4_u8c(b); } else { w.z = pack4_u8c(a); w.w = pack4_u8c(b); } }
;                     gst[(ai * 4 + m) * 512 + tid] = w; MEMFENCE; }
.Ldb_MG0_exit:
	v_mov_b32_e32 v142, v158
	s_lshl_b32 s3, s33, 10
	v_readfirstlane_b32 s2, v142
	s_add_i32 s3, s3, 0
	s_and_b32 s2, s2, 0xffffff00
	v_and_b32_e32 v136, 15, v142
	s_add_i32 s3, s3, s2
	v_lshl_add_u32 v136, v136, 2, s3
	v_add_u32_e32 v136, 0x20010, v136
	ds_read2_b32 v[144:145], v136 offset1:16
	ds_read2_b32 v[140:141], v136 offset0:32 offset1:48
	ds_read2_b32 v[138:139], v136 offset0:128 offset1:144
	ds_read2_b32 v[136:137], v136 offset0:160 offset1:176
	s_and_b32 s2, s33, 1
	s_waitcnt lgkmcnt(0)
	v_mul_f32_e32 v144, 0x3c800000, v144
	v_pk_mul_f32 v[128:129], v[128:129], v[144:145] op_sel_hi:[1,0]
	v_pk_mul_f32 v[130:131], v[130:131], v[144:145] op_sel_hi:[1,0]
	v_mul_f32_e32 v128, 0xbfb8aa3b, v128
	v_mul_f32_e32 v129, 0xbfb8aa3b, v129
	v_mul_f32_e32 v131, 0xbfb8aa3b, v131
	v_exp_f32_e32 v128, v128
	v_exp_f32_e32 v129, v129
	v_mul_f32_e32 v130, 0xbfb8aa3b, v130
	v_exp_f32_e32 v131, v131
	v_exp_f32_e32 v130, v130
	v_add_f32_e32 v128, 1.0, v128
	v_add_f32_e32 v129, 1.0, v129
	s_or_b32 s2, s2, s60
	v_pk_mul_f32 v[132:133], v[132:133], v[144:145] op_sel_hi:[1,0]
	v_add_f32_e32 v131, 1.0, v131
	v_rcp_f32_e32 v128, v128
	v_rcp_f32_e32 v129, v129
	v_add_f32_e32 v130, 1.0, v130
	s_mul_hi_u32 s3, s2, 3
	s_mul_i32 s2, s2, 3
	s_ashr_i32 s4, s36, 31
	v_pk_mul_f32 v[134:135], v[134:135], v[144:145] op_sel_hi:[1,0]
	v_mul_f32_e32 v132, 0xbfb8aa3b, v132
	v_mul_f32_e32 v133, 0xbfb8aa3b, v133
	v_rcp_f32_e32 v131, v131
	v_rcp_f32_e32 v130, v130
	s_add_u32 s2, s2, s36
	v_mul_f32_e32 v135, 0xbfb8aa3b, v135
	v_exp_f32_e32 v132, v132
	v_exp_f32_e32 v133, v133
	v_mul_f32_e32 v134, 0xbfb8aa3b, v134
	s_addc_u32 s3, s3, s4
	v_exp_f32_e32 v135, v135
	v_exp_f32_e32 v134, v134
	s_mov_b32 s4, 0x437f0000
	v_fma_f32 v128, v128, s4, 0.5
	v_fma_f32 v129, v129, s4, 0.5
	v_max_f32_e32 v128, 1.0, v128
	v_max_f32_e32 v129, 1.0, v129
	v_fma_f32 v130, v130, s4, 0.5
	v_fma_f32 v131, v131, s4, 0.5
	v_add_f32_e32 v132, 1.0, v132
	v_add_f32_e32 v133, 1.0, v133
	v_cvt_u32_f32_e32 v128, v128
	v_cvt_u32_f32_e32 v129, v129
	v_max_f32_e32 v130, 1.0, v130
	v_max_f32_e32 v131, 1.0, v131
	v_add_f32_e32 v135, 1.0, v135
	v_rcp_f32_e32 v132, v132
	v_rcp_f32_e32 v133, v133
	v_cvt_u32_f32_sdwa v130, v130 dst_sel:WORD_1 dst_unused:UNUSED_PAD src0_sel:DWORD
	v_cvt_u32_f32_sdwa v131, v131 dst_sel:BYTE_3 dst_unused:UNUSED_PAD src0_sel:DWORD
	v_add_f32_e32 v134, 1.0, v134
	v_rcp_f32_e32 v135, v135
	v_rcp_f32_e32 v134, v134
	v_lshl_or_b32 v128, v129, 8, v128
	v_or3_b32 v128, v128, v130, v131
	v_fma_f32 v129, v132, s4, 0.5
	v_fma_f32 v130, v133, s4, 0.5
	v_pk_mul_f32 v[124:125], v[124:125], v[144:145] op_sel_hi:[1,0]
	v_max_f32_e32 v129, 1.0, v129
	v_max_f32_e32 v130, 1.0, v130
	v_fma_f32 v131, v134, s4, 0.5
	v_fma_f32 v132, v135, s4, 0.5
	v_mul_f32_e32 v125, 0xbfb8aa3b, v125
	v_cvt_u32_f32_e32 v129, v129
	v_cvt_u32_f32_e32 v130, v130
	v_max_f32_e32 v131, 1.0, v131
	v_max_f32_e32 v132, 1.0, v132
	v_exp_f32_e32 v125, v125
	v_cvt_u32_f32_sdwa v131, v131 dst_sel:WORD_1 dst_unused:UNUSED_PAD src0_sel:DWORD
	v_cvt_u32_f32_sdwa v132, v132 dst_sel:BYTE_3 dst_unused:UNUSED_PAD src0_sel:DWORD
	v_pk_mul_f32 v[120:121], v[120:121], v[144:145] op_sel_hi:[1,0]
	v_mul_f32_e32 v124, 0xbfb8aa3b, v124
	v_mul_f32_e32 v121, 0xbfb8aa3b, v121
	v_lshl_or_b32 v129, v130, 8, v129
	v_exp_f32_e32 v130, v124
	v_add_f32_e32 v124, 1.0, v125
	v_exp_f32_e32 v121, v121
	v_or3_b32 v129, v129, v131, v132
	v_rcp_f32_e32 v131, v124
	v_mul_f32_e32 v120, 0xbfb8aa3b, v120
	v_pk_mul_f32 v[124:125], v[126:127], v[144:145] op_sel_hi:[1,0]
	v_add_f32_e32 v126, 1.0, v130
	v_exp_f32_e32 v130, v120
	v_add_f32_e32 v120, 1.0, v121
	v_fma_f32 v127, v131, s4, 0.5
	v_rcp_f32_e32 v131, v120
	v_pk_mul_f32 v[120:121], v[122:123], v[144:145] op_sel_hi:[1,0]
	v_add_f32_e32 v122, 1.0, v130
	v_mul_f32_e32 v120, 0xbfb8aa3b, v120
	v_mul_f32_e32 v121, 0xbfb8aa3b, v121
	v_exp_f32_e32 v120, v120
	v_exp_f32_e32 v121, v121
	v_rcp_f32_e32 v122, v122
	v_fma_f32 v123, v131, s4, 0.5
	v_add_f32_e32 v120, 1.0, v120
	v_add_f32_e32 v121, 1.0, v121
	v_rcp_f32_e32 v120, v120
	v_rcp_f32_e32 v121, v121
	v_fma_f32 v122, v122, s4, 0.5
	v_max_f32_e32 v123, 1.0, v123
	v_max_f32_e32 v122, 1.0, v122
	v_fma_f32 v120, v120, s4, 0.5
	v_fma_f32 v121, v121, s4, 0.5
	v_cvt_u32_f32_e32 v123, v123
	v_cvt_u32_f32_e32 v122, v122
	v_max_f32_e32 v120, 1.0, v120
	v_max_f32_e32 v121, 1.0, v121
	v_cvt_u32_f32_sdwa v120, v120 dst_sel:WORD_1 dst_unused:UNUSED_PAD src0_sel:DWORD
	v_cvt_u32_f32_sdwa v121, v121 dst_sel:BYTE_3 dst_unused:UNUSED_PAD src0_sel:DWORD
	v_lshl_or_b32 v122, v123, 8, v122
	v_mul_f32_e32 v124, 0xbfb8aa3b, v124
	v_mul_f32_e32 v125, 0xbfb8aa3b, v125
	v_or3_b32 v131, v122, v120, v121
	v_mul_f32_e32 v122, 0x3c800000, v145
	v_pk_mul_f32 v[112:113], v[112:113], v[122:123] op_sel_hi:[1,0]
	v_pk_mul_f32 v[114:115], v[114:115], v[122:123] op_sel_hi:[1,0]
	v_mul_f32_e32 v112, 0xbfb8aa3b, v112
	v_mul_f32_e32 v113, 0xbfb8aa3b, v113
	v_mul_f32_e32 v115, 0xbfb8aa3b, v115
	v_exp_f32_e32 v112, v112
	v_exp_f32_e32 v113, v113
	v_mul_f32_e32 v114, 0xbfb8aa3b, v114
	v_exp_f32_e32 v115, v115
	v_exp_f32_e32 v114, v114
	v_add_f32_e32 v112, 1.0, v112
	v_add_f32_e32 v113, 1.0, v113
	v_pk_mul_f32 v[116:117], v[116:117], v[122:123] op_sel_hi:[1,0]
	v_add_f32_e32 v115, 1.0, v115
	v_rcp_f32_e32 v112, v112
	v_rcp_f32_e32 v113, v113
	v_add_f32_e32 v114, 1.0, v114
	v_pk_mul_f32 v[118:119], v[118:119], v[122:123] op_sel_hi:[1,0]
	v_mul_f32_e32 v116, 0xbfb8aa3b, v116
	v_mul_f32_e32 v117, 0xbfb8aa3b, v117
	v_rcp_f32_e32 v115, v115
	v_rcp_f32_e32 v114, v114
	v_mul_f32_e32 v119, 0xbfb8aa3b, v119
	v_exp_f32_e32 v116, v116
	v_exp_f32_e32 v117, v117
	v_mul_f32_e32 v118, 0xbfb8aa3b, v118
; __device__ __forceinline__ float sigmoidf_(float v) { return __builtin_amdgcn_rcpf(1.0f + __expf(-v)); }
; #define MEMFENCE asm volatile("" ::: "memory")
;     template <int KIND> __device__ __forceinline__ void run(f32x4 (&acc)[2][2][4][2], const Unit& u, int tid_in) const {
;     ...
;                 for (int m = 0; m < 4; ++m) { const float r = rs[ai * 4 + m] * (1.0f / GATE_WSCALE); u32x4 w;
; #pragma unroll
;                     for (int bj = 0; bj < 2; ++bj) { f32x4 a = acc[ai][bj][m][0] * r, b = acc[ai][bj][m][1] * r;
; #pragma unroll
;                         for (int j = 0; j < 4; ++j) { a[j] = sigmoidf_(a[j]); b[j] = sigmoidf_(b[j]); }
;                         if (bj == 0) { w.x = pack4_u8c(a); w.y = pack4_u8c(b); } else { w.z = pack4_u8c(a); w.w = pack4_u8c(b); } }
;                     gst[(ai * 4 + m) * 512 + tid] = w; MEMFENCE; }
	v_exp_f32_e32 v119, v119
	v_exp_f32_e32 v118, v118
	v_fma_f32 v112, v112, s4, 0.5
	v_fma_f32 v113, v113, s4, 0.5
	v_max_f32_e32 v112, 1.0, v112
	v_max_f32_e32 v113, 1.0, v113
	v_fma_f32 v114, v114, s4, 0.5
	v_fma_f32 v115, v115, s4, 0.5
	v_add_f32_e32 v116, 1.0, v116
	v_add_f32_e32 v117, 1.0, v117
	v_cvt_u32_f32_e32 v112, v112
	v_cvt_u32_f32_e32 v113, v113
	v_max_f32_e32 v114, 1.0, v114
	v_max_f32_e32 v115, 1.0, v115
	v_add_f32_e32 v119, 1.0, v119
	v_rcp_f32_e32 v116, v116
	v_rcp_f32_e32 v117, v117
	v_cvt_u32_f32_sdwa v114, v114 dst_sel:WORD_1 dst_unused:UNUSED_PAD src0_sel:DWORD
	v_cvt_u32_f32_sdwa v115, v115 dst_sel:BYTE_3 dst_unused:UNUSED_PAD src0_sel:DWORD
	v_add_f32_e32 v118, 1.0, v118
	v_rcp_f32_e32 v119, v119
	v_rcp_f32_e32 v118, v118
	v_lshl_or_b32 v112, v113, 8, v112
	v_or3_b32 v112, v112, v114, v115
	v_fma_f32 v113, v116, s4, 0.5
	v_fma_f32 v114, v117, s4, 0.5
	v_pk_mul_f32 v[108:109], v[108:109], v[122:123] op_sel_hi:[1,0]
	v_max_f32_e32 v113, 1.0, v113
	v_max_f32_e32 v114, 1.0, v114
	v_fma_f32 v115, v118, s4, 0.5
	v_fma_f32 v116, v119, s4, 0.5
	v_mul_f32_e32 v109, 0xbfb8aa3b, v109
	v_cvt_u32_f32_e32 v113, v113
	v_cvt_u32_f32_e32 v114, v114
	v_max_f32_e32 v115, 1.0, v115
	v_max_f32_e32 v116, 1.0, v116
	v_exp_f32_e32 v109, v109
	v_cvt_u32_f32_sdwa v115, v115 dst_sel:WORD_1 dst_unused:UNUSED_PAD src0_sel:DWORD
	v_cvt_u32_f32_sdwa v116, v116 dst_sel:BYTE_3 dst_unused:UNUSED_PAD src0_sel:DWORD
	v_pk_mul_f32 v[104:105], v[104:105], v[122:123] op_sel_hi:[1,0]
	v_mul_f32_e32 v108, 0xbfb8aa3b, v108
	v_mul_f32_e32 v105, 0xbfb8aa3b, v105
	v_lshl_or_b32 v113, v114, 8, v113
	v_exp_f32_e32 v114, v108
	v_add_f32_e32 v108, 1.0, v109
	v_exp_f32_e32 v105, v105
	v_or3_b32 v113, v113, v115, v116
	v_rcp_f32_e32 v115, v108
	v_mul_f32_e32 v104, 0xbfb8aa3b, v104
	v_pk_mul_f32 v[108:109], v[110:111], v[122:123] op_sel_hi:[1,0]
	v_add_f32_e32 v110, 1.0, v114
	v_exp_f32_e32 v114, v104
	v_add_f32_e32 v104, 1.0, v105
	v_fma_f32 v111, v115, s4, 0.5
	v_rcp_f32_e32 v115, v104
	v_pk_mul_f32 v[104:105], v[106:107], v[122:123] op_sel_hi:[1,0]
	v_add_f32_e32 v106, 1.0, v114
	v_mul_f32_e32 v104, 0xbfb8aa3b, v104
	v_mul_f32_e32 v105, 0xbfb8aa3b, v105
	v_exp_f32_e32 v104, v104
	v_exp_f32_e32 v105, v105
	v_rcp_f32_e32 v106, v106
	v_fma_f32 v107, v115, s4, 0.5
	v_add_f32_e32 v104, 1.0, v104
	v_add_f32_e32 v105, 1.0, v105
	v_rcp_f32_e32 v104, v104
	v_rcp_f32_e32 v105, v105
	v_fma_f32 v106, v106, s4, 0.5
	v_max_f32_e32 v107, 1.0, v107
	v_max_f32_e32 v106, 1.0, v106
	v_fma_f32 v104, v104, s4, 0.5
	v_fma_f32 v105, v105, s4, 0.5
	v_cvt_u32_f32_e32 v107, v107
	v_cvt_u32_f32_e32 v106, v106
	v_max_f32_e32 v104, 1.0, v104
	v_max_f32_e32 v105, 1.0, v105
	v_cvt_u32_f32_sdwa v104, v104 dst_sel:WORD_1 dst_unused:UNUSED_PAD src0_sel:DWORD
	v_cvt_u32_f32_sdwa v105, v105 dst_sel:BYTE_3 dst_unused:UNUSED_PAD src0_sel:DWORD
	v_lshl_or_b32 v106, v107, 8, v106
	v_exp_f32_e32 v124, v124
	v_exp_f32_e32 v125, v125
	v_or3_b32 v115, v106, v104, v105
	v_mul_f32_e32 v106, 0x3c800000, v140
	v_pk_mul_f32 v[96:97], v[96:97], v[106:107] op_sel_hi:[1,0]
	v_pk_mul_f32 v[98:99], v[98:99], v[106:107] op_sel_hi:[1,0]
	v_mul_f32_e32 v96, 0xbfb8aa3b, v96
	v_mul_f32_e32 v97, 0xbfb8aa3b, v97
	v_mul_f32_e32 v99, 0xbfb8aa3b, v99
	v_exp_f32_e32 v96, v96
	v_exp_f32_e32 v97, v97
	v_mul_f32_e32 v98, 0xbfb8aa3b, v98
	v_exp_f32_e32 v99, v99
	v_exp_f32_e32 v98, v98
	v_add_f32_e32 v96, 1.0, v96
	v_add_f32_e32 v97, 1.0, v97
	v_pk_mul_f32 v[100:101], v[100:101], v[106:107] op_sel_hi:[1,0]
	v_add_f32_e32 v99, 1.0, v99
	v_rcp_f32_e32 v96, v96
	v_rcp_f32_e32 v97, v97
	v_add_f32_e32 v98, 1.0, v98
	v_pk_mul_f32 v[102:103], v[102:103], v[106:107] op_sel_hi:[1,0]
	v_mul_f32_e32 v100, 0xbfb8aa3b, v100
	v_mul_f32_e32 v101, 0xbfb8aa3b, v101
	v_rcp_f32_e32 v99, v99
	v_rcp_f32_e32 v98, v98
	v_mul_f32_e32 v103, 0xbfb8aa3b, v103
	v_exp_f32_e32 v100, v100
	v_exp_f32_e32 v101, v101
	v_mul_f32_e32 v102, 0xbfb8aa3b, v102
	v_exp_f32_e32 v103, v103
	v_exp_f32_e32 v102, v102
	v_fma_f32 v96, v96, s4, 0.5
	v_fma_f32 v97, v97, s4, 0.5
	v_max_f32_e32 v96, 1.0, v96
	v_max_f32_e32 v97, 1.0, v97
	v_fma_f32 v98, v98, s4, 0.5
	v_fma_f32 v99, v99, s4, 0.5
	v_add_f32_e32 v100, 1.0, v100
	v_add_f32_e32 v101, 1.0, v101
	v_cvt_u32_f32_e32 v96, v96
	v_cvt_u32_f32_e32 v97, v97
	v_max_f32_e32 v98, 1.0, v98
	v_max_f32_e32 v99, 1.0, v99
	v_add_f32_e32 v103, 1.0, v103
	v_rcp_f32_e32 v100, v100
	v_rcp_f32_e32 v101, v101
	v_cvt_u32_f32_sdwa v98, v98 dst_sel:WORD_1 dst_unused:UNUSED_PAD src0_sel:DWORD
	v_cvt_u32_f32_sdwa v99, v99 dst_sel:BYTE_3 dst_unused:UNUSED_PAD src0_sel:DWORD
	v_add_f32_e32 v102, 1.0, v102
	v_rcp_f32_e32 v103, v103
	v_rcp_f32_e32 v102, v102
	v_lshl_or_b32 v96, v97, 8, v96
	v_or3_b32 v96, v96, v98, v99
	v_fma_f32 v97, v100, s4, 0.5
	v_fma_f32 v98, v101, s4, 0.5
	v_pk_mul_f32 v[92:93], v[92:93], v[106:107] op_sel_hi:[1,0]
	v_max_f32_e32 v97, 1.0, v97
	v_max_f32_e32 v98, 1.0, v98
	v_fma_f32 v99, v102, s4, 0.5
	v_fma_f32 v100, v103, s4, 0.5
	v_mul_f32_e32 v93, 0xbfb8aa3b, v93
	v_cvt_u32_f32_e32 v97, v97
	v_cvt_u32_f32_e32 v98, v98
	v_max_f32_e32 v99, 1.0, v99
	v_max_f32_e32 v100, 1.0, v100
	v_exp_f32_e32 v93, v93
	v_cvt_u32_f32_sdwa v99, v99 dst_sel:WORD_1 dst_unused:UNUSED_PAD src0_sel:DWORD
	v_cvt_u32_f32_sdwa v100, v100 dst_sel:BYTE_3 dst_unused:UNUSED_PAD src0_sel:DWORD
	v_pk_mul_f32 v[88:89], v[88:89], v[106:107] op_sel_hi:[1,0]
	v_mul_f32_e32 v92, 0xbfb8aa3b, v92
	v_mul_f32_e32 v89, 0xbfb8aa3b, v89
	v_lshl_or_b32 v97, v98, 8, v97
	v_exp_f32_e32 v98, v92
	v_add_f32_e32 v92, 1.0, v93
	v_exp_f32_e32 v89, v89
	v_or3_b32 v97, v97, v99, v100
	v_rcp_f32_e32 v99, v92
	v_mul_f32_e32 v88, 0xbfb8aa3b, v88
	v_pk_mul_f32 v[92:93], v[94:95], v[106:107] op_sel_hi:[1,0]
; __device__ __forceinline__ float sigmoidf_(float v) { return __builtin_amdgcn_rcpf(1.0f + __expf(-v)); }
; #define MEMFENCE asm volatile("" ::: "memory")
;     template <int KIND> __device__ __forceinline__ void run(f32x4 (&acc)[2][2][4][2], const Unit& u, int tid_in) const {
;     ...
;                 for (int m = 0; m < 4; ++m) { const float r = rs[ai * 4 + m] * (1.0f / GATE_WSCALE); u32x4 w;
; #pragma unroll
;                     for (int bj = 0; bj < 2; ++bj) { f32x4 a = acc[ai][bj][m][0] * r, b = acc[ai][bj][m][1] * r;
; #pragma unroll
;                         for (int j = 0; j < 4; ++j) { a[j] = sigmoidf_(a[j]); b[j] = sigmoidf_(b[j]); }
;                         if (bj == 0) { w.x = pack4_u8c(a); w.y = pack4_u8c(b); } else { w.z = pack4_u8c(a); w.w = pack4_u8c(b); } }
;                     gst[(ai * 4 + m) * 512 + tid] = w; MEMFENCE; }
	v_add_f32_e32 v94, 1.0, v98
	v_exp_f32_e32 v98, v88
	v_add_f32_e32 v88, 1.0, v89
	v_fma_f32 v95, v99, s4, 0.5
	v_rcp_f32_e32 v99, v88
	v_pk_mul_f32 v[88:89], v[90:91], v[106:107] op_sel_hi:[1,0]
	v_add_f32_e32 v90, 1.0, v98
	v_mul_f32_e32 v88, 0xbfb8aa3b, v88
	v_mul_f32_e32 v89, 0xbfb8aa3b, v89
	v_exp_f32_e32 v88, v88
	v_exp_f32_e32 v89, v89
	v_rcp_f32_e32 v90, v90
	v_fma_f32 v91, v99, s4, 0.5
	v_add_f32_e32 v88, 1.0, v88
	v_add_f32_e32 v89, 1.0, v89
	v_rcp_f32_e32 v88, v88
	v_rcp_f32_e32 v89, v89
	v_fma_f32 v90, v90, s4, 0.5
	v_max_f32_e32 v91, 1.0, v91
	v_max_f32_e32 v90, 1.0, v90
	v_fma_f32 v88, v88, s4, 0.5
	v_fma_f32 v89, v89, s4, 0.5
	v_cvt_u32_f32_e32 v91, v91
	v_cvt_u32_f32_e32 v90, v90
	v_max_f32_e32 v88, 1.0, v88
	v_max_f32_e32 v89, 1.0, v89
	v_cvt_u32_f32_sdwa v88, v88 dst_sel:WORD_1 dst_unused:UNUSED_PAD src0_sel:DWORD
	v_cvt_u32_f32_sdwa v89, v89 dst_sel:BYTE_3 dst_unused:UNUSED_PAD src0_sel:DWORD
	v_lshl_or_b32 v90, v91, 8, v90
	v_mul_f32_e32 v108, 0xbfb8aa3b, v108
	v_mul_f32_e32 v109, 0xbfb8aa3b, v109
	v_or3_b32 v99, v90, v88, v89
	v_mul_f32_e32 v90, 0x3c800000, v141
	v_pk_mul_f32 v[80:81], v[80:81], v[90:91] op_sel_hi:[1,0]
	v_pk_mul_f32 v[82:83], v[82:83], v[90:91] op_sel_hi:[1,0]
	v_mul_f32_e32 v80, 0xbfb8aa3b, v80
	v_mul_f32_e32 v81, 0xbfb8aa3b, v81
	v_mul_f32_e32 v83, 0xbfb8aa3b, v83
	v_exp_f32_e32 v80, v80
	v_exp_f32_e32 v81, v81
	v_mul_f32_e32 v82, 0xbfb8aa3b, v82
	v_exp_f32_e32 v83, v83
	v_exp_f32_e32 v82, v82
	v_add_f32_e32 v80, 1.0, v80
	v_add_f32_e32 v81, 1.0, v81
	v_pk_mul_f32 v[84:85], v[84:85], v[90:91] op_sel_hi:[1,0]
	v_add_f32_e32 v83, 1.0, v83
	v_rcp_f32_e32 v80, v80
	v_rcp_f32_e32 v81, v81
	v_add_f32_e32 v82, 1.0, v82
	v_pk_mul_f32 v[86:87], v[86:87], v[90:91] op_sel_hi:[1,0]
	v_mul_f32_e32 v84, 0xbfb8aa3b, v84
	v_mul_f32_e32 v85, 0xbfb8aa3b, v85
	v_rcp_f32_e32 v83, v83
	v_rcp_f32_e32 v82, v82
	v_mul_f32_e32 v87, 0xbfb8aa3b, v87
	v_exp_f32_e32 v84, v84
	v_exp_f32_e32 v85, v85
	v_mul_f32_e32 v86, 0xbfb8aa3b, v86
	v_exp_f32_e32 v87, v87
	v_exp_f32_e32 v86, v86
	v_fma_f32 v80, v80, s4, 0.5
	v_fma_f32 v81, v81, s4, 0.5
	v_max_f32_e32 v80, 1.0, v80
	v_max_f32_e32 v81, 1.0, v81
	v_fma_f32 v82, v82, s4, 0.5
	v_fma_f32 v83, v83, s4, 0.5
	v_add_f32_e32 v84, 1.0, v84
	v_add_f32_e32 v85, 1.0, v85
	v_cvt_u32_f32_e32 v80, v80
	v_cvt_u32_f32_e32 v81, v81
	v_max_f32_e32 v82, 1.0, v82
	v_max_f32_e32 v83, 1.0, v83
	v_add_f32_e32 v87, 1.0, v87
	v_rcp_f32_e32 v84, v84
	v_rcp_f32_e32 v85, v85
	v_cvt_u32_f32_sdwa v82, v82 dst_sel:WORD_1 dst_unused:UNUSED_PAD src0_sel:DWORD
	v_cvt_u32_f32_sdwa v83, v83 dst_sel:BYTE_3 dst_unused:UNUSED_PAD src0_sel:DWORD
	v_add_f32_e32 v86, 1.0, v86
	v_rcp_f32_e32 v87, v87
	v_rcp_f32_e32 v86, v86
	v_lshl_or_b32 v80, v81, 8, v80
	v_or3_b32 v80, v80, v82, v83
	v_fma_f32 v81, v84, s4, 0.5
	v_fma_f32 v82, v85, s4, 0.5
	v_pk_mul_f32 v[76:77], v[76:77], v[90:91] op_sel_hi:[1,0]
	v_max_f32_e32 v81, 1.0, v81
	v_max_f32_e32 v82, 1.0, v82
	v_fma_f32 v83, v86, s4, 0.5
	v_fma_f32 v84, v87, s4, 0.5
	v_mul_f32_e32 v77, 0xbfb8aa3b, v77
	v_cvt_u32_f32_e32 v81, v81
	v_cvt_u32_f32_e32 v82, v82
	v_max_f32_e32 v83, 1.0, v83
	v_max_f32_e32 v84, 1.0, v84
	v_exp_f32_e32 v77, v77
	v_cvt_u32_f32_sdwa v83, v83 dst_sel:WORD_1 dst_unused:UNUSED_PAD src0_sel:DWORD
	v_cvt_u32_f32_sdwa v84, v84 dst_sel:BYTE_3 dst_unused:UNUSED_PAD src0_sel:DWORD
	v_pk_mul_f32 v[72:73], v[72:73], v[90:91] op_sel_hi:[1,0]
	v_mul_f32_e32 v76, 0xbfb8aa3b, v76
	v_mul_f32_e32 v73, 0xbfb8aa3b, v73
	v_lshl_or_b32 v81, v82, 8, v81
	v_exp_f32_e32 v82, v76
	v_add_f32_e32 v76, 1.0, v77
	v_exp_f32_e32 v73, v73
	v_or3_b32 v81, v81, v83, v84
	v_rcp_f32_e32 v83, v76
	v_mul_f32_e32 v72, 0xbfb8aa3b, v72
	v_pk_mul_f32 v[76:77], v[78:79], v[90:91] op_sel_hi:[1,0]
	v_add_f32_e32 v78, 1.0, v82
	v_exp_f32_e32 v82, v72
	v_add_f32_e32 v72, 1.0, v73
	v_fma_f32 v79, v83, s4, 0.5
	v_rcp_f32_e32 v83, v72
	v_pk_mul_f32 v[72:73], v[74:75], v[90:91] op_sel_hi:[1,0]
	v_add_f32_e32 v74, 1.0, v82
	v_mul_f32_e32 v72, 0xbfb8aa3b, v72
	v_mul_f32_e32 v73, 0xbfb8aa3b, v73
	v_exp_f32_e32 v72, v72
	v_exp_f32_e32 v73, v73
	v_rcp_f32_e32 v74, v74
	v_fma_f32 v75, v83, s4, 0.5
	v_add_f32_e32 v72, 1.0, v72
	v_add_f32_e32 v73, 1.0, v73
	v_rcp_f32_e32 v72, v72
	v_rcp_f32_e32 v73, v73
	v_fma_f32 v74, v74, s4, 0.5
	v_max_f32_e32 v75, 1.0, v75
	v_max_f32_e32 v74, 1.0, v74
	v_fma_f32 v72, v72, s4, 0.5
	v_fma_f32 v73, v73, s4, 0.5
	v_cvt_u32_f32_e32 v75, v75
	v_cvt_u32_f32_e32 v74, v74
	v_max_f32_e32 v72, 1.0, v72
	v_max_f32_e32 v73, 1.0, v73
	v_cvt_u32_f32_sdwa v72, v72 dst_sel:WORD_1 dst_unused:UNUSED_PAD src0_sel:DWORD
	v_cvt_u32_f32_sdwa v73, v73 dst_sel:BYTE_3 dst_unused:UNUSED_PAD src0_sel:DWORD
	v_lshl_or_b32 v74, v75, 8, v74
	v_exp_f32_e32 v108, v108
	v_exp_f32_e32 v109, v109
	v_or3_b32 v83, v74, v72, v73
	v_mul_f32_e32 v74, 0x3c800000, v138
	v_pk_mul_f32 v[64:65], v[64:65], v[74:75] op_sel_hi:[1,0]
	v_pk_mul_f32 v[66:67], v[66:67], v[74:75] op_sel_hi:[1,0]
	v_mul_f32_e32 v64, 0xbfb8aa3b, v64
	v_mul_f32_e32 v65, 0xbfb8aa3b, v65
	v_mul_f32_e32 v67, 0xbfb8aa3b, v67
	v_exp_f32_e32 v64, v64
	v_exp_f32_e32 v65, v65
	v_mul_f32_e32 v66, 0xbfb8aa3b, v66
	v_exp_f32_e32 v67, v67
	v_exp_f32_e32 v66, v66
	v_add_f32_e32 v64, 1.0, v64
	v_add_f32_e32 v65, 1.0, v65
	v_pk_mul_f32 v[68:69], v[68:69], v[74:75] op_sel_hi:[1,0]
	v_add_f32_e32 v67, 1.0, v67
	v_rcp_f32_e32 v64, v64
	v_rcp_f32_e32 v65, v65
	v_add_f32_e32 v66, 1.0, v66
	v_pk_mul_f32 v[70:71], v[70:71], v[74:75] op_sel_hi:[1,0]
	v_mul_f32_e32 v68, 0xbfb8aa3b, v68
	v_mul_f32_e32 v69, 0xbfb8aa3b, v69
	v_rcp_f32_e32 v67, v67
	v_rcp_f32_e32 v66, v66
	v_mul_f32_e32 v71, 0xbfb8aa3b, v71
	v_exp_f32_e32 v68, v68
	v_exp_f32_e32 v69, v69
; __device__ __forceinline__ float sigmoidf_(float v) { return __builtin_amdgcn_rcpf(1.0f + __expf(-v)); }
; #define MEMFENCE asm volatile("" ::: "memory")
;     template <int KIND> __device__ __forceinline__ void run(f32x4 (&acc)[2][2][4][2], const Unit& u, int tid_in) const {
;     ...
;                 for (int m = 0; m < 4; ++m) { const float r = rs[ai * 4 + m] * (1.0f / GATE_WSCALE); u32x4 w;
; #pragma unroll
;                     for (int bj = 0; bj < 2; ++bj) { f32x4 a = acc[ai][bj][m][0] * r, b = acc[ai][bj][m][1] * r;
; #pragma unroll
;                         for (int j = 0; j < 4; ++j) { a[j] = sigmoidf_(a[j]); b[j] = sigmoidf_(b[j]); }
;                         if (bj == 0) { w.x = pack4_u8c(a); w.y = pack4_u8c(b); } else { w.z = pack4_u8c(a); w.w = pack4_u8c(b); } }
;                     gst[(ai * 4 + m) * 512 + tid] = w; MEMFENCE; }
	v_mul_f32_e32 v70, 0xbfb8aa3b, v70
	v_exp_f32_e32 v71, v71
	v_exp_f32_e32 v70, v70
	v_fma_f32 v64, v64, s4, 0.5
	v_fma_f32 v65, v65, s4, 0.5
	v_max_f32_e32 v64, 1.0, v64
	v_max_f32_e32 v65, 1.0, v65
	v_fma_f32 v66, v66, s4, 0.5
	v_fma_f32 v67, v67, s4, 0.5
	v_add_f32_e32 v68, 1.0, v68
	v_add_f32_e32 v69, 1.0, v69
	v_cvt_u32_f32_e32 v64, v64
	v_cvt_u32_f32_e32 v65, v65
	v_max_f32_e32 v66, 1.0, v66
	v_max_f32_e32 v67, 1.0, v67
	v_add_f32_e32 v71, 1.0, v71
	v_rcp_f32_e32 v68, v68
	v_rcp_f32_e32 v69, v69
	v_cvt_u32_f32_sdwa v66, v66 dst_sel:WORD_1 dst_unused:UNUSED_PAD src0_sel:DWORD
	v_cvt_u32_f32_sdwa v67, v67 dst_sel:BYTE_3 dst_unused:UNUSED_PAD src0_sel:DWORD
	v_add_f32_e32 v70, 1.0, v70
	v_rcp_f32_e32 v71, v71
	v_rcp_f32_e32 v70, v70
	v_lshl_or_b32 v64, v65, 8, v64
	v_or3_b32 v64, v64, v66, v67
	v_fma_f32 v65, v68, s4, 0.5
	v_fma_f32 v66, v69, s4, 0.5
	v_pk_mul_f32 v[60:61], v[60:61], v[74:75] op_sel_hi:[1,0]
	v_max_f32_e32 v65, 1.0, v65
	v_max_f32_e32 v66, 1.0, v66
	v_fma_f32 v67, v70, s4, 0.5
	v_fma_f32 v68, v71, s4, 0.5
	v_mul_f32_e32 v61, 0xbfb8aa3b, v61
	v_cvt_u32_f32_e32 v65, v65
	v_cvt_u32_f32_e32 v66, v66
	v_max_f32_e32 v67, 1.0, v67
	v_max_f32_e32 v68, 1.0, v68
	v_exp_f32_e32 v61, v61
	v_cvt_u32_f32_sdwa v67, v67 dst_sel:WORD_1 dst_unused:UNUSED_PAD src0_sel:DWORD
	v_cvt_u32_f32_sdwa v68, v68 dst_sel:BYTE_3 dst_unused:UNUSED_PAD src0_sel:DWORD
	v_pk_mul_f32 v[56:57], v[56:57], v[74:75] op_sel_hi:[1,0]
	v_mul_f32_e32 v60, 0xbfb8aa3b, v60
	v_mul_f32_e32 v57, 0xbfb8aa3b, v57
	v_lshl_or_b32 v65, v66, 8, v65
	v_exp_f32_e32 v66, v60
	v_add_f32_e32 v60, 1.0, v61
	v_exp_f32_e32 v57, v57
	v_or3_b32 v65, v65, v67, v68
	v_rcp_f32_e32 v67, v60
	v_mul_f32_e32 v56, 0xbfb8aa3b, v56
	v_pk_mul_f32 v[60:61], v[62:63], v[74:75] op_sel_hi:[1,0]
	v_add_f32_e32 v62, 1.0, v66
	v_exp_f32_e32 v66, v56
	v_add_f32_e32 v56, 1.0, v57
	v_fma_f32 v63, v67, s4, 0.5
	v_rcp_f32_e32 v67, v56
	v_pk_mul_f32 v[56:57], v[58:59], v[74:75] op_sel_hi:[1,0]
	v_add_f32_e32 v58, 1.0, v66
	v_mul_f32_e32 v56, 0xbfb8aa3b, v56
	v_mul_f32_e32 v57, 0xbfb8aa3b, v57
	v_exp_f32_e32 v56, v56
	v_exp_f32_e32 v57, v57
	v_rcp_f32_e32 v58, v58
	v_fma_f32 v59, v67, s4, 0.5
	v_add_f32_e32 v56, 1.0, v56
	v_add_f32_e32 v57, 1.0, v57
	v_rcp_f32_e32 v56, v56
	v_rcp_f32_e32 v57, v57
	v_fma_f32 v58, v58, s4, 0.5
	v_max_f32_e32 v59, 1.0, v59
	v_max_f32_e32 v58, 1.0, v58
	v_fma_f32 v56, v56, s4, 0.5
	v_fma_f32 v57, v57, s4, 0.5
	v_cvt_u32_f32_e32 v59, v59
	v_cvt_u32_f32_e32 v58, v58
	v_max_f32_e32 v56, 1.0, v56
	v_max_f32_e32 v57, 1.0, v57
	v_cvt_u32_f32_sdwa v56, v56 dst_sel:WORD_1 dst_unused:UNUSED_PAD src0_sel:DWORD
	v_cvt_u32_f32_sdwa v57, v57 dst_sel:BYTE_3 dst_unused:UNUSED_PAD src0_sel:DWORD
	v_lshl_or_b32 v58, v59, 8, v58
	v_mul_f32_e32 v92, 0xbfb8aa3b, v92
	v_mul_f32_e32 v93, 0xbfb8aa3b, v93
	v_or3_b32 v67, v58, v56, v57
	v_mul_f32_e32 v58, 0x3c800000, v139
	v_pk_mul_f32 v[48:49], v[48:49], v[58:59] op_sel_hi:[1,0]
	v_pk_mul_f32 v[50:51], v[50:51], v[58:59] op_sel_hi:[1,0]
	v_mul_f32_e32 v48, 0xbfb8aa3b, v48
	v_mul_f32_e32 v49, 0xbfb8aa3b, v49
	v_mul_f32_e32 v51, 0xbfb8aa3b, v51
	v_exp_f32_e32 v48, v48
	v_exp_f32_e32 v49, v49
	v_mul_f32_e32 v50, 0xbfb8aa3b, v50
	v_exp_f32_e32 v51, v51
	v_exp_f32_e32 v50, v50
	v_add_f32_e32 v48, 1.0, v48
	v_add_f32_e32 v49, 1.0, v49
	v_pk_mul_f32 v[52:53], v[52:53], v[58:59] op_sel_hi:[1,0]
	v_add_f32_e32 v51, 1.0, v51
	v_rcp_f32_e32 v48, v48
	v_rcp_f32_e32 v49, v49
	v_add_f32_e32 v50, 1.0, v50
	v_pk_mul_f32 v[54:55], v[54:55], v[58:59] op_sel_hi:[1,0]
	v_mul_f32_e32 v52, 0xbfb8aa3b, v52
	v_mul_f32_e32 v53, 0xbfb8aa3b, v53
	v_rcp_f32_e32 v51, v51
	v_rcp_f32_e32 v50, v50
	v_mul_f32_e32 v55, 0xbfb8aa3b, v55
	v_exp_f32_e32 v52, v52
	v_exp_f32_e32 v53, v53
	v_mul_f32_e32 v54, 0xbfb8aa3b, v54
	v_exp_f32_e32 v55, v55
	v_exp_f32_e32 v54, v54
	v_fma_f32 v48, v48, s4, 0.5
	v_fma_f32 v49, v49, s4, 0.5
	v_max_f32_e32 v48, 1.0, v48
	v_max_f32_e32 v49, 1.0, v49
	v_fma_f32 v50, v50, s4, 0.5
	v_fma_f32 v51, v51, s4, 0.5
	v_add_f32_e32 v52, 1.0, v52
	v_add_f32_e32 v53, 1.0, v53
	v_cvt_u32_f32_e32 v48, v48
	v_cvt_u32_f32_e32 v49, v49
	v_max_f32_e32 v50, 1.0, v50
	v_max_f32_e32 v51, 1.0, v51
	v_add_f32_e32 v55, 1.0, v55
	v_rcp_f32_e32 v52, v52
	v_rcp_f32_e32 v53, v53
	v_cvt_u32_f32_sdwa v50, v50 dst_sel:WORD_1 dst_unused:UNUSED_PAD src0_sel:DWORD
	v_cvt_u32_f32_sdwa v51, v51 dst_sel:BYTE_3 dst_unused:UNUSED_PAD src0_sel:DWORD
	v_add_f32_e32 v54, 1.0, v54
	v_rcp_f32_e32 v55, v55
	v_rcp_f32_e32 v54, v54
	v_lshl_or_b32 v48, v49, 8, v48
	v_or3_b32 v48, v48, v50, v51
	v_fma_f32 v49, v52, s4, 0.5
	v_fma_f32 v50, v53, s4, 0.5
	v_pk_mul_f32 v[44:45], v[44:45], v[58:59] op_sel_hi:[1,0]
	v_max_f32_e32 v49, 1.0, v49
	v_max_f32_e32 v50, 1.0, v50
	v_fma_f32 v51, v54, s4, 0.5
	v_fma_f32 v52, v55, s4, 0.5
	v_mul_f32_e32 v45, 0xbfb8aa3b, v45
	v_cvt_u32_f32_e32 v49, v49
	v_cvt_u32_f32_e32 v50, v50
	v_max_f32_e32 v51, 1.0, v51
	v_max_f32_e32 v52, 1.0, v52
	v_exp_f32_e32 v45, v45
	v_cvt_u32_f32_sdwa v51, v51 dst_sel:WORD_1 dst_unused:UNUSED_PAD src0_sel:DWORD
	v_cvt_u32_f32_sdwa v52, v52 dst_sel:BYTE_3 dst_unused:UNUSED_PAD src0_sel:DWORD
	v_pk_mul_f32 v[40:41], v[40:41], v[58:59] op_sel_hi:[1,0]
	v_mul_f32_e32 v44, 0xbfb8aa3b, v44
	v_mul_f32_e32 v41, 0xbfb8aa3b, v41
	v_lshl_or_b32 v49, v50, 8, v49
	v_exp_f32_e32 v50, v44
	v_add_f32_e32 v44, 1.0, v45
	v_exp_f32_e32 v41, v41
	v_or3_b32 v49, v49, v51, v52
	v_rcp_f32_e32 v51, v44
	v_mul_f32_e32 v40, 0xbfb8aa3b, v40
	v_pk_mul_f32 v[44:45], v[46:47], v[58:59] op_sel_hi:[1,0]
	v_add_f32_e32 v46, 1.0, v50
	v_exp_f32_e32 v50, v40
	v_add_f32_e32 v40, 1.0, v41
	v_fma_f32 v47, v51, s4, 0.5
	v_rcp_f32_e32 v51, v40
	v_pk_mul_f32 v[40:41], v[42:43], v[58:59] op_sel_hi:[1,0]
; __device__ __forceinline__ float sigmoidf_(float v) { return __builtin_amdgcn_rcpf(1.0f + __expf(-v)); }
; #define MEMFENCE asm volatile("" ::: "memory")
;     template <int KIND> __device__ __forceinline__ void run(f32x4 (&acc)[2][2][4][2], const Unit& u, int tid_in) const {
;     ...
;                 for (int m = 0; m < 4; ++m) { const float r = rs[ai * 4 + m] * (1.0f / GATE_WSCALE); u32x4 w;
; #pragma unroll
;                     for (int bj = 0; bj < 2; ++bj) { f32x4 a = acc[ai][bj][m][0] * r, b = acc[ai][bj][m][1] * r;
; #pragma unroll
;                         for (int j = 0; j < 4; ++j) { a[j] = sigmoidf_(a[j]); b[j] = sigmoidf_(b[j]); }
;                         if (bj == 0) { w.x = pack4_u8c(a); w.y = pack4_u8c(b); } else { w.z = pack4_u8c(a); w.w = pack4_u8c(b); } }
;                     gst[(ai * 4 + m) * 512 + tid] = w; MEMFENCE; }
	v_add_f32_e32 v42, 1.0, v50
	v_mul_f32_e32 v40, 0xbfb8aa3b, v40
	v_mul_f32_e32 v41, 0xbfb8aa3b, v41
	v_exp_f32_e32 v40, v40
	v_exp_f32_e32 v41, v41
	v_rcp_f32_e32 v42, v42
	v_fma_f32 v43, v51, s4, 0.5
	v_add_f32_e32 v40, 1.0, v40
	v_add_f32_e32 v41, 1.0, v41
	v_rcp_f32_e32 v40, v40
	v_rcp_f32_e32 v41, v41
	v_fma_f32 v42, v42, s4, 0.5
	v_max_f32_e32 v43, 1.0, v43
	v_max_f32_e32 v42, 1.0, v42
	v_fma_f32 v40, v40, s4, 0.5
	v_fma_f32 v41, v41, s4, 0.5
	v_cvt_u32_f32_e32 v43, v43
	v_cvt_u32_f32_e32 v42, v42
	v_max_f32_e32 v40, 1.0, v40
	v_max_f32_e32 v41, 1.0, v41
	v_cvt_u32_f32_sdwa v40, v40 dst_sel:WORD_1 dst_unused:UNUSED_PAD src0_sel:DWORD
	v_cvt_u32_f32_sdwa v41, v41 dst_sel:BYTE_3 dst_unused:UNUSED_PAD src0_sel:DWORD
	v_lshl_or_b32 v42, v43, 8, v42
	v_exp_f32_e32 v92, v92
	v_exp_f32_e32 v93, v93
	v_or3_b32 v51, v42, v40, v41
	v_mul_f32_e32 v42, 0x3c800000, v136
	v_pk_mul_f32 v[32:33], v[32:33], v[42:43] op_sel_hi:[1,0]
	v_pk_mul_f32 v[34:35], v[34:35], v[42:43] op_sel_hi:[1,0]
	v_mul_f32_e32 v32, 0xbfb8aa3b, v32
	v_mul_f32_e32 v33, 0xbfb8aa3b, v33
	v_mul_f32_e32 v35, 0xbfb8aa3b, v35
	v_exp_f32_e32 v32, v32
	v_exp_f32_e32 v33, v33
	v_mul_f32_e32 v34, 0xbfb8aa3b, v34
	v_exp_f32_e32 v35, v35
	v_exp_f32_e32 v34, v34
	v_add_f32_e32 v32, 1.0, v32
	v_add_f32_e32 v33, 1.0, v33
	v_pk_mul_f32 v[36:37], v[36:37], v[42:43] op_sel_hi:[1,0]
	v_add_f32_e32 v35, 1.0, v35
	v_rcp_f32_e32 v32, v32
	v_rcp_f32_e32 v33, v33
	v_add_f32_e32 v34, 1.0, v34
	v_pk_mul_f32 v[38:39], v[38:39], v[42:43] op_sel_hi:[1,0]
	v_mul_f32_e32 v36, 0xbfb8aa3b, v36
	v_mul_f32_e32 v37, 0xbfb8aa3b, v37
	v_rcp_f32_e32 v35, v35
	v_rcp_f32_e32 v34, v34
	v_mul_f32_e32 v39, 0xbfb8aa3b, v39
	v_exp_f32_e32 v36, v36
	v_exp_f32_e32 v37, v37
	v_mul_f32_e32 v38, 0xbfb8aa3b, v38
	v_exp_f32_e32 v39, v39
	v_exp_f32_e32 v38, v38
	v_fma_f32 v32, v32, s4, 0.5
	v_fma_f32 v33, v33, s4, 0.5
	v_max_f32_e32 v32, 1.0, v32
	v_max_f32_e32 v33, 1.0, v33
	v_fma_f32 v34, v34, s4, 0.5
	v_fma_f32 v35, v35, s4, 0.5
	v_add_f32_e32 v36, 1.0, v36
	v_add_f32_e32 v37, 1.0, v37
	v_cvt_u32_f32_e32 v32, v32
	v_cvt_u32_f32_e32 v33, v33
	v_max_f32_e32 v34, 1.0, v34
	v_max_f32_e32 v35, 1.0, v35
	v_add_f32_e32 v39, 1.0, v39
	v_rcp_f32_e32 v36, v36
	v_rcp_f32_e32 v37, v37
	v_cvt_u32_f32_sdwa v34, v34 dst_sel:WORD_1 dst_unused:UNUSED_PAD src0_sel:DWORD
	v_cvt_u32_f32_sdwa v35, v35 dst_sel:BYTE_3 dst_unused:UNUSED_PAD src0_sel:DWORD
	v_add_f32_e32 v38, 1.0, v38
	v_rcp_f32_e32 v39, v39
	v_rcp_f32_e32 v38, v38
	v_lshl_or_b32 v32, v33, 8, v32
	v_or3_b32 v32, v32, v34, v35
	v_fma_f32 v33, v36, s4, 0.5
	v_fma_f32 v34, v37, s4, 0.5
	v_pk_mul_f32 v[28:29], v[28:29], v[42:43] op_sel_hi:[1,0]
	v_max_f32_e32 v33, 1.0, v33
	v_max_f32_e32 v34, 1.0, v34
	v_fma_f32 v35, v38, s4, 0.5
	v_fma_f32 v36, v39, s4, 0.5
	v_mul_f32_e32 v29, 0xbfb8aa3b, v29
	v_cvt_u32_f32_e32 v33, v33
	v_cvt_u32_f32_e32 v34, v34
	v_max_f32_e32 v35, 1.0, v35
	v_max_f32_e32 v36, 1.0, v36
	v_exp_f32_e32 v29, v29
	v_cvt_u32_f32_sdwa v35, v35 dst_sel:WORD_1 dst_unused:UNUSED_PAD src0_sel:DWORD
	v_cvt_u32_f32_sdwa v36, v36 dst_sel:BYTE_3 dst_unused:UNUSED_PAD src0_sel:DWORD
	v_pk_mul_f32 v[24:25], v[24:25], v[42:43] op_sel_hi:[1,0]
	v_mul_f32_e32 v28, 0xbfb8aa3b, v28
	v_mul_f32_e32 v25, 0xbfb8aa3b, v25
	v_lshl_or_b32 v33, v34, 8, v33
	v_exp_f32_e32 v34, v28
	v_add_f32_e32 v28, 1.0, v29
	v_exp_f32_e32 v25, v25
	v_or3_b32 v33, v33, v35, v36
	v_rcp_f32_e32 v35, v28
	v_mul_f32_e32 v24, 0xbfb8aa3b, v24
	v_mul_f32_e32 v76, 0xbfb8aa3b, v76
	v_mul_f32_e32 v77, 0xbfb8aa3b, v77
	v_pk_mul_f32 v[28:29], v[30:31], v[42:43] op_sel_hi:[1,0]
	v_add_f32_e32 v30, 1.0, v34
	v_exp_f32_e32 v34, v24
	v_add_f32_e32 v24, 1.0, v25
	v_exp_f32_e32 v76, v76
	v_exp_f32_e32 v77, v77
	v_mul_f32_e32 v60, 0xbfb8aa3b, v60
	v_mul_f32_e32 v61, 0xbfb8aa3b, v61
	v_fma_f32 v31, v35, s4, 0.5
	v_rcp_f32_e32 v35, v24
	v_pk_mul_f32 v[24:25], v[26:27], v[42:43] op_sel_hi:[1,0]
	v_rcp_f32_e32 v126, v126
	v_add_f32_e32 v124, 1.0, v124
	v_add_f32_e32 v125, 1.0, v125
	v_exp_f32_e32 v60, v60
	v_exp_f32_e32 v61, v61
	v_mul_f32_e32 v44, 0xbfb8aa3b, v44
	v_mul_f32_e32 v45, 0xbfb8aa3b, v45
	v_mul_f32_e32 v24, 0xbfb8aa3b, v24
	v_mul_f32_e32 v25, 0xbfb8aa3b, v25
	v_rcp_f32_e32 v124, v124
	v_rcp_f32_e32 v125, v125
	v_rcp_f32_e32 v110, v110
	v_add_f32_e32 v108, 1.0, v108
	v_add_f32_e32 v109, 1.0, v109
	v_exp_f32_e32 v44, v44
	v_exp_f32_e32 v45, v45
	v_mul_f32_e32 v28, 0xbfb8aa3b, v28
	v_mul_f32_e32 v29, 0xbfb8aa3b, v29
	v_exp_f32_e32 v24, v24
	v_exp_f32_e32 v25, v25
	s_lshl_b64 s[2:3], s[2:3], 16
	v_rcp_f32_e32 v108, v108
	v_rcp_f32_e32 v109, v109
	v_rcp_f32_e32 v94, v94
	v_add_f32_e32 v92, 1.0, v92
	v_add_f32_e32 v93, 1.0, v93
	v_exp_f32_e32 v28, v28
	v_exp_f32_e32 v29, v29
	s_add_u32 s2, s29, s2
	v_rcp_f32_e32 v92, v92
	v_rcp_f32_e32 v93, v93
	v_rcp_f32_e32 v78, v78
	v_add_f32_e32 v76, 1.0, v76
	v_add_f32_e32 v77, 1.0, v77
	s_addc_u32 s3, s30, s3
	v_fma_f32 v126, v126, s4, 0.5
	v_ashrrev_i32_e32 v143, 31, v142
	v_rcp_f32_e32 v76, v76
	v_rcp_f32_e32 v77, v77
	v_rcp_f32_e32 v62, v62
	v_add_f32_e32 v60, 1.0, v60
	v_add_f32_e32 v61, 1.0, v61
	v_add_f32_e32 v26, 1.0, v34
	v_max_f32_e32 v127, 1.0, v127
	v_max_f32_e32 v126, 1.0, v126
	v_fma_f32 v124, v124, s4, 0.5
	v_fma_f32 v125, v125, s4, 0.5
	v_lshl_add_u64 v[120:121], v[142:143], 4, s[2:3]
	v_fma_f32 v110, v110, s4, 0.5
	s_movk_i32 s2, 0x2000
	v_rcp_f32_e32 v60, v60
	v_rcp_f32_e32 v61, v61
	v_rcp_f32_e32 v46, v46
	v_add_f32_e32 v44, 1.0, v44
	v_add_f32_e32 v45, 1.0, v45
	v_rcp_f32_e32 v26, v26
	v_add_f32_e32 v24, 1.0, v24
	v_add_f32_e32 v25, 1.0, v25
	v_cvt_u32_f32_e32 v127, v127
	v_cvt_u32_f32_e32 v126, v126
	v_max_f32_e32 v124, 1.0, v124
	v_max_f32_e32 v125, 1.0, v125
; __device__ __forceinline__ float sigmoidf_(float v) { return __builtin_amdgcn_rcpf(1.0f + __expf(-v)); }
; #define MEMFENCE asm volatile("" ::: "memory")
;     template <int KIND> __device__ __forceinline__ void run(f32x4 (&acc)[2][2][4][2], const Unit& u, int tid_in) const {
;     ...
;                 for (int m = 0; m < 4; ++m) { const float r = rs[ai * 4 + m] * (1.0f / GATE_WSCALE); u32x4 w;
; #pragma unroll
;                     for (int bj = 0; bj < 2; ++bj) { f32x4 a = acc[ai][bj][m][0] * r, b = acc[ai][bj][m][1] * r;
; #pragma unroll
;                         for (int j = 0; j < 4; ++j) { a[j] = sigmoidf_(a[j]); b[j] = sigmoidf_(b[j]); }
;                         if (bj == 0) { w.x = pack4_u8c(a); w.y = pack4_u8c(b); } else { w.z = pack4_u8c(a); w.w = pack4_u8c(b); } }
;                     gst[(ai * 4 + m) * 512 + tid] = w; MEMFENCE; }
	v_max_f32_e32 v111, 1.0, v111
	v_max_f32_e32 v110, 1.0, v110
	v_fma_f32 v108, v108, s4, 0.5
	v_fma_f32 v109, v109, s4, 0.5
	v_add_co_u32_e32 v104, vcc, s2, v120
	v_fma_f32 v94, v94, s4, 0.5
	v_rcp_f32_e32 v44, v44
	v_rcp_f32_e32 v45, v45
	v_rcp_f32_e32 v30, v30
	v_add_f32_e32 v28, 1.0, v28
	v_add_f32_e32 v29, 1.0, v29
	v_rcp_f32_e32 v24, v24
	v_rcp_f32_e32 v25, v25
	v_cvt_u32_f32_sdwa v124, v124 dst_sel:WORD_1 dst_unused:UNUSED_PAD src0_sel:DWORD
	v_cvt_u32_f32_sdwa v125, v125 dst_sel:BYTE_3 dst_unused:UNUSED_PAD src0_sel:DWORD
	v_cvt_u32_f32_e32 v111, v111
	v_cvt_u32_f32_e32 v110, v110
	v_max_f32_e32 v108, 1.0, v108
	v_max_f32_e32 v109, 1.0, v109
	v_addc_co_u32_e32 v105, vcc, 0, v121, vcc
	v_max_f32_e32 v95, 1.0, v95
	v_max_f32_e32 v94, 1.0, v94
	v_fma_f32 v92, v92, s4, 0.5
	v_fma_f32 v93, v93, s4, 0.5
	v_fma_f32 v78, v78, s4, 0.5
	v_rcp_f32_e32 v28, v28
	v_rcp_f32_e32 v29, v29
	v_cvt_u32_f32_sdwa v108, v108 dst_sel:WORD_1 dst_unused:UNUSED_PAD src0_sel:DWORD
	v_cvt_u32_f32_sdwa v109, v109 dst_sel:BYTE_3 dst_unused:UNUSED_PAD src0_sel:DWORD
	v_cvt_u32_f32_e32 v95, v95
	v_cvt_u32_f32_e32 v94, v94
	v_max_f32_e32 v92, 1.0, v92
	v_max_f32_e32 v93, 1.0, v93
	v_add_co_u32_e32 v88, vcc, s49, v120
	v_max_f32_e32 v79, 1.0, v79
	v_max_f32_e32 v78, 1.0, v78
	v_fma_f32 v76, v76, s4, 0.5
	v_fma_f32 v77, v77, s4, 0.5
	v_fma_f32 v62, v62, s4, 0.5
	v_cvt_u32_f32_sdwa v92, v92 dst_sel:WORD_1 dst_unused:UNUSED_PAD src0_sel:DWORD
	v_cvt_u32_f32_sdwa v93, v93 dst_sel:BYTE_3 dst_unused:UNUSED_PAD src0_sel:DWORD
	v_addc_co_u32_e32 v89, vcc, 0, v121, vcc
	v_cvt_u32_f32_e32 v79, v79
	v_cvt_u32_f32_e32 v78, v78
	v_max_f32_e32 v76, 1.0, v76
	v_max_f32_e32 v77, 1.0, v77
	s_movk_i32 s2, 0x6000
	v_max_f32_e32 v63, 1.0, v63
	v_max_f32_e32 v62, 1.0, v62
	v_fma_f32 v60, v60, s4, 0.5
	v_fma_f32 v61, v61, s4, 0.5
	v_fma_f32 v46, v46, s4, 0.5
	v_fma_f32 v27, v35, s4, 0.5
	v_fma_f32 v26, v26, s4, 0.5
	v_lshl_or_b32 v126, v127, 8, v126
	v_cvt_u32_f32_sdwa v76, v76 dst_sel:WORD_1 dst_unused:UNUSED_PAD src0_sel:DWORD
	v_cvt_u32_f32_sdwa v77, v77 dst_sel:BYTE_3 dst_unused:UNUSED_PAD src0_sel:DWORD
	v_add_co_u32_e32 v72, vcc, s2, v120
	v_cvt_u32_f32_e32 v63, v63
	v_cvt_u32_f32_e32 v62, v62
	v_max_f32_e32 v60, 1.0, v60
	v_max_f32_e32 v61, 1.0, v61
	v_max_f32_e32 v47, 1.0, v47
	v_max_f32_e32 v46, 1.0, v46
	v_fma_f32 v44, v44, s4, 0.5
	v_fma_f32 v45, v45, s4, 0.5
	v_fma_f32 v30, v30, s4, 0.5
	v_max_f32_e32 v27, 1.0, v27
	v_max_f32_e32 v26, 1.0, v26
	v_fma_f32 v24, v24, s4, 0.5
	v_fma_f32 v25, v25, s4, 0.5
	v_or3_b32 v130, v126, v124, v125
	v_lshl_or_b32 v110, v111, 8, v110
	v_addc_co_u32_e32 v73, vcc, 0, v121, vcc
	v_cvt_u32_f32_sdwa v60, v60 dst_sel:WORD_1 dst_unused:UNUSED_PAD src0_sel:DWORD
	v_cvt_u32_f32_sdwa v61, v61 dst_sel:BYTE_3 dst_unused:UNUSED_PAD src0_sel:DWORD
	v_cvt_u32_f32_e32 v47, v47
	v_cvt_u32_f32_e32 v46, v46
	v_max_f32_e32 v44, 1.0, v44
	v_max_f32_e32 v45, 1.0, v45
	v_max_f32_e32 v31, 1.0, v31
	v_max_f32_e32 v30, 1.0, v30
	v_fma_f32 v28, v28, s4, 0.5
	v_fma_f32 v29, v29, s4, 0.5
	v_cvt_u32_f32_e32 v27, v27
	v_cvt_u32_f32_e32 v26, v26
	v_max_f32_e32 v24, 1.0, v24
	v_max_f32_e32 v25, 1.0, v25
	global_store_dwordx4 v[120:121], v[128:131], off
	v_or3_b32 v114, v110, v108, v109
	v_lshl_or_b32 v94, v95, 8, v94
	v_add_co_u32_e32 v56, vcc, s77, v120
	v_cvt_u32_f32_sdwa v44, v44 dst_sel:WORD_1 dst_unused:UNUSED_PAD src0_sel:DWORD
	v_cvt_u32_f32_sdwa v45, v45 dst_sel:BYTE_3 dst_unused:UNUSED_PAD src0_sel:DWORD
	v_cvt_u32_f32_e32 v31, v31
	v_cvt_u32_f32_e32 v30, v30
	v_max_f32_e32 v28, 1.0, v28
	v_max_f32_e32 v29, 1.0, v29
	v_cvt_u32_f32_sdwa v24, v24 dst_sel:WORD_1 dst_unused:UNUSED_PAD src0_sel:DWORD
	v_cvt_u32_f32_sdwa v25, v25 dst_sel:BYTE_3 dst_unused:UNUSED_PAD src0_sel:DWORD
	global_store_dwordx4 v[104:105], v[112:115], off
	v_or3_b32 v98, v94, v92, v93
	v_lshl_or_b32 v78, v79, 8, v78
	v_addc_co_u32_e32 v57, vcc, 0, v121, vcc
	s_mov_b32 s2, 0xa000
	v_cvt_u32_f32_sdwa v28, v28 dst_sel:WORD_1 dst_unused:UNUSED_PAD src0_sel:DWORD
	v_cvt_u32_f32_sdwa v29, v29 dst_sel:BYTE_3 dst_unused:UNUSED_PAD src0_sel:DWORD
	global_store_dwordx4 v[88:89], v[96:99], off
	v_or3_b32 v82, v78, v76, v77
	v_lshl_or_b32 v62, v63, 8, v62
	v_add_co_u32_e32 v40, vcc, s2, v120
	global_store_dwordx4 v[72:73], v[80:83], off
	v_or3_b32 v66, v62, v60, v61
	v_lshl_or_b32 v46, v47, 8, v46
	v_addc_co_u32_e32 v41, vcc, 0, v121, vcc
	v_lshl_or_b32 v26, v27, 8, v26
	s_mov_b32 s2, 0xc000
	global_store_dwordx4 v[56:57], v[64:67], off
	v_or3_b32 v50, v46, v44, v45
	v_lshl_or_b32 v30, v31, 8, v30
	v_or3_b32 v35, v26, v24, v25
	v_add_co_u32_e32 v24, vcc, s2, v120
	global_store_dwordx4 v[40:41], v[48:51], off
	v_or3_b32 v34, v30, v28, v29
	v_addc_co_u32_e32 v25, vcc, 0, v121, vcc
	global_store_dwordx4 v[24:25], v[32:35], off
; __device__ __forceinline__ float sigmoidf_(float v) { return __builtin_amdgcn_rcpf(1.0f + __expf(-v)); }
; #define MEMFENCE asm volatile("" ::: "memory")
;     template <int KIND> __device__ __forceinline__ void run(f32x4 (&acc)[2][2][4][2], const Unit& u, int tid_in) const {
;     ...
;                 for (int m = 0; m < 4; ++m) { const float r = rs[ai * 4 + m] * (1.0f / GATE_WSCALE); u32x4 w;
; #pragma unroll
;                     for (int bj = 0; bj < 2; ++bj) { f32x4 a = acc[ai][bj][m][0] * r, b = acc[ai][bj][m][1] * r;
; #pragma unroll
;                         for (int j = 0; j < 4; ++j) { a[j] = sigmoidf_(a[j]); b[j] = sigmoidf_(b[j]); }
;                         if (bj == 0) { w.x = pack4_u8c(a); w.y = pack4_u8c(b); } else { w.z = pack4_u8c(a); w.w = pack4_u8c(b); } }
;                     gst[(ai * 4 + m) * 512 + tid] = w; MEMFENCE; }
;     ...
;         if (!has_next) break;
;         if (!(cs.kind == K_MG_B && cur.aux < 2))
; #pragma unroll
;         for (int a = 0; a < 2; ++a)
; #pragma unroll
;             for (int b = 0; b < 2; ++b)
; #pragma unroll
;                 for (int m = 0; m < 4; ++m)
; #pragma unroll
;                     for (int n = 0; n < 2; ++n) acc[a][b][m][n] = (f32x4){0.f, 0.f, 0.f, 0.f};
;         cur = nxt; cA = nA; cB = nB; ++ui;
	v_mul_f32_e32 v24, 0x3c800000, v137
	v_pk_mul_f32 v[20:21], v[20:21], v[24:25] op_sel_hi:[1,0]
	s_mov_b32 s33, s35
	v_mul_f32_e32 v21, 0xbfb8aa3b, v21
	v_exp_f32_e32 v21, v21
	v_mul_f32_e32 v20, 0xbfb8aa3b, v20
	v_exp_f32_e32 v25, v20
	s_mov_b32 s36, s34
	v_add_f32_e32 v20, 1.0, v21
	v_rcp_f32_e32 v26, v20
	v_pk_mul_f32 v[20:21], v[22:23], v[24:25] op_sel_hi:[1,0]
	v_add_f32_e32 v22, 1.0, v25
	v_mul_f32_e32 v20, 0xbfb8aa3b, v20
	v_exp_f32_e32 v20, v20
	v_rcp_f32_e32 v22, v22
	v_mul_f32_e32 v21, 0xbfb8aa3b, v21
	v_exp_f32_e32 v21, v21
	v_add_f32_e32 v20, 1.0, v20
	v_fma_f32 v23, v26, s4, 0.5
	v_fma_f32 v22, v22, s4, 0.5
	v_rcp_f32_e32 v20, v20
	v_max_f32_e32 v23, 1.0, v23
	v_max_f32_e32 v22, 1.0, v22
	v_add_f32_e32 v21, 1.0, v21
	v_cvt_u32_f32_e32 v23, v23
	v_cvt_u32_f32_e32 v22, v22
	v_rcp_f32_e32 v21, v21
	v_fma_f32 v20, v20, s4, 0.5
	v_max_f32_e32 v20, 1.0, v20
	v_lshl_or_b32 v22, v23, 8, v22
	v_cvt_u32_f32_sdwa v23, v20 dst_sel:WORD_1 dst_unused:UNUSED_PAD src0_sel:DWORD
	v_fma_f32 v20, v21, s4, 0.5
	v_max_f32_e32 v20, 1.0, v20
	v_cvt_u32_f32_sdwa v25, v20 dst_sel:BYTE_3 dst_unused:UNUSED_PAD src0_sel:DWORD
	s_mov_b64 s[12:13], s[10:11]
	s_mov_b64 s[2:3], s[8:9]
	v_pk_mul_f32 v[20:21], v[16:17], v[24:25] op_sel_hi:[1,0]
	s_nop 0
	v_mul_f32_e32 v16, 0xbfb8aa3b, v21
	v_mul_f32_e32 v20, 0xbfb8aa3b, v20
	v_pk_mul_f32 v[18:19], v[18:19], v[24:25] op_sel_hi:[1,0]
	v_exp_f32_e32 v17, v16
	v_exp_f32_e32 v20, v20
	v_mul_f32_e32 v18, 0xbfb8aa3b, v18
	v_mul_f32_e32 v19, 0xbfb8aa3b, v19
	v_exp_f32_e32 v18, v18
	v_exp_f32_e32 v19, v19
	v_add_f32_e32 v17, 1.0, v17
	v_add_f32_e32 v20, 1.0, v20
	v_rcp_f32_e32 v17, v17
	v_rcp_f32_e32 v20, v20
	v_add_f32_e32 v18, 1.0, v18
	v_add_f32_e32 v19, 1.0, v19
	v_rcp_f32_e32 v18, v18
	v_rcp_f32_e32 v19, v19
	v_fma_f32 v17, v17, s4, 0.5
	v_fma_f32 v20, v20, s4, 0.5
	v_max_f32_e32 v17, 1.0, v17
	v_max_f32_e32 v20, 1.0, v20
	v_fma_f32 v18, v18, s4, 0.5
	v_fma_f32 v19, v19, s4, 0.5
	v_pk_mul_f32 v[12:13], v[12:13], v[24:25] op_sel_hi:[1,0]
	v_cvt_u32_f32_e32 v17, v17
	v_cvt_u32_f32_e32 v20, v20
	v_max_f32_e32 v18, 1.0, v18
	v_max_f32_e32 v19, 1.0, v19
	v_mul_f32_e32 v13, 0xbfb8aa3b, v13
	v_cvt_u32_f32_sdwa v18, v18 dst_sel:WORD_1 dst_unused:UNUSED_PAD src0_sel:DWORD
	v_cvt_u32_f32_sdwa v19, v19 dst_sel:BYTE_3 dst_unused:UNUSED_PAD src0_sel:DWORD
	v_exp_f32_e32 v13, v13
	v_pk_mul_f32 v[8:9], v[8:9], v[24:25] op_sel_hi:[1,0]
	v_lshl_or_b32 v17, v17, 8, v20
	v_mul_f32_e32 v12, 0xbfb8aa3b, v12
	v_mul_f32_e32 v9, 0xbfb8aa3b, v9
	v_or3_b32 v17, v17, v18, v19
	v_exp_f32_e32 v18, v12
	v_add_f32_e32 v12, 1.0, v13
	v_exp_f32_e32 v9, v9
	v_rcp_f32_e32 v19, v12
	v_mul_f32_e32 v8, 0xbfb8aa3b, v8
	v_pk_mul_f32 v[12:13], v[14:15], v[24:25] op_sel_hi:[1,0]
	v_add_f32_e32 v14, 1.0, v18
	v_exp_f32_e32 v18, v8
	v_add_f32_e32 v8, 1.0, v9
	v_fma_f32 v15, v19, s4, 0.5
	v_rcp_f32_e32 v19, v8
	v_pk_mul_f32 v[8:9], v[10:11], v[24:25] op_sel_hi:[1,0]
	v_mul_f32_e32 v12, 0xbfb8aa3b, v12
	v_mul_f32_e32 v8, 0xbfb8aa3b, v8
	v_mul_f32_e32 v9, 0xbfb8aa3b, v9
	v_mul_f32_e32 v13, 0xbfb8aa3b, v13
	v_exp_f32_e32 v8, v8
	v_exp_f32_e32 v9, v9
	v_exp_f32_e32 v12, v12
	v_exp_f32_e32 v13, v13
	v_add_f32_e32 v10, 1.0, v18
	v_rcp_f32_e32 v10, v10
	v_add_f32_e32 v8, 1.0, v8
	v_add_f32_e32 v9, 1.0, v9
	v_rcp_f32_e32 v14, v14
	v_add_f32_e32 v12, 1.0, v12
	v_add_f32_e32 v13, 1.0, v13
	v_rcp_f32_e32 v8, v8
	v_rcp_f32_e32 v9, v9
	v_rcp_f32_e32 v12, v12
	v_rcp_f32_e32 v13, v13
	v_fma_f32 v11, v19, s4, 0.5
	v_fma_f32 v10, v10, s4, 0.5
	v_fma_f32 v14, v14, s4, 0.5
	v_max_f32_e32 v11, 1.0, v11
	v_max_f32_e32 v10, 1.0, v10
	v_fma_f32 v8, v8, s4, 0.5
	v_fma_f32 v9, v9, s4, 0.5
	v_max_f32_e32 v15, 1.0, v15
	v_max_f32_e32 v14, 1.0, v14
	v_fma_f32 v12, v12, s4, 0.5
	v_fma_f32 v13, v13, s4, 0.5
	v_cvt_u32_f32_e32 v11, v11
	v_cvt_u32_f32_e32 v10, v10
	v_max_f32_e32 v8, 1.0, v8
	v_max_f32_e32 v9, 1.0, v9
	v_cvt_u32_f32_e32 v15, v15
	v_cvt_u32_f32_e32 v14, v14
	v_max_f32_e32 v12, 1.0, v12
	v_max_f32_e32 v13, 1.0, v13
	v_cvt_u32_f32_sdwa v8, v8 dst_sel:WORD_1 dst_unused:UNUSED_PAD src0_sel:DWORD
	v_cvt_u32_f32_sdwa v9, v9 dst_sel:BYTE_3 dst_unused:UNUSED_PAD src0_sel:DWORD
	v_cvt_u32_f32_sdwa v12, v12 dst_sel:WORD_1 dst_unused:UNUSED_PAD src0_sel:DWORD
	v_cvt_u32_f32_sdwa v13, v13 dst_sel:BYTE_3 dst_unused:UNUSED_PAD src0_sel:DWORD
	v_lshl_or_b32 v10, v11, 8, v10
	v_lshl_or_b32 v14, v15, 8, v14
	v_or3_b32 v19, v10, v8, v9
	v_add_co_u32_e32 v8, vcc, 0xe000, v120
	v_or3_b32 v16, v22, v23, v25
	v_or3_b32 v18, v14, v12, v13
	v_addc_co_u32_e32 v9, vcc, 0, v121, vcc
	global_store_dwordx4 v[8:9], v[16:19], off
	s_and_b64 vcc, exec, s[6:7]
	s_cmpk_gt_u32 s101, 0xff
	s_cbranch_scc0 .Ldb_MG0_nob
	s_barrier
.Ldb_MG0_nob:
	s_cbranch_vccz .LBB0_867
	s_waitcnt vmcnt(0)
	s_cmpk_gt_u32 s16, 0xff
	s_cbranch_scc1 .LBB0_876
	s_barrier

; #define G_STAGE(bufoff, gbase, o0, h64) do { \
;         __builtin_amdgcn_global_load_lds((const unsigned*)((const char*)(gbase) + (o0)), (LAS unsigned*)(lds + (bufoff) + ldsw), 16, 0, 0); \
;         __builtin_amdgcn_global_load_lds((const unsigned*)((const char*)(gbase) + (h64) + (o0)), (LAS unsigned*)(lds + (bufoff) + ldsw + 8192), 16, 0, 0); } while (0)
; #define G_LDA(dst, b, h) do { _Pragma("unroll") for (int m = 0; m < 4; ++m) _Pragma("unroll") for (int k = 0; k < 2; ++k) dst[m][k] = *(const LAS bf16x8*)(lds + G_SA(b, h) + aoff + m * 2048 + k * 1024); } while (0)
; #define G_LDB(dst, b, h) do { _Pragma("unroll") for (int n = 0; n < 2; ++n) _Pragma("unroll") for (int k = 0; k < 2; ++k) dst[n][k] = *(const LAS bf16x8*)(lds + G_SB(b, h) + boff + n * 2048 + k * 1024); } while (0)
; #define G_WAIT_V(n) asm volatile("s_waitcnt vmcnt(" #n ")" ::: "memory")
; #define G_WAIT_L(n) asm volatile("s_waitcnt lgkmcnt(" #n ")" ::: "memory")
; #define G_BAR __builtin_amdgcn_s_barrier()
; #define G_SCHED __builtin_amdgcn_sched_barrier(0)
;     ...
;         for (int t = 0; t < nt; t += 2) {
;             const bool last = (t == nt - 2);
;             const char* a1 = cA + (size_t)(t + 1) * ckA;
;             const char* a2 = last ? nA : cA + (size_t)(t + 2) * ckA; const char* b2 = last ? nB : cB + (size_t)(t + 2) * kB;
;             const char* a3 = a2 + ckA; const char* b3 = b2 + kB;
;             G_LDB(B0, 0, 0); G_SCHED; G_LDA(At, 0, 0); G_STAGE(G_SA(1, 1), a1 + chA, cA0, qA);
;             G_WAIT_L(8); G_BAR; G_WAIT_L(0); G_MMA(0, 0, At, B0); G_BAR; G_SCHED;
;             G_LDB(B1, 0, 1); G_STAGE(G_SB(0, 0), b2, cB0, qB);
;             G_BAR; G_WAIT_L(0); G_MMA(0, 1, At, B1); G_BAR;
;             G_LDA(At, 0, 1); G_STAGE(G_SA(0, 0), a2, cA0, qA);
;             G_BAR; G_WAIT_L(0); G_MMA(1, 0, At, B0); G_BAR; G_SCHED;
;             G_STAGE(G_SB(0, 1), b2 + chB, cB0, qB);
;             G_WAIT_V(6); G_BAR; G_MMA(1, 1, At, B1); G_BAR;
.LBB0_890:
	s_add_u32 s4, s6, 0xfff50080
	s_addc_u32 s5, s7, -1
	s_add_i32 s19, 0, 0x10000
	v_add_u32_e32 v0, s19, v175
	ds_read_b128 v[136:139], v0
	ds_read_b128 v[140:143], v0 offset:1024
	ds_read_b128 v[144:147], v0 offset:2048
	ds_read_b128 v[148:151], v0 offset:3072
	s_cmp_eq_u32 s18, 4
	s_cselect_b32 s45, s15, s9
	s_cselect_b32 s44, s14, s8
	s_cselect_b32 s5, s13, s5
	s_cselect_b32 s4, s12, s4
	v_lshl_add_u64 v[2:3], s[6:7], 0, v[156:157]
	s_add_i32 m0, s22, 0xc000
	ds_read_b128 v[158:161], v176
	ds_read_b128 v[162:165], v176 offset:1024
	ds_read_b128 v[178:181], v176 offset:2048
	ds_read_b128 v[182:185], v176 offset:3072
	ds_read_b128 v[196:199], v176 offset:4096
	ds_read_b128 v[200:203], v176 offset:5120
	ds_read_b128 v[204:207], v176 offset:6144
	ds_read_b128 v[208:211], v176 offset:7168
	global_load_lds_dwordx4 v[2:3], off
	v_lshl_add_u64 v[2:3], v[2:3], 0, s[86:87]
	s_add_i32 m0, s22, 0xe000
	s_nop 0
	global_load_lds_dwordx4 v[2:3], off
	s_waitcnt lgkmcnt(8)
	s_barrier
	s_waitcnt lgkmcnt(0)
	s_setprio 3
	s_waitcnt lgkmcnt(0)
	v_mfma_f32_16x16x32_bf16 v[104:107], v[136:139], v[158:161], v[104:107]
	v_mfma_f32_16x16x32_bf16 v[108:111], v[144:147], v[158:161], v[108:111]
	v_mfma_f32_16x16x32_bf16 v[132:135], v[136:139], v[178:181], v[132:135]
	v_mfma_f32_16x16x32_bf16 v[128:131], v[144:147], v[178:181], v[128:131]
	v_mfma_f32_16x16x32_bf16 v[124:127], v[136:139], v[196:199], v[124:127]
	v_mfma_f32_16x16x32_bf16 v[120:123], v[144:147], v[196:199], v[120:123]
	v_mfma_f32_16x16x32_bf16 v[116:119], v[136:139], v[204:207], v[116:119]
	v_mfma_f32_16x16x32_bf16 v[112:115], v[144:147], v[204:207], v[112:115]
	v_mfma_f32_16x16x32_bf16 v[104:107], v[140:143], v[162:165], v[104:107]
	v_mfma_f32_16x16x32_bf16 v[108:111], v[148:151], v[162:165], v[108:111]
	v_mfma_f32_16x16x32_bf16 v[132:135], v[140:143], v[182:185], v[132:135]
	v_mfma_f32_16x16x32_bf16 v[128:131], v[148:151], v[182:185], v[128:131]
	v_mfma_f32_16x16x32_bf16 v[124:127], v[140:143], v[200:203], v[124:127]
	v_mfma_f32_16x16x32_bf16 v[120:123], v[148:151], v[200:203], v[120:123]
	v_mfma_f32_16x16x32_bf16 v[116:119], v[140:143], v[208:211], v[116:119]
	v_mfma_f32_16x16x32_bf16 v[112:115], v[148:151], v[208:211], v[112:115]
	s_setprio 0
	s_barrier
	s_add_i32 s43, 0, 0x14000
	s_add_i32 s19, s19, s21
	v_add_u32_e32 v0, s43, v175
	v_lshl_add_u64 v[2:3], s[44:45], 0, v[154:155]
	s_mov_b64 s[44:45], 0x10000
	s_mov_b32 m0, s19
	ds_read_b128 v[212:215], v0
	ds_read_b128 v[216:219], v0 offset:1024
	ds_read_b128 v[220:223], v0 offset:2048
	ds_read_b128 v[224:227], v0 offset:3072
	global_load_lds_dwordx4 v[2:3], off
	v_lshl_add_u64 v[166:167], v[2:3], 0, s[44:45]
	s_add_i32 m0, s19, 0x2000
	s_nop 0
	global_load_lds_dwordx4 v[166:167], off
	s_barrier
	s_waitcnt lgkmcnt(0)
	s_setprio 3
	s_waitcnt lgkmcnt(0)
	v_mfma_f32_16x16x32_bf16 v[100:103], v[212:215], v[158:161], v[100:103]
	v_mfma_f32_16x16x32_bf16 v[96:99], v[220:223], v[158:161], v[96:99]
	v_mfma_f32_16x16x32_bf16 v[92:95], v[212:215], v[178:181], v[92:95]
	v_mfma_f32_16x16x32_bf16 v[88:91], v[220:223], v[178:181], v[88:91]
	v_mfma_f32_16x16x32_bf16 v[84:87], v[212:215], v[196:199], v[84:87]
	v_mfma_f32_16x16x32_bf16 v[80:83], v[220:223], v[196:199], v[80:83]
	v_mfma_f32_16x16x32_bf16 v[76:79], v[212:215], v[204:207], v[76:79]
	v_mfma_f32_16x16x32_bf16 v[72:75], v[220:223], v[204:207], v[72:75]
	v_mfma_f32_16x16x32_bf16 v[100:103], v[216:219], v[162:165], v[100:103]
	v_mfma_f32_16x16x32_bf16 v[96:99], v[224:227], v[162:165], v[96:99]
	v_mfma_f32_16x16x32_bf16 v[92:95], v[216:219], v[182:185], v[92:95]
	v_mfma_f32_16x16x32_bf16 v[88:91], v[224:227], v[182:185], v[88:91]
	v_mfma_f32_16x16x32_bf16 v[84:87], v[216:219], v[200:203], v[84:87]
	v_mfma_f32_16x16x32_bf16 v[80:83], v[224:227], v[200:203], v[80:83]
	v_mfma_f32_16x16x32_bf16 v[76:79], v[216:219], v[208:211], v[76:79]
	v_mfma_f32_16x16x32_bf16 v[72:75], v[224:227], v[208:211], v[72:75]
	s_setprio 0
	s_mov_b32 m0, s22
	v_lshl_add_u64 v[166:167], s[4:5], 0, v[152:153]
	s_barrier
	ds_read_b128 v[158:161], v176 offset:16384
	ds_read_b128 v[162:165], v176 offset:17408
	ds_read_b128 v[178:181], v176 offset:18432
	ds_read_b128 v[182:185], v176 offset:19456
	ds_read_b128 v[196:199], v176 offset:20480
	ds_read_b128 v[200:203], v176 offset:21504
	ds_read_b128 v[204:207], v176 offset:22528
	ds_read_b128 v[208:211], v176 offset:23552
	global_load_lds_dwordx4 v[166:167], off
	v_lshl_add_u64 v[172:173], v[166:167], 0, s[86:87]
	s_mov_b32 m0, s23
	s_nop 0
	global_load_lds_dwordx4 v[172:173], off
	s_barrier
	s_waitcnt lgkmcnt(0)
	s_setprio 3
	s_waitcnt lgkmcnt(0)
	v_mfma_f32_16x16x32_bf16 v[68:71], v[136:139], v[158:161], v[68:71]
	v_mfma_f32_16x16x32_bf16 v[64:67], v[144:147], v[158:161], v[64:67]
	v_mfma_f32_16x16x32_bf16 v[60:63], v[136:139], v[178:181], v[60:63]
	v_mfma_f32_16x16x32_bf16 v[56:59], v[144:147], v[178:181], v[56:59]
	v_mfma_f32_16x16x32_bf16 v[52:55], v[136:139], v[196:199], v[52:55]
	v_mfma_f32_16x16x32_bf16 v[48:51], v[144:147], v[196:199], v[48:51]
	v_mfma_f32_16x16x32_bf16 v[44:47], v[136:139], v[204:207], v[44:47]
	v_mfma_f32_16x16x32_bf16 v[40:43], v[144:147], v[204:207], v[40:43]
	v_mfma_f32_16x16x32_bf16 v[68:71], v[140:143], v[162:165], v[68:71]
	v_mfma_f32_16x16x32_bf16 v[64:67], v[148:151], v[162:165], v[64:67]
	v_mfma_f32_16x16x32_bf16 v[60:63], v[140:143], v[182:185], v[60:63]
	v_mfma_f32_16x16x32_bf16 v[56:59], v[148:151], v[182:185], v[56:59]
	v_mfma_f32_16x16x32_bf16 v[52:55], v[140:143], v[200:203], v[52:55]
	v_mfma_f32_16x16x32_bf16 v[48:51], v[148:151], v[200:203], v[48:51]
	v_mfma_f32_16x16x32_bf16 v[44:47], v[140:143], v[208:211], v[44:47]
	v_mfma_f32_16x16x32_bf16 v[40:43], v[148:151], v[208:211], v[40:43]
	s_setprio 0
	s_barrier
; #define G_STAGE(bufoff, gbase, o0, h64) do { \
;         __builtin_amdgcn_global_load_lds((const unsigned*)((const char*)(gbase) + (o0)), (LAS unsigned*)(lds + (bufoff) + ldsw), 16, 0, 0); \
;         __builtin_amdgcn_global_load_lds((const unsigned*)((const char*)(gbase) + (h64) + (o0)), (LAS unsigned*)(lds + (bufoff) + ldsw + 8192), 16, 0, 0); } while (0)
; #define G_LDA(dst, b, h) do { _Pragma("unroll") for (int m = 0; m < 4; ++m) _Pragma("unroll") for (int k = 0; k < 2; ++k) dst[m][k] = *(const LAS bf16x8*)(lds + G_SA(b, h) + aoff + m * 2048 + k * 1024); } while (0)
; #define G_LDB(dst, b, h) do { _Pragma("unroll") for (int n = 0; n < 2; ++n) _Pragma("unroll") for (int k = 0; k < 2; ++k) dst[n][k] = *(const LAS bf16x8*)(lds + G_SB(b, h) + boff + n * 2048 + k * 1024); } while (0)
; #define G_WAIT_V(n) asm volatile("s_waitcnt vmcnt(" #n ")" ::: "memory")
; #define G_WAIT_L(n) asm volatile("s_waitcnt lgkmcnt(" #n ")" ::: "memory")
; #define G_BAR __builtin_amdgcn_s_barrier()
; #define G_SCHED __builtin_amdgcn_sched_barrier(0)
;     ...
;             G_STAGE(G_SB(0, 1), b2 + chB, cB0, qB);
;             G_WAIT_V(6); G_BAR; G_MMA(1, 1, At, B1); G_BAR;
;             G_LDB(B0, 1, 0); G_SCHED; G_LDA(At, 1, 0); G_STAGE(G_SA(0, 1), a2 + chA, cA0, qA);
;             G_WAIT_L(8); G_BAR; G_WAIT_L(0); G_MMA(0, 0, At, B0); G_BAR; G_SCHED;
;             G_LDB(B1, 1, 1); G_STAGE(G_SB(1, 0), b3, cB0, qB);
;             G_BAR; G_WAIT_L(0); G_MMA(0, 1, At, B1); G_BAR;
;             G_LDA(At, 1, 1); G_STAGE(G_SA(1, 0), a3, cA0, qA);
;             G_BAR; G_WAIT_L(0); G_MMA(1, 0, At, B0); G_BAR; G_SCHED;
	s_add_i32 s4, s43, s21
	v_lshl_add_u64 v[136:137], v[2:3], 0, s[0:1]
	s_mov_b32 m0, s4
	s_nop 0
	global_load_lds_dwordx4 v[136:137], off
	v_lshl_add_u64 v[136:137], v[2:3], 0, s[52:53]
	s_add_i32 m0, s4, 0x2000
	s_nop 0
	global_load_lds_dwordx4 v[136:137], off
	s_waitcnt vmcnt(6)
	s_barrier
	s_setprio 3
	v_mfma_f32_16x16x32_bf16 v[36:39], v[212:215], v[158:161], v[36:39]
	v_mfma_f32_16x16x32_bf16 v[32:35], v[220:223], v[158:161], v[32:35]
	v_mfma_f32_16x16x32_bf16 v[28:31], v[212:215], v[178:181], v[28:31]
	v_mfma_f32_16x16x32_bf16 v[24:27], v[220:223], v[178:181], v[24:27]
	v_mfma_f32_16x16x32_bf16 v[20:23], v[212:215], v[196:199], v[20:23]
	v_mfma_f32_16x16x32_bf16 v[16:19], v[220:223], v[196:199], v[16:19]
	v_mfma_f32_16x16x32_bf16 v[12:15], v[212:215], v[204:207], v[12:15]
	v_mfma_f32_16x16x32_bf16 v[8:11], v[220:223], v[204:207], v[8:11]
	v_mfma_f32_16x16x32_bf16 v[36:39], v[216:219], v[162:165], v[36:39]
	v_mfma_f32_16x16x32_bf16 v[32:35], v[224:227], v[162:165], v[32:35]
	v_mfma_f32_16x16x32_bf16 v[28:31], v[216:219], v[182:185], v[28:31]
	v_mfma_f32_16x16x32_bf16 v[24:27], v[224:227], v[182:185], v[24:27]
	v_mfma_f32_16x16x32_bf16 v[20:23], v[216:219], v[200:203], v[20:23]
	v_mfma_f32_16x16x32_bf16 v[16:19], v[224:227], v[200:203], v[16:19]
	v_mfma_f32_16x16x32_bf16 v[12:15], v[216:219], v[208:211], v[12:15]
	v_mfma_f32_16x16x32_bf16 v[8:11], v[224:227], v[208:211], v[8:11]
	s_setprio 0
	s_add_i32 s4, 0, 0x18000
	v_add_u32_e32 v0, s4, v175
	s_barrier
	ds_read_b128 v[136:139], v0
	ds_read_b128 v[140:143], v0 offset:1024
	ds_read_b128 v[144:147], v0 offset:2048
	ds_read_b128 v[148:151], v0 offset:3072
	s_mov_b32 m0, s24
	v_lshl_add_u64 v[172:173], v[166:167], 0, s[88:89]
	ds_read_b128 v[158:161], v176 offset:32768
	ds_read_b128 v[162:165], v176 offset:33792
	ds_read_b128 v[178:181], v176 offset:34816
	ds_read_b128 v[182:185], v176 offset:35840
	ds_read_b128 v[196:199], v176 offset:36864
	ds_read_b128 v[200:203], v176 offset:37888
	ds_read_b128 v[204:207], v176 offset:38912
	ds_read_b128 v[208:211], v176 offset:39936
	global_load_lds_dwordx4 v[172:173], off
	v_lshl_add_u64 v[172:173], v[166:167], 0, s[64:65]
	s_mov_b32 m0, s25
	s_nop 0
	global_load_lds_dwordx4 v[172:173], off
	s_waitcnt lgkmcnt(8)
	s_barrier
	s_waitcnt lgkmcnt(0)
	s_setprio 3
	s_waitcnt lgkmcnt(0)
	v_mfma_f32_16x16x32_bf16 v[104:107], v[136:139], v[158:161], v[104:107]
	v_mfma_f32_16x16x32_bf16 v[108:111], v[144:147], v[158:161], v[108:111]
	v_mfma_f32_16x16x32_bf16 v[132:135], v[136:139], v[178:181], v[132:135]
	v_mfma_f32_16x16x32_bf16 v[128:131], v[144:147], v[178:181], v[128:131]
	v_mfma_f32_16x16x32_bf16 v[124:127], v[136:139], v[196:199], v[124:127]
	v_mfma_f32_16x16x32_bf16 v[120:123], v[144:147], v[196:199], v[120:123]
	v_mfma_f32_16x16x32_bf16 v[116:119], v[136:139], v[204:207], v[116:119]
	v_mfma_f32_16x16x32_bf16 v[112:115], v[144:147], v[204:207], v[112:115]
	v_mfma_f32_16x16x32_bf16 v[104:107], v[140:143], v[162:165], v[104:107]
	v_mfma_f32_16x16x32_bf16 v[108:111], v[148:151], v[162:165], v[108:111]
	v_mfma_f32_16x16x32_bf16 v[132:135], v[140:143], v[182:185], v[132:135]
	v_mfma_f32_16x16x32_bf16 v[128:131], v[148:151], v[182:185], v[128:131]
	v_mfma_f32_16x16x32_bf16 v[124:127], v[140:143], v[200:203], v[124:127]
	v_mfma_f32_16x16x32_bf16 v[120:123], v[148:151], v[200:203], v[120:123]
	v_mfma_f32_16x16x32_bf16 v[116:119], v[140:143], v[208:211], v[116:119]
	v_mfma_f32_16x16x32_bf16 v[112:115], v[148:151], v[208:211], v[112:115]
	s_setprio 0
	s_barrier
	s_add_i32 s5, 0, 0x1c000
	s_add_i32 s4, s4, s21
	v_add_u32_e32 v0, s5, v175
	v_lshl_add_u64 v[172:173], v[2:3], 0, s[46:47]
	s_mov_b32 m0, s4
	ds_read_b128 v[212:215], v0
	ds_read_b128 v[216:219], v0 offset:1024
	ds_read_b128 v[220:223], v0 offset:2048
	ds_read_b128 v[224:227], v0 offset:3072
	global_load_lds_dwordx4 v[172:173], off
	v_lshl_add_u64 v[172:173], v[2:3], 0, s[54:55]
	s_add_i32 m0, s4, 0x2000
	s_nop 0
	global_load_lds_dwordx4 v[172:173], off
	s_barrier
; #define G_STAGE(bufoff, gbase, o0, h64) do { \
;         __builtin_amdgcn_global_load_lds((const unsigned*)((const char*)(gbase) + (o0)), (LAS unsigned*)(lds + (bufoff) + ldsw), 16, 0, 0); \
;         __builtin_amdgcn_global_load_lds((const unsigned*)((const char*)(gbase) + (h64) + (o0)), (LAS unsigned*)(lds + (bufoff) + ldsw + 8192), 16, 0, 0); } while (0)
; #define G_LDA(dst, b, h) do { _Pragma("unroll") for (int m = 0; m < 4; ++m) _Pragma("unroll") for (int k = 0; k < 2; ++k) dst[m][k] = *(const LAS bf16x8*)(lds + G_SA(b, h) + aoff + m * 2048 + k * 1024); } while (0)
; #define G_WAIT_V(n) asm volatile("s_waitcnt vmcnt(" #n ")" ::: "memory")
; #define G_WAIT_L(n) asm volatile("s_waitcnt lgkmcnt(" #n ")" ::: "memory")
; #define G_BAR __builtin_amdgcn_s_barrier()
; #define G_SCHED __builtin_amdgcn_sched_barrier(0)
;     ...
;             G_BAR; G_WAIT_L(0); G_MMA(0, 1, At, B1); G_BAR;
;             G_LDA(At, 1, 1); G_STAGE(G_SA(1, 0), a3, cA0, qA);
;             G_BAR; G_WAIT_L(0); G_MMA(1, 0, At, B0); G_BAR; G_SCHED;
;             G_STAGE(G_SB(1, 1), b3 + chB, cB0, qB);
;             G_WAIT_V(6); G_BAR; G_MMA(1, 1, At, B1); G_BAR;
;         }
	s_waitcnt lgkmcnt(0)
	s_setprio 3
	s_waitcnt lgkmcnt(0)
	v_mfma_f32_16x16x32_bf16 v[100:103], v[212:215], v[158:161], v[100:103]
	v_mfma_f32_16x16x32_bf16 v[96:99], v[220:223], v[158:161], v[96:99]
	v_mfma_f32_16x16x32_bf16 v[92:95], v[212:215], v[178:181], v[92:95]
	v_mfma_f32_16x16x32_bf16 v[88:91], v[220:223], v[178:181], v[88:91]
	v_mfma_f32_16x16x32_bf16 v[84:87], v[212:215], v[196:199], v[84:87]
	v_mfma_f32_16x16x32_bf16 v[80:83], v[220:223], v[196:199], v[80:83]
	v_mfma_f32_16x16x32_bf16 v[76:79], v[212:215], v[204:207], v[76:79]
	v_mfma_f32_16x16x32_bf16 v[72:75], v[220:223], v[204:207], v[72:75]
	v_mfma_f32_16x16x32_bf16 v[100:103], v[216:219], v[162:165], v[100:103]
	v_mfma_f32_16x16x32_bf16 v[96:99], v[224:227], v[162:165], v[96:99]
	v_mfma_f32_16x16x32_bf16 v[92:95], v[216:219], v[182:185], v[92:95]
	v_mfma_f32_16x16x32_bf16 v[88:91], v[224:227], v[182:185], v[88:91]
	v_mfma_f32_16x16x32_bf16 v[84:87], v[216:219], v[200:203], v[84:87]
	v_mfma_f32_16x16x32_bf16 v[80:83], v[224:227], v[200:203], v[80:83]
	v_mfma_f32_16x16x32_bf16 v[76:79], v[216:219], v[208:211], v[76:79]
	v_mfma_f32_16x16x32_bf16 v[72:75], v[224:227], v[208:211], v[72:75]
	s_setprio 0
	s_mov_b32 m0, s26
	v_lshl_add_u64 v[172:173], v[166:167], 0, s[46:47]
	s_barrier
	ds_read_b128 v[158:161], v176 offset:49152
	ds_read_b128 v[162:165], v176 offset:50176
	ds_read_b128 v[178:181], v176 offset:51200
	ds_read_b128 v[182:185], v176 offset:52224
	ds_read_b128 v[196:199], v176 offset:53248
	ds_read_b128 v[200:203], v176 offset:54272
	ds_read_b128 v[204:207], v176 offset:55296
	ds_read_b128 v[208:211], v176 offset:56320
	global_load_lds_dwordx4 v[172:173], off
	v_lshl_add_u64 v[166:167], v[166:167], 0, s[66:67]
	s_mov_b32 m0, s27
	s_nop 0
	global_load_lds_dwordx4 v[166:167], off
	s_barrier
	s_waitcnt lgkmcnt(0)
	s_setprio 3
	s_waitcnt lgkmcnt(0)
	v_mfma_f32_16x16x32_bf16 v[68:71], v[136:139], v[158:161], v[68:71]
	v_mfma_f32_16x16x32_bf16 v[64:67], v[144:147], v[158:161], v[64:67]
	v_mfma_f32_16x16x32_bf16 v[60:63], v[136:139], v[178:181], v[60:63]
	v_mfma_f32_16x16x32_bf16 v[56:59], v[144:147], v[178:181], v[56:59]
	v_mfma_f32_16x16x32_bf16 v[52:55], v[136:139], v[196:199], v[52:55]
	v_mfma_f32_16x16x32_bf16 v[48:51], v[144:147], v[196:199], v[48:51]
	v_mfma_f32_16x16x32_bf16 v[44:47], v[136:139], v[204:207], v[44:47]
	v_mfma_f32_16x16x32_bf16 v[40:43], v[144:147], v[204:207], v[40:43]
	v_mfma_f32_16x16x32_bf16 v[68:71], v[140:143], v[162:165], v[68:71]
	v_mfma_f32_16x16x32_bf16 v[64:67], v[148:151], v[162:165], v[64:67]
	v_mfma_f32_16x16x32_bf16 v[60:63], v[140:143], v[182:185], v[60:63]
	v_mfma_f32_16x16x32_bf16 v[56:59], v[148:151], v[182:185], v[56:59]
	v_mfma_f32_16x16x32_bf16 v[52:55], v[140:143], v[200:203], v[52:55]
	v_mfma_f32_16x16x32_bf16 v[48:51], v[148:151], v[200:203], v[48:51]
	v_mfma_f32_16x16x32_bf16 v[44:47], v[140:143], v[208:211], v[44:47]
	v_mfma_f32_16x16x32_bf16 v[40:43], v[148:151], v[208:211], v[40:43]
	s_setprio 0
	s_barrier
	s_add_i32 s4, s5, s21
	v_lshl_add_u64 v[136:137], v[2:3], 0, s[50:51]
	s_mov_b32 m0, s4
	v_lshl_add_u64 v[2:3], v[2:3], 0, s[58:59]
	global_load_lds_dwordx4 v[136:137], off
	s_add_i32 m0, s4, 0x2000
	s_nop 0
	global_load_lds_dwordx4 v[2:3], off
	s_waitcnt vmcnt(6)
	s_barrier
	s_setprio 3
	v_mfma_f32_16x16x32_bf16 v[36:39], v[212:215], v[158:161], v[36:39]
	v_mfma_f32_16x16x32_bf16 v[32:35], v[220:223], v[158:161], v[32:35]
	v_mfma_f32_16x16x32_bf16 v[28:31], v[212:215], v[178:181], v[28:31]
	v_mfma_f32_16x16x32_bf16 v[24:27], v[220:223], v[178:181], v[24:27]
	v_mfma_f32_16x16x32_bf16 v[20:23], v[212:215], v[196:199], v[20:23]
	v_mfma_f32_16x16x32_bf16 v[16:19], v[220:223], v[196:199], v[16:19]
	v_mfma_f32_16x16x32_bf16 v[12:15], v[212:215], v[204:207], v[12:15]
	v_mfma_f32_16x16x32_bf16 v[8:11], v[220:223], v[204:207], v[8:11]
	v_mfma_f32_16x16x32_bf16 v[36:39], v[216:219], v[162:165], v[36:39]
	v_mfma_f32_16x16x32_bf16 v[32:35], v[224:227], v[162:165], v[32:35]
	v_mfma_f32_16x16x32_bf16 v[28:31], v[216:219], v[182:185], v[28:31]
	v_mfma_f32_16x16x32_bf16 v[24:27], v[224:227], v[182:185], v[24:27]
	v_mfma_f32_16x16x32_bf16 v[20:23], v[216:219], v[200:203], v[20:23]
	v_mfma_f32_16x16x32_bf16 v[16:19], v[224:227], v[200:203], v[16:19]
	v_mfma_f32_16x16x32_bf16 v[12:15], v[216:219], v[208:211], v[12:15]
	v_mfma_f32_16x16x32_bf16 v[8:11], v[224:227], v[208:211], v[8:11]
	s_setprio 0
	s_add_i32 s18, s18, 2
	s_add_u32 s6, s6, 0x100
	s_addc_u32 s7, s7, 0
	s_add_u32 s8, s8, 0x100
	s_addc_u32 s9, s9, 0
	s_cmp_gt_u32 s18, 5
	s_cbranch_scc0 .Ldb_MG1_cont
	v_readfirstlane_b32 s101, v186
	s_cmpk_gt_u32 s101, 0xff
	s_cbranch_scc1 .Ldb_MG1_exit
	s_barrier
	s_branch .Ldb_MG1_exit

;     template <int KIND> __device__ __forceinline__ void run(f32x4 (&acc)[2][2][4][2], const Unit& u, int tid_in) const {
;     ...
;         if constexpr (KIND == K_MG_B) { const int r = u.aux;
;             const u32x4* gst = (const u32x4*)((unsigned char*)x + 32 * MiB) + ((size_t)(blockIdx.x * 2 + (u.ord & 1)) * 3) * 4096;
; #pragma unroll
;             for (int ai = 0; ai < 2; ++ai)
; #pragma unroll
;                 for (int mh = 0; mh < 2; ++mh) { u32x4 qa[2], qb[2];
; #pragma unroll
;                     for (int ml = 0; ml < 2; ++ml) { const int m = mh * 2 + ml; qa[ml] = gst[(size_t)r * 4096 + (ai * 4 + m) * 512 + tid]; qb[ml] = (r < 2) ? gst[(size_t)(r + 1) * 4096 + (ai * 4 + m) * 512 + tid] : qa[ml]; }
; #pragma unroll
;                     for (int ml = 0; ml < 2; ++ml) { const int m = mh * 2 + ml; int row = rbase + ai * 128 + m * 16; asm volatile("" : "+v"(row));
; #pragma unroll
;                         for (int bj = 0; bj < 2; ++bj) {
;                             const f32x4 n0 = unpack4_raw(bj == 0 ? qa[ml].x : qa[ml].z), n1 = unpack4_raw(bj == 0 ? qa[ml].y : qa[ml].w);
;                             if (r < 2) { const f32x4 d0 = unpack4_raw(bj == 0 ? qb[ml].x : qb[ml].z), d1 = unpack4_raw(bj == 0 ? qb[ml].y : qb[ml].w);
; #pragma unroll
;                                 for (int j = 0; j < 4; ++j) { acc[ai][bj][m][0][j] *= n0[j] * __builtin_amdgcn_rcpf(d0[j]); acc[ai][bj][m][1][j] *= n1[j] * __builtin_amdgcn_rcpf(d1[j]); } }
.Ldb_MG1_exit:
	s_and_b32 s3, s3, 1
	s_or_b32 s3, s3, s60
	s_mul_hi_u32 s4, s3, 0x30000
	s_mul_i32 s3, s3, 0x30000
	s_add_u32 s6, s35, s3
	s_addc_u32 s7, s36, s4
	s_ashr_i32 s3, s2, 31
	s_lshl_b64 s[4:5], s[2:3], 16
	s_add_u32 s4, s6, s4
	s_addc_u32 s5, s7, s5
	v_lshlrev_b32_e32 v166, 4, v174
	s_cmp_gt_i32 s2, 1
	s_cbranch_scc1 .Lmg1_r2
	s_add_u32 s8, s4, 0x10000
	s_addc_u32 s9, s5, 0
	global_load_dwordx4 v[136:139], v166, s[4:5]
	global_load_dwordx4 v[212:215], v166, s[8:9]
	s_add_u32 s4, s4, 0x2000
	s_addc_u32 s5, s5, 0
	s_add_u32 s8, s8, 0x2000
	s_addc_u32 s9, s9, 0
	global_load_dwordx4 v[140:143], v166, s[4:5]
	global_load_dwordx4 v[216:219], v166, s[8:9]
	s_add_u32 s4, s4, 0x2000
	s_addc_u32 s5, s5, 0
	s_add_u32 s8, s8, 0x2000
	s_addc_u32 s9, s9, 0
	global_load_dwordx4 v[144:147], v166, s[4:5]
	global_load_dwordx4 v[220:223], v166, s[8:9]
	s_add_u32 s4, s4, 0x2000
	s_addc_u32 s5, s5, 0
	s_add_u32 s8, s8, 0x2000
	s_addc_u32 s9, s9, 0
	global_load_dwordx4 v[148:151], v166, s[4:5]
	global_load_dwordx4 v[224:227], v166, s[8:9]
	s_add_u32 s4, s4, 0x2000
	s_addc_u32 s5, s5, 0
	s_add_u32 s8, s8, 0x2000
	s_addc_u32 s9, s9, 0
	global_load_dwordx4 v[196:199], v166, s[4:5]
	global_load_dwordx4 v[178:181], v166, s[8:9]
	s_add_u32 s4, s4, 0x2000
	s_addc_u32 s5, s5, 0
	s_add_u32 s8, s8, 0x2000
	s_addc_u32 s9, s9, 0
	global_load_dwordx4 v[200:203], v166, s[4:5]
	global_load_dwordx4 v[182:185], v166, s[8:9]
	s_add_u32 s4, s4, 0x2000
	s_addc_u32 s5, s5, 0
	s_add_u32 s8, s8, 0x2000
	s_addc_u32 s9, s9, 0
	global_load_dwordx4 v[204:207], v166, s[4:5]
	global_load_dwordx4 v[158:161], v166, s[8:9]
	s_add_u32 s4, s4, 0x2000
	s_addc_u32 s5, s5, 0
	s_add_u32 s8, s8, 0x2000
	s_addc_u32 s9, s9, 0
	global_load_dwordx4 v[208:211], v166, s[4:5]
	global_load_dwordx4 v[162:165], v166, s[8:9]
	s_waitcnt vmcnt(14)
	v_cvt_f32_ubyte0_e32 v240, v136
	v_cvt_f32_ubyte1_e32 v241, v136
	v_cvt_f32_ubyte2_e32 v242, v136
	v_cvt_f32_ubyte3_e32 v243, v136
	v_cvt_f32_ubyte0_e32 v244, v137
	v_cvt_f32_ubyte1_e32 v245, v137
	v_cvt_f32_ubyte2_e32 v246, v137
	v_cvt_f32_ubyte3_e32 v247, v137
	v_cvt_f32_ubyte0_e32 v248, v212
	v_cvt_f32_ubyte1_e32 v249, v212
	v_cvt_f32_ubyte2_e32 v250, v212
	v_cvt_f32_ubyte3_e32 v251, v212
	v_cvt_f32_ubyte0_e32 v252, v213
	v_cvt_f32_ubyte1_e32 v253, v213
	v_cvt_f32_ubyte2_e32 v254, v213
	v_cvt_f32_ubyte3_e32 v255, v213
	v_rcp_iflag_f32_e32 v248, v248
	v_rcp_iflag_f32_e32 v249, v249
	v_rcp_iflag_f32_e32 v250, v250
	v_rcp_iflag_f32_e32 v251, v251
	v_rcp_iflag_f32_e32 v252, v252
	v_rcp_iflag_f32_e32 v253, v253
	v_rcp_iflag_f32_e32 v254, v254
	v_rcp_iflag_f32_e32 v255, v255
	v_pk_mul_f32 v[240:241], v[248:249], v[240:241]
	v_pk_mul_f32 v[242:243], v[250:251], v[242:243]
	v_pk_mul_f32 v[244:245], v[252:253], v[244:245]
	v_pk_mul_f32 v[246:247], v[254:255], v[246:247]
	v_pk_mul_f32 v[104:105], v[104:105], v[240:241]
	v_pk_mul_f32 v[106:107], v[106:107], v[242:243]
	v_pk_mul_f32 v[108:109], v[108:109], v[244:245]
	v_pk_mul_f32 v[110:111], v[110:111], v[246:247]
	v_cvt_f32_ubyte0_e32 v240, v138
	v_cvt_f32_ubyte1_e32 v241, v138
	v_cvt_f32_ubyte2_e32 v242, v138
	v_cvt_f32_ubyte3_e32 v243, v138
	v_cvt_f32_ubyte0_e32 v244, v139
	v_cvt_f32_ubyte1_e32 v245, v139
	v_cvt_f32_ubyte2_e32 v246, v139
	v_cvt_f32_ubyte3_e32 v247, v139
	v_cvt_f32_ubyte0_e32 v248, v214
	v_cvt_f32_ubyte1_e32 v249, v214
	v_cvt_f32_ubyte2_e32 v250, v214
	v_cvt_f32_ubyte3_e32 v251, v214
	v_cvt_f32_ubyte0_e32 v252, v215
	v_cvt_f32_ubyte1_e32 v253, v215
	v_cvt_f32_ubyte2_e32 v254, v215
	v_cvt_f32_ubyte3_e32 v255, v215
	v_rcp_iflag_f32_e32 v248, v248
	v_rcp_iflag_f32_e32 v249, v249
	v_rcp_iflag_f32_e32 v250, v250
	v_rcp_iflag_f32_e32 v251, v251
	v_rcp_iflag_f32_e32 v252, v252
	v_rcp_iflag_f32_e32 v253, v253
	v_rcp_iflag_f32_e32 v254, v254
	v_rcp_iflag_f32_e32 v255, v255
	v_pk_mul_f32 v[240:241], v[248:249], v[240:241]
	v_pk_mul_f32 v[242:243], v[250:251], v[242:243]
	v_pk_mul_f32 v[244:245], v[252:253], v[244:245]
	v_pk_mul_f32 v[246:247], v[254:255], v[246:247]
	v_pk_mul_f32 v[100:101], v[100:101], v[240:241]
	v_pk_mul_f32 v[102:103], v[102:103], v[242:243]
	v_pk_mul_f32 v[96:97], v[96:97], v[244:245]
	v_pk_mul_f32 v[98:99], v[98:99], v[246:247]
	s_waitcnt vmcnt(12)
	v_cvt_f32_ubyte0_e32 v240, v140
	v_cvt_f32_ubyte1_e32 v241, v140
	v_cvt_f32_ubyte2_e32 v242, v140
	v_cvt_f32_ubyte3_e32 v243, v140
	v_cvt_f32_ubyte0_e32 v244, v141
	v_cvt_f32_ubyte1_e32 v245, v141
	v_cvt_f32_ubyte2_e32 v246, v141
	v_cvt_f32_ubyte3_e32 v247, v141
	v_cvt_f32_ubyte0_e32 v248, v216
	v_cvt_f32_ubyte1_e32 v249, v216
	v_cvt_f32_ubyte2_e32 v250, v216
	v_cvt_f32_ubyte3_e32 v251, v216
	v_cvt_f32_ubyte0_e32 v252, v217
	v_cvt_f32_ubyte1_e32 v253, v217
	v_cvt_f32_ubyte2_e32 v254, v217
	v_cvt_f32_ubyte3_e32 v255, v217
	v_rcp_iflag_f32_e32 v248, v248
	v_rcp_iflag_f32_e32 v249, v249
	v_rcp_iflag_f32_e32 v250, v250
	v_rcp_iflag_f32_e32 v251, v251
	v_rcp_iflag_f32_e32 v252, v252
	v_rcp_iflag_f32_e32 v253, v253
	v_rcp_iflag_f32_e32 v254, v254
	v_rcp_iflag_f32_e32 v255, v255
	v_pk_mul_f32 v[240:241], v[248:249], v[240:241]
	v_pk_mul_f32 v[242:243], v[250:251], v[242:243]
	v_pk_mul_f32 v[244:245], v[252:253], v[244:245]
	v_pk_mul_f32 v[246:247], v[254:255], v[246:247]
	v_pk_mul_f32 v[132:133], v[132:133], v[240:241]
	v_pk_mul_f32 v[134:135], v[134:135], v[242:243]
	v_pk_mul_f32 v[128:129], v[128:129], v[244:245]
	v_pk_mul_f32 v[130:131], v[130:131], v[246:247]
	v_cvt_f32_ubyte0_e32 v240, v142
	v_cvt_f32_ubyte1_e32 v241, v142
	v_cvt_f32_ubyte2_e32 v242, v142
	v_cvt_f32_ubyte3_e32 v243, v142
	v_cvt_f32_ubyte0_e32 v244, v143
	v_cvt_f32_ubyte1_e32 v245, v143
	v_cvt_f32_ubyte2_e32 v246, v143
	v_cvt_f32_ubyte3_e32 v247, v143
	v_cvt_f32_ubyte0_e32 v248, v218
	v_cvt_f32_ubyte1_e32 v249, v218
	v_cvt_f32_ubyte2_e32 v250, v218
	v_cvt_f32_ubyte3_e32 v251, v218
	v_cvt_f32_ubyte0_e32 v252, v219
	v_cvt_f32_ubyte1_e32 v253, v219
	v_cvt_f32_ubyte2_e32 v254, v219
	v_cvt_f32_ubyte3_e32 v255, v219
	v_rcp_iflag_f32_e32 v248, v248
	v_rcp_iflag_f32_e32 v249, v249
	v_rcp_iflag_f32_e32 v250, v250
	v_rcp_iflag_f32_e32 v251, v251
	v_rcp_iflag_f32_e32 v252, v252
	v_rcp_iflag_f32_e32 v253, v253
	v_rcp_iflag_f32_e32 v254, v254
	v_rcp_iflag_f32_e32 v255, v255
	v_pk_mul_f32 v[240:241], v[248:249], v[240:241]
	v_pk_mul_f32 v[242:243], v[250:251], v[242:243]
	v_pk_mul_f32 v[244:245], v[252:253], v[244:245]
	v_pk_mul_f32 v[246:247], v[254:255], v[246:247]
	v_pk_mul_f32 v[92:93], v[92:93], v[240:241]
	v_pk_mul_f32 v[94:95], v[94:95], v[242:243]
	v_pk_mul_f32 v[88:89], v[88:89], v[244:245]
	v_pk_mul_f32 v[90:91], v[90:91], v[246:247]
	s_waitcnt vmcnt(10)
;     template <int KIND> __device__ __forceinline__ void run(f32x4 (&acc)[2][2][4][2], const Unit& u, int tid_in) const {
;     ...
;                     for (int ml = 0; ml < 2; ++ml) { const int m = mh * 2 + ml; qa[ml] = gst[(size_t)r * 4096 + (ai * 4 + m) * 512 + tid]; qb[ml] = (r < 2) ? gst[(size_t)(r + 1) * 4096 + (ai * 4 + m) * 512 + tid] : qa[ml]; }
; #pragma unroll
;                     for (int ml = 0; ml < 2; ++ml) { const int m = mh * 2 + ml; int row = rbase + ai * 128 + m * 16; asm volatile("" : "+v"(row));
; #pragma unroll
;                         for (int bj = 0; bj < 2; ++bj) {
;                             const f32x4 n0 = unpack4_raw(bj == 0 ? qa[ml].x : qa[ml].z), n1 = unpack4_raw(bj == 0 ? qa[ml].y : qa[ml].w);
;                             if (r < 2) { const f32x4 d0 = unpack4_raw(bj == 0 ? qb[ml].x : qb[ml].z), d1 = unpack4_raw(bj == 0 ? qb[ml].y : qb[ml].w);
; #pragma unroll
;                                 for (int j = 0; j < 4; ++j) { acc[ai][bj][m][0][j] *= n0[j] * __builtin_amdgcn_rcpf(d0[j]); acc[ai][bj][m][1][j] *= n1[j] * __builtin_amdgcn_rcpf(d1[j]); } }
	v_cvt_f32_ubyte0_e32 v240, v144
	v_cvt_f32_ubyte1_e32 v241, v144
	v_cvt_f32_ubyte2_e32 v242, v144
	v_cvt_f32_ubyte3_e32 v243, v144
	v_cvt_f32_ubyte0_e32 v244, v145
	v_cvt_f32_ubyte1_e32 v245, v145
	v_cvt_f32_ubyte2_e32 v246, v145
	v_cvt_f32_ubyte3_e32 v247, v145
	v_cvt_f32_ubyte0_e32 v248, v220
	v_cvt_f32_ubyte1_e32 v249, v220
	v_cvt_f32_ubyte2_e32 v250, v220
	v_cvt_f32_ubyte3_e32 v251, v220
	v_cvt_f32_ubyte0_e32 v252, v221
	v_cvt_f32_ubyte1_e32 v253, v221
	v_cvt_f32_ubyte2_e32 v254, v221
	v_cvt_f32_ubyte3_e32 v255, v221
	v_rcp_iflag_f32_e32 v248, v248
	v_rcp_iflag_f32_e32 v249, v249
	v_rcp_iflag_f32_e32 v250, v250
	v_rcp_iflag_f32_e32 v251, v251
	v_rcp_iflag_f32_e32 v252, v252
	v_rcp_iflag_f32_e32 v253, v253
	v_rcp_iflag_f32_e32 v254, v254
	v_rcp_iflag_f32_e32 v255, v255
	v_pk_mul_f32 v[240:241], v[248:249], v[240:241]
	v_pk_mul_f32 v[242:243], v[250:251], v[242:243]
	v_pk_mul_f32 v[244:245], v[252:253], v[244:245]
	v_pk_mul_f32 v[246:247], v[254:255], v[246:247]
	v_pk_mul_f32 v[124:125], v[124:125], v[240:241]
	v_pk_mul_f32 v[126:127], v[126:127], v[242:243]
	v_pk_mul_f32 v[120:121], v[120:121], v[244:245]
	v_pk_mul_f32 v[122:123], v[122:123], v[246:247]
	v_cvt_f32_ubyte0_e32 v240, v146
	v_cvt_f32_ubyte1_e32 v241, v146
	v_cvt_f32_ubyte2_e32 v242, v146
	v_cvt_f32_ubyte3_e32 v243, v146
	v_cvt_f32_ubyte0_e32 v244, v147
	v_cvt_f32_ubyte1_e32 v245, v147
	v_cvt_f32_ubyte2_e32 v246, v147
	v_cvt_f32_ubyte3_e32 v247, v147
	v_cvt_f32_ubyte0_e32 v248, v222
	v_cvt_f32_ubyte1_e32 v249, v222
	v_cvt_f32_ubyte2_e32 v250, v222
	v_cvt_f32_ubyte3_e32 v251, v222
	v_cvt_f32_ubyte0_e32 v252, v223
	v_cvt_f32_ubyte1_e32 v253, v223
	v_cvt_f32_ubyte2_e32 v254, v223
	v_cvt_f32_ubyte3_e32 v255, v223
	v_rcp_iflag_f32_e32 v248, v248
	v_rcp_iflag_f32_e32 v249, v249
	v_rcp_iflag_f32_e32 v250, v250
	v_rcp_iflag_f32_e32 v251, v251
	v_rcp_iflag_f32_e32 v252, v252
	v_rcp_iflag_f32_e32 v253, v253
	v_rcp_iflag_f32_e32 v254, v254
	v_rcp_iflag_f32_e32 v255, v255
	v_pk_mul_f32 v[240:241], v[248:249], v[240:241]
	v_pk_mul_f32 v[242:243], v[250:251], v[242:243]
	v_pk_mul_f32 v[244:245], v[252:253], v[244:245]
	v_pk_mul_f32 v[246:247], v[254:255], v[246:247]
	v_pk_mul_f32 v[84:85], v[84:85], v[240:241]
	v_pk_mul_f32 v[86:87], v[86:87], v[242:243]
	v_pk_mul_f32 v[80:81], v[80:81], v[244:245]
	v_pk_mul_f32 v[82:83], v[82:83], v[246:247]
	s_waitcnt vmcnt(8)
	v_cvt_f32_ubyte0_e32 v240, v148
	v_cvt_f32_ubyte1_e32 v241, v148
	v_cvt_f32_ubyte2_e32 v242, v148
	v_cvt_f32_ubyte3_e32 v243, v148
	v_cvt_f32_ubyte0_e32 v244, v149
	v_cvt_f32_ubyte1_e32 v245, v149
	v_cvt_f32_ubyte2_e32 v246, v149
	v_cvt_f32_ubyte3_e32 v247, v149
	v_cvt_f32_ubyte0_e32 v248, v224
	v_cvt_f32_ubyte1_e32 v249, v224
	v_cvt_f32_ubyte2_e32 v250, v224
	v_cvt_f32_ubyte3_e32 v251, v224
	v_cvt_f32_ubyte0_e32 v252, v225
	v_cvt_f32_ubyte1_e32 v253, v225
	v_cvt_f32_ubyte2_e32 v254, v225
	v_cvt_f32_ubyte3_e32 v255, v225
	v_rcp_iflag_f32_e32 v248, v248
	v_rcp_iflag_f32_e32 v249, v249
	v_rcp_iflag_f32_e32 v250, v250
	v_rcp_iflag_f32_e32 v251, v251
	v_rcp_iflag_f32_e32 v252, v252
	v_rcp_iflag_f32_e32 v253, v253
	v_rcp_iflag_f32_e32 v254, v254
	v_rcp_iflag_f32_e32 v255, v255
	v_pk_mul_f32 v[240:241], v[248:249], v[240:241]
	v_pk_mul_f32 v[242:243], v[250:251], v[242:243]
	v_pk_mul_f32 v[244:245], v[252:253], v[244:245]
	v_pk_mul_f32 v[246:247], v[254:255], v[246:247]
	v_pk_mul_f32 v[116:117], v[116:117], v[240:241]
	v_pk_mul_f32 v[118:119], v[118:119], v[242:243]
	v_pk_mul_f32 v[112:113], v[112:113], v[244:245]
	v_pk_mul_f32 v[114:115], v[114:115], v[246:247]
	v_cvt_f32_ubyte0_e32 v240, v150
	v_cvt_f32_ubyte1_e32 v241, v150
	v_cvt_f32_ubyte2_e32 v242, v150
	v_cvt_f32_ubyte3_e32 v243, v150
	v_cvt_f32_ubyte0_e32 v244, v151
	v_cvt_f32_ubyte1_e32 v245, v151
	v_cvt_f32_ubyte2_e32 v246, v151
	v_cvt_f32_ubyte3_e32 v247, v151
	v_cvt_f32_ubyte0_e32 v248, v226
	v_cvt_f32_ubyte1_e32 v249, v226
	v_cvt_f32_ubyte2_e32 v250, v226
	v_cvt_f32_ubyte3_e32 v251, v226
	v_cvt_f32_ubyte0_e32 v252, v227
	v_cvt_f32_ubyte1_e32 v253, v227
	v_cvt_f32_ubyte2_e32 v254, v227
	v_cvt_f32_ubyte3_e32 v255, v227
	v_rcp_iflag_f32_e32 v248, v248
	v_rcp_iflag_f32_e32 v249, v249
	v_rcp_iflag_f32_e32 v250, v250
	v_rcp_iflag_f32_e32 v251, v251
	v_rcp_iflag_f32_e32 v252, v252
	v_rcp_iflag_f32_e32 v253, v253
	v_rcp_iflag_f32_e32 v254, v254
	v_rcp_iflag_f32_e32 v255, v255
	v_pk_mul_f32 v[240:241], v[248:249], v[240:241]
	v_pk_mul_f32 v[242:243], v[250:251], v[242:243]
	v_pk_mul_f32 v[244:245], v[252:253], v[244:245]
	v_pk_mul_f32 v[246:247], v[254:255], v[246:247]
	v_pk_mul_f32 v[76:77], v[76:77], v[240:241]
	v_pk_mul_f32 v[78:79], v[78:79], v[242:243]
	v_pk_mul_f32 v[72:73], v[72:73], v[244:245]
	v_pk_mul_f32 v[74:75], v[74:75], v[246:247]
	s_waitcnt vmcnt(6)
;     template <int KIND> __device__ __forceinline__ void run(f32x4 (&acc)[2][2][4][2], const Unit& u, int tid_in) const {
;     ...
;                     for (int ml = 0; ml < 2; ++ml) { const int m = mh * 2 + ml; qa[ml] = gst[(size_t)r * 4096 + (ai * 4 + m) * 512 + tid]; qb[ml] = (r < 2) ? gst[(size_t)(r + 1) * 4096 + (ai * 4 + m) * 512 + tid] : qa[ml]; }
; #pragma unroll
;                     for (int ml = 0; ml < 2; ++ml) { const int m = mh * 2 + ml; int row = rbase + ai * 128 + m * 16; asm volatile("" : "+v"(row));
; #pragma unroll
;                         for (int bj = 0; bj < 2; ++bj) {
;                             const f32x4 n0 = unpack4_raw(bj == 0 ? qa[ml].x : qa[ml].z), n1 = unpack4_raw(bj == 0 ? qa[ml].y : qa[ml].w);
;                             if (r < 2) { const f32x4 d0 = unpack4_raw(bj == 0 ? qb[ml].x : qb[ml].z), d1 = unpack4_raw(bj == 0 ? qb[ml].y : qb[ml].w);
; #pragma unroll
;                                 for (int j = 0; j < 4; ++j) { acc[ai][bj][m][0][j] *= n0[j] * __builtin_amdgcn_rcpf(d0[j]); acc[ai][bj][m][1][j] *= n1[j] * __builtin_amdgcn_rcpf(d1[j]); } }
	v_cvt_f32_ubyte0_e32 v240, v196
	v_cvt_f32_ubyte1_e32 v241, v196
	v_cvt_f32_ubyte2_e32 v242, v196
	v_cvt_f32_ubyte3_e32 v243, v196
	v_cvt_f32_ubyte0_e32 v244, v197
	v_cvt_f32_ubyte1_e32 v245, v197
	v_cvt_f32_ubyte2_e32 v246, v197
	v_cvt_f32_ubyte3_e32 v247, v197
	v_cvt_f32_ubyte0_e32 v248, v178
	v_cvt_f32_ubyte1_e32 v249, v178
	v_cvt_f32_ubyte2_e32 v250, v178
	v_cvt_f32_ubyte3_e32 v251, v178
	v_cvt_f32_ubyte0_e32 v252, v179
	v_cvt_f32_ubyte1_e32 v253, v179
	v_cvt_f32_ubyte2_e32 v254, v179
	v_cvt_f32_ubyte3_e32 v255, v179
	v_rcp_iflag_f32_e32 v248, v248
	v_rcp_iflag_f32_e32 v249, v249
	v_rcp_iflag_f32_e32 v250, v250
	v_rcp_iflag_f32_e32 v251, v251
	v_rcp_iflag_f32_e32 v252, v252
	v_rcp_iflag_f32_e32 v253, v253
	v_rcp_iflag_f32_e32 v254, v254
	v_rcp_iflag_f32_e32 v255, v255
	v_pk_mul_f32 v[240:241], v[248:249], v[240:241]
	v_pk_mul_f32 v[242:243], v[250:251], v[242:243]
	v_pk_mul_f32 v[244:245], v[252:253], v[244:245]
	v_pk_mul_f32 v[246:247], v[254:255], v[246:247]
	v_pk_mul_f32 v[68:69], v[68:69], v[240:241]
	v_pk_mul_f32 v[70:71], v[70:71], v[242:243]
	v_pk_mul_f32 v[64:65], v[64:65], v[244:245]
	v_pk_mul_f32 v[66:67], v[66:67], v[246:247]
	v_cvt_f32_ubyte0_e32 v240, v198
	v_cvt_f32_ubyte1_e32 v241, v198
	v_cvt_f32_ubyte2_e32 v242, v198
	v_cvt_f32_ubyte3_e32 v243, v198
	v_cvt_f32_ubyte0_e32 v244, v199
	v_cvt_f32_ubyte1_e32 v245, v199
	v_cvt_f32_ubyte2_e32 v246, v199
	v_cvt_f32_ubyte3_e32 v247, v199
	v_cvt_f32_ubyte0_e32 v248, v180
	v_cvt_f32_ubyte1_e32 v249, v180
	v_cvt_f32_ubyte2_e32 v250, v180
	v_cvt_f32_ubyte3_e32 v251, v180
	v_cvt_f32_ubyte0_e32 v252, v181
	v_cvt_f32_ubyte1_e32 v253, v181
	v_cvt_f32_ubyte2_e32 v254, v181
	v_cvt_f32_ubyte3_e32 v255, v181
	v_rcp_iflag_f32_e32 v248, v248
	v_rcp_iflag_f32_e32 v249, v249
	v_rcp_iflag_f32_e32 v250, v250
	v_rcp_iflag_f32_e32 v251, v251
	v_rcp_iflag_f32_e32 v252, v252
	v_rcp_iflag_f32_e32 v253, v253
	v_rcp_iflag_f32_e32 v254, v254
	v_rcp_iflag_f32_e32 v255, v255
	v_pk_mul_f32 v[240:241], v[248:249], v[240:241]
	v_pk_mul_f32 v[242:243], v[250:251], v[242:243]
	v_pk_mul_f32 v[244:245], v[252:253], v[244:245]
	v_pk_mul_f32 v[246:247], v[254:255], v[246:247]
	v_pk_mul_f32 v[36:37], v[36:37], v[240:241]
	v_pk_mul_f32 v[38:39], v[38:39], v[242:243]
	v_pk_mul_f32 v[32:33], v[32:33], v[244:245]
	v_pk_mul_f32 v[34:35], v[34:35], v[246:247]
	s_waitcnt vmcnt(4)
	v_cvt_f32_ubyte0_e32 v240, v200
	v_cvt_f32_ubyte1_e32 v241, v200
	v_cvt_f32_ubyte2_e32 v242, v200
	v_cvt_f32_ubyte3_e32 v243, v200
	v_cvt_f32_ubyte0_e32 v244, v201
	v_cvt_f32_ubyte1_e32 v245, v201
	v_cvt_f32_ubyte2_e32 v246, v201
	v_cvt_f32_ubyte3_e32 v247, v201
	v_cvt_f32_ubyte0_e32 v248, v182
	v_cvt_f32_ubyte1_e32 v249, v182
	v_cvt_f32_ubyte2_e32 v250, v182
	v_cvt_f32_ubyte3_e32 v251, v182
	v_cvt_f32_ubyte0_e32 v252, v183
	v_cvt_f32_ubyte1_e32 v253, v183
	v_cvt_f32_ubyte2_e32 v254, v183
	v_cvt_f32_ubyte3_e32 v255, v183
	v_rcp_iflag_f32_e32 v248, v248
	v_rcp_iflag_f32_e32 v249, v249
	v_rcp_iflag_f32_e32 v250, v250
	v_rcp_iflag_f32_e32 v251, v251
	v_rcp_iflag_f32_e32 v252, v252
	v_rcp_iflag_f32_e32 v253, v253
	v_rcp_iflag_f32_e32 v254, v254
	v_rcp_iflag_f32_e32 v255, v255
	v_pk_mul_f32 v[240:241], v[248:249], v[240:241]
	v_pk_mul_f32 v[242:243], v[250:251], v[242:243]
	v_pk_mul_f32 v[244:245], v[252:253], v[244:245]
	v_pk_mul_f32 v[246:247], v[254:255], v[246:247]
	v_pk_mul_f32 v[60:61], v[60:61], v[240:241]
	v_pk_mul_f32 v[62:63], v[62:63], v[242:243]
	v_pk_mul_f32 v[56:57], v[56:57], v[244:245]
	v_pk_mul_f32 v[58:59], v[58:59], v[246:247]
	v_cvt_f32_ubyte0_e32 v240, v202
	v_cvt_f32_ubyte1_e32 v241, v202
	v_cvt_f32_ubyte2_e32 v242, v202
	v_cvt_f32_ubyte3_e32 v243, v202
	v_cvt_f32_ubyte0_e32 v244, v203
	v_cvt_f32_ubyte1_e32 v245, v203
	v_cvt_f32_ubyte2_e32 v246, v203
	v_cvt_f32_ubyte3_e32 v247, v203
	v_cvt_f32_ubyte0_e32 v248, v184
	v_cvt_f32_ubyte1_e32 v249, v184
	v_cvt_f32_ubyte2_e32 v250, v184
	v_cvt_f32_ubyte3_e32 v251, v184
	v_cvt_f32_ubyte0_e32 v252, v185
	v_cvt_f32_ubyte1_e32 v253, v185
	v_cvt_f32_ubyte2_e32 v254, v185
	v_cvt_f32_ubyte3_e32 v255, v185
	v_rcp_iflag_f32_e32 v248, v248
	v_rcp_iflag_f32_e32 v249, v249
	v_rcp_iflag_f32_e32 v250, v250
	v_rcp_iflag_f32_e32 v251, v251
	v_rcp_iflag_f32_e32 v252, v252
	v_rcp_iflag_f32_e32 v253, v253
	v_rcp_iflag_f32_e32 v254, v254
	v_rcp_iflag_f32_e32 v255, v255
	v_pk_mul_f32 v[240:241], v[248:249], v[240:241]
	v_pk_mul_f32 v[242:243], v[250:251], v[242:243]
	v_pk_mul_f32 v[244:245], v[252:253], v[244:245]
	v_pk_mul_f32 v[246:247], v[254:255], v[246:247]
	v_pk_mul_f32 v[28:29], v[28:29], v[240:241]
	v_pk_mul_f32 v[30:31], v[30:31], v[242:243]
	v_pk_mul_f32 v[24:25], v[24:25], v[244:245]
	v_pk_mul_f32 v[26:27], v[26:27], v[246:247]
	s_waitcnt vmcnt(2)
;     template <int KIND> __device__ __forceinline__ void run(f32x4 (&acc)[2][2][4][2], const Unit& u, int tid_in) const {
;     ...
;                     for (int ml = 0; ml < 2; ++ml) { const int m = mh * 2 + ml; qa[ml] = gst[(size_t)r * 4096 + (ai * 4 + m) * 512 + tid]; qb[ml] = (r < 2) ? gst[(size_t)(r + 1) * 4096 + (ai * 4 + m) * 512 + tid] : qa[ml]; }
; #pragma unroll
;                     for (int ml = 0; ml < 2; ++ml) { const int m = mh * 2 + ml; int row = rbase + ai * 128 + m * 16; asm volatile("" : "+v"(row));
; #pragma unroll
;                         for (int bj = 0; bj < 2; ++bj) {
;                             const f32x4 n0 = unpack4_raw(bj == 0 ? qa[ml].x : qa[ml].z), n1 = unpack4_raw(bj == 0 ? qa[ml].y : qa[ml].w);
;                             if (r < 2) { const f32x4 d0 = unpack4_raw(bj == 0 ? qb[ml].x : qb[ml].z), d1 = unpack4_raw(bj == 0 ? qb[ml].y : qb[ml].w);
; #pragma unroll
;                                 for (int j = 0; j < 4; ++j) { acc[ai][bj][m][0][j] *= n0[j] * __builtin_amdgcn_rcpf(d0[j]); acc[ai][bj][m][1][j] *= n1[j] * __builtin_amdgcn_rcpf(d1[j]); } }
	v_cvt_f32_ubyte0_e32 v240, v204
	v_cvt_f32_ubyte1_e32 v241, v204
	v_cvt_f32_ubyte2_e32 v242, v204
	v_cvt_f32_ubyte3_e32 v243, v204
	v_cvt_f32_ubyte0_e32 v244, v205
	v_cvt_f32_ubyte1_e32 v245, v205
	v_cvt_f32_ubyte2_e32 v246, v205
	v_cvt_f32_ubyte3_e32 v247, v205
	v_cvt_f32_ubyte0_e32 v248, v158
	v_cvt_f32_ubyte1_e32 v249, v158
	v_cvt_f32_ubyte2_e32 v250, v158
	v_cvt_f32_ubyte3_e32 v251, v158
	v_cvt_f32_ubyte0_e32 v252, v159
	v_cvt_f32_ubyte1_e32 v253, v159
	v_cvt_f32_ubyte2_e32 v254, v159
	v_cvt_f32_ubyte3_e32 v255, v159
	v_rcp_iflag_f32_e32 v248, v248
	v_rcp_iflag_f32_e32 v249, v249
	v_rcp_iflag_f32_e32 v250, v250
	v_rcp_iflag_f32_e32 v251, v251
	v_rcp_iflag_f32_e32 v252, v252
	v_rcp_iflag_f32_e32 v253, v253
	v_rcp_iflag_f32_e32 v254, v254
	v_rcp_iflag_f32_e32 v255, v255
	v_pk_mul_f32 v[240:241], v[248:249], v[240:241]
	v_pk_mul_f32 v[242:243], v[250:251], v[242:243]
	v_pk_mul_f32 v[244:245], v[252:253], v[244:245]
	v_pk_mul_f32 v[246:247], v[254:255], v[246:247]
	v_pk_mul_f32 v[52:53], v[52:53], v[240:241]
	v_pk_mul_f32 v[54:55], v[54:55], v[242:243]
	v_pk_mul_f32 v[48:49], v[48:49], v[244:245]
	v_pk_mul_f32 v[50:51], v[50:51], v[246:247]
	v_cvt_f32_ubyte0_e32 v240, v206
	v_cvt_f32_ubyte1_e32 v241, v206
	v_cvt_f32_ubyte2_e32 v242, v206
	v_cvt_f32_ubyte3_e32 v243, v206
	v_cvt_f32_ubyte0_e32 v244, v207
	v_cvt_f32_ubyte1_e32 v245, v207
	v_cvt_f32_ubyte2_e32 v246, v207
	v_cvt_f32_ubyte3_e32 v247, v207
	v_cvt_f32_ubyte0_e32 v248, v160
	v_cvt_f32_ubyte1_e32 v249, v160
	v_cvt_f32_ubyte2_e32 v250, v160
	v_cvt_f32_ubyte3_e32 v251, v160
	v_cvt_f32_ubyte0_e32 v252, v161
	v_cvt_f32_ubyte1_e32 v253, v161
	v_cvt_f32_ubyte2_e32 v254, v161
	v_cvt_f32_ubyte3_e32 v255, v161
	v_rcp_iflag_f32_e32 v248, v248
	v_rcp_iflag_f32_e32 v249, v249
	v_rcp_iflag_f32_e32 v250, v250
	v_rcp_iflag_f32_e32 v251, v251
	v_rcp_iflag_f32_e32 v252, v252
	v_rcp_iflag_f32_e32 v253, v253
	v_rcp_iflag_f32_e32 v254, v254
	v_rcp_iflag_f32_e32 v255, v255
	v_pk_mul_f32 v[240:241], v[248:249], v[240:241]
	v_pk_mul_f32 v[242:243], v[250:251], v[242:243]
	v_pk_mul_f32 v[244:245], v[252:253], v[244:245]
	v_pk_mul_f32 v[246:247], v[254:255], v[246:247]
	v_pk_mul_f32 v[20:21], v[20:21], v[240:241]
	v_pk_mul_f32 v[22:23], v[22:23], v[242:243]
	v_pk_mul_f32 v[16:17], v[16:17], v[244:245]
	v_pk_mul_f32 v[18:19], v[18:19], v[246:247]
	s_waitcnt vmcnt(0)
	v_cvt_f32_ubyte0_e32 v240, v208
	v_cvt_f32_ubyte1_e32 v241, v208
	v_cvt_f32_ubyte2_e32 v242, v208
	v_cvt_f32_ubyte3_e32 v243, v208
	v_cvt_f32_ubyte0_e32 v244, v209
	v_cvt_f32_ubyte1_e32 v245, v209
	v_cvt_f32_ubyte2_e32 v246, v209
	v_cvt_f32_ubyte3_e32 v247, v209
	v_cvt_f32_ubyte0_e32 v248, v162
	v_cvt_f32_ubyte1_e32 v249, v162
	v_cvt_f32_ubyte2_e32 v250, v162
	v_cvt_f32_ubyte3_e32 v251, v162
	v_cvt_f32_ubyte0_e32 v252, v163
	v_cvt_f32_ubyte1_e32 v253, v163
	v_cvt_f32_ubyte2_e32 v254, v163
	v_cvt_f32_ubyte3_e32 v255, v163
	v_rcp_iflag_f32_e32 v248, v248
	v_rcp_iflag_f32_e32 v249, v249
	v_rcp_iflag_f32_e32 v250, v250
	v_rcp_iflag_f32_e32 v251, v251
	v_rcp_iflag_f32_e32 v252, v252
	v_rcp_iflag_f32_e32 v253, v253
	v_rcp_iflag_f32_e32 v254, v254
	v_rcp_iflag_f32_e32 v255, v255
	v_pk_mul_f32 v[240:241], v[248:249], v[240:241]
	v_pk_mul_f32 v[242:243], v[250:251], v[242:243]
	v_pk_mul_f32 v[244:245], v[252:253], v[244:245]
	v_pk_mul_f32 v[246:247], v[254:255], v[246:247]
	v_pk_mul_f32 v[44:45], v[44:45], v[240:241]
	v_pk_mul_f32 v[46:47], v[46:47], v[242:243]
	v_pk_mul_f32 v[40:41], v[40:41], v[244:245]
	v_pk_mul_f32 v[42:43], v[42:43], v[246:247]
	v_cvt_f32_ubyte0_e32 v240, v210
	v_cvt_f32_ubyte1_e32 v241, v210
	v_cvt_f32_ubyte2_e32 v242, v210
	v_cvt_f32_ubyte3_e32 v243, v210
	v_cvt_f32_ubyte0_e32 v244, v211
	v_cvt_f32_ubyte1_e32 v245, v211
	v_cvt_f32_ubyte2_e32 v246, v211
	v_cvt_f32_ubyte3_e32 v247, v211
	v_cvt_f32_ubyte0_e32 v248, v164
	v_cvt_f32_ubyte1_e32 v249, v164
	v_cvt_f32_ubyte2_e32 v250, v164
	v_cvt_f32_ubyte3_e32 v251, v164
	v_cvt_f32_ubyte0_e32 v252, v165
	v_cvt_f32_ubyte1_e32 v253, v165
	v_cvt_f32_ubyte2_e32 v254, v165
	v_cvt_f32_ubyte3_e32 v255, v165
	v_rcp_iflag_f32_e32 v248, v248
	v_rcp_iflag_f32_e32 v249, v249
	v_rcp_iflag_f32_e32 v250, v250
	v_rcp_iflag_f32_e32 v251, v251
	v_rcp_iflag_f32_e32 v252, v252
	v_rcp_iflag_f32_e32 v253, v253
	v_rcp_iflag_f32_e32 v254, v254
	v_rcp_iflag_f32_e32 v255, v255
	v_pk_mul_f32 v[240:241], v[248:249], v[240:241]
	v_pk_mul_f32 v[242:243], v[250:251], v[242:243]
	v_pk_mul_f32 v[244:245], v[252:253], v[244:245]
	v_pk_mul_f32 v[246:247], v[254:255], v[246:247]
	v_pk_mul_f32 v[12:13], v[12:13], v[240:241]
	v_pk_mul_f32 v[14:15], v[14:15], v[242:243]
	v_pk_mul_f32 v[8:9], v[8:9], v[244:245]
	v_pk_mul_f32 v[10:11], v[10:11], v[246:247]
	s_mov_b64 s[6:7], -1
	s_branch .Lmg1_done
; __device__ __forceinline__ u32x4 pack8(const f32x4 a, const f32x4 b) { u32x4 w; w.x = cvt_pk_bf16(a[0], a[1]); w.y = cvt_pk_bf16(a[2], a[3]); w.z = cvt_pk_bf16(b[0], b[1]); w.w = cvt_pk_bf16(b[2], b[3]); return w; }
;     template <int KIND> __device__ __forceinline__ void run(f32x4 (&acc)[2][2][4][2], const Unit& u, int tid_in) const {
;     ...
;                     for (int ml = 0; ml < 2; ++ml) { const int m = mh * 2 + ml; qa[ml] = gst[(size_t)r * 4096 + (ai * 4 + m) * 512 + tid]; qb[ml] = (r < 2) ? gst[(size_t)(r + 1) * 4096 + (ai * 4 + m) * 512 + tid] : qa[ml]; }
; #pragma unroll
;                     for (int ml = 0; ml < 2; ++ml) { const int m = mh * 2 + ml; int row = rbase + ai * 128 + m * 16; asm volatile("" : "+v"(row));
; #pragma unroll
;                         for (int bj = 0; bj < 2; ++bj) {
;                             const f32x4 n0 = unpack4_raw(bj == 0 ? qa[ml].x : qa[ml].z), n1 = unpack4_raw(bj == 0 ? qa[ml].y : qa[ml].w);
;                             if (r < 2) { const f32x4 d0 = unpack4_raw(bj == 0 ? qb[ml].x : qb[ml].z), d1 = unpack4_raw(bj == 0 ? qb[ml].y : qb[ml].w);
; #pragma unroll
;                                 for (int j = 0; j < 4; ++j) { acc[ai][bj][m][0][j] *= n0[j] * __builtin_amdgcn_rcpf(d0[j]); acc[ai][bj][m][1][j] *= n1[j] * __builtin_amdgcn_rcpf(d1[j]); } }
;                             else { const f32x4 o0 = acc[ai][bj][m][0] * n0 * (1.0f / 255.0f), o1 = acc[ai][bj][m][1] * n1 * (1.0f / 255.0f);
;                                 *(u32x4*)(mg + (size_t)row * 1024 + u.pn * 256 + bj * 128 + cl) = pack8(o0, o1); } } }
.Lmg1_r2:
	global_load_dwordx4 v[136:139], v166, s[4:5]
	s_add_u32 s4, s4, 0x2000
	s_addc_u32 s5, s5, 0
	global_load_dwordx4 v[140:143], v166, s[4:5]
	s_add_u32 s4, s4, 0x2000
	s_addc_u32 s5, s5, 0
	global_load_dwordx4 v[144:147], v166, s[4:5]
	s_add_u32 s4, s4, 0x2000
	s_addc_u32 s5, s5, 0
	global_load_dwordx4 v[148:151], v166, s[4:5]
	s_add_u32 s4, s4, 0x2000
	s_addc_u32 s5, s5, 0
	global_load_dwordx4 v[196:199], v166, s[4:5]
	s_add_u32 s4, s4, 0x2000
	s_addc_u32 s5, s5, 0
	global_load_dwordx4 v[200:203], v166, s[4:5]
	s_add_u32 s4, s4, 0x2000
	s_addc_u32 s5, s5, 0
	global_load_dwordx4 v[204:207], v166, s[4:5]
	s_add_u32 s4, s4, 0x2000
	s_addc_u32 s5, s5, 0
	global_load_dwordx4 v[208:211], v166, s[4:5]
	v_readfirstlane_b32 s18, v174
	s_ashr_i32 s8, s18, 2
	s_andn2_b32 s8, s8, 63
	v_and_or_b32 v167, v174, 15, s8
	v_lshl_add_u32 v167, s33, 8, v167
	s_lshr_b32 s9, s18, 1
	s_and_b32 s9, s9, 0x60
	v_lshrrev_b32_e32 v172, 1, v174
	v_and_or_b32 v172, v172, 24, s9
	v_lshlrev_b32_e32 v172, 1, v172
	v_lshlrev_b32_e32 v167, 11, v167
	s_lshl_b32 s8, s40, 9
	v_add3_u32 v167, v167, v172, s8
	s_mov_b64 s[8:9], s[10:11]
	s_mov_b32 s2, 0x3b808081
	s_waitcnt vmcnt(7)
	v_cvt_f32_ubyte0_e32 v240, v136
	v_cvt_f32_ubyte1_e32 v241, v136
	v_cvt_f32_ubyte2_e32 v242, v136
	v_cvt_f32_ubyte3_e32 v243, v136
	v_cvt_f32_ubyte0_e32 v244, v137
	v_cvt_f32_ubyte1_e32 v245, v137
	v_cvt_f32_ubyte2_e32 v246, v137
	v_cvt_f32_ubyte3_e32 v247, v137
	v_pk_mul_f32 v[248:249], v[104:105], v[240:241]
	v_pk_mul_f32 v[250:251], v[106:107], v[242:243]
	v_pk_mul_f32 v[252:253], v[108:109], v[244:245]
	v_pk_mul_f32 v[254:255], v[110:111], v[246:247]
	v_pk_mul_f32 v[248:249], v[248:249], s[2:3] op_sel_hi:[1,0]
	v_pk_mul_f32 v[250:251], v[250:251], s[2:3] op_sel_hi:[1,0]
	v_pk_mul_f32 v[252:253], v[252:253], s[2:3] op_sel_hi:[1,0]
	v_pk_mul_f32 v[254:255], v[254:255], s[2:3] op_sel_hi:[1,0]
	v_cvt_pk_bf16_f32 v234, v248, v249
	v_cvt_pk_bf16_f32 v235, v250, v251
	v_cvt_pk_bf16_f32 v236, v252, v253
	v_cvt_pk_bf16_f32 v237, v254, v255
	global_store_dwordx4 v167, v[234:237], s[8:9]
	v_cvt_f32_ubyte0_e32 v240, v138
	v_cvt_f32_ubyte1_e32 v241, v138
	v_cvt_f32_ubyte2_e32 v242, v138
	v_cvt_f32_ubyte3_e32 v243, v138
	v_cvt_f32_ubyte0_e32 v244, v139
	v_cvt_f32_ubyte1_e32 v245, v139
	v_cvt_f32_ubyte2_e32 v246, v139
	v_cvt_f32_ubyte3_e32 v247, v139
	v_pk_mul_f32 v[248:249], v[100:101], v[240:241]
	v_pk_mul_f32 v[250:251], v[102:103], v[242:243]
	v_pk_mul_f32 v[252:253], v[96:97], v[244:245]
	v_pk_mul_f32 v[254:255], v[98:99], v[246:247]
	v_pk_mul_f32 v[248:249], v[248:249], s[2:3] op_sel_hi:[1,0]
	v_pk_mul_f32 v[250:251], v[250:251], s[2:3] op_sel_hi:[1,0]
	v_pk_mul_f32 v[252:253], v[252:253], s[2:3] op_sel_hi:[1,0]
	v_pk_mul_f32 v[254:255], v[254:255], s[2:3] op_sel_hi:[1,0]
	v_cvt_pk_bf16_f32 v234, v248, v249
	v_cvt_pk_bf16_f32 v235, v250, v251
	v_cvt_pk_bf16_f32 v236, v252, v253
	v_cvt_pk_bf16_f32 v237, v254, v255
	global_store_dwordx4 v167, v[234:237], s[8:9] offset:256
	s_add_u32 s8, s8, 0x8000
	s_addc_u32 s9, s9, 0
	s_waitcnt vmcnt(8)
	v_cvt_f32_ubyte0_e32 v240, v140
	v_cvt_f32_ubyte1_e32 v241, v140
	v_cvt_f32_ubyte2_e32 v242, v140
	v_cvt_f32_ubyte3_e32 v243, v140
	v_cvt_f32_ubyte0_e32 v244, v141
	v_cvt_f32_ubyte1_e32 v245, v141
	v_cvt_f32_ubyte2_e32 v246, v141
	v_cvt_f32_ubyte3_e32 v247, v141
	v_pk_mul_f32 v[248:249], v[132:133], v[240:241]
	v_pk_mul_f32 v[250:251], v[134:135], v[242:243]
	v_pk_mul_f32 v[252:253], v[128:129], v[244:245]
	v_pk_mul_f32 v[254:255], v[130:131], v[246:247]
	v_pk_mul_f32 v[248:249], v[248:249], s[2:3] op_sel_hi:[1,0]
	v_pk_mul_f32 v[250:251], v[250:251], s[2:3] op_sel_hi:[1,0]
	v_pk_mul_f32 v[252:253], v[252:253], s[2:3] op_sel_hi:[1,0]
	v_pk_mul_f32 v[254:255], v[254:255], s[2:3] op_sel_hi:[1,0]
	v_cvt_pk_bf16_f32 v234, v248, v249
	v_cvt_pk_bf16_f32 v235, v250, v251
	v_cvt_pk_bf16_f32 v236, v252, v253
	v_cvt_pk_bf16_f32 v237, v254, v255
	global_store_dwordx4 v167, v[234:237], s[8:9]
	v_cvt_f32_ubyte0_e32 v240, v142
	v_cvt_f32_ubyte1_e32 v241, v142
	v_cvt_f32_ubyte2_e32 v242, v142
	v_cvt_f32_ubyte3_e32 v243, v142
	v_cvt_f32_ubyte0_e32 v244, v143
	v_cvt_f32_ubyte1_e32 v245, v143
	v_cvt_f32_ubyte2_e32 v246, v143
	v_cvt_f32_ubyte3_e32 v247, v143
	v_pk_mul_f32 v[248:249], v[92:93], v[240:241]
	v_pk_mul_f32 v[250:251], v[94:95], v[242:243]
	v_pk_mul_f32 v[252:253], v[88:89], v[244:245]
	v_pk_mul_f32 v[254:255], v[90:91], v[246:247]
	v_pk_mul_f32 v[248:249], v[248:249], s[2:3] op_sel_hi:[1,0]
	v_pk_mul_f32 v[250:251], v[250:251], s[2:3] op_sel_hi:[1,0]
	v_pk_mul_f32 v[252:253], v[252:253], s[2:3] op_sel_hi:[1,0]
	v_pk_mul_f32 v[254:255], v[254:255], s[2:3] op_sel_hi:[1,0]
	v_cvt_pk_bf16_f32 v234, v248, v249
	v_cvt_pk_bf16_f32 v235, v250, v251
	v_cvt_pk_bf16_f32 v236, v252, v253
	v_cvt_pk_bf16_f32 v237, v254, v255
	global_store_dwordx4 v167, v[234:237], s[8:9] offset:256
	s_add_u32 s8, s8, 0x8000
	s_addc_u32 s9, s9, 0
	s_waitcnt vmcnt(9)
; __device__ __forceinline__ u32x4 pack8(const f32x4 a, const f32x4 b) { u32x4 w; w.x = cvt_pk_bf16(a[0], a[1]); w.y = cvt_pk_bf16(a[2], a[3]); w.z = cvt_pk_bf16(b[0], b[1]); w.w = cvt_pk_bf16(b[2], b[3]); return w; }
; #define MEMFENCE asm volatile("" ::: "memory")
;     template <int KIND> __device__ __forceinline__ void run(f32x4 (&acc)[2][2][4][2], const Unit& u, int tid_in) const {
;     ...
;                     for (int ml = 0; ml < 2; ++ml) { const int m = mh * 2 + ml; int row = rbase + ai * 128 + m * 16; asm volatile("" : "+v"(row));
; #pragma unroll
;                         for (int bj = 0; bj < 2; ++bj) {
;                             const f32x4 n0 = unpack4_raw(bj == 0 ? qa[ml].x : qa[ml].z), n1 = unpack4_raw(bj == 0 ? qa[ml].y : qa[ml].w);
;                             if (r < 2) { const f32x4 d0 = unpack4_raw(bj == 0 ? qb[ml].x : qb[ml].z), d1 = unpack4_raw(bj == 0 ? qb[ml].y : qb[ml].w);
; #pragma unroll
;                                 for (int j = 0; j < 4; ++j) { acc[ai][bj][m][0][j] *= n0[j] * __builtin_amdgcn_rcpf(d0[j]); acc[ai][bj][m][1][j] *= n1[j] * __builtin_amdgcn_rcpf(d1[j]); } }
;                             else { const f32x4 o0 = acc[ai][bj][m][0] * n0 * (1.0f / 255.0f), o1 = acc[ai][bj][m][1] * n1 * (1.0f / 255.0f);
;                                 *(u32x4*)(mg + (size_t)row * 1024 + u.pn * 256 + bj * 128 + cl) = pack8(o0, o1); } } }
;                     MEMFENCE; }
	v_cvt_f32_ubyte0_e32 v240, v144
	v_cvt_f32_ubyte1_e32 v241, v144
	v_cvt_f32_ubyte2_e32 v242, v144
	v_cvt_f32_ubyte3_e32 v243, v144
	v_cvt_f32_ubyte0_e32 v244, v145
	v_cvt_f32_ubyte1_e32 v245, v145
	v_cvt_f32_ubyte2_e32 v246, v145
	v_cvt_f32_ubyte3_e32 v247, v145
	v_pk_mul_f32 v[248:249], v[124:125], v[240:241]
	v_pk_mul_f32 v[250:251], v[126:127], v[242:243]
	v_pk_mul_f32 v[252:253], v[120:121], v[244:245]
	v_pk_mul_f32 v[254:255], v[122:123], v[246:247]
	v_pk_mul_f32 v[248:249], v[248:249], s[2:3] op_sel_hi:[1,0]
	v_pk_mul_f32 v[250:251], v[250:251], s[2:3] op_sel_hi:[1,0]
	v_pk_mul_f32 v[252:253], v[252:253], s[2:3] op_sel_hi:[1,0]
	v_pk_mul_f32 v[254:255], v[254:255], s[2:3] op_sel_hi:[1,0]
	v_cvt_pk_bf16_f32 v234, v248, v249
	v_cvt_pk_bf16_f32 v235, v250, v251
	v_cvt_pk_bf16_f32 v236, v252, v253
	v_cvt_pk_bf16_f32 v237, v254, v255
	global_store_dwordx4 v167, v[234:237], s[8:9]
	v_cvt_f32_ubyte0_e32 v240, v146
	v_cvt_f32_ubyte1_e32 v241, v146
	v_cvt_f32_ubyte2_e32 v242, v146
	v_cvt_f32_ubyte3_e32 v243, v146
	v_cvt_f32_ubyte0_e32 v244, v147
	v_cvt_f32_ubyte1_e32 v245, v147
	v_cvt_f32_ubyte2_e32 v246, v147
	v_cvt_f32_ubyte3_e32 v247, v147
	v_pk_mul_f32 v[248:249], v[84:85], v[240:241]
	v_pk_mul_f32 v[250:251], v[86:87], v[242:243]
	v_pk_mul_f32 v[252:253], v[80:81], v[244:245]
	v_pk_mul_f32 v[254:255], v[82:83], v[246:247]
	v_pk_mul_f32 v[248:249], v[248:249], s[2:3] op_sel_hi:[1,0]
	v_pk_mul_f32 v[250:251], v[250:251], s[2:3] op_sel_hi:[1,0]
	v_pk_mul_f32 v[252:253], v[252:253], s[2:3] op_sel_hi:[1,0]
	v_pk_mul_f32 v[254:255], v[254:255], s[2:3] op_sel_hi:[1,0]
	v_cvt_pk_bf16_f32 v234, v248, v249
	v_cvt_pk_bf16_f32 v235, v250, v251
	v_cvt_pk_bf16_f32 v236, v252, v253
	v_cvt_pk_bf16_f32 v237, v254, v255
	global_store_dwordx4 v167, v[234:237], s[8:9] offset:256
	s_add_u32 s8, s8, 0x8000
	s_addc_u32 s9, s9, 0
	s_waitcnt vmcnt(10)
	v_cvt_f32_ubyte0_e32 v240, v148
	v_cvt_f32_ubyte1_e32 v241, v148
	v_cvt_f32_ubyte2_e32 v242, v148
	v_cvt_f32_ubyte3_e32 v243, v148
	v_cvt_f32_ubyte0_e32 v244, v149
	v_cvt_f32_ubyte1_e32 v245, v149
	v_cvt_f32_ubyte2_e32 v246, v149
	v_cvt_f32_ubyte3_e32 v247, v149
	v_pk_mul_f32 v[248:249], v[116:117], v[240:241]
	v_pk_mul_f32 v[250:251], v[118:119], v[242:243]
	v_pk_mul_f32 v[252:253], v[112:113], v[244:245]
	v_pk_mul_f32 v[254:255], v[114:115], v[246:247]
	v_pk_mul_f32 v[248:249], v[248:249], s[2:3] op_sel_hi:[1,0]
	v_pk_mul_f32 v[250:251], v[250:251], s[2:3] op_sel_hi:[1,0]
	v_pk_mul_f32 v[252:253], v[252:253], s[2:3] op_sel_hi:[1,0]
	v_pk_mul_f32 v[254:255], v[254:255], s[2:3] op_sel_hi:[1,0]
	v_cvt_pk_bf16_f32 v234, v248, v249
	v_cvt_pk_bf16_f32 v235, v250, v251
	v_cvt_pk_bf16_f32 v236, v252, v253
	v_cvt_pk_bf16_f32 v237, v254, v255
	global_store_dwordx4 v167, v[234:237], s[8:9]
	v_cvt_f32_ubyte0_e32 v240, v150
	v_cvt_f32_ubyte1_e32 v241, v150
	v_cvt_f32_ubyte2_e32 v242, v150
	v_cvt_f32_ubyte3_e32 v243, v150
	v_cvt_f32_ubyte0_e32 v244, v151
	v_cvt_f32_ubyte1_e32 v245, v151
	v_cvt_f32_ubyte2_e32 v246, v151
	v_cvt_f32_ubyte3_e32 v247, v151
	v_pk_mul_f32 v[248:249], v[76:77], v[240:241]
	v_pk_mul_f32 v[250:251], v[78:79], v[242:243]
	v_pk_mul_f32 v[252:253], v[72:73], v[244:245]
	v_pk_mul_f32 v[254:255], v[74:75], v[246:247]
	v_pk_mul_f32 v[248:249], v[248:249], s[2:3] op_sel_hi:[1,0]
	v_pk_mul_f32 v[250:251], v[250:251], s[2:3] op_sel_hi:[1,0]
	v_pk_mul_f32 v[252:253], v[252:253], s[2:3] op_sel_hi:[1,0]
	v_pk_mul_f32 v[254:255], v[254:255], s[2:3] op_sel_hi:[1,0]
	v_cvt_pk_bf16_f32 v234, v248, v249
	v_cvt_pk_bf16_f32 v235, v250, v251
	v_cvt_pk_bf16_f32 v236, v252, v253
	v_cvt_pk_bf16_f32 v237, v254, v255
	global_store_dwordx4 v167, v[234:237], s[8:9] offset:256
	s_add_u32 s8, s8, 0x28000
	s_addc_u32 s9, s9, 0
	s_waitcnt vmcnt(11)
	v_cvt_f32_ubyte0_e32 v240, v196
	v_cvt_f32_ubyte1_e32 v241, v196
	v_cvt_f32_ubyte2_e32 v242, v196
	v_cvt_f32_ubyte3_e32 v243, v196
	v_cvt_f32_ubyte0_e32 v244, v197
	v_cvt_f32_ubyte1_e32 v245, v197
	v_cvt_f32_ubyte2_e32 v246, v197
	v_cvt_f32_ubyte3_e32 v247, v197
	v_pk_mul_f32 v[248:249], v[68:69], v[240:241]
	v_pk_mul_f32 v[250:251], v[70:71], v[242:243]
	v_pk_mul_f32 v[252:253], v[64:65], v[244:245]
	v_pk_mul_f32 v[254:255], v[66:67], v[246:247]
	v_pk_mul_f32 v[248:249], v[248:249], s[2:3] op_sel_hi:[1,0]
	v_pk_mul_f32 v[250:251], v[250:251], s[2:3] op_sel_hi:[1,0]
	v_pk_mul_f32 v[252:253], v[252:253], s[2:3] op_sel_hi:[1,0]
	v_pk_mul_f32 v[254:255], v[254:255], s[2:3] op_sel_hi:[1,0]
	v_cvt_pk_bf16_f32 v234, v248, v249
	v_cvt_pk_bf16_f32 v235, v250, v251
	v_cvt_pk_bf16_f32 v236, v252, v253
	v_cvt_pk_bf16_f32 v237, v254, v255
	global_store_dwordx4 v167, v[234:237], s[8:9]
	v_cvt_f32_ubyte0_e32 v240, v198
	v_cvt_f32_ubyte1_e32 v241, v198
	v_cvt_f32_ubyte2_e32 v242, v198
	v_cvt_f32_ubyte3_e32 v243, v198
	v_cvt_f32_ubyte0_e32 v244, v199
	v_cvt_f32_ubyte1_e32 v245, v199
	v_cvt_f32_ubyte2_e32 v246, v199
	v_cvt_f32_ubyte3_e32 v247, v199
	v_pk_mul_f32 v[248:249], v[36:37], v[240:241]
	v_pk_mul_f32 v[250:251], v[38:39], v[242:243]
	v_pk_mul_f32 v[252:253], v[32:33], v[244:245]
	v_pk_mul_f32 v[254:255], v[34:35], v[246:247]
	v_pk_mul_f32 v[248:249], v[248:249], s[2:3] op_sel_hi:[1,0]
	v_pk_mul_f32 v[250:251], v[250:251], s[2:3] op_sel_hi:[1,0]
	v_pk_mul_f32 v[252:253], v[252:253], s[2:3] op_sel_hi:[1,0]
	v_pk_mul_f32 v[254:255], v[254:255], s[2:3] op_sel_hi:[1,0]
	v_cvt_pk_bf16_f32 v234, v248, v249
	v_cvt_pk_bf16_f32 v235, v250, v251
	v_cvt_pk_bf16_f32 v236, v252, v253
	v_cvt_pk_bf16_f32 v237, v254, v255
	global_store_dwordx4 v167, v[234:237], s[8:9] offset:256
	s_add_u32 s8, s8, 0x8000
	s_addc_u32 s9, s9, 0
	s_waitcnt vmcnt(12)
; __device__ __forceinline__ u32x4 pack8(const f32x4 a, const f32x4 b) { u32x4 w; w.x = cvt_pk_bf16(a[0], a[1]); w.y = cvt_pk_bf16(a[2], a[3]); w.z = cvt_pk_bf16(b[0], b[1]); w.w = cvt_pk_bf16(b[2], b[3]); return w; }
; #define MEMFENCE asm volatile("" ::: "memory")
;     template <int KIND> __device__ __forceinline__ void run(f32x4 (&acc)[2][2][4][2], const Unit& u, int tid_in) const {
;     ...
;                     for (int ml = 0; ml < 2; ++ml) { const int m = mh * 2 + ml; int row = rbase + ai * 128 + m * 16; asm volatile("" : "+v"(row));
; #pragma unroll
;                         for (int bj = 0; bj < 2; ++bj) {
;                             const f32x4 n0 = unpack4_raw(bj == 0 ? qa[ml].x : qa[ml].z), n1 = unpack4_raw(bj == 0 ? qa[ml].y : qa[ml].w);
;                             if (r < 2) { const f32x4 d0 = unpack4_raw(bj == 0 ? qb[ml].x : qb[ml].z), d1 = unpack4_raw(bj == 0 ? qb[ml].y : qb[ml].w);
; #pragma unroll
;                                 for (int j = 0; j < 4; ++j) { acc[ai][bj][m][0][j] *= n0[j] * __builtin_amdgcn_rcpf(d0[j]); acc[ai][bj][m][1][j] *= n1[j] * __builtin_amdgcn_rcpf(d1[j]); } }
;                             else { const f32x4 o0 = acc[ai][bj][m][0] * n0 * (1.0f / 255.0f), o1 = acc[ai][bj][m][1] * n1 * (1.0f / 255.0f);
;                                 *(u32x4*)(mg + (size_t)row * 1024 + u.pn * 256 + bj * 128 + cl) = pack8(o0, o1); } } }
;                     MEMFENCE; }
	v_cvt_f32_ubyte0_e32 v240, v200
	v_cvt_f32_ubyte1_e32 v241, v200
	v_cvt_f32_ubyte2_e32 v242, v200
	v_cvt_f32_ubyte3_e32 v243, v200
	v_cvt_f32_ubyte0_e32 v244, v201
	v_cvt_f32_ubyte1_e32 v245, v201
	v_cvt_f32_ubyte2_e32 v246, v201
	v_cvt_f32_ubyte3_e32 v247, v201
	v_pk_mul_f32 v[248:249], v[60:61], v[240:241]
	v_pk_mul_f32 v[250:251], v[62:63], v[242:243]
	v_pk_mul_f32 v[252:253], v[56:57], v[244:245]
	v_pk_mul_f32 v[254:255], v[58:59], v[246:247]
	v_pk_mul_f32 v[248:249], v[248:249], s[2:3] op_sel_hi:[1,0]
	v_pk_mul_f32 v[250:251], v[250:251], s[2:3] op_sel_hi:[1,0]
	v_pk_mul_f32 v[252:253], v[252:253], s[2:3] op_sel_hi:[1,0]
	v_pk_mul_f32 v[254:255], v[254:255], s[2:3] op_sel_hi:[1,0]
	v_cvt_pk_bf16_f32 v234, v248, v249
	v_cvt_pk_bf16_f32 v235, v250, v251
	v_cvt_pk_bf16_f32 v236, v252, v253
	v_cvt_pk_bf16_f32 v237, v254, v255
	global_store_dwordx4 v167, v[234:237], s[8:9]
	v_cvt_f32_ubyte0_e32 v240, v202
	v_cvt_f32_ubyte1_e32 v241, v202
	v_cvt_f32_ubyte2_e32 v242, v202
	v_cvt_f32_ubyte3_e32 v243, v202
	v_cvt_f32_ubyte0_e32 v244, v203
	v_cvt_f32_ubyte1_e32 v245, v203
	v_cvt_f32_ubyte2_e32 v246, v203
	v_cvt_f32_ubyte3_e32 v247, v203
	v_pk_mul_f32 v[248:249], v[28:29], v[240:241]
	v_pk_mul_f32 v[250:251], v[30:31], v[242:243]
	v_pk_mul_f32 v[252:253], v[24:25], v[244:245]
	v_pk_mul_f32 v[254:255], v[26:27], v[246:247]
	v_pk_mul_f32 v[248:249], v[248:249], s[2:3] op_sel_hi:[1,0]
	v_pk_mul_f32 v[250:251], v[250:251], s[2:3] op_sel_hi:[1,0]
	v_pk_mul_f32 v[252:253], v[252:253], s[2:3] op_sel_hi:[1,0]
	v_pk_mul_f32 v[254:255], v[254:255], s[2:3] op_sel_hi:[1,0]
	v_cvt_pk_bf16_f32 v234, v248, v249
	v_cvt_pk_bf16_f32 v235, v250, v251
	v_cvt_pk_bf16_f32 v236, v252, v253
	v_cvt_pk_bf16_f32 v237, v254, v255
	global_store_dwordx4 v167, v[234:237], s[8:9] offset:256
	s_add_u32 s8, s8, 0x8000
	s_addc_u32 s9, s9, 0
	s_waitcnt vmcnt(13)
	v_cvt_f32_ubyte0_e32 v240, v204
	v_cvt_f32_ubyte1_e32 v241, v204
	v_cvt_f32_ubyte2_e32 v242, v204
	v_cvt_f32_ubyte3_e32 v243, v204
	v_cvt_f32_ubyte0_e32 v244, v205
	v_cvt_f32_ubyte1_e32 v245, v205
	v_cvt_f32_ubyte2_e32 v246, v205
	v_cvt_f32_ubyte3_e32 v247, v205
	v_pk_mul_f32 v[248:249], v[52:53], v[240:241]
	v_pk_mul_f32 v[250:251], v[54:55], v[242:243]
	v_pk_mul_f32 v[252:253], v[48:49], v[244:245]
	v_pk_mul_f32 v[254:255], v[50:51], v[246:247]
	v_pk_mul_f32 v[248:249], v[248:249], s[2:3] op_sel_hi:[1,0]
	v_pk_mul_f32 v[250:251], v[250:251], s[2:3] op_sel_hi:[1,0]
	v_pk_mul_f32 v[252:253], v[252:253], s[2:3] op_sel_hi:[1,0]
	v_pk_mul_f32 v[254:255], v[254:255], s[2:3] op_sel_hi:[1,0]
	v_cvt_pk_bf16_f32 v234, v248, v249
	v_cvt_pk_bf16_f32 v235, v250, v251
	v_cvt_pk_bf16_f32 v236, v252, v253
	v_cvt_pk_bf16_f32 v237, v254, v255
	global_store_dwordx4 v167, v[234:237], s[8:9]
	v_cvt_f32_ubyte0_e32 v240, v206
	v_cvt_f32_ubyte1_e32 v241, v206
	v_cvt_f32_ubyte2_e32 v242, v206
	v_cvt_f32_ubyte3_e32 v243, v206
	v_cvt_f32_ubyte0_e32 v244, v207
	v_cvt_f32_ubyte1_e32 v245, v207
	v_cvt_f32_ubyte2_e32 v246, v207
	v_cvt_f32_ubyte3_e32 v247, v207
	v_pk_mul_f32 v[248:249], v[20:21], v[240:241]
	v_pk_mul_f32 v[250:251], v[22:23], v[242:243]
	v_pk_mul_f32 v[252:253], v[16:17], v[244:245]
	v_pk_mul_f32 v[254:255], v[18:19], v[246:247]
	v_pk_mul_f32 v[248:249], v[248:249], s[2:3] op_sel_hi:[1,0]
	v_pk_mul_f32 v[250:251], v[250:251], s[2:3] op_sel_hi:[1,0]
	v_pk_mul_f32 v[252:253], v[252:253], s[2:3] op_sel_hi:[1,0]
	v_pk_mul_f32 v[254:255], v[254:255], s[2:3] op_sel_hi:[1,0]
	v_cvt_pk_bf16_f32 v234, v248, v249
	v_cvt_pk_bf16_f32 v235, v250, v251
	v_cvt_pk_bf16_f32 v236, v252, v253
	v_cvt_pk_bf16_f32 v237, v254, v255
	global_store_dwordx4 v167, v[234:237], s[8:9] offset:256
	s_add_u32 s8, s8, 0x8000
	s_addc_u32 s9, s9, 0
	s_waitcnt vmcnt(14)
	v_cvt_f32_ubyte0_e32 v240, v208
	v_cvt_f32_ubyte1_e32 v241, v208
	v_cvt_f32_ubyte2_e32 v242, v208
	v_cvt_f32_ubyte3_e32 v243, v208
	v_cvt_f32_ubyte0_e32 v244, v209
	v_cvt_f32_ubyte1_e32 v245, v209
	v_cvt_f32_ubyte2_e32 v246, v209
	v_cvt_f32_ubyte3_e32 v247, v209
	v_pk_mul_f32 v[248:249], v[44:45], v[240:241]
	v_pk_mul_f32 v[250:251], v[46:47], v[242:243]
	v_pk_mul_f32 v[252:253], v[40:41], v[244:245]
	v_pk_mul_f32 v[254:255], v[42:43], v[246:247]
	v_pk_mul_f32 v[248:249], v[248:249], s[2:3] op_sel_hi:[1,0]
	v_pk_mul_f32 v[250:251], v[250:251], s[2:3] op_sel_hi:[1,0]
	v_pk_mul_f32 v[252:253], v[252:253], s[2:3] op_sel_hi:[1,0]
	v_pk_mul_f32 v[254:255], v[254:255], s[2:3] op_sel_hi:[1,0]
	v_cvt_pk_bf16_f32 v234, v248, v249
	v_cvt_pk_bf16_f32 v235, v250, v251
	v_cvt_pk_bf16_f32 v236, v252, v253
	v_cvt_pk_bf16_f32 v237, v254, v255
	global_store_dwordx4 v167, v[234:237], s[8:9]
	v_cvt_f32_ubyte0_e32 v240, v210
	v_cvt_f32_ubyte1_e32 v241, v210
	v_cvt_f32_ubyte2_e32 v242, v210
	v_cvt_f32_ubyte3_e32 v243, v210
	v_cvt_f32_ubyte0_e32 v244, v211
	v_cvt_f32_ubyte1_e32 v245, v211
	v_cvt_f32_ubyte2_e32 v246, v211
	v_cvt_f32_ubyte3_e32 v247, v211
	v_pk_mul_f32 v[248:249], v[12:13], v[240:241]
	v_pk_mul_f32 v[250:251], v[14:15], v[242:243]
	v_pk_mul_f32 v[252:253], v[8:9], v[244:245]
	v_pk_mul_f32 v[254:255], v[10:11], v[246:247]
	v_pk_mul_f32 v[248:249], v[248:249], s[2:3] op_sel_hi:[1,0]
	v_pk_mul_f32 v[250:251], v[250:251], s[2:3] op_sel_hi:[1,0]
	v_pk_mul_f32 v[252:253], v[252:253], s[2:3] op_sel_hi:[1,0]
	v_pk_mul_f32 v[254:255], v[254:255], s[2:3] op_sel_hi:[1,0]
	v_cvt_pk_bf16_f32 v234, v248, v249
	v_cvt_pk_bf16_f32 v235, v250, v251
	v_cvt_pk_bf16_f32 v236, v252, v253
	v_cvt_pk_bf16_f32 v237, v254, v255
	global_store_dwordx4 v167, v[234:237], s[8:9] offset:256
	s_mov_b64 s[6:7], 0
.Lmg1_done:
	s_cmpk_gt_u32 s101, 0xff
	s_cbranch_scc0 .Ldb_MG1_nob
	s_barrier
.Ldb_MG1_nob:
	v_readlane_b32 s44, v230, 7
	v_readlane_b32 s45, v230, 8

; #define G_STAGE(bufoff, gbase, o0, h64) do { \
;         __builtin_amdgcn_global_load_lds((const unsigned*)((const char*)(gbase) + (o0)), (LAS unsigned*)(lds + (bufoff) + ldsw), 16, 0, 0); \
;         __builtin_amdgcn_global_load_lds((const unsigned*)((const char*)(gbase) + (h64) + (o0)), (LAS unsigned*)(lds + (bufoff) + ldsw + 8192), 16, 0, 0); } while (0)
; #define G_LDA(dst, b, h) do { _Pragma("unroll") for (int m = 0; m < 4; ++m) _Pragma("unroll") for (int k = 0; k < 2; ++k) dst[m][k] = *(const LAS bf16x8*)(lds + G_SA(b, h) + aoff + m * 2048 + k * 1024); } while (0)
; #define G_LDB(dst, b, h) do { _Pragma("unroll") for (int n = 0; n < 2; ++n) _Pragma("unroll") for (int k = 0; k < 2; ++k) dst[n][k] = *(const LAS bf16x8*)(lds + G_SB(b, h) + boff + n * 2048 + k * 1024); } while (0)
; #define G_WAIT_L(n) asm volatile("s_waitcnt lgkmcnt(" #n ")" ::: "memory")
; #define G_BAR __builtin_amdgcn_s_barrier()
; #define G_SCHED __builtin_amdgcn_sched_barrier(0)
;     ...
;         for (int t = 0; t < nt; t += 2) {
;             const bool last = (t == nt - 2);
;             const char* a1 = cA + (size_t)(t + 1) * ckA;
;             const char* a2 = last ? nA : cA + (size_t)(t + 2) * ckA; const char* b2 = last ? nB : cB + (size_t)(t + 2) * kB;
;             const char* a3 = a2 + ckA; const char* b3 = b2 + kB;
;             G_LDB(B0, 0, 0); G_SCHED; G_LDA(At, 0, 0); G_STAGE(G_SA(1, 1), a1 + chA, cA0, qA);
;             G_WAIT_L(8); G_BAR; G_WAIT_L(0); G_MMA(0, 0, At, B0); G_BAR; G_SCHED;
;             G_LDB(B1, 0, 1); G_STAGE(G_SB(0, 0), b2, cB0, qB);
;             G_BAR; G_WAIT_L(0); G_MMA(0, 1, At, B1); G_BAR;
;             G_LDA(At, 0, 1); G_STAGE(G_SA(0, 0), a2, cA0, qA);
;             G_BAR; G_WAIT_L(0); G_MMA(1, 0, At, B0); G_BAR; G_SCHED;
;             G_STAGE(G_SB(0, 1), b2 + chB, cB0, qB);
.LBB0_1260:
	s_add_u32 s22, s10, s18
	s_addc_u32 s23, s11, s19
	s_add_u32 s20, s22, 0x100
	s_addc_u32 s21, s23, 0
	s_and_b64 s[4:5], s[16:17], exec
	s_cselect_b32 s20, s6, s20
	s_cselect_b32 s21, s7, s21
	s_add_u32 s4, s12, s18
	s_addc_u32 s5, s13, s19
	s_add_u32 s18, s4, 0x100
	s_addc_u32 s19, s5, 0
	s_add_i32 s44, 0, 0x10000
	v_add_u32_e32 v139, s44, v137
	ds_read_b128 v[140:143], v139
	ds_read_b128 v[144:147], v139 offset:1024
	ds_read_b128 v[148:151], v139 offset:2048
	ds_read_b128 v[152:155], v139 offset:3072
	s_and_b64 s[4:5], s[16:17], exec
	s_cselect_b32 s16, s8, s18
	s_cselect_b32 s17, s9, s19
	s_add_i32 s5, 0, 0x14000
	s_add_i32 s43, 0, 0x18000
	s_add_i32 s18, 0, 0x1c000
	s_add_i32 s45, s44, s25
	s_add_i32 s51, s5, s25
	s_add_i32 s19, s43, s25
	s_add_i32 s53, s18, s25
	s_mov_b64 s[64:65], 0x8000
	s_mov_b64 s[62:63], 0x10080
	s_add_i32 m0, s31, 0xc000
	s_add_i32 s4, s31, 0xe000
	s_add_i32 s54, s45, 0x2000
	s_add_i32 s50, s51, 0x2000
	s_add_i32 s44, s19, 0x2000
	s_add_i32 s52, s53, 0x2000
	v_lshl_add_u64 v[184:185], s[22:23], 0, v[2:3]
	v_lshl_add_u64 v[204:205], v[184:185], 0, s[62:63]
	ds_read_b128 v[156:159], v138
	ds_read_b128 v[160:163], v138 offset:1024
	ds_read_b128 v[164:167], v138 offset:2048
	ds_read_b128 v[172:175], v138 offset:3072
	ds_read_b128 v[176:179], v138 offset:4096
	ds_read_b128 v[180:183], v138 offset:5120
	ds_read_b128 v[196:199], v138 offset:6144
	ds_read_b128 v[200:203], v138 offset:7168
	global_load_lds_dwordx4 v[204:205], off
	v_lshl_add_u64 v[184:185], v[184:185], 0, s[68:69]
	s_mov_b32 m0, s4
	s_nop 0
	global_load_lds_dwordx4 v[184:185], off
	s_waitcnt lgkmcnt(8)
	s_barrier
	s_waitcnt lgkmcnt(0)
	s_setprio 3
	s_waitcnt lgkmcnt(0)
	v_mfma_f32_16x16x32_bf16 v[132:135], v[140:143], v[156:159], v[132:135]
	v_mfma_f32_16x16x32_bf16 v[128:131], v[148:151], v[156:159], v[128:131]
	v_mfma_f32_16x16x32_bf16 v[124:127], v[140:143], v[164:167], v[124:127]
	v_mfma_f32_16x16x32_bf16 v[116:119], v[148:151], v[164:167], v[116:119]
	v_mfma_f32_16x16x32_bf16 v[108:111], v[140:143], v[176:179], v[108:111]
	v_mfma_f32_16x16x32_bf16 v[100:103], v[148:151], v[176:179], v[100:103]
	v_mfma_f32_16x16x32_bf16 v[92:95], v[140:143], v[196:199], v[92:95]
	v_mfma_f32_16x16x32_bf16 v[84:87], v[148:151], v[196:199], v[84:87]
	v_mfma_f32_16x16x32_bf16 v[132:135], v[144:147], v[160:163], v[132:135]
	v_mfma_f32_16x16x32_bf16 v[128:131], v[152:155], v[160:163], v[128:131]
	v_mfma_f32_16x16x32_bf16 v[124:127], v[144:147], v[172:175], v[124:127]
	v_mfma_f32_16x16x32_bf16 v[116:119], v[152:155], v[172:175], v[116:119]
	v_mfma_f32_16x16x32_bf16 v[108:111], v[144:147], v[180:183], v[108:111]
	v_mfma_f32_16x16x32_bf16 v[100:103], v[152:155], v[180:183], v[100:103]
	v_mfma_f32_16x16x32_bf16 v[92:95], v[144:147], v[200:203], v[92:95]
	v_mfma_f32_16x16x32_bf16 v[84:87], v[152:155], v[200:203], v[84:87]
	s_setprio 0
	s_barrier
	s_mov_b32 m0, s45
	v_add_u32_e32 v139, s5, v137
	v_lshl_add_u64 v[184:185], s[16:17], 0, v[0:1]
	ds_read_b128 v[204:207], v139
	ds_read_b128 v[208:211], v139 offset:1024
	ds_read_b128 v[212:215], v139 offset:2048
	ds_read_b128 v[216:219], v139 offset:3072
	global_load_lds_dwordx4 v[184:185], off
	v_lshl_add_u64 v[220:221], v[184:185], 0, s[64:65]
	s_mov_b32 m0, s54
	s_nop 0
	global_load_lds_dwordx4 v[220:221], off
	s_barrier
	s_waitcnt lgkmcnt(0)
	s_setprio 3
	s_waitcnt lgkmcnt(0)
	v_mfma_f32_16x16x32_bf16 v[120:123], v[204:207], v[156:159], v[120:123]
	v_mfma_f32_16x16x32_bf16 v[112:115], v[212:215], v[156:159], v[112:115]
	v_mfma_f32_16x16x32_bf16 v[104:107], v[204:207], v[164:167], v[104:107]
	v_mfma_f32_16x16x32_bf16 v[96:99], v[212:215], v[164:167], v[96:99]
	v_mfma_f32_16x16x32_bf16 v[88:91], v[204:207], v[176:179], v[88:91]
	v_mfma_f32_16x16x32_bf16 v[80:83], v[212:215], v[176:179], v[80:83]
	v_mfma_f32_16x16x32_bf16 v[76:79], v[204:207], v[196:199], v[76:79]
	v_mfma_f32_16x16x32_bf16 v[72:75], v[212:215], v[196:199], v[72:75]
	v_mfma_f32_16x16x32_bf16 v[120:123], v[208:211], v[160:163], v[120:123]
	v_mfma_f32_16x16x32_bf16 v[112:115], v[216:219], v[160:163], v[112:115]
	v_mfma_f32_16x16x32_bf16 v[104:107], v[208:211], v[172:175], v[104:107]
	v_mfma_f32_16x16x32_bf16 v[96:99], v[216:219], v[172:175], v[96:99]
	v_mfma_f32_16x16x32_bf16 v[88:91], v[208:211], v[180:183], v[88:91]
	v_mfma_f32_16x16x32_bf16 v[80:83], v[216:219], v[180:183], v[80:83]
	v_mfma_f32_16x16x32_bf16 v[76:79], v[208:211], v[200:203], v[76:79]
	v_mfma_f32_16x16x32_bf16 v[72:75], v[216:219], v[200:203], v[72:75]
	s_setprio 0
	s_mov_b32 m0, s31
	v_lshl_add_u64 v[220:221], s[20:21], 0, v[2:3]
	s_mov_b64 s[4:5], 0x8000
	s_barrier
	ds_read_b128 v[156:159], v138 offset:16384
	ds_read_b128 v[160:163], v138 offset:17408
	ds_read_b128 v[164:167], v138 offset:18432
	ds_read_b128 v[172:175], v138 offset:19456
	ds_read_b128 v[176:179], v138 offset:20480
	ds_read_b128 v[180:183], v138 offset:21504
	ds_read_b128 v[196:199], v138 offset:22528
	ds_read_b128 v[200:203], v138 offset:23552
	global_load_lds_dwordx4 v[220:221], off
	v_lshl_add_u64 v[222:223], v[220:221], 0, s[4:5]
	s_mov_b32 m0, s33
	s_mov_b64 s[16:17], 0x18000
	global_load_lds_dwordx4 v[222:223], off
	s_barrier
; #define G_STAGE(bufoff, gbase, o0, h64) do { \
;         __builtin_amdgcn_global_load_lds((const unsigned*)((const char*)(gbase) + (o0)), (LAS unsigned*)(lds + (bufoff) + ldsw), 16, 0, 0); \
;         __builtin_amdgcn_global_load_lds((const unsigned*)((const char*)(gbase) + (h64) + (o0)), (LAS unsigned*)(lds + (bufoff) + ldsw + 8192), 16, 0, 0); } while (0)
; #define G_LDA(dst, b, h) do { _Pragma("unroll") for (int m = 0; m < 4; ++m) _Pragma("unroll") for (int k = 0; k < 2; ++k) dst[m][k] = *(const LAS bf16x8*)(lds + G_SA(b, h) + aoff + m * 2048 + k * 1024); } while (0)
; #define G_LDB(dst, b, h) do { _Pragma("unroll") for (int n = 0; n < 2; ++n) _Pragma("unroll") for (int k = 0; k < 2; ++k) dst[n][k] = *(const LAS bf16x8*)(lds + G_SB(b, h) + boff + n * 2048 + k * 1024); } while (0)
; #define G_WAIT_V(n) asm volatile("s_waitcnt vmcnt(" #n ")" ::: "memory")
; #define G_WAIT_L(n) asm volatile("s_waitcnt lgkmcnt(" #n ")" ::: "memory")
; #define G_BAR __builtin_amdgcn_s_barrier()
; #define G_SCHED __builtin_amdgcn_sched_barrier(0)
;     ...
;             G_BAR; G_WAIT_L(0); G_MMA(1, 0, At, B0); G_BAR; G_SCHED;
;             G_STAGE(G_SB(0, 1), b2 + chB, cB0, qB);
;             G_WAIT_V(6); G_BAR; G_MMA(1, 1, At, B1); G_BAR;
;             G_LDB(B0, 1, 0); G_SCHED; G_LDA(At, 1, 0); G_STAGE(G_SA(0, 1), a2 + chA, cA0, qA);
;             G_WAIT_L(8); G_BAR; G_WAIT_L(0); G_MMA(0, 0, At, B0); G_BAR; G_SCHED;
	s_waitcnt lgkmcnt(0)
	s_mov_b64 s[20:21], 0x8080
	s_setprio 3
	s_waitcnt lgkmcnt(0)
	v_mfma_f32_16x16x32_bf16 v[68:71], v[140:143], v[156:159], v[68:71]
	v_mfma_f32_16x16x32_bf16 v[64:67], v[148:151], v[156:159], v[64:67]
	v_mfma_f32_16x16x32_bf16 v[60:63], v[140:143], v[164:167], v[60:63]
	v_mfma_f32_16x16x32_bf16 v[52:55], v[148:151], v[164:167], v[52:55]
	v_mfma_f32_16x16x32_bf16 v[44:47], v[140:143], v[176:179], v[44:47]
	v_mfma_f32_16x16x32_bf16 v[36:39], v[148:151], v[176:179], v[36:39]
	v_mfma_f32_16x16x32_bf16 v[28:31], v[140:143], v[196:199], v[28:31]
	v_mfma_f32_16x16x32_bf16 v[20:23], v[148:151], v[196:199], v[20:23]
	v_mfma_f32_16x16x32_bf16 v[68:71], v[144:147], v[160:163], v[68:71]
	v_mfma_f32_16x16x32_bf16 v[64:67], v[152:155], v[160:163], v[64:67]
	v_mfma_f32_16x16x32_bf16 v[60:63], v[144:147], v[172:175], v[60:63]
	v_mfma_f32_16x16x32_bf16 v[52:55], v[152:155], v[172:175], v[52:55]
	v_mfma_f32_16x16x32_bf16 v[44:47], v[144:147], v[180:183], v[44:47]
	v_mfma_f32_16x16x32_bf16 v[36:39], v[152:155], v[180:183], v[36:39]
	v_mfma_f32_16x16x32_bf16 v[28:31], v[144:147], v[200:203], v[28:31]
	v_mfma_f32_16x16x32_bf16 v[20:23], v[152:155], v[200:203], v[20:23]
	s_setprio 0
	s_barrier
	s_mov_b32 m0, s51
	v_lshl_add_u64 v[140:141], v[184:185], 0, s[58:59]
	global_load_lds_dwordx4 v[140:141], off
	v_lshl_add_u64 v[140:141], v[184:185], 0, s[16:17]
	s_mov_b32 m0, s50
	s_nop 0
	global_load_lds_dwordx4 v[140:141], off
	s_waitcnt vmcnt(6)
	s_barrier
	s_setprio 3
	v_mfma_f32_16x16x32_bf16 v[56:59], v[204:207], v[156:159], v[56:59]
	v_mfma_f32_16x16x32_bf16 v[48:51], v[212:215], v[156:159], v[48:51]
	v_mfma_f32_16x16x32_bf16 v[40:43], v[204:207], v[164:167], v[40:43]
	v_mfma_f32_16x16x32_bf16 v[32:35], v[212:215], v[164:167], v[32:35]
	v_mfma_f32_16x16x32_bf16 v[24:27], v[204:207], v[176:179], v[24:27]
	v_mfma_f32_16x16x32_bf16 v[16:19], v[212:215], v[176:179], v[16:19]
	v_mfma_f32_16x16x32_bf16 v[12:15], v[204:207], v[196:199], v[12:15]
	v_mfma_f32_16x16x32_bf16 v[8:11], v[212:215], v[196:199], v[8:11]
	v_mfma_f32_16x16x32_bf16 v[56:59], v[208:211], v[160:163], v[56:59]
	v_mfma_f32_16x16x32_bf16 v[48:51], v[216:219], v[160:163], v[48:51]
	v_mfma_f32_16x16x32_bf16 v[40:43], v[208:211], v[172:175], v[40:43]
	v_mfma_f32_16x16x32_bf16 v[32:35], v[216:219], v[172:175], v[32:35]
	v_mfma_f32_16x16x32_bf16 v[24:27], v[208:211], v[180:183], v[24:27]
	v_mfma_f32_16x16x32_bf16 v[16:19], v[216:219], v[180:183], v[16:19]
	v_mfma_f32_16x16x32_bf16 v[12:15], v[208:211], v[200:203], v[12:15]
	v_mfma_f32_16x16x32_bf16 v[8:11], v[216:219], v[200:203], v[8:11]
	s_setprio 0
	v_add_u32_e32 v139, s43, v137
	s_barrier
	ds_read_b128 v[140:143], v139
	ds_read_b128 v[144:147], v139 offset:1024
	ds_read_b128 v[148:151], v139 offset:2048
	ds_read_b128 v[152:155], v139 offset:3072
	s_mov_b32 m0, s34
	v_lshl_add_u64 v[204:205], v[220:221], 0, s[58:59]
	ds_read_b128 v[156:159], v138 offset:32768
	ds_read_b128 v[160:163], v138 offset:33792
	ds_read_b128 v[164:167], v138 offset:34816
	ds_read_b128 v[172:175], v138 offset:35840
	ds_read_b128 v[176:179], v138 offset:36864
	ds_read_b128 v[180:183], v138 offset:37888
	ds_read_b128 v[196:199], v138 offset:38912
	ds_read_b128 v[200:203], v138 offset:39936
	global_load_lds_dwordx4 v[204:205], off
	v_lshl_add_u64 v[204:205], v[220:221], 0, s[16:17]
	s_mov_b32 m0, s35
	s_nop 0
	global_load_lds_dwordx4 v[204:205], off
	s_waitcnt lgkmcnt(8)
	s_barrier
	s_waitcnt lgkmcnt(0)
	s_setprio 3
	s_waitcnt lgkmcnt(0)
	v_mfma_f32_16x16x32_bf16 v[132:135], v[140:143], v[156:159], v[132:135]
	v_mfma_f32_16x16x32_bf16 v[128:131], v[148:151], v[156:159], v[128:131]
	v_mfma_f32_16x16x32_bf16 v[124:127], v[140:143], v[164:167], v[124:127]
	v_mfma_f32_16x16x32_bf16 v[116:119], v[148:151], v[164:167], v[116:119]
	v_mfma_f32_16x16x32_bf16 v[108:111], v[140:143], v[176:179], v[108:111]
	v_mfma_f32_16x16x32_bf16 v[100:103], v[148:151], v[176:179], v[100:103]
	v_mfma_f32_16x16x32_bf16 v[92:95], v[140:143], v[196:199], v[92:95]
	v_mfma_f32_16x16x32_bf16 v[84:87], v[148:151], v[196:199], v[84:87]
	v_mfma_f32_16x16x32_bf16 v[132:135], v[144:147], v[160:163], v[132:135]
	v_mfma_f32_16x16x32_bf16 v[128:131], v[152:155], v[160:163], v[128:131]
	v_mfma_f32_16x16x32_bf16 v[124:127], v[144:147], v[172:175], v[124:127]
	v_mfma_f32_16x16x32_bf16 v[116:119], v[152:155], v[172:175], v[116:119]
	v_mfma_f32_16x16x32_bf16 v[108:111], v[144:147], v[180:183], v[108:111]
	v_mfma_f32_16x16x32_bf16 v[100:103], v[152:155], v[180:183], v[100:103]
	v_mfma_f32_16x16x32_bf16 v[92:95], v[144:147], v[200:203], v[92:95]
	v_mfma_f32_16x16x32_bf16 v[84:87], v[152:155], v[200:203], v[84:87]
	s_setprio 0
	s_barrier
; #define G_STAGE(bufoff, gbase, o0, h64) do { \
;         __builtin_amdgcn_global_load_lds((const unsigned*)((const char*)(gbase) + (o0)), (LAS unsigned*)(lds + (bufoff) + ldsw), 16, 0, 0); \
;         __builtin_amdgcn_global_load_lds((const unsigned*)((const char*)(gbase) + (h64) + (o0)), (LAS unsigned*)(lds + (bufoff) + ldsw + 8192), 16, 0, 0); } while (0)
; #define G_LDA(dst, b, h) do { _Pragma("unroll") for (int m = 0; m < 4; ++m) _Pragma("unroll") for (int k = 0; k < 2; ++k) dst[m][k] = *(const LAS bf16x8*)(lds + G_SA(b, h) + aoff + m * 2048 + k * 1024); } while (0)
; #define G_LDB(dst, b, h) do { _Pragma("unroll") for (int n = 0; n < 2; ++n) _Pragma("unroll") for (int k = 0; k < 2; ++k) dst[n][k] = *(const LAS bf16x8*)(lds + G_SB(b, h) + boff + n * 2048 + k * 1024); } while (0)
; #define G_WAIT_V(n) asm volatile("s_waitcnt vmcnt(" #n ")" ::: "memory")
; #define G_WAIT_L(n) asm volatile("s_waitcnt lgkmcnt(" #n ")" ::: "memory")
; #define G_BAR __builtin_amdgcn_s_barrier()
; #define G_SCHED __builtin_amdgcn_sched_barrier(0)
;     ...
;             G_LDB(B1, 1, 1); G_STAGE(G_SB(1, 0), b3, cB0, qB);
;             G_BAR; G_WAIT_L(0); G_MMA(0, 1, At, B1); G_BAR;
;             G_LDA(At, 1, 1); G_STAGE(G_SA(1, 0), a3, cA0, qA);
;             G_BAR; G_WAIT_L(0); G_MMA(1, 0, At, B0); G_BAR; G_SCHED;
;             G_STAGE(G_SB(1, 1), b3 + chB, cB0, qB);
;             G_WAIT_V(6); G_BAR; G_MMA(1, 1, At, B1); G_BAR;
;         }
;         E.template run<cs.kind>(acc, cur, tid);
;         if (!has_next) break;
	s_mov_b32 m0, s19
	v_add_u32_e32 v139, s18, v137
	v_lshl_add_u64 v[222:223], v[184:185], 0, s[46:47]
	ds_read_b128 v[204:207], v139
	ds_read_b128 v[208:211], v139 offset:1024
	ds_read_b128 v[212:215], v139 offset:2048
	ds_read_b128 v[216:219], v139 offset:3072
	global_load_lds_dwordx4 v[222:223], off
	v_lshl_add_u64 v[222:223], v[184:185], 0, s[20:21]
	s_mov_b32 m0, s44
	s_mov_b64 s[4:5], 0x10080
	global_load_lds_dwordx4 v[222:223], off
	s_barrier
	s_waitcnt lgkmcnt(0)
	s_setprio 3
	s_waitcnt lgkmcnt(0)
	v_mfma_f32_16x16x32_bf16 v[120:123], v[204:207], v[156:159], v[120:123]
	v_mfma_f32_16x16x32_bf16 v[112:115], v[212:215], v[156:159], v[112:115]
	v_mfma_f32_16x16x32_bf16 v[104:107], v[204:207], v[164:167], v[104:107]
	v_mfma_f32_16x16x32_bf16 v[96:99], v[212:215], v[164:167], v[96:99]
	v_mfma_f32_16x16x32_bf16 v[88:91], v[204:207], v[176:179], v[88:91]
	v_mfma_f32_16x16x32_bf16 v[80:83], v[212:215], v[176:179], v[80:83]
	v_mfma_f32_16x16x32_bf16 v[76:79], v[204:207], v[196:199], v[76:79]
	v_mfma_f32_16x16x32_bf16 v[72:75], v[212:215], v[196:199], v[72:75]
	v_mfma_f32_16x16x32_bf16 v[120:123], v[208:211], v[160:163], v[120:123]
	v_mfma_f32_16x16x32_bf16 v[112:115], v[216:219], v[160:163], v[112:115]
	v_mfma_f32_16x16x32_bf16 v[104:107], v[208:211], v[172:175], v[104:107]
	v_mfma_f32_16x16x32_bf16 v[96:99], v[216:219], v[172:175], v[96:99]
	v_mfma_f32_16x16x32_bf16 v[88:91], v[208:211], v[180:183], v[88:91]
	v_mfma_f32_16x16x32_bf16 v[80:83], v[216:219], v[180:183], v[80:83]
	v_mfma_f32_16x16x32_bf16 v[76:79], v[208:211], v[200:203], v[76:79]
	v_mfma_f32_16x16x32_bf16 v[72:75], v[216:219], v[200:203], v[72:75]
	s_setprio 0
	s_mov_b32 m0, s36
	v_lshl_add_u64 v[222:223], v[220:221], 0, s[46:47]
	s_barrier
	ds_read_b128 v[156:159], v138 offset:49152
	ds_read_b128 v[160:163], v138 offset:50176
	ds_read_b128 v[164:167], v138 offset:51200
	ds_read_b128 v[172:175], v138 offset:52224
	ds_read_b128 v[176:179], v138 offset:53248
	ds_read_b128 v[180:183], v138 offset:54272
	ds_read_b128 v[196:199], v138 offset:55296
	ds_read_b128 v[200:203], v138 offset:56320
	global_load_lds_dwordx4 v[222:223], off
	v_lshl_add_u64 v[220:221], v[220:221], 0, s[20:21]
	s_mov_b32 m0, s37
	s_nop 0
	global_load_lds_dwordx4 v[220:221], off
	s_barrier
	s_waitcnt lgkmcnt(0)
	s_setprio 3
	s_waitcnt lgkmcnt(0)
	v_mfma_f32_16x16x32_bf16 v[68:71], v[140:143], v[156:159], v[68:71]
	v_mfma_f32_16x16x32_bf16 v[64:67], v[148:151], v[156:159], v[64:67]
	v_mfma_f32_16x16x32_bf16 v[60:63], v[140:143], v[164:167], v[60:63]
	v_mfma_f32_16x16x32_bf16 v[52:55], v[148:151], v[164:167], v[52:55]
	v_mfma_f32_16x16x32_bf16 v[44:47], v[140:143], v[176:179], v[44:47]
	v_mfma_f32_16x16x32_bf16 v[36:39], v[148:151], v[176:179], v[36:39]
	v_mfma_f32_16x16x32_bf16 v[28:31], v[140:143], v[196:199], v[28:31]
	v_mfma_f32_16x16x32_bf16 v[20:23], v[148:151], v[196:199], v[20:23]
	v_mfma_f32_16x16x32_bf16 v[68:71], v[144:147], v[160:163], v[68:71]
	v_mfma_f32_16x16x32_bf16 v[64:67], v[152:155], v[160:163], v[64:67]
	v_mfma_f32_16x16x32_bf16 v[60:63], v[144:147], v[172:175], v[60:63]
	v_mfma_f32_16x16x32_bf16 v[52:55], v[152:155], v[172:175], v[52:55]
	v_mfma_f32_16x16x32_bf16 v[44:47], v[144:147], v[180:183], v[44:47]
	v_mfma_f32_16x16x32_bf16 v[36:39], v[152:155], v[180:183], v[36:39]
	v_mfma_f32_16x16x32_bf16 v[28:31], v[144:147], v[200:203], v[28:31]
	v_mfma_f32_16x16x32_bf16 v[20:23], v[152:155], v[200:203], v[20:23]
	s_setprio 0
	s_barrier
	s_mov_b32 m0, s53
	v_lshl_add_u64 v[140:141], v[184:185], 0, s[4:5]
	global_load_lds_dwordx4 v[140:141], off
	v_lshl_add_u64 v[140:141], v[184:185], 0, s[68:69]
	s_mov_b32 m0, s52
	s_nop 0
	global_load_lds_dwordx4 v[140:141], off
	s_waitcnt vmcnt(6)
	s_barrier
	s_setprio 3
	v_mfma_f32_16x16x32_bf16 v[56:59], v[204:207], v[156:159], v[56:59]
	v_mfma_f32_16x16x32_bf16 v[48:51], v[212:215], v[156:159], v[48:51]
	v_mfma_f32_16x16x32_bf16 v[40:43], v[204:207], v[164:167], v[40:43]
	v_mfma_f32_16x16x32_bf16 v[32:35], v[212:215], v[164:167], v[32:35]
	v_mfma_f32_16x16x32_bf16 v[24:27], v[204:207], v[176:179], v[24:27]
	v_mfma_f32_16x16x32_bf16 v[16:19], v[212:215], v[176:179], v[16:19]
	v_mfma_f32_16x16x32_bf16 v[12:15], v[204:207], v[196:199], v[12:15]
	v_mfma_f32_16x16x32_bf16 v[8:11], v[212:215], v[196:199], v[8:11]
	v_mfma_f32_16x16x32_bf16 v[56:59], v[208:211], v[160:163], v[56:59]
	v_mfma_f32_16x16x32_bf16 v[48:51], v[216:219], v[160:163], v[48:51]
	v_mfma_f32_16x16x32_bf16 v[40:43], v[208:211], v[172:175], v[40:43]
	v_mfma_f32_16x16x32_bf16 v[32:35], v[216:219], v[172:175], v[32:35]
	v_mfma_f32_16x16x32_bf16 v[24:27], v[208:211], v[180:183], v[24:27]
	v_mfma_f32_16x16x32_bf16 v[16:19], v[216:219], v[180:183], v[16:19]
	v_mfma_f32_16x16x32_bf16 v[12:15], v[208:211], v[200:203], v[12:15]
	v_mfma_f32_16x16x32_bf16 v[8:11], v[216:219], v[200:203], v[8:11]
	s_setprio 0
	s_andn2_b64 vcc, exec, s[14:15]
	s_mov_b64 s[16:17], -1
	s_mov_b64 s[14:15], 0
	s_mov_b64 s[18:19], 0x100
	s_cbranch_vccz .Ldb_PLE0_cont
	v_readfirstlane_b32 s101, v186
	s_cmpk_gt_u32 s101, 0xff
	s_cbranch_scc1 .Ldb_PLE0_exit
	s_barrier
	s_branch .Ldb_PLE0_exit

; __device__ __forceinline__ u32x4 pack8(const f32x4 a, const f32x4 b) { u32x4 w; w.x = cvt_pk_bf16(a[0], a[1]); w.y = cvt_pk_bf16(a[2], a[3]); w.z = cvt_pk_bf16(b[0], b[1]); w.w = cvt_pk_bf16(b[2], b[3]); return w; }
; #define MEMFENCE asm volatile("" ::: "memory")
;     template <int KIND> __device__ __forceinline__ void run(f32x4 (&acc)[2][2][4][2], const Unit& u, int tid_in) const {
;     ...
;         if constexpr (KIND == K_PP) {
; #pragma unroll
;             for (int ai = 0; ai < 2; ++ai)
; #pragma unroll
;                 for (int m = 0; m < 4; ++m)
; #pragma unroll
;                     for (int bj = 0; bj < 2; ++bj) { scr[((ai * 4 + m) * 2 + bj) * 512 + tid] = pack8(acc[ai][bj][m][0], acc[ai][bj][m][1]); if (bj == 1) MEMFENCE; }
;         }
;     ...
;         E.template run<cs.kind>(acc, cur, tid);
;         if (!has_next) break;
;         if (!(cs.kind == K_MG_B && cur.aux < 2))
.Ldb_PLE0_exit:
	s_lshl_b32 s4, s42, 17
	s_and_b32 s4, s4, 0x20000
	v_mov_b32_e32 v140, v136
	s_add_u32 s4, s38, s4
	s_addc_u32 s5, s39, 0
	v_ashrrev_i32_e32 v141, 31, v140
	v_cvt_pk_bf16_f32 v132, v132, v133
	v_cvt_pk_bf16_f32 v133, v134, v135
	v_cvt_pk_bf16_f32 v134, v128, v129
	v_lshl_add_u64 v[128:129], v[140:141], 4, s[4:5]
	s_movk_i32 s4, 0x2000
	v_cvt_pk_bf16_f32 v135, v130, v131
	global_store_dwordx4 v[128:129], v[132:135], off
	v_cvt_pk_bf16_f32 v120, v120, v121
	v_cvt_pk_bf16_f32 v121, v122, v123
	v_cvt_pk_bf16_f32 v122, v112, v113
	v_add_co_u32_e32 v112, vcc, s4, v128
	v_cvt_pk_bf16_f32 v123, v114, v115
	s_movk_i32 s4, 0x6000
	s_nop 0
	v_addc_co_u32_e32 v113, vcc, 0, v129, vcc
	global_store_dwordx4 v[112:113], v[120:123], off
	v_cvt_pk_bf16_f32 v112, v124, v125
	v_cvt_pk_bf16_f32 v113, v126, v127
	v_cvt_pk_bf16_f32 v114, v116, v117
	v_add_co_u32_e32 v116, vcc, s49, v128
	v_cvt_pk_bf16_f32 v115, v118, v119
	s_mov_b32 s42, s41
	s_nop 0
	v_addc_co_u32_e32 v117, vcc, 0, v129, vcc
	global_store_dwordx4 v[116:117], v[112:115], off
	v_cvt_pk_bf16_f32 v104, v104, v105
	v_cvt_pk_bf16_f32 v105, v106, v107
	v_cvt_pk_bf16_f32 v106, v96, v97
	v_add_co_u32_e32 v96, vcc, s4, v128
	v_cvt_pk_bf16_f32 v107, v98, v99
	s_mov_b32 s4, 0xa000
	s_nop 0
	v_addc_co_u32_e32 v97, vcc, 0, v129, vcc
	global_store_dwordx4 v[96:97], v[104:107], off
	v_cvt_pk_bf16_f32 v96, v108, v109
	v_cvt_pk_bf16_f32 v97, v110, v111
	v_cvt_pk_bf16_f32 v98, v100, v101
	v_add_co_u32_e32 v100, vcc, s77, v128
	v_cvt_pk_bf16_f32 v99, v102, v103
	s_mov_b64 s[12:13], s[8:9]
	s_nop 0
	v_addc_co_u32_e32 v101, vcc, 0, v129, vcc
	global_store_dwordx4 v[100:101], v[96:99], off
	v_cvt_pk_bf16_f32 v88, v88, v89
	v_cvt_pk_bf16_f32 v89, v90, v91
	v_cvt_pk_bf16_f32 v90, v80, v81
	v_add_co_u32_e32 v80, vcc, s4, v128
	v_cvt_pk_bf16_f32 v91, v82, v83
	s_mov_b32 s4, 0xc000
	s_nop 0
	v_addc_co_u32_e32 v81, vcc, 0, v129, vcc
	global_store_dwordx4 v[80:81], v[88:91], off
	v_cvt_pk_bf16_f32 v80, v92, v93
	v_cvt_pk_bf16_f32 v81, v94, v95
	v_cvt_pk_bf16_f32 v82, v84, v85
	v_add_co_u32_e32 v84, vcc, s4, v128
	s_mov_b32 s4, 0xe000
	s_nop 0
	v_addc_co_u32_e32 v85, vcc, 0, v129, vcc
	v_cvt_pk_bf16_f32 v83, v86, v87
	global_store_dwordx4 v[84:85], v[80:83], off
	v_cvt_pk_bf16_f32 v76, v76, v77
	v_cvt_pk_bf16_f32 v77, v78, v79
	v_cvt_pk_bf16_f32 v78, v72, v73
	v_add_co_u32_e32 v72, vcc, s4, v128
	v_cvt_pk_bf16_f32 v79, v74, v75
	s_mov_b32 s4, 0x12000
	s_nop 0
	v_addc_co_u32_e32 v73, vcc, 0, v129, vcc
	global_store_dwordx4 v[72:73], v[76:79], off
	v_cvt_pk_bf16_f32 v68, v68, v69
	v_cvt_pk_bf16_f32 v69, v70, v71
	v_cvt_pk_bf16_f32 v70, v64, v65
	v_add_co_u32_e32 v64, vcc, s91, v128
	v_cvt_pk_bf16_f32 v71, v66, v67
	s_mov_b64 s[10:11], s[6:7]
	s_nop 0
	v_addc_co_u32_e32 v65, vcc, 0, v129, vcc
	global_store_dwordx4 v[64:65], v[68:71], off
	v_cvt_pk_bf16_f32 v56, v56, v57
	v_cvt_pk_bf16_f32 v57, v58, v59
	v_cvt_pk_bf16_f32 v58, v48, v49
	v_add_co_u32_e32 v48, vcc, s4, v128
	v_cvt_pk_bf16_f32 v59, v50, v51
	s_mov_b32 s4, 0x14000
	s_nop 0
	v_addc_co_u32_e32 v49, vcc, 0, v129, vcc
	global_store_dwordx4 v[48:49], v[56:59], off
	v_cvt_pk_bf16_f32 v48, v60, v61
	v_cvt_pk_bf16_f32 v49, v62, v63
	v_cvt_pk_bf16_f32 v50, v52, v53
	v_add_co_u32_e32 v52, vcc, s4, v128
	s_mov_b32 s4, 0x16000
	s_nop 0
	v_addc_co_u32_e32 v53, vcc, 0, v129, vcc
	v_cvt_pk_bf16_f32 v51, v54, v55
	global_store_dwordx4 v[52:53], v[48:51], off
	v_cvt_pk_bf16_f32 v40, v40, v41
	v_cvt_pk_bf16_f32 v41, v42, v43
	v_cvt_pk_bf16_f32 v42, v32, v33
	v_add_co_u32_e32 v32, vcc, s4, v128
	v_cvt_pk_bf16_f32 v43, v34, v35
	s_mov_b32 s4, 0x18000
	s_nop 0
	v_addc_co_u32_e32 v33, vcc, 0, v129, vcc
	global_store_dwordx4 v[32:33], v[40:43], off
	v_cvt_pk_bf16_f32 v32, v44, v45
	v_cvt_pk_bf16_f32 v33, v46, v47
	v_cvt_pk_bf16_f32 v34, v36, v37
	v_add_co_u32_e32 v36, vcc, s4, v128
	s_mov_b32 s4, 0x1a000
	s_nop 0
	v_addc_co_u32_e32 v37, vcc, 0, v129, vcc
	v_cvt_pk_bf16_f32 v35, v38, v39
	global_store_dwordx4 v[36:37], v[32:35], off
	v_cvt_pk_bf16_f32 v24, v24, v25
	v_cvt_pk_bf16_f32 v25, v26, v27
	v_cvt_pk_bf16_f32 v26, v16, v17
	v_add_co_u32_e32 v16, vcc, s4, v128
	v_cvt_pk_bf16_f32 v27, v18, v19
	s_mov_b32 s4, 0x1c000
	s_nop 0
	v_addc_co_u32_e32 v17, vcc, 0, v129, vcc
	global_store_dwordx4 v[16:17], v[24:27], off
	v_cvt_pk_bf16_f32 v16, v28, v29
	v_cvt_pk_bf16_f32 v17, v30, v31
	v_cvt_pk_bf16_f32 v18, v20, v21
	v_add_co_u32_e32 v20, vcc, s4, v128
	v_cvt_pk_bf16_f32 v19, v22, v23
	s_nop 1
	v_addc_co_u32_e32 v21, vcc, 0, v129, vcc
	global_store_dwordx4 v[20:21], v[16:19], off
	v_cvt_pk_bf16_f32 v12, v12, v13
	v_cvt_pk_bf16_f32 v13, v14, v15
	v_cvt_pk_bf16_f32 v14, v8, v9
	v_add_co_u32_e32 v8, vcc, 0x1e000, v128
	v_cvt_pk_bf16_f32 v15, v10, v11
	s_nop 1
	v_addc_co_u32_e32 v9, vcc, 0, v129, vcc
	global_store_dwordx4 v[8:9], v[12:15], off
	s_and_b64 vcc, exec, s[2:3]
	s_cmpk_gt_u32 s101, 0xff
	s_cbranch_scc0 .Ldb_PLE0_nob
	s_barrier
.Ldb_PLE0_nob:
	s_cbranch_vccz .LBB0_1257
	s_waitcnt vmcnt(0)
	s_cmpk_gt_u32 s24, 0xff
	s_cbranch_scc1 .LBB0_1264
	s_barrier
